# MLP-down unrolled K-loop: LDS fragment reads renamed onto 4 rotating register tuples and issued one k-slice ahead, lgkmcnt waits recomputed; MFMA order canonical per K-step
# speedup vs baseline: 1.1040x; 1.0010x over previous
; #define GLOADQ(RA, RB, KT, q) do { const int k0_ = (KT) << 6; \
;     RA[q] = ldg16(ap.ptr(m0 + lrow + 32 * (q), k0_) + lkc); RB[q] = ldg16(W + (size_t)(n0 + lrow + 32 * (q)) * ldw + k0_ + lkc); } while (0)
; #define GLOAD(RA, RB, KT) do { GLOADQ(RA, RB, KT, 0); GLOADQ(RA, RB, KT, 1); GLOADQ(RA, RB, KT, 2); GLOADQ(RA, RB, KT, 3); } while (0)
; #define SSTOREQ(RA, RB, ST, q) do { \
;     *(u32x4*)(sA + (ST) * SBUF + (lrow + 32 * (q)) * GP + lkc) = RA[q]; *(u32x4*)(sB + (ST) * SBUF + (lrow + 32 * (q)) * GP + lkc) = RB[q]; } while (0)
; #define SSTORE(RA, RB, ST) do { SSTOREQ(RA, RB, ST, 0); SSTOREQ(RA, RB, ST, 1); SSTOREQ(RA, RB, ST, 2); SSTOREQ(RA, RB, ST, 3); } while (0)
; #define FLOAD(F, ST, ks) do { _Pragma("unroll") for (int a = 0; a < 2; ++a) { \
;     F[a] = *(const bf16x8*)(sB + (ST) * SBUF + (wn * 64 + a * 32 + r) * GP + (ks) * 16 + h * 8); \
;     F[2 + a] = *(const bf16x8*)(sA + (ST) * SBUF + (wm * 64 + a * 32 + r) * GP + (ks) * 16 + h * 8); } } while (0)
; template <bool MIDK, class AP, class EPI>
; DI void gemm_tile(const AP& ap, const u16* __restrict__ W, int ldw, int K, int m0, int n0, const EPI& epi, char* smem, float r0, float r1, int tid, bool dry) {
;     ...
;   GLOAD(ra0, rb0, 0);
;   GLOAD(ra1, rb1, 1);
;   __syncthreads();
;   SSTORE(ra0, rb0, 0);
;   if (nk > 2) GLOAD(ra0, rb0, 2);
;   __syncthreads();
;   for (int kt = 0; kt < nk; kt += 2) {
;     const bool l3 = kt + 3 < nk, s2 = kt + 2 < nk, l4 = kt + 4 < nk;
;     FLOAD(f0, 0, 0); FLOAD(f1, 0, 1);
;     FMMA(f0); SSTOREQ(ra1, rb1, 1, 0); if (l3) GLOADQ(ra1, rb1, kt + 3, 0);
;     FLOAD(f0, 0, 2);
;     FMMA(f1); SSTOREQ(ra1, rb1, 1, 1); if (l3) GLOADQ(ra1, rb1, kt + 3, 1);
;     FLOAD(f1, 0, 3);
;     FMMA(f0); SSTOREQ(ra1, rb1, 1, 2); if (l3) GLOADQ(ra1, rb1, kt + 3, 2);
;     FMMA(f1); SSTOREQ(ra1, rb1, 1, 3); if (l3) GLOADQ(ra1, rb1, kt + 3, 3);
;     __syncthreads();
;     FLOAD(f0, 1, 0); FLOAD(f1, 1, 1);
;     FMMA(f0); if (s2) SSTOREQ(ra0, rb0, 0, 0); if (l4) GLOADQ(ra0, rb0, kt + 4, 0);
;     FLOAD(f0, 1, 2);
;     FMMA(f1); if (s2) SSTOREQ(ra0, rb0, 0, 1); if (l4) GLOADQ(ra0, rb0, kt + 4, 1);
;     FLOAD(f1, 1, 3);
;     FMMA(f0); if (s2) SSTOREQ(ra0, rb0, 0, 2); if (l4) GLOADQ(ra0, rb0, kt + 4, 2);
;     FMMA(f1); if (s2) SSTOREQ(ra0, rb0, 0, 3); if (l4) GLOADQ(ra0, rb0, kt + 4, 3);
.LBB0_396:
	v_lshl_add_u32 v0, s10, 7, v166
	s_and_b32 s4, s19, 0x380
	v_ashrrev_i32_e32 v1, 31, v0
	v_lshlrev_b64 v[0:1], 13, v[0:1]
	v_add_u32_e32 v4, s4, v166
	v_lshl_add_u64 v[150:151], v[134:135], 0, v[0:1]
	v_ashrrev_i32_e32 v5, 31, v4
	s_mov_b32 s5, 0x41000
	v_lshlrev_b64 v[4:5], 13, v[4:5]
	v_add_co_u32_e32 v138, vcc, s5, v150
	v_lshl_add_u64 v[152:153], v[136:137], 0, v[4:5]
	s_nop 0
	v_addc_co_u32_e32 v139, vcc, 0, v151, vcc
	v_add_co_u32_e32 v140, vcc, s5, v152
	s_mov_b32 s5, 0x81000
	s_nop 0
	v_addc_co_u32_e32 v141, vcc, 0, v153, vcc
	v_add_co_u32_e32 v142, vcc, s5, v150
	global_load_dwordx4 v[0:3], v[150:151], off
	s_nop 0
	v_addc_co_u32_e32 v143, vcc, 0, v151, vcc
	v_add_co_u32_e32 v144, vcc, s5, v152
	s_mov_b32 s5, 0xc1000
	s_nop 0
	v_addc_co_u32_e32 v145, vcc, 0, v153, vcc
	v_add_co_u32_e32 v146, vcc, s5, v150
	global_load_dwordx4 v[4:7], v[152:153], off
	s_nop 0
	v_addc_co_u32_e32 v147, vcc, 0, v151, vcc
	v_add_co_u32_e32 v148, vcc, s5, v152
	global_load_dwordx4 v[8:11], v[138:139], off offset:-4096
	global_load_dwordx4 v[12:15], v[140:141], off offset:-4096
	global_load_dwordx4 v[16:19], v[142:143], off offset:-4096
	global_load_dwordx4 v[20:23], v[144:145], off offset:-4096
	v_addc_co_u32_e32 v149, vcc, 0, v153, vcc
	global_load_dwordx4 v[24:27], v[146:147], off offset:-4096
	global_load_dwordx4 v[28:31], v[148:149], off offset:-4096
	global_load_dwordx4 v[80:83], v[150:151], off offset:128
	s_mov_b64 s[6:7], 0x40000
	s_mov_b64 s[8:9], 0x80000
	s_mov_b64 s[10:11], 0xc0000
	v_lshl_add_u64 v[158:159], v[150:151], 0, s[6:7]
	v_lshl_add_u64 v[156:157], v[150:151], 0, s[8:9]
	v_lshl_add_u64 v[154:155], v[150:151], 0, s[10:11]
	v_lshl_add_u64 v[164:165], v[152:153], 0, s[6:7]
	v_lshl_add_u64 v[162:163], v[152:153], 0, s[8:9]
	v_lshl_add_u64 v[160:161], v[152:153], 0, s[10:11]
	global_load_dwordx4 v[84:87], v[152:153], off offset:128
	global_load_dwordx4 v[88:91], v[158:159], off offset:128
	global_load_dwordx4 v[92:95], v[156:157], off offset:128
	global_load_dwordx4 v[112:115], v[154:155], off offset:128
	global_load_dwordx4 v[104:107], v[164:165], off offset:128
	global_load_dwordx4 v[116:119], v[162:163], off offset:128
	global_load_dwordx4 v[120:123], v[160:161], off offset:128
	s_waitcnt lgkmcnt(0)
	s_barrier
	global_load_dwordx4 v[124:127], v[150:151], off offset:256
	global_load_dwordx4 v[186:189], v[152:153], off offset:256
	global_load_dwordx4 v[96:99], v[158:159], off offset:256
	global_load_dwordx4 v[100:103], v[164:165], off offset:256
	global_load_dwordx4 v[72:75], v[156:157], off offset:256
	global_load_dwordx4 v[76:79], v[162:163], off offset:256
	global_load_dwordx4 v[64:67], v[154:155], off offset:256
	global_load_dwordx4 v[68:71], v[160:161], off offset:256
	s_movk_i32 s5, 0x1000
	s_waitcnt vmcnt(23)
	ds_write_b128 v130, v[0:3]
	s_waitcnt vmcnt(22)
	ds_write_b128 v130, v[4:7] offset:18432
	s_waitcnt vmcnt(21)
	ds_write_b128 v130, v[8:11] offset:4608
	s_waitcnt vmcnt(20)
	ds_write_b128 v130, v[12:15] offset:23040
	s_waitcnt vmcnt(19)
	ds_write_b128 v130, v[16:19] offset:9216
	s_waitcnt vmcnt(18)
	ds_write_b128 v130, v[20:23] offset:27648
	s_waitcnt vmcnt(17)
	ds_write_b128 v130, v[24:27] offset:13824
	s_waitcnt vmcnt(16)
	ds_write_b128 v130, v[28:31] offset:32256
	s_waitcnt lgkmcnt(0)
	s_barrier
	ds_read_b128 v[208:211], v167 offset:18432
	ds_read_b128 v[212:215], v132
	ds_read_b128 v[236:239], v132 offset:4608
	ds_read_b128 v[246:249], v167 offset:23040
	s_waitcnt lgkmcnt(2)
	v_mfma_f32_32x32x16_bf16 v[48:63], v[208:211], v[212:215], 0
	s_waitcnt lgkmcnt(1)
	v_mfma_f32_32x32x16_bf16 v[32:47], v[208:211], v[236:239], 0
	ds_read_b128 v[208:211], v167 offset:18464
	s_waitcnt lgkmcnt(1)
	v_mfma_f32_32x32x16_bf16 v[16:31], v[246:249], v[212:215], 0
	ds_read_b128 v[212:215], v132 offset:32
	v_mfma_f32_32x32x16_bf16 v[0:15], v[246:249], v[236:239], 0
	ds_read_b128 v[246:249], v132 offset:4640
	ds_read_b128 v[236:239], v167 offset:23072
	s_waitcnt vmcnt(15)
	ds_write_b128 v130, v[80:83] offset:36864
	s_waitcnt vmcnt(14)
	ds_write_b128 v130, v[84:87] offset:55296
	s_waitcnt lgkmcnt(4)
	v_mfma_f32_32x32x16_bf16 v[48:63], v[208:211], v[212:215], v[48:63]
	s_waitcnt lgkmcnt(3)
	v_mfma_f32_32x32x16_bf16 v[32:47], v[208:211], v[246:249], v[32:47]
	ds_read_b128 v[208:211], v167 offset:18496
	s_waitcnt lgkmcnt(3)
	v_mfma_f32_32x32x16_bf16 v[16:31], v[236:239], v[212:215], v[16:31]
	ds_read_b128 v[212:215], v132 offset:64
	v_mfma_f32_32x32x16_bf16 v[0:15], v[236:239], v[246:249], v[0:15]
	ds_read_b128 v[236:239], v132 offset:4672
	ds_read_b128 v[246:249], v167 offset:23104
	s_waitcnt lgkmcnt(2)
	v_mfma_f32_32x32x16_bf16 v[48:63], v[208:211], v[212:215], v[48:63]
	s_waitcnt lgkmcnt(1)
	v_mfma_f32_32x32x16_bf16 v[32:47], v[208:211], v[236:239], v[32:47]
	ds_read_b128 v[208:211], v167 offset:18528
	s_waitcnt vmcnt(13)
	ds_write_b128 v130, v[88:91] offset:41472
	s_waitcnt vmcnt(10)
	ds_write_b128 v130, v[104:107] offset:59904
	s_waitcnt lgkmcnt(3)
	v_mfma_f32_32x32x16_bf16 v[16:31], v[246:249], v[212:215], v[16:31]
	ds_read_b128 v[212:215], v132 offset:96
	v_mfma_f32_32x32x16_bf16 v[0:15], v[246:249], v[236:239], v[0:15]
	ds_read_b128 v[246:249], v132 offset:4704
	ds_read_b128 v[236:239], v167 offset:23136
	global_load_dwordx4 v[200:203], v[150:151], off offset:384
	s_waitcnt lgkmcnt(2)
	v_mfma_f32_32x32x16_bf16 v[48:63], v[208:211], v[212:215], v[48:63]
	s_waitcnt lgkmcnt(1)
	v_mfma_f32_32x32x16_bf16 v[32:47], v[208:211], v[246:249], v[32:47]
	s_waitcnt lgkmcnt(0)
	v_mfma_f32_32x32x16_bf16 v[16:31], v[236:239], v[212:215], v[16:31]
	global_load_dwordx4 v[204:207], v[152:153], off offset:384
	global_load_dwordx4 v[104:107], v[158:159], off offset:384
	global_load_dwordx4 v[108:111], v[164:165], off offset:384
	global_load_dwordx4 v[80:83], v[156:157], off offset:384
	global_load_dwordx4 v[84:87], v[162:163], off offset:384
	ds_write_b128 v130, v[92:95] offset:46080
	s_waitcnt vmcnt(15)
	ds_write_b128 v130, v[116:119] offset:64512
	ds_write_b128 v130, v[112:115] offset:50688
	s_waitcnt vmcnt(14)
	ds_write_b128 v131, v[120:123] offset:13824
	v_mfma_f32_32x32x16_bf16 v[0:15], v[236:239], v[246:249], v[0:15]
	global_load_dwordx4 v[88:91], v[154:155], off offset:384
	global_load_dwordx4 v[92:95], v[160:161], off offset:384
	s_waitcnt lgkmcnt(0)
	s_barrier
; #define GLOADQ(RA, RB, KT, q) do { const int k0_ = (KT) << 6; \
;     RA[q] = ldg16(ap.ptr(m0 + lrow + 32 * (q), k0_) + lkc); RB[q] = ldg16(W + (size_t)(n0 + lrow + 32 * (q)) * ldw + k0_ + lkc); } while (0)
; #define SSTOREQ(RA, RB, ST, q) do { \
;     *(u32x4*)(sA + (ST) * SBUF + (lrow + 32 * (q)) * GP + lkc) = RA[q]; *(u32x4*)(sB + (ST) * SBUF + (lrow + 32 * (q)) * GP + lkc) = RB[q]; } while (0)
; #define FLOAD(F, ST, ks) do { _Pragma("unroll") for (int a = 0; a < 2; ++a) { \
;     F[a] = *(const bf16x8*)(sB + (ST) * SBUF + (wn * 64 + a * 32 + r) * GP + (ks) * 16 + h * 8); \
;     F[2 + a] = *(const bf16x8*)(sA + (ST) * SBUF + (wm * 64 + a * 32 + r) * GP + (ks) * 16 + h * 8); } } while (0)
; #define FMMA(F) do { _Pragma("unroll") for (int a = 0; a < 2; ++a) _Pragma("unroll") for (int b = 0; b < 2; ++b) acc[a][b] = MFMA(F[a], F[2 + b], acc[a][b]); } while (0)
; template <bool MIDK, class AP, class EPI>
; DI void gemm_tile(const AP& ap, const u16* __restrict__ W, int ldw, int K, int m0, int n0, const EPI& epi, char* smem, float r0, float r1, int tid, bool dry) {
;     ...
;   for (int kt = 0; kt < nk; kt += 2) {
;     const bool l3 = kt + 3 < nk, s2 = kt + 2 < nk, l4 = kt + 4 < nk;
;     FLOAD(f0, 0, 0); FLOAD(f1, 0, 1);
;     FMMA(f0); SSTOREQ(ra1, rb1, 1, 0); if (l3) GLOADQ(ra1, rb1, kt + 3, 0);
;     FLOAD(f0, 0, 2);
;     FMMA(f1); SSTOREQ(ra1, rb1, 1, 1); if (l3) GLOADQ(ra1, rb1, kt + 3, 1);
;     FLOAD(f1, 0, 3);
;     FMMA(f0); SSTOREQ(ra1, rb1, 1, 2); if (l3) GLOADQ(ra1, rb1, kt + 3, 2);
;     FMMA(f1); SSTOREQ(ra1, rb1, 1, 3); if (l3) GLOADQ(ra1, rb1, kt + 3, 3);
;     __syncthreads();
;     FLOAD(f0, 1, 0); FLOAD(f1, 1, 1);
;     FMMA(f0); if (s2) SSTOREQ(ra0, rb0, 0, 0); if (l4) GLOADQ(ra0, rb0, kt + 4, 0);
;     FLOAD(f0, 1, 2);
;     FMMA(f1); if (s2) SSTOREQ(ra0, rb0, 0, 1); if (l4) GLOADQ(ra0, rb0, kt + 4, 1);
;     FLOAD(f1, 1, 3);
;     FMMA(f0); if (s2) SSTOREQ(ra0, rb0, 0, 2); if (l4) GLOADQ(ra0, rb0, kt + 4, 2);
;     FMMA(f1); if (s2) SSTOREQ(ra0, rb0, 0, 3); if (l4) GLOADQ(ra0, rb0, kt + 4, 3);
	ds_read_b128 v[208:211], v167 offset:55296
	ds_read_b128 v[212:215], v132 offset:36864
	ds_read_b128 v[236:239], v132 offset:41472
	ds_read_b128 v[246:249], v167 offset:59904
	s_waitcnt lgkmcnt(2)
	v_mfma_f32_32x32x16_bf16 v[48:63], v[208:211], v[212:215], v[48:63]
	s_waitcnt lgkmcnt(1)
	v_mfma_f32_32x32x16_bf16 v[32:47], v[208:211], v[236:239], v[32:47]
	ds_read_b128 v[208:211], v167 offset:55328
	s_waitcnt lgkmcnt(1)
	v_mfma_f32_32x32x16_bf16 v[16:31], v[246:249], v[212:215], v[16:31]
	ds_read_b128 v[212:215], v132 offset:36896
	v_mfma_f32_32x32x16_bf16 v[0:15], v[246:249], v[236:239], v[0:15]
	ds_read_b128 v[246:249], v132 offset:41504
	ds_read_b128 v[236:239], v167 offset:59936
	s_waitcnt lgkmcnt(2)
	v_mfma_f32_32x32x16_bf16 v[48:63], v[208:211], v[212:215], v[48:63]
	s_waitcnt lgkmcnt(1)
	v_mfma_f32_32x32x16_bf16 v[32:47], v[208:211], v[246:249], v[32:47]
	ds_read_b128 v[208:211], v167 offset:55360
	s_waitcnt vmcnt(15)
	ds_write_b128 v130, v[124:127]
	s_waitcnt vmcnt(14)
	ds_write_b128 v130, v[186:189] offset:18432
	s_waitcnt lgkmcnt(3)
	v_mfma_f32_32x32x16_bf16 v[16:31], v[236:239], v[212:215], v[16:31]
	ds_read_b128 v[212:215], v132 offset:36928
	v_mfma_f32_32x32x16_bf16 v[0:15], v[236:239], v[246:249], v[0:15]
	ds_read_b128 v[236:239], v132 offset:41536
	ds_read_b128 v[246:249], v167 offset:59968
	s_waitcnt lgkmcnt(2)
	v_mfma_f32_32x32x16_bf16 v[48:63], v[208:211], v[212:215], v[48:63]
	s_waitcnt lgkmcnt(1)
	v_mfma_f32_32x32x16_bf16 v[32:47], v[208:211], v[236:239], v[32:47]
	ds_read_b128 v[208:211], v167 offset:55392
	s_waitcnt vmcnt(13)
	ds_write_b128 v130, v[96:99] offset:4608
	s_waitcnt vmcnt(12)
	ds_write_b128 v130, v[100:103] offset:23040
	s_waitcnt lgkmcnt(3)
	v_mfma_f32_32x32x16_bf16 v[16:31], v[246:249], v[212:215], v[16:31]
	ds_read_b128 v[212:215], v132 offset:36960
	v_mfma_f32_32x32x16_bf16 v[0:15], v[246:249], v[236:239], v[0:15]
	ds_read_b128 v[246:249], v132 offset:41568
	ds_read_b128 v[236:239], v167 offset:60000
	s_waitcnt lgkmcnt(2)
	v_mfma_f32_32x32x16_bf16 v[48:63], v[208:211], v[212:215], v[48:63]
	s_waitcnt lgkmcnt(1)
	v_mfma_f32_32x32x16_bf16 v[32:47], v[208:211], v[246:249], v[32:47]
	s_waitcnt lgkmcnt(0)
	v_mfma_f32_32x32x16_bf16 v[16:31], v[236:239], v[212:215], v[16:31]
	global_load_dwordx4 v[120:123], v[150:151], off offset:512
	global_load_dwordx4 v[124:127], v[152:153], off offset:512
	global_load_dwordx4 v[96:99], v[158:159], off offset:512
	global_load_dwordx4 v[100:103], v[164:165], off offset:512
	s_waitcnt vmcnt(15)
	ds_write_b128 v130, v[72:75] offset:9216
	s_waitcnt vmcnt(14)
	ds_write_b128 v130, v[76:79] offset:27648
	global_load_dwordx4 v[72:75], v[156:157], off offset:512
	global_load_dwordx4 v[76:79], v[162:163], off offset:512
	s_waitcnt vmcnt(15)
	ds_write_b128 v130, v[64:67] offset:13824
	s_waitcnt vmcnt(14)
	ds_write_b128 v130, v[68:71] offset:32256
	global_load_dwordx4 v[64:67], v[154:155], off offset:512
	global_load_dwordx4 v[68:71], v[160:161], off offset:512
	s_waitcnt lgkmcnt(0)
	s_barrier
	ds_read_b128 v[208:211], v167 offset:18432
	ds_read_b128 v[212:215], v132
	v_mfma_f32_32x32x16_bf16 v[0:15], v[236:239], v[246:249], v[0:15]
	ds_read_b128 v[236:239], v132 offset:4608
	ds_read_b128 v[246:249], v167 offset:23040
	s_waitcnt lgkmcnt(2)
	v_mfma_f32_32x32x16_bf16 v[48:63], v[208:211], v[212:215], v[48:63]
	s_waitcnt lgkmcnt(1)
	v_mfma_f32_32x32x16_bf16 v[32:47], v[208:211], v[236:239], v[32:47]
	ds_read_b128 v[208:211], v167 offset:18464
	s_waitcnt lgkmcnt(1)
	v_mfma_f32_32x32x16_bf16 v[16:31], v[246:249], v[212:215], v[16:31]
	ds_read_b128 v[212:215], v132 offset:32
	v_mfma_f32_32x32x16_bf16 v[0:15], v[246:249], v[236:239], v[0:15]
	ds_read_b128 v[246:249], v132 offset:4640
	ds_read_b128 v[236:239], v167 offset:23072
	s_waitcnt lgkmcnt(2)
	v_mfma_f32_32x32x16_bf16 v[48:63], v[208:211], v[212:215], v[48:63]
	s_waitcnt lgkmcnt(1)
	v_mfma_f32_32x32x16_bf16 v[32:47], v[208:211], v[246:249], v[32:47]
	ds_read_b128 v[208:211], v167 offset:18496
	s_waitcnt vmcnt(15)
	ds_write_b128 v130, v[200:203] offset:36864
	s_waitcnt vmcnt(14)
	ds_write_b128 v130, v[204:207] offset:55296
	s_waitcnt lgkmcnt(3)
	v_mfma_f32_32x32x16_bf16 v[16:31], v[236:239], v[212:215], v[16:31]
	ds_read_b128 v[212:215], v132 offset:64
	v_mfma_f32_32x32x16_bf16 v[0:15], v[236:239], v[246:249], v[0:15]
	ds_read_b128 v[236:239], v132 offset:4672
	ds_read_b128 v[246:249], v167 offset:23104
	s_waitcnt lgkmcnt(2)
	v_mfma_f32_32x32x16_bf16 v[48:63], v[208:211], v[212:215], v[48:63]
	s_waitcnt lgkmcnt(1)
	v_mfma_f32_32x32x16_bf16 v[32:47], v[208:211], v[236:239], v[32:47]
	ds_read_b128 v[208:211], v167 offset:18528
	s_waitcnt vmcnt(13)
	ds_write_b128 v130, v[104:107] offset:41472
	s_waitcnt vmcnt(12)
	ds_write_b128 v130, v[108:111] offset:59904
	s_waitcnt lgkmcnt(3)
	v_mfma_f32_32x32x16_bf16 v[16:31], v[246:249], v[212:215], v[16:31]
	ds_read_b128 v[212:215], v132 offset:96
	v_mfma_f32_32x32x16_bf16 v[0:15], v[246:249], v[236:239], v[0:15]
	ds_read_b128 v[246:249], v132 offset:4704
	ds_read_b128 v[236:239], v167 offset:23136
	s_waitcnt lgkmcnt(2)
	v_mfma_f32_32x32x16_bf16 v[48:63], v[208:211], v[212:215], v[48:63]
	s_waitcnt lgkmcnt(1)
	v_mfma_f32_32x32x16_bf16 v[32:47], v[208:211], v[246:249], v[32:47]
	s_waitcnt lgkmcnt(0)
	v_mfma_f32_32x32x16_bf16 v[16:31], v[236:239], v[212:215], v[16:31]
	global_load_dwordx4 v[186:189], v[150:151], off offset:640
	global_load_dwordx4 v[194:197], v[152:153], off offset:640
	global_load_dwordx4 v[104:107], v[158:159], off offset:640
	global_load_dwordx4 v[108:111], v[164:165], off offset:640
	s_waitcnt vmcnt(15)
	ds_write_b128 v130, v[80:83] offset:46080
	s_waitcnt vmcnt(14)
	ds_write_b128 v130, v[84:87] offset:64512
	global_load_dwordx4 v[80:83], v[156:157], off offset:640
	global_load_dwordx4 v[84:87], v[162:163], off offset:640
	s_waitcnt vmcnt(15)
	ds_write_b128 v130, v[88:91] offset:50688
	s_waitcnt vmcnt(14)
	ds_write_b128 v131, v[92:95] offset:13824
	global_load_dwordx4 v[88:91], v[154:155], off offset:640
	global_load_dwordx4 v[92:95], v[160:161], off offset:640
	s_waitcnt lgkmcnt(0)
	s_barrier
; #define GLOADQ(RA, RB, KT, q) do { const int k0_ = (KT) << 6; \
;     RA[q] = ldg16(ap.ptr(m0 + lrow + 32 * (q), k0_) + lkc); RB[q] = ldg16(W + (size_t)(n0 + lrow + 32 * (q)) * ldw + k0_ + lkc); } while (0)
; #define SSTOREQ(RA, RB, ST, q) do { \
;     *(u32x4*)(sA + (ST) * SBUF + (lrow + 32 * (q)) * GP + lkc) = RA[q]; *(u32x4*)(sB + (ST) * SBUF + (lrow + 32 * (q)) * GP + lkc) = RB[q]; } while (0)
; #define FLOAD(F, ST, ks) do { _Pragma("unroll") for (int a = 0; a < 2; ++a) { \
;     F[a] = *(const bf16x8*)(sB + (ST) * SBUF + (wn * 64 + a * 32 + r) * GP + (ks) * 16 + h * 8); \
;     F[2 + a] = *(const bf16x8*)(sA + (ST) * SBUF + (wm * 64 + a * 32 + r) * GP + (ks) * 16 + h * 8); } } while (0)
; #define FMMA(F) do { _Pragma("unroll") for (int a = 0; a < 2; ++a) _Pragma("unroll") for (int b = 0; b < 2; ++b) acc[a][b] = MFMA(F[a], F[2 + b], acc[a][b]); } while (0)
; template <bool MIDK, class AP, class EPI>
; DI void gemm_tile(const AP& ap, const u16* __restrict__ W, int ldw, int K, int m0, int n0, const EPI& epi, char* smem, float r0, float r1, int tid, bool dry) {
;     ...
;   for (int kt = 0; kt < nk; kt += 2) {
;     const bool l3 = kt + 3 < nk, s2 = kt + 2 < nk, l4 = kt + 4 < nk;
;     FLOAD(f0, 0, 0); FLOAD(f1, 0, 1);
;     FMMA(f0); SSTOREQ(ra1, rb1, 1, 0); if (l3) GLOADQ(ra1, rb1, kt + 3, 0);
;     FLOAD(f0, 0, 2);
;     FMMA(f1); SSTOREQ(ra1, rb1, 1, 1); if (l3) GLOADQ(ra1, rb1, kt + 3, 1);
;     FLOAD(f1, 0, 3);
;     FMMA(f0); SSTOREQ(ra1, rb1, 1, 2); if (l3) GLOADQ(ra1, rb1, kt + 3, 2);
;     FMMA(f1); SSTOREQ(ra1, rb1, 1, 3); if (l3) GLOADQ(ra1, rb1, kt + 3, 3);
;     __syncthreads();
;     FLOAD(f0, 1, 0); FLOAD(f1, 1, 1);
;     FMMA(f0); if (s2) SSTOREQ(ra0, rb0, 0, 0); if (l4) GLOADQ(ra0, rb0, kt + 4, 0);
;     FLOAD(f0, 1, 2);
;     FMMA(f1); if (s2) SSTOREQ(ra0, rb0, 0, 1); if (l4) GLOADQ(ra0, rb0, kt + 4, 1);
;     FLOAD(f1, 1, 3);
;     FMMA(f0); if (s2) SSTOREQ(ra0, rb0, 0, 2); if (l4) GLOADQ(ra0, rb0, kt + 4, 2);
;     FMMA(f1); if (s2) SSTOREQ(ra0, rb0, 0, 3); if (l4) GLOADQ(ra0, rb0, kt + 4, 3);
	ds_read_b128 v[208:211], v167 offset:55296
	ds_read_b128 v[212:215], v132 offset:36864
	v_mfma_f32_32x32x16_bf16 v[0:15], v[236:239], v[246:249], v[0:15]
	ds_read_b128 v[236:239], v132 offset:41472
	ds_read_b128 v[246:249], v167 offset:59904
	s_waitcnt lgkmcnt(2)
	v_mfma_f32_32x32x16_bf16 v[48:63], v[208:211], v[212:215], v[48:63]
	s_waitcnt lgkmcnt(1)
	v_mfma_f32_32x32x16_bf16 v[32:47], v[208:211], v[236:239], v[32:47]
	ds_read_b128 v[208:211], v167 offset:55328
	s_waitcnt lgkmcnt(1)
	v_mfma_f32_32x32x16_bf16 v[16:31], v[246:249], v[212:215], v[16:31]
	ds_read_b128 v[212:215], v132 offset:36896
	v_mfma_f32_32x32x16_bf16 v[0:15], v[246:249], v[236:239], v[0:15]
	ds_read_b128 v[246:249], v132 offset:41504
	ds_read_b128 v[236:239], v167 offset:59936
	s_waitcnt lgkmcnt(2)
	v_mfma_f32_32x32x16_bf16 v[48:63], v[208:211], v[212:215], v[48:63]
	s_waitcnt lgkmcnt(1)
	v_mfma_f32_32x32x16_bf16 v[32:47], v[208:211], v[246:249], v[32:47]
	ds_read_b128 v[208:211], v167 offset:55360
	s_waitcnt vmcnt(15)
	ds_write_b128 v130, v[120:123]
	s_waitcnt vmcnt(14)
	ds_write_b128 v130, v[124:127] offset:18432
	s_waitcnt lgkmcnt(3)
	v_mfma_f32_32x32x16_bf16 v[16:31], v[236:239], v[212:215], v[16:31]
	ds_read_b128 v[212:215], v132 offset:36928
	v_mfma_f32_32x32x16_bf16 v[0:15], v[236:239], v[246:249], v[0:15]
	ds_read_b128 v[236:239], v132 offset:41536
	ds_read_b128 v[246:249], v167 offset:59968
	s_waitcnt lgkmcnt(2)
	v_mfma_f32_32x32x16_bf16 v[48:63], v[208:211], v[212:215], v[48:63]
	s_waitcnt lgkmcnt(1)
	v_mfma_f32_32x32x16_bf16 v[32:47], v[208:211], v[236:239], v[32:47]
	ds_read_b128 v[208:211], v167 offset:55392
	s_waitcnt vmcnt(13)
	ds_write_b128 v130, v[96:99] offset:4608
	s_waitcnt vmcnt(12)
	ds_write_b128 v130, v[100:103] offset:23040
	s_waitcnt lgkmcnt(3)
	v_mfma_f32_32x32x16_bf16 v[16:31], v[246:249], v[212:215], v[16:31]
	ds_read_b128 v[212:215], v132 offset:36960
	v_mfma_f32_32x32x16_bf16 v[0:15], v[246:249], v[236:239], v[0:15]
	ds_read_b128 v[246:249], v132 offset:41568
	ds_read_b128 v[236:239], v167 offset:60000
	s_waitcnt lgkmcnt(2)
	v_mfma_f32_32x32x16_bf16 v[48:63], v[208:211], v[212:215], v[48:63]
	s_waitcnt lgkmcnt(1)
	v_mfma_f32_32x32x16_bf16 v[32:47], v[208:211], v[246:249], v[32:47]
	s_waitcnt lgkmcnt(0)
	v_mfma_f32_32x32x16_bf16 v[16:31], v[236:239], v[212:215], v[16:31]
	global_load_dwordx4 v[120:123], v[150:151], off offset:768
	global_load_dwordx4 v[124:127], v[152:153], off offset:768
	global_load_dwordx4 v[96:99], v[158:159], off offset:768
	global_load_dwordx4 v[100:103], v[164:165], off offset:768
	s_waitcnt vmcnt(15)
	ds_write_b128 v130, v[72:75] offset:9216
	s_waitcnt vmcnt(14)
	ds_write_b128 v130, v[76:79] offset:27648
	global_load_dwordx4 v[72:75], v[156:157], off offset:768
	global_load_dwordx4 v[76:79], v[162:163], off offset:768
	s_waitcnt vmcnt(15)
	ds_write_b128 v130, v[64:67] offset:13824
	s_waitcnt vmcnt(14)
	ds_write_b128 v130, v[68:71] offset:32256
	global_load_dwordx4 v[64:67], v[154:155], off offset:768
	global_load_dwordx4 v[68:71], v[160:161], off offset:768
	s_waitcnt lgkmcnt(0)
	s_barrier
	ds_read_b128 v[208:211], v167 offset:18432
	ds_read_b128 v[212:215], v132
	v_mfma_f32_32x32x16_bf16 v[0:15], v[236:239], v[246:249], v[0:15]
	ds_read_b128 v[236:239], v132 offset:4608
	ds_read_b128 v[246:249], v167 offset:23040
	s_waitcnt lgkmcnt(2)
	v_mfma_f32_32x32x16_bf16 v[48:63], v[208:211], v[212:215], v[48:63]
	s_waitcnt lgkmcnt(1)
	v_mfma_f32_32x32x16_bf16 v[32:47], v[208:211], v[236:239], v[32:47]
	ds_read_b128 v[208:211], v167 offset:18464
	s_waitcnt lgkmcnt(1)
	v_mfma_f32_32x32x16_bf16 v[16:31], v[246:249], v[212:215], v[16:31]
	ds_read_b128 v[212:215], v132 offset:32
	v_mfma_f32_32x32x16_bf16 v[0:15], v[246:249], v[236:239], v[0:15]
	ds_read_b128 v[246:249], v132 offset:4640
	ds_read_b128 v[236:239], v167 offset:23072
	s_waitcnt lgkmcnt(2)
	v_mfma_f32_32x32x16_bf16 v[48:63], v[208:211], v[212:215], v[48:63]
	s_waitcnt lgkmcnt(1)
	v_mfma_f32_32x32x16_bf16 v[32:47], v[208:211], v[246:249], v[32:47]
	ds_read_b128 v[208:211], v167 offset:18496
	s_waitcnt vmcnt(15)
	ds_write_b128 v130, v[186:189] offset:36864
	s_waitcnt vmcnt(14)
	ds_write_b128 v130, v[194:197] offset:55296
	s_waitcnt lgkmcnt(3)
	v_mfma_f32_32x32x16_bf16 v[16:31], v[236:239], v[212:215], v[16:31]
	ds_read_b128 v[212:215], v132 offset:64
	v_mfma_f32_32x32x16_bf16 v[0:15], v[236:239], v[246:249], v[0:15]
	ds_read_b128 v[236:239], v132 offset:4672
	ds_read_b128 v[246:249], v167 offset:23104
	s_waitcnt lgkmcnt(2)
	v_mfma_f32_32x32x16_bf16 v[48:63], v[208:211], v[212:215], v[48:63]
	s_waitcnt lgkmcnt(1)
	v_mfma_f32_32x32x16_bf16 v[32:47], v[208:211], v[236:239], v[32:47]
	ds_read_b128 v[208:211], v167 offset:18528
	s_waitcnt vmcnt(13)
	ds_write_b128 v130, v[104:107] offset:41472
	s_waitcnt vmcnt(12)
	ds_write_b128 v130, v[108:111] offset:59904
	s_waitcnt lgkmcnt(3)
	v_mfma_f32_32x32x16_bf16 v[16:31], v[246:249], v[212:215], v[16:31]
	ds_read_b128 v[212:215], v132 offset:96
	v_mfma_f32_32x32x16_bf16 v[0:15], v[246:249], v[236:239], v[0:15]
	ds_read_b128 v[246:249], v132 offset:4704
	ds_read_b128 v[236:239], v167 offset:23136
	s_waitcnt lgkmcnt(2)
	v_mfma_f32_32x32x16_bf16 v[48:63], v[208:211], v[212:215], v[48:63]
	s_waitcnt lgkmcnt(1)
	v_mfma_f32_32x32x16_bf16 v[32:47], v[208:211], v[246:249], v[32:47]
	s_waitcnt lgkmcnt(0)
	v_mfma_f32_32x32x16_bf16 v[16:31], v[236:239], v[212:215], v[16:31]
	global_load_dwordx4 v[186:189], v[150:151], off offset:896
	global_load_dwordx4 v[194:197], v[152:153], off offset:896
	global_load_dwordx4 v[104:107], v[158:159], off offset:896
	global_load_dwordx4 v[108:111], v[164:165], off offset:896
	s_waitcnt vmcnt(15)
	ds_write_b128 v130, v[80:83] offset:46080
	s_waitcnt vmcnt(14)
	ds_write_b128 v130, v[84:87] offset:64512
	global_load_dwordx4 v[80:83], v[156:157], off offset:896
	global_load_dwordx4 v[84:87], v[162:163], off offset:896
	s_waitcnt vmcnt(15)
	ds_write_b128 v130, v[88:91] offset:50688
	s_waitcnt vmcnt(14)
	ds_write_b128 v131, v[92:95] offset:13824
	global_load_dwordx4 v[88:91], v[154:155], off offset:896
	global_load_dwordx4 v[92:95], v[160:161], off offset:896
	s_waitcnt lgkmcnt(0)
	s_barrier
; #define GLOADQ(RA, RB, KT, q) do { const int k0_ = (KT) << 6; \
;     RA[q] = ldg16(ap.ptr(m0 + lrow + 32 * (q), k0_) + lkc); RB[q] = ldg16(W + (size_t)(n0 + lrow + 32 * (q)) * ldw + k0_ + lkc); } while (0)
; #define SSTOREQ(RA, RB, ST, q) do { \
;     *(u32x4*)(sA + (ST) * SBUF + (lrow + 32 * (q)) * GP + lkc) = RA[q]; *(u32x4*)(sB + (ST) * SBUF + (lrow + 32 * (q)) * GP + lkc) = RB[q]; } while (0)
; #define FLOAD(F, ST, ks) do { _Pragma("unroll") for (int a = 0; a < 2; ++a) { \
;     F[a] = *(const bf16x8*)(sB + (ST) * SBUF + (wn * 64 + a * 32 + r) * GP + (ks) * 16 + h * 8); \
;     F[2 + a] = *(const bf16x8*)(sA + (ST) * SBUF + (wm * 64 + a * 32 + r) * GP + (ks) * 16 + h * 8); } } while (0)
; #define FMMA(F) do { _Pragma("unroll") for (int a = 0; a < 2; ++a) _Pragma("unroll") for (int b = 0; b < 2; ++b) acc[a][b] = MFMA(F[a], F[2 + b], acc[a][b]); } while (0)
; template <bool MIDK, class AP, class EPI>
; DI void gemm_tile(const AP& ap, const u16* __restrict__ W, int ldw, int K, int m0, int n0, const EPI& epi, char* smem, float r0, float r1, int tid, bool dry) {
;     ...
;   for (int kt = 0; kt < nk; kt += 2) {
;     const bool l3 = kt + 3 < nk, s2 = kt + 2 < nk, l4 = kt + 4 < nk;
;     FLOAD(f0, 0, 0); FLOAD(f1, 0, 1);
;     FMMA(f0); SSTOREQ(ra1, rb1, 1, 0); if (l3) GLOADQ(ra1, rb1, kt + 3, 0);
;     FLOAD(f0, 0, 2);
;     FMMA(f1); SSTOREQ(ra1, rb1, 1, 1); if (l3) GLOADQ(ra1, rb1, kt + 3, 1);
;     FLOAD(f1, 0, 3);
;     FMMA(f0); SSTOREQ(ra1, rb1, 1, 2); if (l3) GLOADQ(ra1, rb1, kt + 3, 2);
;     FMMA(f1); SSTOREQ(ra1, rb1, 1, 3); if (l3) GLOADQ(ra1, rb1, kt + 3, 3);
;     __syncthreads();
;     FLOAD(f0, 1, 0); FLOAD(f1, 1, 1);
;     FMMA(f0); if (s2) SSTOREQ(ra0, rb0, 0, 0); if (l4) GLOADQ(ra0, rb0, kt + 4, 0);
;     FLOAD(f0, 1, 2);
;     FMMA(f1); if (s2) SSTOREQ(ra0, rb0, 0, 1); if (l4) GLOADQ(ra0, rb0, kt + 4, 1);
;     FLOAD(f1, 1, 3);
;     FMMA(f0); if (s2) SSTOREQ(ra0, rb0, 0, 2); if (l4) GLOADQ(ra0, rb0, kt + 4, 2);
;     FMMA(f1); if (s2) SSTOREQ(ra0, rb0, 0, 3); if (l4) GLOADQ(ra0, rb0, kt + 4, 3);
	ds_read_b128 v[208:211], v167 offset:55296
	ds_read_b128 v[212:215], v132 offset:36864
	v_mfma_f32_32x32x16_bf16 v[0:15], v[236:239], v[246:249], v[0:15]
	ds_read_b128 v[236:239], v132 offset:41472
	ds_read_b128 v[246:249], v167 offset:59904
	s_waitcnt lgkmcnt(2)
	v_mfma_f32_32x32x16_bf16 v[48:63], v[208:211], v[212:215], v[48:63]
	s_waitcnt lgkmcnt(1)
	v_mfma_f32_32x32x16_bf16 v[32:47], v[208:211], v[236:239], v[32:47]
	ds_read_b128 v[208:211], v167 offset:55328
	s_waitcnt lgkmcnt(1)
	v_mfma_f32_32x32x16_bf16 v[16:31], v[246:249], v[212:215], v[16:31]
	ds_read_b128 v[212:215], v132 offset:36896
	v_mfma_f32_32x32x16_bf16 v[0:15], v[246:249], v[236:239], v[0:15]
	ds_read_b128 v[246:249], v132 offset:41504
	ds_read_b128 v[236:239], v167 offset:59936
	s_waitcnt lgkmcnt(2)
	v_mfma_f32_32x32x16_bf16 v[48:63], v[208:211], v[212:215], v[48:63]
	s_waitcnt lgkmcnt(1)
	v_mfma_f32_32x32x16_bf16 v[32:47], v[208:211], v[246:249], v[32:47]
	ds_read_b128 v[208:211], v167 offset:55360
	s_waitcnt vmcnt(15)
	ds_write_b128 v130, v[120:123]
	s_waitcnt vmcnt(14)
	ds_write_b128 v130, v[124:127] offset:18432
	s_waitcnt lgkmcnt(3)
	v_mfma_f32_32x32x16_bf16 v[16:31], v[236:239], v[212:215], v[16:31]
	ds_read_b128 v[212:215], v132 offset:36928
	v_mfma_f32_32x32x16_bf16 v[0:15], v[236:239], v[246:249], v[0:15]
	ds_read_b128 v[236:239], v132 offset:41536
	ds_read_b128 v[246:249], v167 offset:59968
	s_waitcnt lgkmcnt(2)
	v_mfma_f32_32x32x16_bf16 v[48:63], v[208:211], v[212:215], v[48:63]
	s_waitcnt lgkmcnt(1)
	v_mfma_f32_32x32x16_bf16 v[32:47], v[208:211], v[236:239], v[32:47]
	ds_read_b128 v[208:211], v167 offset:55392
	s_waitcnt vmcnt(13)
	ds_write_b128 v130, v[96:99] offset:4608
	s_waitcnt vmcnt(12)
	ds_write_b128 v130, v[100:103] offset:23040
	s_waitcnt lgkmcnt(3)
	v_mfma_f32_32x32x16_bf16 v[16:31], v[246:249], v[212:215], v[16:31]
	ds_read_b128 v[212:215], v132 offset:36960
	v_mfma_f32_32x32x16_bf16 v[0:15], v[246:249], v[236:239], v[0:15]
	ds_read_b128 v[246:249], v132 offset:41568
	ds_read_b128 v[236:239], v167 offset:60000
	s_waitcnt lgkmcnt(2)
	v_mfma_f32_32x32x16_bf16 v[48:63], v[208:211], v[212:215], v[48:63]
	s_waitcnt lgkmcnt(1)
	v_mfma_f32_32x32x16_bf16 v[32:47], v[208:211], v[246:249], v[32:47]
	s_waitcnt lgkmcnt(0)
	v_mfma_f32_32x32x16_bf16 v[16:31], v[236:239], v[212:215], v[16:31]
	global_load_dwordx4 v[120:123], v[150:151], off offset:1024
	global_load_dwordx4 v[124:127], v[152:153], off offset:1024
	global_load_dwordx4 v[96:99], v[158:159], off offset:1024
	global_load_dwordx4 v[100:103], v[164:165], off offset:1024
	s_waitcnt vmcnt(15)
	ds_write_b128 v130, v[72:75] offset:9216
	s_waitcnt vmcnt(14)
	ds_write_b128 v130, v[76:79] offset:27648
	global_load_dwordx4 v[72:75], v[156:157], off offset:1024
	global_load_dwordx4 v[76:79], v[162:163], off offset:1024
	s_waitcnt vmcnt(15)
	ds_write_b128 v130, v[64:67] offset:13824
	s_waitcnt vmcnt(14)
	ds_write_b128 v130, v[68:71] offset:32256
	global_load_dwordx4 v[64:67], v[154:155], off offset:1024
	global_load_dwordx4 v[68:71], v[160:161], off offset:1024
	s_waitcnt lgkmcnt(0)
	s_barrier
	ds_read_b128 v[208:211], v167 offset:18432
	ds_read_b128 v[212:215], v132
	v_mfma_f32_32x32x16_bf16 v[0:15], v[236:239], v[246:249], v[0:15]
	ds_read_b128 v[236:239], v132 offset:4608
	ds_read_b128 v[246:249], v167 offset:23040
	s_waitcnt lgkmcnt(2)
	v_mfma_f32_32x32x16_bf16 v[48:63], v[208:211], v[212:215], v[48:63]
	s_waitcnt lgkmcnt(1)
	v_mfma_f32_32x32x16_bf16 v[32:47], v[208:211], v[236:239], v[32:47]
	ds_read_b128 v[208:211], v167 offset:18464
	s_waitcnt lgkmcnt(1)
	v_mfma_f32_32x32x16_bf16 v[16:31], v[246:249], v[212:215], v[16:31]
	ds_read_b128 v[212:215], v132 offset:32
	v_mfma_f32_32x32x16_bf16 v[0:15], v[246:249], v[236:239], v[0:15]
	ds_read_b128 v[246:249], v132 offset:4640
	ds_read_b128 v[236:239], v167 offset:23072
	s_waitcnt lgkmcnt(2)
	v_mfma_f32_32x32x16_bf16 v[48:63], v[208:211], v[212:215], v[48:63]
	s_waitcnt lgkmcnt(1)
	v_mfma_f32_32x32x16_bf16 v[32:47], v[208:211], v[246:249], v[32:47]
	ds_read_b128 v[208:211], v167 offset:18496
	s_waitcnt vmcnt(15)
	ds_write_b128 v130, v[186:189] offset:36864
	s_waitcnt vmcnt(14)
	ds_write_b128 v130, v[194:197] offset:55296
	s_waitcnt lgkmcnt(3)
	v_mfma_f32_32x32x16_bf16 v[16:31], v[236:239], v[212:215], v[16:31]
	ds_read_b128 v[212:215], v132 offset:64
	v_mfma_f32_32x32x16_bf16 v[0:15], v[236:239], v[246:249], v[0:15]
	ds_read_b128 v[236:239], v132 offset:4672
	ds_read_b128 v[246:249], v167 offset:23104
	s_waitcnt lgkmcnt(2)
	v_mfma_f32_32x32x16_bf16 v[48:63], v[208:211], v[212:215], v[48:63]
	s_waitcnt lgkmcnt(1)
	v_mfma_f32_32x32x16_bf16 v[32:47], v[208:211], v[236:239], v[32:47]
	ds_read_b128 v[208:211], v167 offset:18528
	s_waitcnt vmcnt(13)
	ds_write_b128 v130, v[104:107] offset:41472
	s_waitcnt vmcnt(12)
	ds_write_b128 v130, v[108:111] offset:59904
	s_waitcnt lgkmcnt(3)
	v_mfma_f32_32x32x16_bf16 v[16:31], v[246:249], v[212:215], v[16:31]
	ds_read_b128 v[212:215], v132 offset:96
	v_mfma_f32_32x32x16_bf16 v[0:15], v[246:249], v[236:239], v[0:15]
	ds_read_b128 v[246:249], v132 offset:4704
	ds_read_b128 v[236:239], v167 offset:23136
	s_waitcnt lgkmcnt(2)
	v_mfma_f32_32x32x16_bf16 v[48:63], v[208:211], v[212:215], v[48:63]
	s_waitcnt lgkmcnt(1)
	v_mfma_f32_32x32x16_bf16 v[32:47], v[208:211], v[246:249], v[32:47]
	s_waitcnt lgkmcnt(0)
	v_mfma_f32_32x32x16_bf16 v[16:31], v[236:239], v[212:215], v[16:31]
	global_load_dwordx4 v[186:189], v[150:151], off offset:1152
	global_load_dwordx4 v[194:197], v[152:153], off offset:1152
	global_load_dwordx4 v[104:107], v[158:159], off offset:1152
	global_load_dwordx4 v[108:111], v[164:165], off offset:1152
	s_waitcnt vmcnt(15)
	ds_write_b128 v130, v[80:83] offset:46080
	s_waitcnt vmcnt(14)
	ds_write_b128 v130, v[84:87] offset:64512
	global_load_dwordx4 v[80:83], v[156:157], off offset:1152
	global_load_dwordx4 v[84:87], v[162:163], off offset:1152
	s_waitcnt vmcnt(15)
	ds_write_b128 v130, v[88:91] offset:50688
	s_waitcnt vmcnt(14)
	ds_write_b128 v131, v[92:95] offset:13824
	global_load_dwordx4 v[88:91], v[154:155], off offset:1152
	global_load_dwordx4 v[92:95], v[160:161], off offset:1152
	s_waitcnt lgkmcnt(0)
	s_barrier
; #define GLOADQ(RA, RB, KT, q) do { const int k0_ = (KT) << 6; \
;     RA[q] = ldg16(ap.ptr(m0 + lrow + 32 * (q), k0_) + lkc); RB[q] = ldg16(W + (size_t)(n0 + lrow + 32 * (q)) * ldw + k0_ + lkc); } while (0)
; #define SSTOREQ(RA, RB, ST, q) do { \
;     *(u32x4*)(sA + (ST) * SBUF + (lrow + 32 * (q)) * GP + lkc) = RA[q]; *(u32x4*)(sB + (ST) * SBUF + (lrow + 32 * (q)) * GP + lkc) = RB[q]; } while (0)
; #define FLOAD(F, ST, ks) do { _Pragma("unroll") for (int a = 0; a < 2; ++a) { \
;     F[a] = *(const bf16x8*)(sB + (ST) * SBUF + (wn * 64 + a * 32 + r) * GP + (ks) * 16 + h * 8); \
;     F[2 + a] = *(const bf16x8*)(sA + (ST) * SBUF + (wm * 64 + a * 32 + r) * GP + (ks) * 16 + h * 8); } } while (0)
; #define FMMA(F) do { _Pragma("unroll") for (int a = 0; a < 2; ++a) _Pragma("unroll") for (int b = 0; b < 2; ++b) acc[a][b] = MFMA(F[a], F[2 + b], acc[a][b]); } while (0)
; template <bool MIDK, class AP, class EPI>
; DI void gemm_tile(const AP& ap, const u16* __restrict__ W, int ldw, int K, int m0, int n0, const EPI& epi, char* smem, float r0, float r1, int tid, bool dry) {
;     ...
;   for (int kt = 0; kt < nk; kt += 2) {
;     const bool l3 = kt + 3 < nk, s2 = kt + 2 < nk, l4 = kt + 4 < nk;
;     FLOAD(f0, 0, 0); FLOAD(f1, 0, 1);
;     FMMA(f0); SSTOREQ(ra1, rb1, 1, 0); if (l3) GLOADQ(ra1, rb1, kt + 3, 0);
;     FLOAD(f0, 0, 2);
;     FMMA(f1); SSTOREQ(ra1, rb1, 1, 1); if (l3) GLOADQ(ra1, rb1, kt + 3, 1);
;     FLOAD(f1, 0, 3);
;     FMMA(f0); SSTOREQ(ra1, rb1, 1, 2); if (l3) GLOADQ(ra1, rb1, kt + 3, 2);
;     FMMA(f1); SSTOREQ(ra1, rb1, 1, 3); if (l3) GLOADQ(ra1, rb1, kt + 3, 3);
;     __syncthreads();
;     FLOAD(f0, 1, 0); FLOAD(f1, 1, 1);
;     FMMA(f0); if (s2) SSTOREQ(ra0, rb0, 0, 0); if (l4) GLOADQ(ra0, rb0, kt + 4, 0);
;     FLOAD(f0, 1, 2);
;     FMMA(f1); if (s2) SSTOREQ(ra0, rb0, 0, 1); if (l4) GLOADQ(ra0, rb0, kt + 4, 1);
;     FLOAD(f1, 1, 3);
;     FMMA(f0); if (s2) SSTOREQ(ra0, rb0, 0, 2); if (l4) GLOADQ(ra0, rb0, kt + 4, 2);
;     FMMA(f1); if (s2) SSTOREQ(ra0, rb0, 0, 3); if (l4) GLOADQ(ra0, rb0, kt + 4, 3);
	ds_read_b128 v[208:211], v167 offset:55296
	ds_read_b128 v[212:215], v132 offset:36864
	v_mfma_f32_32x32x16_bf16 v[0:15], v[236:239], v[246:249], v[0:15]
	ds_read_b128 v[236:239], v132 offset:41472
	ds_read_b128 v[246:249], v167 offset:59904
	s_waitcnt lgkmcnt(2)
	v_mfma_f32_32x32x16_bf16 v[48:63], v[208:211], v[212:215], v[48:63]
	s_waitcnt lgkmcnt(1)
	v_mfma_f32_32x32x16_bf16 v[32:47], v[208:211], v[236:239], v[32:47]
	ds_read_b128 v[208:211], v167 offset:55328
	s_waitcnt lgkmcnt(1)
	v_mfma_f32_32x32x16_bf16 v[16:31], v[246:249], v[212:215], v[16:31]
	ds_read_b128 v[212:215], v132 offset:36896
	v_mfma_f32_32x32x16_bf16 v[0:15], v[246:249], v[236:239], v[0:15]
	ds_read_b128 v[246:249], v132 offset:41504
	ds_read_b128 v[236:239], v167 offset:59936
	s_waitcnt lgkmcnt(2)
	v_mfma_f32_32x32x16_bf16 v[48:63], v[208:211], v[212:215], v[48:63]
	s_waitcnt lgkmcnt(1)
	v_mfma_f32_32x32x16_bf16 v[32:47], v[208:211], v[246:249], v[32:47]
	ds_read_b128 v[208:211], v167 offset:55360
	s_waitcnt vmcnt(15)
	ds_write_b128 v130, v[120:123]
	s_waitcnt vmcnt(14)
	ds_write_b128 v130, v[124:127] offset:18432
	s_waitcnt lgkmcnt(3)
	v_mfma_f32_32x32x16_bf16 v[16:31], v[236:239], v[212:215], v[16:31]
	ds_read_b128 v[212:215], v132 offset:36928
	v_mfma_f32_32x32x16_bf16 v[0:15], v[236:239], v[246:249], v[0:15]
	ds_read_b128 v[236:239], v132 offset:41536
	ds_read_b128 v[246:249], v167 offset:59968
	s_waitcnt lgkmcnt(2)
	v_mfma_f32_32x32x16_bf16 v[48:63], v[208:211], v[212:215], v[48:63]
	s_waitcnt lgkmcnt(1)
	v_mfma_f32_32x32x16_bf16 v[32:47], v[208:211], v[236:239], v[32:47]
	ds_read_b128 v[208:211], v167 offset:55392
	s_waitcnt vmcnt(13)
	ds_write_b128 v130, v[96:99] offset:4608
	s_waitcnt vmcnt(12)
	ds_write_b128 v130, v[100:103] offset:23040
	s_waitcnt lgkmcnt(3)
	v_mfma_f32_32x32x16_bf16 v[16:31], v[246:249], v[212:215], v[16:31]
	ds_read_b128 v[212:215], v132 offset:36960
	v_mfma_f32_32x32x16_bf16 v[0:15], v[246:249], v[236:239], v[0:15]
	ds_read_b128 v[246:249], v132 offset:41568
	ds_read_b128 v[236:239], v167 offset:60000
	s_waitcnt lgkmcnt(2)
	v_mfma_f32_32x32x16_bf16 v[48:63], v[208:211], v[212:215], v[48:63]
	s_waitcnt lgkmcnt(1)
	v_mfma_f32_32x32x16_bf16 v[32:47], v[208:211], v[246:249], v[32:47]
	s_waitcnt lgkmcnt(0)
	v_mfma_f32_32x32x16_bf16 v[16:31], v[236:239], v[212:215], v[16:31]
	global_load_dwordx4 v[120:123], v[150:151], off offset:1280
	global_load_dwordx4 v[124:127], v[152:153], off offset:1280
	global_load_dwordx4 v[96:99], v[158:159], off offset:1280
	global_load_dwordx4 v[100:103], v[164:165], off offset:1280
	s_waitcnt vmcnt(15)
	ds_write_b128 v130, v[72:75] offset:9216
	s_waitcnt vmcnt(14)
	ds_write_b128 v130, v[76:79] offset:27648
	global_load_dwordx4 v[72:75], v[156:157], off offset:1280
	global_load_dwordx4 v[76:79], v[162:163], off offset:1280
	s_waitcnt vmcnt(15)
	ds_write_b128 v130, v[64:67] offset:13824
	s_waitcnt vmcnt(14)
	ds_write_b128 v130, v[68:71] offset:32256
	global_load_dwordx4 v[64:67], v[154:155], off offset:1280
	global_load_dwordx4 v[68:71], v[160:161], off offset:1280
	s_waitcnt lgkmcnt(0)
	s_barrier
	ds_read_b128 v[208:211], v167 offset:18432
	ds_read_b128 v[212:215], v132
	v_mfma_f32_32x32x16_bf16 v[0:15], v[236:239], v[246:249], v[0:15]
	ds_read_b128 v[236:239], v132 offset:4608
	ds_read_b128 v[246:249], v167 offset:23040
	s_waitcnt lgkmcnt(2)
	v_mfma_f32_32x32x16_bf16 v[48:63], v[208:211], v[212:215], v[48:63]
	s_waitcnt lgkmcnt(1)
	v_mfma_f32_32x32x16_bf16 v[32:47], v[208:211], v[236:239], v[32:47]
	ds_read_b128 v[208:211], v167 offset:18464
	s_waitcnt lgkmcnt(1)
	v_mfma_f32_32x32x16_bf16 v[16:31], v[246:249], v[212:215], v[16:31]
	ds_read_b128 v[212:215], v132 offset:32
	v_mfma_f32_32x32x16_bf16 v[0:15], v[246:249], v[236:239], v[0:15]
	ds_read_b128 v[246:249], v132 offset:4640
	ds_read_b128 v[236:239], v167 offset:23072
	s_waitcnt lgkmcnt(2)
	v_mfma_f32_32x32x16_bf16 v[48:63], v[208:211], v[212:215], v[48:63]
	s_waitcnt lgkmcnt(1)
	v_mfma_f32_32x32x16_bf16 v[32:47], v[208:211], v[246:249], v[32:47]
	ds_read_b128 v[208:211], v167 offset:18496
	s_waitcnt vmcnt(15)
	ds_write_b128 v130, v[186:189] offset:36864
	s_waitcnt vmcnt(14)
	ds_write_b128 v130, v[194:197] offset:55296
	s_waitcnt lgkmcnt(3)
	v_mfma_f32_32x32x16_bf16 v[16:31], v[236:239], v[212:215], v[16:31]
	ds_read_b128 v[212:215], v132 offset:64
	v_mfma_f32_32x32x16_bf16 v[0:15], v[236:239], v[246:249], v[0:15]
	ds_read_b128 v[236:239], v132 offset:4672
	ds_read_b128 v[246:249], v167 offset:23104
	s_waitcnt lgkmcnt(2)
	v_mfma_f32_32x32x16_bf16 v[48:63], v[208:211], v[212:215], v[48:63]
	s_waitcnt lgkmcnt(1)
	v_mfma_f32_32x32x16_bf16 v[32:47], v[208:211], v[236:239], v[32:47]
	ds_read_b128 v[208:211], v167 offset:18528
	s_waitcnt vmcnt(13)
	ds_write_b128 v130, v[104:107] offset:41472
	s_waitcnt vmcnt(12)
	ds_write_b128 v130, v[108:111] offset:59904
	s_waitcnt lgkmcnt(3)
	v_mfma_f32_32x32x16_bf16 v[16:31], v[246:249], v[212:215], v[16:31]
	ds_read_b128 v[212:215], v132 offset:96
	v_mfma_f32_32x32x16_bf16 v[0:15], v[246:249], v[236:239], v[0:15]
	ds_read_b128 v[246:249], v132 offset:4704
	ds_read_b128 v[236:239], v167 offset:23136
	s_waitcnt lgkmcnt(2)
	v_mfma_f32_32x32x16_bf16 v[48:63], v[208:211], v[212:215], v[48:63]
	s_waitcnt lgkmcnt(1)
	v_mfma_f32_32x32x16_bf16 v[32:47], v[208:211], v[246:249], v[32:47]
	s_waitcnt lgkmcnt(0)
	v_mfma_f32_32x32x16_bf16 v[16:31], v[236:239], v[212:215], v[16:31]
	global_load_dwordx4 v[186:189], v[150:151], off offset:1408
	global_load_dwordx4 v[194:197], v[152:153], off offset:1408
	global_load_dwordx4 v[104:107], v[158:159], off offset:1408
	global_load_dwordx4 v[108:111], v[164:165], off offset:1408
	s_waitcnt vmcnt(15)
	ds_write_b128 v130, v[80:83] offset:46080
	s_waitcnt vmcnt(14)
	ds_write_b128 v130, v[84:87] offset:64512
	global_load_dwordx4 v[80:83], v[156:157], off offset:1408
	global_load_dwordx4 v[84:87], v[162:163], off offset:1408
	s_waitcnt vmcnt(15)
	ds_write_b128 v130, v[88:91] offset:50688
	s_waitcnt vmcnt(14)
	ds_write_b128 v131, v[92:95] offset:13824
	global_load_dwordx4 v[88:91], v[154:155], off offset:1408
	global_load_dwordx4 v[92:95], v[160:161], off offset:1408
	s_waitcnt lgkmcnt(0)
	s_barrier
; #define GLOADQ(RA, RB, KT, q) do { const int k0_ = (KT) << 6; \
;     RA[q] = ldg16(ap.ptr(m0 + lrow + 32 * (q), k0_) + lkc); RB[q] = ldg16(W + (size_t)(n0 + lrow + 32 * (q)) * ldw + k0_ + lkc); } while (0)
; #define SSTOREQ(RA, RB, ST, q) do { \
;     *(u32x4*)(sA + (ST) * SBUF + (lrow + 32 * (q)) * GP + lkc) = RA[q]; *(u32x4*)(sB + (ST) * SBUF + (lrow + 32 * (q)) * GP + lkc) = RB[q]; } while (0)
; #define FLOAD(F, ST, ks) do { _Pragma("unroll") for (int a = 0; a < 2; ++a) { \
;     F[a] = *(const bf16x8*)(sB + (ST) * SBUF + (wn * 64 + a * 32 + r) * GP + (ks) * 16 + h * 8); \
;     F[2 + a] = *(const bf16x8*)(sA + (ST) * SBUF + (wm * 64 + a * 32 + r) * GP + (ks) * 16 + h * 8); } } while (0)
; #define FMMA(F) do { _Pragma("unroll") for (int a = 0; a < 2; ++a) _Pragma("unroll") for (int b = 0; b < 2; ++b) acc[a][b] = MFMA(F[a], F[2 + b], acc[a][b]); } while (0)
; template <bool MIDK, class AP, class EPI>
; DI void gemm_tile(const AP& ap, const u16* __restrict__ W, int ldw, int K, int m0, int n0, const EPI& epi, char* smem, float r0, float r1, int tid, bool dry) {
;     ...
;   for (int kt = 0; kt < nk; kt += 2) {
;     const bool l3 = kt + 3 < nk, s2 = kt + 2 < nk, l4 = kt + 4 < nk;
;     FLOAD(f0, 0, 0); FLOAD(f1, 0, 1);
;     FMMA(f0); SSTOREQ(ra1, rb1, 1, 0); if (l3) GLOADQ(ra1, rb1, kt + 3, 0);
;     FLOAD(f0, 0, 2);
;     FMMA(f1); SSTOREQ(ra1, rb1, 1, 1); if (l3) GLOADQ(ra1, rb1, kt + 3, 1);
;     FLOAD(f1, 0, 3);
;     FMMA(f0); SSTOREQ(ra1, rb1, 1, 2); if (l3) GLOADQ(ra1, rb1, kt + 3, 2);
;     FMMA(f1); SSTOREQ(ra1, rb1, 1, 3); if (l3) GLOADQ(ra1, rb1, kt + 3, 3);
;     __syncthreads();
;     FLOAD(f0, 1, 0); FLOAD(f1, 1, 1);
;     FMMA(f0); if (s2) SSTOREQ(ra0, rb0, 0, 0); if (l4) GLOADQ(ra0, rb0, kt + 4, 0);
;     FLOAD(f0, 1, 2);
;     FMMA(f1); if (s2) SSTOREQ(ra0, rb0, 0, 1); if (l4) GLOADQ(ra0, rb0, kt + 4, 1);
;     FLOAD(f1, 1, 3);
;     FMMA(f0); if (s2) SSTOREQ(ra0, rb0, 0, 2); if (l4) GLOADQ(ra0, rb0, kt + 4, 2);
;     FMMA(f1); if (s2) SSTOREQ(ra0, rb0, 0, 3); if (l4) GLOADQ(ra0, rb0, kt + 4, 3);
	ds_read_b128 v[208:211], v167 offset:55296
	ds_read_b128 v[212:215], v132 offset:36864
	v_mfma_f32_32x32x16_bf16 v[0:15], v[236:239], v[246:249], v[0:15]
	ds_read_b128 v[236:239], v132 offset:41472
	ds_read_b128 v[246:249], v167 offset:59904
	s_waitcnt lgkmcnt(2)
	v_mfma_f32_32x32x16_bf16 v[48:63], v[208:211], v[212:215], v[48:63]
	s_waitcnt lgkmcnt(1)
	v_mfma_f32_32x32x16_bf16 v[32:47], v[208:211], v[236:239], v[32:47]
	ds_read_b128 v[208:211], v167 offset:55328
	s_waitcnt lgkmcnt(1)
	v_mfma_f32_32x32x16_bf16 v[16:31], v[246:249], v[212:215], v[16:31]
	ds_read_b128 v[212:215], v132 offset:36896
	v_mfma_f32_32x32x16_bf16 v[0:15], v[246:249], v[236:239], v[0:15]
	ds_read_b128 v[246:249], v132 offset:41504
	ds_read_b128 v[236:239], v167 offset:59936
	s_waitcnt lgkmcnt(2)
	v_mfma_f32_32x32x16_bf16 v[48:63], v[208:211], v[212:215], v[48:63]
	s_waitcnt lgkmcnt(1)
	v_mfma_f32_32x32x16_bf16 v[32:47], v[208:211], v[246:249], v[32:47]
	ds_read_b128 v[208:211], v167 offset:55360
	s_waitcnt vmcnt(15)
	ds_write_b128 v130, v[120:123]
	s_waitcnt vmcnt(14)
	ds_write_b128 v130, v[124:127] offset:18432
	s_waitcnt lgkmcnt(3)
	v_mfma_f32_32x32x16_bf16 v[16:31], v[236:239], v[212:215], v[16:31]
	ds_read_b128 v[212:215], v132 offset:36928
	v_mfma_f32_32x32x16_bf16 v[0:15], v[236:239], v[246:249], v[0:15]
	ds_read_b128 v[236:239], v132 offset:41536
	ds_read_b128 v[246:249], v167 offset:59968
	s_waitcnt lgkmcnt(2)
	v_mfma_f32_32x32x16_bf16 v[48:63], v[208:211], v[212:215], v[48:63]
	s_waitcnt lgkmcnt(1)
	v_mfma_f32_32x32x16_bf16 v[32:47], v[208:211], v[236:239], v[32:47]
	ds_read_b128 v[208:211], v167 offset:55392
	s_waitcnt vmcnt(13)
	ds_write_b128 v130, v[96:99] offset:4608
	s_waitcnt vmcnt(12)
	ds_write_b128 v130, v[100:103] offset:23040
	s_waitcnt lgkmcnt(3)
	v_mfma_f32_32x32x16_bf16 v[16:31], v[246:249], v[212:215], v[16:31]
	ds_read_b128 v[212:215], v132 offset:36960
	v_mfma_f32_32x32x16_bf16 v[0:15], v[246:249], v[236:239], v[0:15]
	ds_read_b128 v[246:249], v132 offset:41568
	ds_read_b128 v[236:239], v167 offset:60000
	s_waitcnt lgkmcnt(2)
	v_mfma_f32_32x32x16_bf16 v[48:63], v[208:211], v[212:215], v[48:63]
	s_waitcnt lgkmcnt(1)
	v_mfma_f32_32x32x16_bf16 v[32:47], v[208:211], v[246:249], v[32:47]
	s_waitcnt lgkmcnt(0)
	v_mfma_f32_32x32x16_bf16 v[16:31], v[236:239], v[212:215], v[16:31]
	global_load_dwordx4 v[120:123], v[150:151], off offset:1536
	global_load_dwordx4 v[124:127], v[152:153], off offset:1536
	global_load_dwordx4 v[96:99], v[158:159], off offset:1536
	global_load_dwordx4 v[100:103], v[164:165], off offset:1536
	s_waitcnt vmcnt(15)
	ds_write_b128 v130, v[72:75] offset:9216
	s_waitcnt vmcnt(14)
	ds_write_b128 v130, v[76:79] offset:27648
	global_load_dwordx4 v[72:75], v[156:157], off offset:1536
	global_load_dwordx4 v[76:79], v[162:163], off offset:1536
	s_waitcnt vmcnt(15)
	ds_write_b128 v130, v[64:67] offset:13824
	s_waitcnt vmcnt(14)
	ds_write_b128 v130, v[68:71] offset:32256
	global_load_dwordx4 v[64:67], v[154:155], off offset:1536
	global_load_dwordx4 v[68:71], v[160:161], off offset:1536
	s_waitcnt lgkmcnt(0)
	s_barrier
	ds_read_b128 v[208:211], v167 offset:18432
	ds_read_b128 v[212:215], v132
	v_mfma_f32_32x32x16_bf16 v[0:15], v[236:239], v[246:249], v[0:15]
	ds_read_b128 v[236:239], v132 offset:4608
	ds_read_b128 v[246:249], v167 offset:23040
	s_waitcnt lgkmcnt(2)
	v_mfma_f32_32x32x16_bf16 v[48:63], v[208:211], v[212:215], v[48:63]
	s_waitcnt lgkmcnt(1)
	v_mfma_f32_32x32x16_bf16 v[32:47], v[208:211], v[236:239], v[32:47]
	ds_read_b128 v[208:211], v167 offset:18464
	s_waitcnt lgkmcnt(1)
	v_mfma_f32_32x32x16_bf16 v[16:31], v[246:249], v[212:215], v[16:31]
	ds_read_b128 v[212:215], v132 offset:32
	v_mfma_f32_32x32x16_bf16 v[0:15], v[246:249], v[236:239], v[0:15]
	ds_read_b128 v[246:249], v132 offset:4640
	ds_read_b128 v[236:239], v167 offset:23072
	s_waitcnt lgkmcnt(2)
	v_mfma_f32_32x32x16_bf16 v[48:63], v[208:211], v[212:215], v[48:63]
	s_waitcnt lgkmcnt(1)
	v_mfma_f32_32x32x16_bf16 v[32:47], v[208:211], v[246:249], v[32:47]
	ds_read_b128 v[208:211], v167 offset:18496
	s_waitcnt vmcnt(15)
	ds_write_b128 v130, v[186:189] offset:36864
	s_waitcnt vmcnt(14)
	ds_write_b128 v130, v[194:197] offset:55296
	s_waitcnt lgkmcnt(3)
	v_mfma_f32_32x32x16_bf16 v[16:31], v[236:239], v[212:215], v[16:31]
	ds_read_b128 v[212:215], v132 offset:64
	v_mfma_f32_32x32x16_bf16 v[0:15], v[236:239], v[246:249], v[0:15]
	ds_read_b128 v[236:239], v132 offset:4672
	ds_read_b128 v[246:249], v167 offset:23104
	s_waitcnt lgkmcnt(2)
	v_mfma_f32_32x32x16_bf16 v[48:63], v[208:211], v[212:215], v[48:63]
	s_waitcnt lgkmcnt(1)
	v_mfma_f32_32x32x16_bf16 v[32:47], v[208:211], v[236:239], v[32:47]
	ds_read_b128 v[208:211], v167 offset:18528
	s_waitcnt vmcnt(13)
	ds_write_b128 v130, v[104:107] offset:41472
	s_waitcnt vmcnt(12)
	ds_write_b128 v130, v[108:111] offset:59904
	s_waitcnt lgkmcnt(3)
	v_mfma_f32_32x32x16_bf16 v[16:31], v[246:249], v[212:215], v[16:31]
	ds_read_b128 v[212:215], v132 offset:96
	v_mfma_f32_32x32x16_bf16 v[0:15], v[246:249], v[236:239], v[0:15]
	ds_read_b128 v[246:249], v132 offset:4704
	ds_read_b128 v[236:239], v167 offset:23136
	s_waitcnt lgkmcnt(2)
	v_mfma_f32_32x32x16_bf16 v[48:63], v[208:211], v[212:215], v[48:63]
	s_waitcnt lgkmcnt(1)
	v_mfma_f32_32x32x16_bf16 v[32:47], v[208:211], v[246:249], v[32:47]
	s_waitcnt lgkmcnt(0)
	v_mfma_f32_32x32x16_bf16 v[16:31], v[236:239], v[212:215], v[16:31]
	global_load_dwordx4 v[186:189], v[150:151], off offset:1664
	global_load_dwordx4 v[194:197], v[152:153], off offset:1664
	global_load_dwordx4 v[104:107], v[158:159], off offset:1664
	global_load_dwordx4 v[108:111], v[164:165], off offset:1664
	s_waitcnt vmcnt(15)
	ds_write_b128 v130, v[80:83] offset:46080
	s_waitcnt vmcnt(14)
	ds_write_b128 v130, v[84:87] offset:64512
	global_load_dwordx4 v[80:83], v[156:157], off offset:1664
	global_load_dwordx4 v[84:87], v[162:163], off offset:1664
	s_waitcnt vmcnt(15)
	ds_write_b128 v130, v[88:91] offset:50688
	s_waitcnt vmcnt(14)
	ds_write_b128 v131, v[92:95] offset:13824
	global_load_dwordx4 v[88:91], v[154:155], off offset:1664
	global_load_dwordx4 v[92:95], v[160:161], off offset:1664
	s_waitcnt lgkmcnt(0)
	s_barrier
; #define GLOADQ(RA, RB, KT, q) do { const int k0_ = (KT) << 6; \
;     RA[q] = ldg16(ap.ptr(m0 + lrow + 32 * (q), k0_) + lkc); RB[q] = ldg16(W + (size_t)(n0 + lrow + 32 * (q)) * ldw + k0_ + lkc); } while (0)
; #define SSTOREQ(RA, RB, ST, q) do { \
;     *(u32x4*)(sA + (ST) * SBUF + (lrow + 32 * (q)) * GP + lkc) = RA[q]; *(u32x4*)(sB + (ST) * SBUF + (lrow + 32 * (q)) * GP + lkc) = RB[q]; } while (0)
; #define FLOAD(F, ST, ks) do { _Pragma("unroll") for (int a = 0; a < 2; ++a) { \
;     F[a] = *(const bf16x8*)(sB + (ST) * SBUF + (wn * 64 + a * 32 + r) * GP + (ks) * 16 + h * 8); \
;     F[2 + a] = *(const bf16x8*)(sA + (ST) * SBUF + (wm * 64 + a * 32 + r) * GP + (ks) * 16 + h * 8); } } while (0)
; #define FMMA(F) do { _Pragma("unroll") for (int a = 0; a < 2; ++a) _Pragma("unroll") for (int b = 0; b < 2; ++b) acc[a][b] = MFMA(F[a], F[2 + b], acc[a][b]); } while (0)
; template <bool MIDK, class AP, class EPI>
; DI void gemm_tile(const AP& ap, const u16* __restrict__ W, int ldw, int K, int m0, int n0, const EPI& epi, char* smem, float r0, float r1, int tid, bool dry) {
;     ...
;   for (int kt = 0; kt < nk; kt += 2) {
;     const bool l3 = kt + 3 < nk, s2 = kt + 2 < nk, l4 = kt + 4 < nk;
;     FLOAD(f0, 0, 0); FLOAD(f1, 0, 1);
;     FMMA(f0); SSTOREQ(ra1, rb1, 1, 0); if (l3) GLOADQ(ra1, rb1, kt + 3, 0);
;     FLOAD(f0, 0, 2);
;     FMMA(f1); SSTOREQ(ra1, rb1, 1, 1); if (l3) GLOADQ(ra1, rb1, kt + 3, 1);
;     FLOAD(f1, 0, 3);
;     FMMA(f0); SSTOREQ(ra1, rb1, 1, 2); if (l3) GLOADQ(ra1, rb1, kt + 3, 2);
;     FMMA(f1); SSTOREQ(ra1, rb1, 1, 3); if (l3) GLOADQ(ra1, rb1, kt + 3, 3);
;     __syncthreads();
;     FLOAD(f0, 1, 0); FLOAD(f1, 1, 1);
;     FMMA(f0); if (s2) SSTOREQ(ra0, rb0, 0, 0); if (l4) GLOADQ(ra0, rb0, kt + 4, 0);
;     FLOAD(f0, 1, 2);
;     FMMA(f1); if (s2) SSTOREQ(ra0, rb0, 0, 1); if (l4) GLOADQ(ra0, rb0, kt + 4, 1);
;     FLOAD(f1, 1, 3);
;     FMMA(f0); if (s2) SSTOREQ(ra0, rb0, 0, 2); if (l4) GLOADQ(ra0, rb0, kt + 4, 2);
;     FMMA(f1); if (s2) SSTOREQ(ra0, rb0, 0, 3); if (l4) GLOADQ(ra0, rb0, kt + 4, 3);
	ds_read_b128 v[208:211], v167 offset:55296
	ds_read_b128 v[212:215], v132 offset:36864
	v_mfma_f32_32x32x16_bf16 v[0:15], v[236:239], v[246:249], v[0:15]
	ds_read_b128 v[236:239], v132 offset:41472
	ds_read_b128 v[246:249], v167 offset:59904
	s_waitcnt lgkmcnt(2)
	v_mfma_f32_32x32x16_bf16 v[48:63], v[208:211], v[212:215], v[48:63]
	s_waitcnt lgkmcnt(1)
	v_mfma_f32_32x32x16_bf16 v[32:47], v[208:211], v[236:239], v[32:47]
	ds_read_b128 v[208:211], v167 offset:55328
	s_waitcnt lgkmcnt(1)
	v_mfma_f32_32x32x16_bf16 v[16:31], v[246:249], v[212:215], v[16:31]
	ds_read_b128 v[212:215], v132 offset:36896
	v_mfma_f32_32x32x16_bf16 v[0:15], v[246:249], v[236:239], v[0:15]
	ds_read_b128 v[246:249], v132 offset:41504
	ds_read_b128 v[236:239], v167 offset:59936
	s_waitcnt lgkmcnt(2)
	v_mfma_f32_32x32x16_bf16 v[48:63], v[208:211], v[212:215], v[48:63]
	s_waitcnt lgkmcnt(1)
	v_mfma_f32_32x32x16_bf16 v[32:47], v[208:211], v[246:249], v[32:47]
	ds_read_b128 v[208:211], v167 offset:55360
	s_waitcnt vmcnt(15)
	ds_write_b128 v130, v[120:123]
	s_waitcnt vmcnt(14)
	ds_write_b128 v130, v[124:127] offset:18432
	s_waitcnt lgkmcnt(3)
	v_mfma_f32_32x32x16_bf16 v[16:31], v[236:239], v[212:215], v[16:31]
	ds_read_b128 v[212:215], v132 offset:36928
	v_mfma_f32_32x32x16_bf16 v[0:15], v[236:239], v[246:249], v[0:15]
	ds_read_b128 v[236:239], v132 offset:41536
	ds_read_b128 v[246:249], v167 offset:59968
	s_waitcnt lgkmcnt(2)
	v_mfma_f32_32x32x16_bf16 v[48:63], v[208:211], v[212:215], v[48:63]
	s_waitcnt lgkmcnt(1)
	v_mfma_f32_32x32x16_bf16 v[32:47], v[208:211], v[236:239], v[32:47]
	ds_read_b128 v[208:211], v167 offset:55392
	s_waitcnt vmcnt(13)
	ds_write_b128 v130, v[96:99] offset:4608
	s_waitcnt vmcnt(12)
	ds_write_b128 v130, v[100:103] offset:23040
	s_waitcnt lgkmcnt(3)
	v_mfma_f32_32x32x16_bf16 v[16:31], v[246:249], v[212:215], v[16:31]
	ds_read_b128 v[212:215], v132 offset:36960
	v_mfma_f32_32x32x16_bf16 v[0:15], v[246:249], v[236:239], v[0:15]
	ds_read_b128 v[246:249], v132 offset:41568
	ds_read_b128 v[236:239], v167 offset:60000
	s_waitcnt lgkmcnt(2)
	v_mfma_f32_32x32x16_bf16 v[48:63], v[208:211], v[212:215], v[48:63]
	s_waitcnt lgkmcnt(1)
	v_mfma_f32_32x32x16_bf16 v[32:47], v[208:211], v[246:249], v[32:47]
	s_waitcnt lgkmcnt(0)
	v_mfma_f32_32x32x16_bf16 v[16:31], v[236:239], v[212:215], v[16:31]
	global_load_dwordx4 v[120:123], v[150:151], off offset:1792
	global_load_dwordx4 v[124:127], v[152:153], off offset:1792
	global_load_dwordx4 v[96:99], v[158:159], off offset:1792
	global_load_dwordx4 v[100:103], v[164:165], off offset:1792
	s_waitcnt vmcnt(15)
	ds_write_b128 v130, v[72:75] offset:9216
	s_waitcnt vmcnt(14)
	ds_write_b128 v130, v[76:79] offset:27648
	global_load_dwordx4 v[72:75], v[156:157], off offset:1792
	global_load_dwordx4 v[76:79], v[162:163], off offset:1792
	s_waitcnt vmcnt(15)
	ds_write_b128 v130, v[64:67] offset:13824
	s_waitcnt vmcnt(14)
	ds_write_b128 v130, v[68:71] offset:32256
	global_load_dwordx4 v[64:67], v[154:155], off offset:1792
	global_load_dwordx4 v[68:71], v[160:161], off offset:1792
	s_waitcnt lgkmcnt(0)
	s_barrier
	ds_read_b128 v[208:211], v167 offset:18432
	ds_read_b128 v[212:215], v132
	v_mfma_f32_32x32x16_bf16 v[0:15], v[236:239], v[246:249], v[0:15]
	ds_read_b128 v[236:239], v132 offset:4608
	ds_read_b128 v[246:249], v167 offset:23040
	s_waitcnt lgkmcnt(2)
	v_mfma_f32_32x32x16_bf16 v[48:63], v[208:211], v[212:215], v[48:63]
	s_waitcnt lgkmcnt(1)
	v_mfma_f32_32x32x16_bf16 v[32:47], v[208:211], v[236:239], v[32:47]
	ds_read_b128 v[208:211], v167 offset:18464
	s_waitcnt lgkmcnt(1)
	v_mfma_f32_32x32x16_bf16 v[16:31], v[246:249], v[212:215], v[16:31]
	ds_read_b128 v[212:215], v132 offset:32
	v_mfma_f32_32x32x16_bf16 v[0:15], v[246:249], v[236:239], v[0:15]
	ds_read_b128 v[246:249], v132 offset:4640
	ds_read_b128 v[236:239], v167 offset:23072
	s_waitcnt lgkmcnt(2)
	v_mfma_f32_32x32x16_bf16 v[48:63], v[208:211], v[212:215], v[48:63]
	s_waitcnt lgkmcnt(1)
	v_mfma_f32_32x32x16_bf16 v[32:47], v[208:211], v[246:249], v[32:47]
	ds_read_b128 v[208:211], v167 offset:18496
	s_waitcnt vmcnt(15)
	ds_write_b128 v130, v[186:189] offset:36864
	s_waitcnt vmcnt(14)
	ds_write_b128 v130, v[194:197] offset:55296
	s_waitcnt lgkmcnt(3)
	v_mfma_f32_32x32x16_bf16 v[16:31], v[236:239], v[212:215], v[16:31]
	ds_read_b128 v[212:215], v132 offset:64
	v_mfma_f32_32x32x16_bf16 v[0:15], v[236:239], v[246:249], v[0:15]
	ds_read_b128 v[236:239], v132 offset:4672
	ds_read_b128 v[246:249], v167 offset:23104
	s_waitcnt lgkmcnt(2)
	v_mfma_f32_32x32x16_bf16 v[48:63], v[208:211], v[212:215], v[48:63]
	s_waitcnt lgkmcnt(1)
	v_mfma_f32_32x32x16_bf16 v[32:47], v[208:211], v[236:239], v[32:47]
	ds_read_b128 v[208:211], v167 offset:18528
	s_waitcnt vmcnt(13)
	ds_write_b128 v130, v[104:107] offset:41472
	s_waitcnt vmcnt(12)
	ds_write_b128 v130, v[108:111] offset:59904
	s_waitcnt lgkmcnt(3)
	v_mfma_f32_32x32x16_bf16 v[16:31], v[246:249], v[212:215], v[16:31]
	ds_read_b128 v[212:215], v132 offset:96
	v_mfma_f32_32x32x16_bf16 v[0:15], v[246:249], v[236:239], v[0:15]
	ds_read_b128 v[246:249], v132 offset:4704
	ds_read_b128 v[236:239], v167 offset:23136
	s_waitcnt lgkmcnt(2)
	v_mfma_f32_32x32x16_bf16 v[48:63], v[208:211], v[212:215], v[48:63]
	s_waitcnt lgkmcnt(1)
	v_mfma_f32_32x32x16_bf16 v[32:47], v[208:211], v[246:249], v[32:47]
	s_waitcnt lgkmcnt(0)
	v_mfma_f32_32x32x16_bf16 v[16:31], v[236:239], v[212:215], v[16:31]
	global_load_dwordx4 v[186:189], v[150:151], off offset:1920
	global_load_dwordx4 v[194:197], v[152:153], off offset:1920
	global_load_dwordx4 v[104:107], v[158:159], off offset:1920
	global_load_dwordx4 v[108:111], v[164:165], off offset:1920
	s_waitcnt vmcnt(15)
	ds_write_b128 v130, v[80:83] offset:46080
	s_waitcnt vmcnt(14)
	ds_write_b128 v130, v[84:87] offset:64512
	global_load_dwordx4 v[80:83], v[156:157], off offset:1920
	global_load_dwordx4 v[84:87], v[162:163], off offset:1920
	s_waitcnt vmcnt(15)
	ds_write_b128 v130, v[88:91] offset:50688
	s_waitcnt vmcnt(14)
	ds_write_b128 v131, v[92:95] offset:13824
	global_load_dwordx4 v[88:91], v[154:155], off offset:1920
	global_load_dwordx4 v[92:95], v[160:161], off offset:1920
	s_waitcnt lgkmcnt(0)
	s_barrier
; #define GLOADQ(RA, RB, KT, q) do { const int k0_ = (KT) << 6; \
;     RA[q] = ldg16(ap.ptr(m0 + lrow + 32 * (q), k0_) + lkc); RB[q] = ldg16(W + (size_t)(n0 + lrow + 32 * (q)) * ldw + k0_ + lkc); } while (0)
; #define SSTOREQ(RA, RB, ST, q) do { \
;     *(u32x4*)(sA + (ST) * SBUF + (lrow + 32 * (q)) * GP + lkc) = RA[q]; *(u32x4*)(sB + (ST) * SBUF + (lrow + 32 * (q)) * GP + lkc) = RB[q]; } while (0)
; #define FLOAD(F, ST, ks) do { _Pragma("unroll") for (int a = 0; a < 2; ++a) { \
;     F[a] = *(const bf16x8*)(sB + (ST) * SBUF + (wn * 64 + a * 32 + r) * GP + (ks) * 16 + h * 8); \
;     F[2 + a] = *(const bf16x8*)(sA + (ST) * SBUF + (wm * 64 + a * 32 + r) * GP + (ks) * 16 + h * 8); } } while (0)
; #define FMMA(F) do { _Pragma("unroll") for (int a = 0; a < 2; ++a) _Pragma("unroll") for (int b = 0; b < 2; ++b) acc[a][b] = MFMA(F[a], F[2 + b], acc[a][b]); } while (0)
; template <bool MIDK, class AP, class EPI>
; DI void gemm_tile(const AP& ap, const u16* __restrict__ W, int ldw, int K, int m0, int n0, const EPI& epi, char* smem, float r0, float r1, int tid, bool dry) {
;     ...
;   for (int kt = 0; kt < nk; kt += 2) {
;     const bool l3 = kt + 3 < nk, s2 = kt + 2 < nk, l4 = kt + 4 < nk;
;     FLOAD(f0, 0, 0); FLOAD(f1, 0, 1);
;     FMMA(f0); SSTOREQ(ra1, rb1, 1, 0); if (l3) GLOADQ(ra1, rb1, kt + 3, 0);
;     FLOAD(f0, 0, 2);
;     FMMA(f1); SSTOREQ(ra1, rb1, 1, 1); if (l3) GLOADQ(ra1, rb1, kt + 3, 1);
;     FLOAD(f1, 0, 3);
;     FMMA(f0); SSTOREQ(ra1, rb1, 1, 2); if (l3) GLOADQ(ra1, rb1, kt + 3, 2);
;     FMMA(f1); SSTOREQ(ra1, rb1, 1, 3); if (l3) GLOADQ(ra1, rb1, kt + 3, 3);
;     __syncthreads();
;     FLOAD(f0, 1, 0); FLOAD(f1, 1, 1);
;     FMMA(f0); if (s2) SSTOREQ(ra0, rb0, 0, 0); if (l4) GLOADQ(ra0, rb0, kt + 4, 0);
;     FLOAD(f0, 1, 2);
;     FMMA(f1); if (s2) SSTOREQ(ra0, rb0, 0, 1); if (l4) GLOADQ(ra0, rb0, kt + 4, 1);
;     FLOAD(f1, 1, 3);
;     FMMA(f0); if (s2) SSTOREQ(ra0, rb0, 0, 2); if (l4) GLOADQ(ra0, rb0, kt + 4, 2);
;     FMMA(f1); if (s2) SSTOREQ(ra0, rb0, 0, 3); if (l4) GLOADQ(ra0, rb0, kt + 4, 3);
	ds_read_b128 v[208:211], v167 offset:55296
	ds_read_b128 v[212:215], v132 offset:36864
	v_mfma_f32_32x32x16_bf16 v[0:15], v[236:239], v[246:249], v[0:15]
	ds_read_b128 v[236:239], v132 offset:41472
	ds_read_b128 v[246:249], v167 offset:59904
	s_waitcnt lgkmcnt(2)
	v_mfma_f32_32x32x16_bf16 v[48:63], v[208:211], v[212:215], v[48:63]
	s_waitcnt lgkmcnt(1)
	v_mfma_f32_32x32x16_bf16 v[32:47], v[208:211], v[236:239], v[32:47]
	ds_read_b128 v[208:211], v167 offset:55328
	s_waitcnt lgkmcnt(1)
	v_mfma_f32_32x32x16_bf16 v[16:31], v[246:249], v[212:215], v[16:31]
	ds_read_b128 v[212:215], v132 offset:36896
	v_mfma_f32_32x32x16_bf16 v[0:15], v[246:249], v[236:239], v[0:15]
	ds_read_b128 v[246:249], v132 offset:41504
	ds_read_b128 v[236:239], v167 offset:59936
	s_waitcnt lgkmcnt(2)
	v_mfma_f32_32x32x16_bf16 v[48:63], v[208:211], v[212:215], v[48:63]
	s_waitcnt lgkmcnt(1)
	v_mfma_f32_32x32x16_bf16 v[32:47], v[208:211], v[246:249], v[32:47]
	ds_read_b128 v[208:211], v167 offset:55360
	s_waitcnt vmcnt(15)
	ds_write_b128 v130, v[120:123]
	s_waitcnt vmcnt(14)
	ds_write_b128 v130, v[124:127] offset:18432
	s_waitcnt lgkmcnt(3)
	v_mfma_f32_32x32x16_bf16 v[16:31], v[236:239], v[212:215], v[16:31]
	ds_read_b128 v[212:215], v132 offset:36928
	v_mfma_f32_32x32x16_bf16 v[0:15], v[236:239], v[246:249], v[0:15]
	ds_read_b128 v[236:239], v132 offset:41536
	ds_read_b128 v[246:249], v167 offset:59968
	s_waitcnt lgkmcnt(2)
	v_mfma_f32_32x32x16_bf16 v[48:63], v[208:211], v[212:215], v[48:63]
	s_waitcnt lgkmcnt(1)
	v_mfma_f32_32x32x16_bf16 v[32:47], v[208:211], v[236:239], v[32:47]
	ds_read_b128 v[208:211], v167 offset:55392
	s_waitcnt vmcnt(13)
	ds_write_b128 v130, v[96:99] offset:4608
	s_waitcnt vmcnt(12)
	ds_write_b128 v130, v[100:103] offset:23040
	s_waitcnt lgkmcnt(3)
	v_mfma_f32_32x32x16_bf16 v[16:31], v[246:249], v[212:215], v[16:31]
	ds_read_b128 v[212:215], v132 offset:36960
	v_mfma_f32_32x32x16_bf16 v[0:15], v[246:249], v[236:239], v[0:15]
	ds_read_b128 v[246:249], v132 offset:41568
	ds_read_b128 v[236:239], v167 offset:60000
	s_waitcnt lgkmcnt(2)
	v_mfma_f32_32x32x16_bf16 v[48:63], v[208:211], v[212:215], v[48:63]
	s_waitcnt lgkmcnt(1)
	v_mfma_f32_32x32x16_bf16 v[32:47], v[208:211], v[246:249], v[32:47]
	s_waitcnt lgkmcnt(0)
	v_mfma_f32_32x32x16_bf16 v[16:31], v[236:239], v[212:215], v[16:31]
	global_load_dwordx4 v[120:123], v[150:151], off offset:2048
	global_load_dwordx4 v[124:127], v[152:153], off offset:2048
	global_load_dwordx4 v[96:99], v[158:159], off offset:2048
	global_load_dwordx4 v[100:103], v[164:165], off offset:2048
	s_waitcnt vmcnt(15)
	ds_write_b128 v130, v[72:75] offset:9216
	s_waitcnt vmcnt(14)
	ds_write_b128 v130, v[76:79] offset:27648
	global_load_dwordx4 v[72:75], v[156:157], off offset:2048
	global_load_dwordx4 v[76:79], v[162:163], off offset:2048
	s_waitcnt vmcnt(15)
	ds_write_b128 v130, v[64:67] offset:13824
	s_waitcnt vmcnt(14)
	ds_write_b128 v130, v[68:71] offset:32256
	global_load_dwordx4 v[64:67], v[154:155], off offset:2048
	global_load_dwordx4 v[68:71], v[160:161], off offset:2048
	s_waitcnt lgkmcnt(0)
	s_barrier
	ds_read_b128 v[208:211], v167 offset:18432
	ds_read_b128 v[212:215], v132
	v_mfma_f32_32x32x16_bf16 v[0:15], v[236:239], v[246:249], v[0:15]
	ds_read_b128 v[236:239], v132 offset:4608
	ds_read_b128 v[246:249], v167 offset:23040
	s_waitcnt lgkmcnt(2)
	v_mfma_f32_32x32x16_bf16 v[48:63], v[208:211], v[212:215], v[48:63]
	s_waitcnt lgkmcnt(1)
	v_mfma_f32_32x32x16_bf16 v[32:47], v[208:211], v[236:239], v[32:47]
	ds_read_b128 v[208:211], v167 offset:18464
	s_waitcnt lgkmcnt(1)
	v_mfma_f32_32x32x16_bf16 v[16:31], v[246:249], v[212:215], v[16:31]
	ds_read_b128 v[212:215], v132 offset:32
	v_mfma_f32_32x32x16_bf16 v[0:15], v[246:249], v[236:239], v[0:15]
	ds_read_b128 v[246:249], v132 offset:4640
	ds_read_b128 v[236:239], v167 offset:23072
	s_waitcnt lgkmcnt(2)
	v_mfma_f32_32x32x16_bf16 v[48:63], v[208:211], v[212:215], v[48:63]
	s_waitcnt lgkmcnt(1)
	v_mfma_f32_32x32x16_bf16 v[32:47], v[208:211], v[246:249], v[32:47]
	ds_read_b128 v[208:211], v167 offset:18496
	s_waitcnt vmcnt(15)
	ds_write_b128 v130, v[186:189] offset:36864
	s_waitcnt vmcnt(14)
	ds_write_b128 v130, v[194:197] offset:55296
	s_waitcnt lgkmcnt(3)
	v_mfma_f32_32x32x16_bf16 v[16:31], v[236:239], v[212:215], v[16:31]
	ds_read_b128 v[212:215], v132 offset:64
	v_mfma_f32_32x32x16_bf16 v[0:15], v[236:239], v[246:249], v[0:15]
	ds_read_b128 v[236:239], v132 offset:4672
	ds_read_b128 v[246:249], v167 offset:23104
	s_waitcnt lgkmcnt(2)
	v_mfma_f32_32x32x16_bf16 v[48:63], v[208:211], v[212:215], v[48:63]
	s_waitcnt lgkmcnt(1)
	v_mfma_f32_32x32x16_bf16 v[32:47], v[208:211], v[236:239], v[32:47]
	ds_read_b128 v[208:211], v167 offset:18528
	s_waitcnt vmcnt(13)
	ds_write_b128 v130, v[104:107] offset:41472
	s_waitcnt vmcnt(12)
	ds_write_b128 v130, v[108:111] offset:59904
	s_waitcnt lgkmcnt(3)
	v_mfma_f32_32x32x16_bf16 v[16:31], v[246:249], v[212:215], v[16:31]
	ds_read_b128 v[212:215], v132 offset:96
	v_mfma_f32_32x32x16_bf16 v[0:15], v[246:249], v[236:239], v[0:15]
	ds_read_b128 v[246:249], v132 offset:4704
	ds_read_b128 v[236:239], v167 offset:23136
	s_waitcnt lgkmcnt(2)
	v_mfma_f32_32x32x16_bf16 v[48:63], v[208:211], v[212:215], v[48:63]
	s_waitcnt lgkmcnt(1)
	v_mfma_f32_32x32x16_bf16 v[32:47], v[208:211], v[246:249], v[32:47]
	s_waitcnt lgkmcnt(0)
	v_mfma_f32_32x32x16_bf16 v[16:31], v[236:239], v[212:215], v[16:31]
	global_load_dwordx4 v[186:189], v[150:151], off offset:2176
	global_load_dwordx4 v[194:197], v[152:153], off offset:2176
	global_load_dwordx4 v[104:107], v[158:159], off offset:2176
	global_load_dwordx4 v[108:111], v[164:165], off offset:2176
	s_waitcnt vmcnt(15)
	ds_write_b128 v130, v[80:83] offset:46080
	s_waitcnt vmcnt(14)
	ds_write_b128 v130, v[84:87] offset:64512
	global_load_dwordx4 v[80:83], v[156:157], off offset:2176
	global_load_dwordx4 v[84:87], v[162:163], off offset:2176
	s_waitcnt vmcnt(15)
	ds_write_b128 v130, v[88:91] offset:50688
	s_waitcnt vmcnt(14)
	ds_write_b128 v131, v[92:95] offset:13824
	global_load_dwordx4 v[88:91], v[154:155], off offset:2176
	global_load_dwordx4 v[92:95], v[160:161], off offset:2176
	s_waitcnt lgkmcnt(0)
	s_barrier
; #define GLOADQ(RA, RB, KT, q) do { const int k0_ = (KT) << 6; \
;     RA[q] = ldg16(ap.ptr(m0 + lrow + 32 * (q), k0_) + lkc); RB[q] = ldg16(W + (size_t)(n0 + lrow + 32 * (q)) * ldw + k0_ + lkc); } while (0)
; #define SSTOREQ(RA, RB, ST, q) do { \
;     *(u32x4*)(sA + (ST) * SBUF + (lrow + 32 * (q)) * GP + lkc) = RA[q]; *(u32x4*)(sB + (ST) * SBUF + (lrow + 32 * (q)) * GP + lkc) = RB[q]; } while (0)
; #define FLOAD(F, ST, ks) do { _Pragma("unroll") for (int a = 0; a < 2; ++a) { \
;     F[a] = *(const bf16x8*)(sB + (ST) * SBUF + (wn * 64 + a * 32 + r) * GP + (ks) * 16 + h * 8); \
;     F[2 + a] = *(const bf16x8*)(sA + (ST) * SBUF + (wm * 64 + a * 32 + r) * GP + (ks) * 16 + h * 8); } } while (0)
; #define FMMA(F) do { _Pragma("unroll") for (int a = 0; a < 2; ++a) _Pragma("unroll") for (int b = 0; b < 2; ++b) acc[a][b] = MFMA(F[a], F[2 + b], acc[a][b]); } while (0)
; template <bool MIDK, class AP, class EPI>
; DI void gemm_tile(const AP& ap, const u16* __restrict__ W, int ldw, int K, int m0, int n0, const EPI& epi, char* smem, float r0, float r1, int tid, bool dry) {
;     ...
;   for (int kt = 0; kt < nk; kt += 2) {
;     const bool l3 = kt + 3 < nk, s2 = kt + 2 < nk, l4 = kt + 4 < nk;
;     FLOAD(f0, 0, 0); FLOAD(f1, 0, 1);
;     FMMA(f0); SSTOREQ(ra1, rb1, 1, 0); if (l3) GLOADQ(ra1, rb1, kt + 3, 0);
;     FLOAD(f0, 0, 2);
;     FMMA(f1); SSTOREQ(ra1, rb1, 1, 1); if (l3) GLOADQ(ra1, rb1, kt + 3, 1);
;     FLOAD(f1, 0, 3);
;     FMMA(f0); SSTOREQ(ra1, rb1, 1, 2); if (l3) GLOADQ(ra1, rb1, kt + 3, 2);
;     FMMA(f1); SSTOREQ(ra1, rb1, 1, 3); if (l3) GLOADQ(ra1, rb1, kt + 3, 3);
;     __syncthreads();
;     FLOAD(f0, 1, 0); FLOAD(f1, 1, 1);
;     FMMA(f0); if (s2) SSTOREQ(ra0, rb0, 0, 0); if (l4) GLOADQ(ra0, rb0, kt + 4, 0);
;     FLOAD(f0, 1, 2);
;     FMMA(f1); if (s2) SSTOREQ(ra0, rb0, 0, 1); if (l4) GLOADQ(ra0, rb0, kt + 4, 1);
;     FLOAD(f1, 1, 3);
;     FMMA(f0); if (s2) SSTOREQ(ra0, rb0, 0, 2); if (l4) GLOADQ(ra0, rb0, kt + 4, 2);
;     FMMA(f1); if (s2) SSTOREQ(ra0, rb0, 0, 3); if (l4) GLOADQ(ra0, rb0, kt + 4, 3);
	ds_read_b128 v[208:211], v167 offset:55296
	ds_read_b128 v[212:215], v132 offset:36864
	v_mfma_f32_32x32x16_bf16 v[0:15], v[236:239], v[246:249], v[0:15]
	ds_read_b128 v[236:239], v132 offset:41472
	ds_read_b128 v[246:249], v167 offset:59904
	s_waitcnt lgkmcnt(2)
	v_mfma_f32_32x32x16_bf16 v[48:63], v[208:211], v[212:215], v[48:63]
	s_waitcnt lgkmcnt(1)
	v_mfma_f32_32x32x16_bf16 v[32:47], v[208:211], v[236:239], v[32:47]
	ds_read_b128 v[208:211], v167 offset:55328
	s_waitcnt lgkmcnt(1)
	v_mfma_f32_32x32x16_bf16 v[16:31], v[246:249], v[212:215], v[16:31]
	ds_read_b128 v[212:215], v132 offset:36896
	v_mfma_f32_32x32x16_bf16 v[0:15], v[246:249], v[236:239], v[0:15]
	ds_read_b128 v[246:249], v132 offset:41504
	ds_read_b128 v[236:239], v167 offset:59936
	s_waitcnt lgkmcnt(2)
	v_mfma_f32_32x32x16_bf16 v[48:63], v[208:211], v[212:215], v[48:63]
	s_waitcnt lgkmcnt(1)
	v_mfma_f32_32x32x16_bf16 v[32:47], v[208:211], v[246:249], v[32:47]
	ds_read_b128 v[208:211], v167 offset:55360
	s_waitcnt vmcnt(15)
	ds_write_b128 v130, v[120:123]
	s_waitcnt vmcnt(14)
	ds_write_b128 v130, v[124:127] offset:18432
	s_waitcnt lgkmcnt(3)
	v_mfma_f32_32x32x16_bf16 v[16:31], v[236:239], v[212:215], v[16:31]
	ds_read_b128 v[212:215], v132 offset:36928
	v_mfma_f32_32x32x16_bf16 v[0:15], v[236:239], v[246:249], v[0:15]
	ds_read_b128 v[236:239], v132 offset:41536
	ds_read_b128 v[246:249], v167 offset:59968
	s_waitcnt lgkmcnt(2)
	v_mfma_f32_32x32x16_bf16 v[48:63], v[208:211], v[212:215], v[48:63]
	s_waitcnt lgkmcnt(1)
	v_mfma_f32_32x32x16_bf16 v[32:47], v[208:211], v[236:239], v[32:47]
	ds_read_b128 v[208:211], v167 offset:55392
	s_waitcnt vmcnt(13)
	ds_write_b128 v130, v[96:99] offset:4608
	s_waitcnt vmcnt(12)
	ds_write_b128 v130, v[100:103] offset:23040
	s_waitcnt lgkmcnt(3)
	v_mfma_f32_32x32x16_bf16 v[16:31], v[246:249], v[212:215], v[16:31]
	ds_read_b128 v[212:215], v132 offset:36960
	v_mfma_f32_32x32x16_bf16 v[0:15], v[246:249], v[236:239], v[0:15]
	ds_read_b128 v[246:249], v132 offset:41568
	ds_read_b128 v[236:239], v167 offset:60000
	s_waitcnt lgkmcnt(2)
	v_mfma_f32_32x32x16_bf16 v[48:63], v[208:211], v[212:215], v[48:63]
	s_waitcnt lgkmcnt(1)
	v_mfma_f32_32x32x16_bf16 v[32:47], v[208:211], v[246:249], v[32:47]
	s_waitcnt lgkmcnt(0)
	v_mfma_f32_32x32x16_bf16 v[16:31], v[236:239], v[212:215], v[16:31]
	global_load_dwordx4 v[120:123], v[150:151], off offset:2304
	global_load_dwordx4 v[124:127], v[152:153], off offset:2304
	global_load_dwordx4 v[96:99], v[158:159], off offset:2304
	global_load_dwordx4 v[100:103], v[164:165], off offset:2304
	s_waitcnt vmcnt(15)
	ds_write_b128 v130, v[72:75] offset:9216
	s_waitcnt vmcnt(14)
	ds_write_b128 v130, v[76:79] offset:27648
	global_load_dwordx4 v[72:75], v[156:157], off offset:2304
	global_load_dwordx4 v[76:79], v[162:163], off offset:2304
	s_waitcnt vmcnt(15)
	ds_write_b128 v130, v[64:67] offset:13824
	s_waitcnt vmcnt(14)
	ds_write_b128 v130, v[68:71] offset:32256
	global_load_dwordx4 v[64:67], v[154:155], off offset:2304
	global_load_dwordx4 v[68:71], v[160:161], off offset:2304
	s_waitcnt lgkmcnt(0)
	s_barrier
	ds_read_b128 v[208:211], v167 offset:18432
	ds_read_b128 v[212:215], v132
	v_mfma_f32_32x32x16_bf16 v[0:15], v[236:239], v[246:249], v[0:15]
	ds_read_b128 v[236:239], v132 offset:4608
	ds_read_b128 v[246:249], v167 offset:23040
	s_waitcnt lgkmcnt(2)
	v_mfma_f32_32x32x16_bf16 v[48:63], v[208:211], v[212:215], v[48:63]
	s_waitcnt lgkmcnt(1)
	v_mfma_f32_32x32x16_bf16 v[32:47], v[208:211], v[236:239], v[32:47]
	ds_read_b128 v[208:211], v167 offset:18464
	s_waitcnt lgkmcnt(1)
	v_mfma_f32_32x32x16_bf16 v[16:31], v[246:249], v[212:215], v[16:31]
	ds_read_b128 v[212:215], v132 offset:32
	v_mfma_f32_32x32x16_bf16 v[0:15], v[246:249], v[236:239], v[0:15]
	ds_read_b128 v[246:249], v132 offset:4640
	ds_read_b128 v[236:239], v167 offset:23072
	s_waitcnt lgkmcnt(2)
	v_mfma_f32_32x32x16_bf16 v[48:63], v[208:211], v[212:215], v[48:63]
	s_waitcnt lgkmcnt(1)
	v_mfma_f32_32x32x16_bf16 v[32:47], v[208:211], v[246:249], v[32:47]
	ds_read_b128 v[208:211], v167 offset:18496
	s_waitcnt vmcnt(15)
	ds_write_b128 v130, v[186:189] offset:36864
	s_waitcnt vmcnt(14)
	ds_write_b128 v130, v[194:197] offset:55296
	s_waitcnt lgkmcnt(3)
	v_mfma_f32_32x32x16_bf16 v[16:31], v[236:239], v[212:215], v[16:31]
	ds_read_b128 v[212:215], v132 offset:64
	v_mfma_f32_32x32x16_bf16 v[0:15], v[236:239], v[246:249], v[0:15]
	ds_read_b128 v[236:239], v132 offset:4672
	ds_read_b128 v[246:249], v167 offset:23104
	s_waitcnt lgkmcnt(2)
	v_mfma_f32_32x32x16_bf16 v[48:63], v[208:211], v[212:215], v[48:63]
	s_waitcnt lgkmcnt(1)
	v_mfma_f32_32x32x16_bf16 v[32:47], v[208:211], v[236:239], v[32:47]
	ds_read_b128 v[208:211], v167 offset:18528
	s_waitcnt vmcnt(13)
	ds_write_b128 v130, v[104:107] offset:41472
	s_waitcnt vmcnt(12)
	ds_write_b128 v130, v[108:111] offset:59904
	s_waitcnt lgkmcnt(3)
	v_mfma_f32_32x32x16_bf16 v[16:31], v[246:249], v[212:215], v[16:31]
	ds_read_b128 v[212:215], v132 offset:96
	v_mfma_f32_32x32x16_bf16 v[0:15], v[246:249], v[236:239], v[0:15]
	ds_read_b128 v[246:249], v132 offset:4704
	ds_read_b128 v[236:239], v167 offset:23136
	s_waitcnt lgkmcnt(2)
	v_mfma_f32_32x32x16_bf16 v[48:63], v[208:211], v[212:215], v[48:63]
	s_waitcnt lgkmcnt(1)
	v_mfma_f32_32x32x16_bf16 v[32:47], v[208:211], v[246:249], v[32:47]
	s_waitcnt lgkmcnt(0)
	v_mfma_f32_32x32x16_bf16 v[16:31], v[236:239], v[212:215], v[16:31]
	global_load_dwordx4 v[186:189], v[150:151], off offset:2432
	global_load_dwordx4 v[194:197], v[152:153], off offset:2432
	global_load_dwordx4 v[104:107], v[158:159], off offset:2432
	global_load_dwordx4 v[108:111], v[164:165], off offset:2432
	s_waitcnt vmcnt(15)
	ds_write_b128 v130, v[80:83] offset:46080
	s_waitcnt vmcnt(14)
	ds_write_b128 v130, v[84:87] offset:64512
	global_load_dwordx4 v[80:83], v[156:157], off offset:2432
	global_load_dwordx4 v[84:87], v[162:163], off offset:2432
	s_waitcnt vmcnt(15)
	ds_write_b128 v130, v[88:91] offset:50688
	s_waitcnt vmcnt(14)
	ds_write_b128 v131, v[92:95] offset:13824
	global_load_dwordx4 v[88:91], v[154:155], off offset:2432
	global_load_dwordx4 v[92:95], v[160:161], off offset:2432
	s_waitcnt lgkmcnt(0)
	s_barrier
; #define GLOADQ(RA, RB, KT, q) do { const int k0_ = (KT) << 6; \
;     RA[q] = ldg16(ap.ptr(m0 + lrow + 32 * (q), k0_) + lkc); RB[q] = ldg16(W + (size_t)(n0 + lrow + 32 * (q)) * ldw + k0_ + lkc); } while (0)
; #define SSTOREQ(RA, RB, ST, q) do { \
;     *(u32x4*)(sA + (ST) * SBUF + (lrow + 32 * (q)) * GP + lkc) = RA[q]; *(u32x4*)(sB + (ST) * SBUF + (lrow + 32 * (q)) * GP + lkc) = RB[q]; } while (0)
; #define FLOAD(F, ST, ks) do { _Pragma("unroll") for (int a = 0; a < 2; ++a) { \
;     F[a] = *(const bf16x8*)(sB + (ST) * SBUF + (wn * 64 + a * 32 + r) * GP + (ks) * 16 + h * 8); \
;     F[2 + a] = *(const bf16x8*)(sA + (ST) * SBUF + (wm * 64 + a * 32 + r) * GP + (ks) * 16 + h * 8); } } while (0)
; #define FMMA(F) do { _Pragma("unroll") for (int a = 0; a < 2; ++a) _Pragma("unroll") for (int b = 0; b < 2; ++b) acc[a][b] = MFMA(F[a], F[2 + b], acc[a][b]); } while (0)
; template <bool MIDK, class AP, class EPI>
; DI void gemm_tile(const AP& ap, const u16* __restrict__ W, int ldw, int K, int m0, int n0, const EPI& epi, char* smem, float r0, float r1, int tid, bool dry) {
;     ...
;   for (int kt = 0; kt < nk; kt += 2) {
;     const bool l3 = kt + 3 < nk, s2 = kt + 2 < nk, l4 = kt + 4 < nk;
;     FLOAD(f0, 0, 0); FLOAD(f1, 0, 1);
;     FMMA(f0); SSTOREQ(ra1, rb1, 1, 0); if (l3) GLOADQ(ra1, rb1, kt + 3, 0);
;     FLOAD(f0, 0, 2);
;     FMMA(f1); SSTOREQ(ra1, rb1, 1, 1); if (l3) GLOADQ(ra1, rb1, kt + 3, 1);
;     FLOAD(f1, 0, 3);
;     FMMA(f0); SSTOREQ(ra1, rb1, 1, 2); if (l3) GLOADQ(ra1, rb1, kt + 3, 2);
;     FMMA(f1); SSTOREQ(ra1, rb1, 1, 3); if (l3) GLOADQ(ra1, rb1, kt + 3, 3);
;     __syncthreads();
;     FLOAD(f0, 1, 0); FLOAD(f1, 1, 1);
;     FMMA(f0); if (s2) SSTOREQ(ra0, rb0, 0, 0); if (l4) GLOADQ(ra0, rb0, kt + 4, 0);
;     FLOAD(f0, 1, 2);
;     FMMA(f1); if (s2) SSTOREQ(ra0, rb0, 0, 1); if (l4) GLOADQ(ra0, rb0, kt + 4, 1);
;     FLOAD(f1, 1, 3);
;     FMMA(f0); if (s2) SSTOREQ(ra0, rb0, 0, 2); if (l4) GLOADQ(ra0, rb0, kt + 4, 2);
;     FMMA(f1); if (s2) SSTOREQ(ra0, rb0, 0, 3); if (l4) GLOADQ(ra0, rb0, kt + 4, 3);
	ds_read_b128 v[208:211], v167 offset:55296
	ds_read_b128 v[212:215], v132 offset:36864
	v_mfma_f32_32x32x16_bf16 v[0:15], v[236:239], v[246:249], v[0:15]
	ds_read_b128 v[236:239], v132 offset:41472
	ds_read_b128 v[246:249], v167 offset:59904
	s_waitcnt lgkmcnt(2)
	v_mfma_f32_32x32x16_bf16 v[48:63], v[208:211], v[212:215], v[48:63]
	s_waitcnt lgkmcnt(1)
	v_mfma_f32_32x32x16_bf16 v[32:47], v[208:211], v[236:239], v[32:47]
	ds_read_b128 v[208:211], v167 offset:55328
	s_waitcnt lgkmcnt(1)
	v_mfma_f32_32x32x16_bf16 v[16:31], v[246:249], v[212:215], v[16:31]
	ds_read_b128 v[212:215], v132 offset:36896
	v_mfma_f32_32x32x16_bf16 v[0:15], v[246:249], v[236:239], v[0:15]
	ds_read_b128 v[246:249], v132 offset:41504
	ds_read_b128 v[236:239], v167 offset:59936
	s_waitcnt lgkmcnt(2)
	v_mfma_f32_32x32x16_bf16 v[48:63], v[208:211], v[212:215], v[48:63]
	s_waitcnt lgkmcnt(1)
	v_mfma_f32_32x32x16_bf16 v[32:47], v[208:211], v[246:249], v[32:47]
	ds_read_b128 v[208:211], v167 offset:55360
	s_waitcnt vmcnt(15)
	ds_write_b128 v130, v[120:123]
	s_waitcnt vmcnt(14)
	ds_write_b128 v130, v[124:127] offset:18432
	s_waitcnt lgkmcnt(3)
	v_mfma_f32_32x32x16_bf16 v[16:31], v[236:239], v[212:215], v[16:31]
	ds_read_b128 v[212:215], v132 offset:36928
	v_mfma_f32_32x32x16_bf16 v[0:15], v[236:239], v[246:249], v[0:15]
	ds_read_b128 v[236:239], v132 offset:41536
	ds_read_b128 v[246:249], v167 offset:59968
	s_waitcnt lgkmcnt(2)
	v_mfma_f32_32x32x16_bf16 v[48:63], v[208:211], v[212:215], v[48:63]
	s_waitcnt lgkmcnt(1)
	v_mfma_f32_32x32x16_bf16 v[32:47], v[208:211], v[236:239], v[32:47]
	ds_read_b128 v[208:211], v167 offset:55392
	s_waitcnt vmcnt(13)
	ds_write_b128 v130, v[96:99] offset:4608
	s_waitcnt vmcnt(12)
	ds_write_b128 v130, v[100:103] offset:23040
	s_waitcnt lgkmcnt(3)
	v_mfma_f32_32x32x16_bf16 v[16:31], v[246:249], v[212:215], v[16:31]
	ds_read_b128 v[212:215], v132 offset:36960
	v_mfma_f32_32x32x16_bf16 v[0:15], v[246:249], v[236:239], v[0:15]
	ds_read_b128 v[246:249], v132 offset:41568
	ds_read_b128 v[236:239], v167 offset:60000
	s_waitcnt lgkmcnt(2)
	v_mfma_f32_32x32x16_bf16 v[48:63], v[208:211], v[212:215], v[48:63]
	s_waitcnt lgkmcnt(1)
	v_mfma_f32_32x32x16_bf16 v[32:47], v[208:211], v[246:249], v[32:47]
	s_waitcnt lgkmcnt(0)
	v_mfma_f32_32x32x16_bf16 v[16:31], v[236:239], v[212:215], v[16:31]
	global_load_dwordx4 v[120:123], v[150:151], off offset:2560
	global_load_dwordx4 v[124:127], v[152:153], off offset:2560
	global_load_dwordx4 v[96:99], v[158:159], off offset:2560
	global_load_dwordx4 v[100:103], v[164:165], off offset:2560
	s_waitcnt vmcnt(15)
	ds_write_b128 v130, v[72:75] offset:9216
	s_waitcnt vmcnt(14)
	ds_write_b128 v130, v[76:79] offset:27648
	global_load_dwordx4 v[72:75], v[156:157], off offset:2560
	global_load_dwordx4 v[76:79], v[162:163], off offset:2560
	s_waitcnt vmcnt(15)
	ds_write_b128 v130, v[64:67] offset:13824
	s_waitcnt vmcnt(14)
	ds_write_b128 v130, v[68:71] offset:32256
	global_load_dwordx4 v[64:67], v[154:155], off offset:2560
	global_load_dwordx4 v[68:71], v[160:161], off offset:2560
	s_waitcnt lgkmcnt(0)
	s_barrier
	ds_read_b128 v[208:211], v167 offset:18432
	ds_read_b128 v[212:215], v132
	v_mfma_f32_32x32x16_bf16 v[0:15], v[236:239], v[246:249], v[0:15]
	ds_read_b128 v[236:239], v132 offset:4608
	ds_read_b128 v[246:249], v167 offset:23040
	s_waitcnt lgkmcnt(2)
	v_mfma_f32_32x32x16_bf16 v[48:63], v[208:211], v[212:215], v[48:63]
	s_waitcnt lgkmcnt(1)
	v_mfma_f32_32x32x16_bf16 v[32:47], v[208:211], v[236:239], v[32:47]
	ds_read_b128 v[208:211], v167 offset:18464
	s_waitcnt lgkmcnt(1)
	v_mfma_f32_32x32x16_bf16 v[16:31], v[246:249], v[212:215], v[16:31]
	ds_read_b128 v[212:215], v132 offset:32
	v_mfma_f32_32x32x16_bf16 v[0:15], v[246:249], v[236:239], v[0:15]
	ds_read_b128 v[246:249], v132 offset:4640
	ds_read_b128 v[236:239], v167 offset:23072
	s_waitcnt lgkmcnt(2)
	v_mfma_f32_32x32x16_bf16 v[48:63], v[208:211], v[212:215], v[48:63]
	s_waitcnt lgkmcnt(1)
	v_mfma_f32_32x32x16_bf16 v[32:47], v[208:211], v[246:249], v[32:47]
	ds_read_b128 v[208:211], v167 offset:18496
	s_waitcnt vmcnt(15)
	ds_write_b128 v130, v[186:189] offset:36864
	s_waitcnt vmcnt(14)
	ds_write_b128 v130, v[194:197] offset:55296
	s_waitcnt lgkmcnt(3)
	v_mfma_f32_32x32x16_bf16 v[16:31], v[236:239], v[212:215], v[16:31]
	ds_read_b128 v[212:215], v132 offset:64
	v_mfma_f32_32x32x16_bf16 v[0:15], v[236:239], v[246:249], v[0:15]
	ds_read_b128 v[236:239], v132 offset:4672
	ds_read_b128 v[246:249], v167 offset:23104
	s_waitcnt lgkmcnt(2)
	v_mfma_f32_32x32x16_bf16 v[48:63], v[208:211], v[212:215], v[48:63]
	s_waitcnt lgkmcnt(1)
	v_mfma_f32_32x32x16_bf16 v[32:47], v[208:211], v[236:239], v[32:47]
	ds_read_b128 v[208:211], v167 offset:18528
	s_waitcnt vmcnt(13)
	ds_write_b128 v130, v[104:107] offset:41472
	s_waitcnt vmcnt(12)
	ds_write_b128 v130, v[108:111] offset:59904
	s_waitcnt lgkmcnt(3)
	v_mfma_f32_32x32x16_bf16 v[16:31], v[246:249], v[212:215], v[16:31]
	ds_read_b128 v[212:215], v132 offset:96
	v_mfma_f32_32x32x16_bf16 v[0:15], v[246:249], v[236:239], v[0:15]
	ds_read_b128 v[246:249], v132 offset:4704
	ds_read_b128 v[236:239], v167 offset:23136
	s_waitcnt lgkmcnt(2)
	v_mfma_f32_32x32x16_bf16 v[48:63], v[208:211], v[212:215], v[48:63]
	s_waitcnt lgkmcnt(1)
	v_mfma_f32_32x32x16_bf16 v[32:47], v[208:211], v[246:249], v[32:47]
	s_waitcnt lgkmcnt(0)
	v_mfma_f32_32x32x16_bf16 v[16:31], v[236:239], v[212:215], v[16:31]
	global_load_dwordx4 v[186:189], v[150:151], off offset:2688
	global_load_dwordx4 v[194:197], v[152:153], off offset:2688
	global_load_dwordx4 v[104:107], v[158:159], off offset:2688
	global_load_dwordx4 v[108:111], v[164:165], off offset:2688
	s_waitcnt vmcnt(15)
	ds_write_b128 v130, v[80:83] offset:46080
	s_waitcnt vmcnt(14)
	ds_write_b128 v130, v[84:87] offset:64512
	global_load_dwordx4 v[80:83], v[156:157], off offset:2688
	global_load_dwordx4 v[84:87], v[162:163], off offset:2688
	s_waitcnt vmcnt(15)
	ds_write_b128 v130, v[88:91] offset:50688
	s_waitcnt vmcnt(14)
	ds_write_b128 v131, v[92:95] offset:13824
	global_load_dwordx4 v[88:91], v[154:155], off offset:2688
	global_load_dwordx4 v[92:95], v[160:161], off offset:2688
	s_waitcnt lgkmcnt(0)
	s_barrier
; #define GLOADQ(RA, RB, KT, q) do { const int k0_ = (KT) << 6; \
;     RA[q] = ldg16(ap.ptr(m0 + lrow + 32 * (q), k0_) + lkc); RB[q] = ldg16(W + (size_t)(n0 + lrow + 32 * (q)) * ldw + k0_ + lkc); } while (0)
; #define SSTOREQ(RA, RB, ST, q) do { \
;     *(u32x4*)(sA + (ST) * SBUF + (lrow + 32 * (q)) * GP + lkc) = RA[q]; *(u32x4*)(sB + (ST) * SBUF + (lrow + 32 * (q)) * GP + lkc) = RB[q]; } while (0)
; #define FLOAD(F, ST, ks) do { _Pragma("unroll") for (int a = 0; a < 2; ++a) { \
;     F[a] = *(const bf16x8*)(sB + (ST) * SBUF + (wn * 64 + a * 32 + r) * GP + (ks) * 16 + h * 8); \
;     F[2 + a] = *(const bf16x8*)(sA + (ST) * SBUF + (wm * 64 + a * 32 + r) * GP + (ks) * 16 + h * 8); } } while (0)
; #define FMMA(F) do { _Pragma("unroll") for (int a = 0; a < 2; ++a) _Pragma("unroll") for (int b = 0; b < 2; ++b) acc[a][b] = MFMA(F[a], F[2 + b], acc[a][b]); } while (0)
; template <bool MIDK, class AP, class EPI>
; DI void gemm_tile(const AP& ap, const u16* __restrict__ W, int ldw, int K, int m0, int n0, const EPI& epi, char* smem, float r0, float r1, int tid, bool dry) {
;     ...
;   for (int kt = 0; kt < nk; kt += 2) {
;     const bool l3 = kt + 3 < nk, s2 = kt + 2 < nk, l4 = kt + 4 < nk;
;     FLOAD(f0, 0, 0); FLOAD(f1, 0, 1);
;     FMMA(f0); SSTOREQ(ra1, rb1, 1, 0); if (l3) GLOADQ(ra1, rb1, kt + 3, 0);
;     FLOAD(f0, 0, 2);
;     FMMA(f1); SSTOREQ(ra1, rb1, 1, 1); if (l3) GLOADQ(ra1, rb1, kt + 3, 1);
;     FLOAD(f1, 0, 3);
;     FMMA(f0); SSTOREQ(ra1, rb1, 1, 2); if (l3) GLOADQ(ra1, rb1, kt + 3, 2);
;     FMMA(f1); SSTOREQ(ra1, rb1, 1, 3); if (l3) GLOADQ(ra1, rb1, kt + 3, 3);
;     __syncthreads();
;     FLOAD(f0, 1, 0); FLOAD(f1, 1, 1);
;     FMMA(f0); if (s2) SSTOREQ(ra0, rb0, 0, 0); if (l4) GLOADQ(ra0, rb0, kt + 4, 0);
;     FLOAD(f0, 1, 2);
;     FMMA(f1); if (s2) SSTOREQ(ra0, rb0, 0, 1); if (l4) GLOADQ(ra0, rb0, kt + 4, 1);
;     FLOAD(f1, 1, 3);
;     FMMA(f0); if (s2) SSTOREQ(ra0, rb0, 0, 2); if (l4) GLOADQ(ra0, rb0, kt + 4, 2);
;     FMMA(f1); if (s2) SSTOREQ(ra0, rb0, 0, 3); if (l4) GLOADQ(ra0, rb0, kt + 4, 3);
	ds_read_b128 v[208:211], v167 offset:55296
	ds_read_b128 v[212:215], v132 offset:36864
	v_mfma_f32_32x32x16_bf16 v[0:15], v[236:239], v[246:249], v[0:15]
	ds_read_b128 v[236:239], v132 offset:41472
	ds_read_b128 v[246:249], v167 offset:59904
	s_waitcnt lgkmcnt(2)
	v_mfma_f32_32x32x16_bf16 v[48:63], v[208:211], v[212:215], v[48:63]
	s_waitcnt lgkmcnt(1)
	v_mfma_f32_32x32x16_bf16 v[32:47], v[208:211], v[236:239], v[32:47]
	ds_read_b128 v[208:211], v167 offset:55328
	s_waitcnt lgkmcnt(1)
	v_mfma_f32_32x32x16_bf16 v[16:31], v[246:249], v[212:215], v[16:31]
	ds_read_b128 v[212:215], v132 offset:36896
	v_mfma_f32_32x32x16_bf16 v[0:15], v[246:249], v[236:239], v[0:15]
	ds_read_b128 v[246:249], v132 offset:41504
	ds_read_b128 v[236:239], v167 offset:59936
	s_waitcnt lgkmcnt(2)
	v_mfma_f32_32x32x16_bf16 v[48:63], v[208:211], v[212:215], v[48:63]
	s_waitcnt lgkmcnt(1)
	v_mfma_f32_32x32x16_bf16 v[32:47], v[208:211], v[246:249], v[32:47]
	ds_read_b128 v[208:211], v167 offset:55360
	s_waitcnt vmcnt(15)
	ds_write_b128 v130, v[120:123]
	s_waitcnt vmcnt(14)
	ds_write_b128 v130, v[124:127] offset:18432
	s_waitcnt lgkmcnt(3)
	v_mfma_f32_32x32x16_bf16 v[16:31], v[236:239], v[212:215], v[16:31]
	ds_read_b128 v[212:215], v132 offset:36928
	v_mfma_f32_32x32x16_bf16 v[0:15], v[236:239], v[246:249], v[0:15]
	ds_read_b128 v[236:239], v132 offset:41536
	ds_read_b128 v[246:249], v167 offset:59968
	s_waitcnt lgkmcnt(2)
	v_mfma_f32_32x32x16_bf16 v[48:63], v[208:211], v[212:215], v[48:63]
	s_waitcnt lgkmcnt(1)
	v_mfma_f32_32x32x16_bf16 v[32:47], v[208:211], v[236:239], v[32:47]
	ds_read_b128 v[208:211], v167 offset:55392
	s_waitcnt vmcnt(13)
	ds_write_b128 v130, v[96:99] offset:4608
	s_waitcnt vmcnt(12)
	ds_write_b128 v130, v[100:103] offset:23040
	s_waitcnt lgkmcnt(3)
	v_mfma_f32_32x32x16_bf16 v[16:31], v[246:249], v[212:215], v[16:31]
	ds_read_b128 v[212:215], v132 offset:36960
	v_mfma_f32_32x32x16_bf16 v[0:15], v[246:249], v[236:239], v[0:15]
	ds_read_b128 v[246:249], v132 offset:41568
	ds_read_b128 v[236:239], v167 offset:60000
	s_waitcnt lgkmcnt(2)
	v_mfma_f32_32x32x16_bf16 v[48:63], v[208:211], v[212:215], v[48:63]
	s_waitcnt lgkmcnt(1)
	v_mfma_f32_32x32x16_bf16 v[32:47], v[208:211], v[246:249], v[32:47]
	s_waitcnt lgkmcnt(0)
	v_mfma_f32_32x32x16_bf16 v[16:31], v[236:239], v[212:215], v[16:31]
	global_load_dwordx4 v[120:123], v[150:151], off offset:2816
	global_load_dwordx4 v[124:127], v[152:153], off offset:2816
	global_load_dwordx4 v[96:99], v[158:159], off offset:2816
	global_load_dwordx4 v[100:103], v[164:165], off offset:2816
	s_waitcnt vmcnt(15)
	ds_write_b128 v130, v[72:75] offset:9216
	s_waitcnt vmcnt(14)
	ds_write_b128 v130, v[76:79] offset:27648
	global_load_dwordx4 v[72:75], v[156:157], off offset:2816
	global_load_dwordx4 v[76:79], v[162:163], off offset:2816
	s_waitcnt vmcnt(15)
	ds_write_b128 v130, v[64:67] offset:13824
	s_waitcnt vmcnt(14)
	ds_write_b128 v130, v[68:71] offset:32256
	global_load_dwordx4 v[64:67], v[154:155], off offset:2816
	global_load_dwordx4 v[68:71], v[160:161], off offset:2816
	s_waitcnt lgkmcnt(0)
	s_barrier
	ds_read_b128 v[208:211], v167 offset:18432
	ds_read_b128 v[212:215], v132
	v_mfma_f32_32x32x16_bf16 v[0:15], v[236:239], v[246:249], v[0:15]
	ds_read_b128 v[236:239], v132 offset:4608
	ds_read_b128 v[246:249], v167 offset:23040
	s_waitcnt lgkmcnt(2)
	v_mfma_f32_32x32x16_bf16 v[48:63], v[208:211], v[212:215], v[48:63]
	s_waitcnt lgkmcnt(1)
	v_mfma_f32_32x32x16_bf16 v[32:47], v[208:211], v[236:239], v[32:47]
	ds_read_b128 v[208:211], v167 offset:18464
	s_waitcnt lgkmcnt(1)
	v_mfma_f32_32x32x16_bf16 v[16:31], v[246:249], v[212:215], v[16:31]
	ds_read_b128 v[212:215], v132 offset:32
	v_mfma_f32_32x32x16_bf16 v[0:15], v[246:249], v[236:239], v[0:15]
	ds_read_b128 v[246:249], v132 offset:4640
	ds_read_b128 v[236:239], v167 offset:23072
	s_waitcnt lgkmcnt(2)
	v_mfma_f32_32x32x16_bf16 v[48:63], v[208:211], v[212:215], v[48:63]
	s_waitcnt lgkmcnt(1)
	v_mfma_f32_32x32x16_bf16 v[32:47], v[208:211], v[246:249], v[32:47]
	ds_read_b128 v[208:211], v167 offset:18496
	s_waitcnt vmcnt(15)
	ds_write_b128 v130, v[186:189] offset:36864
	s_waitcnt vmcnt(14)
	ds_write_b128 v130, v[194:197] offset:55296
	s_waitcnt lgkmcnt(3)
	v_mfma_f32_32x32x16_bf16 v[16:31], v[236:239], v[212:215], v[16:31]
	ds_read_b128 v[212:215], v132 offset:64
	v_mfma_f32_32x32x16_bf16 v[0:15], v[236:239], v[246:249], v[0:15]
	ds_read_b128 v[236:239], v132 offset:4672
	ds_read_b128 v[246:249], v167 offset:23104
	s_waitcnt lgkmcnt(2)
	v_mfma_f32_32x32x16_bf16 v[48:63], v[208:211], v[212:215], v[48:63]
	s_waitcnt lgkmcnt(1)
	v_mfma_f32_32x32x16_bf16 v[32:47], v[208:211], v[236:239], v[32:47]
	ds_read_b128 v[208:211], v167 offset:18528
	s_waitcnt vmcnt(13)
	ds_write_b128 v130, v[104:107] offset:41472
	s_waitcnt vmcnt(12)
	ds_write_b128 v130, v[108:111] offset:59904
	s_waitcnt lgkmcnt(3)
	v_mfma_f32_32x32x16_bf16 v[16:31], v[246:249], v[212:215], v[16:31]
	ds_read_b128 v[212:215], v132 offset:96
	v_mfma_f32_32x32x16_bf16 v[0:15], v[246:249], v[236:239], v[0:15]
	ds_read_b128 v[246:249], v132 offset:4704
	ds_read_b128 v[236:239], v167 offset:23136
	s_waitcnt lgkmcnt(2)
	v_mfma_f32_32x32x16_bf16 v[48:63], v[208:211], v[212:215], v[48:63]
	s_waitcnt lgkmcnt(1)
	v_mfma_f32_32x32x16_bf16 v[32:47], v[208:211], v[246:249], v[32:47]
	s_waitcnt lgkmcnt(0)
	v_mfma_f32_32x32x16_bf16 v[16:31], v[236:239], v[212:215], v[16:31]
	global_load_dwordx4 v[186:189], v[150:151], off offset:2944
	global_load_dwordx4 v[194:197], v[152:153], off offset:2944
	global_load_dwordx4 v[104:107], v[158:159], off offset:2944
	global_load_dwordx4 v[108:111], v[164:165], off offset:2944
	s_waitcnt vmcnt(15)
	ds_write_b128 v130, v[80:83] offset:46080
	s_waitcnt vmcnt(14)
	ds_write_b128 v130, v[84:87] offset:64512
	global_load_dwordx4 v[80:83], v[156:157], off offset:2944
	global_load_dwordx4 v[84:87], v[162:163], off offset:2944
	s_waitcnt vmcnt(15)
	ds_write_b128 v130, v[88:91] offset:50688
	s_waitcnt vmcnt(14)
	ds_write_b128 v131, v[92:95] offset:13824
	global_load_dwordx4 v[88:91], v[154:155], off offset:2944
	global_load_dwordx4 v[92:95], v[160:161], off offset:2944
	s_waitcnt lgkmcnt(0)
	s_barrier
; #define GLOADQ(RA, RB, KT, q) do { const int k0_ = (KT) << 6; \
;     RA[q] = ldg16(ap.ptr(m0 + lrow + 32 * (q), k0_) + lkc); RB[q] = ldg16(W + (size_t)(n0 + lrow + 32 * (q)) * ldw + k0_ + lkc); } while (0)
; #define SSTOREQ(RA, RB, ST, q) do { \
;     *(u32x4*)(sA + (ST) * SBUF + (lrow + 32 * (q)) * GP + lkc) = RA[q]; *(u32x4*)(sB + (ST) * SBUF + (lrow + 32 * (q)) * GP + lkc) = RB[q]; } while (0)
; #define FLOAD(F, ST, ks) do { _Pragma("unroll") for (int a = 0; a < 2; ++a) { \
;     F[a] = *(const bf16x8*)(sB + (ST) * SBUF + (wn * 64 + a * 32 + r) * GP + (ks) * 16 + h * 8); \
;     F[2 + a] = *(const bf16x8*)(sA + (ST) * SBUF + (wm * 64 + a * 32 + r) * GP + (ks) * 16 + h * 8); } } while (0)
; #define FMMA(F) do { _Pragma("unroll") for (int a = 0; a < 2; ++a) _Pragma("unroll") for (int b = 0; b < 2; ++b) acc[a][b] = MFMA(F[a], F[2 + b], acc[a][b]); } while (0)
; template <bool MIDK, class AP, class EPI>
; DI void gemm_tile(const AP& ap, const u16* __restrict__ W, int ldw, int K, int m0, int n0, const EPI& epi, char* smem, float r0, float r1, int tid, bool dry) {
;     ...
;   for (int kt = 0; kt < nk; kt += 2) {
;     const bool l3 = kt + 3 < nk, s2 = kt + 2 < nk, l4 = kt + 4 < nk;
;     FLOAD(f0, 0, 0); FLOAD(f1, 0, 1);
;     FMMA(f0); SSTOREQ(ra1, rb1, 1, 0); if (l3) GLOADQ(ra1, rb1, kt + 3, 0);
;     FLOAD(f0, 0, 2);
;     FMMA(f1); SSTOREQ(ra1, rb1, 1, 1); if (l3) GLOADQ(ra1, rb1, kt + 3, 1);
;     FLOAD(f1, 0, 3);
;     FMMA(f0); SSTOREQ(ra1, rb1, 1, 2); if (l3) GLOADQ(ra1, rb1, kt + 3, 2);
;     FMMA(f1); SSTOREQ(ra1, rb1, 1, 3); if (l3) GLOADQ(ra1, rb1, kt + 3, 3);
;     __syncthreads();
;     FLOAD(f0, 1, 0); FLOAD(f1, 1, 1);
;     FMMA(f0); if (s2) SSTOREQ(ra0, rb0, 0, 0); if (l4) GLOADQ(ra0, rb0, kt + 4, 0);
;     FLOAD(f0, 1, 2);
;     FMMA(f1); if (s2) SSTOREQ(ra0, rb0, 0, 1); if (l4) GLOADQ(ra0, rb0, kt + 4, 1);
;     FLOAD(f1, 1, 3);
;     FMMA(f0); if (s2) SSTOREQ(ra0, rb0, 0, 2); if (l4) GLOADQ(ra0, rb0, kt + 4, 2);
;     FMMA(f1); if (s2) SSTOREQ(ra0, rb0, 0, 3); if (l4) GLOADQ(ra0, rb0, kt + 4, 3);
	ds_read_b128 v[208:211], v167 offset:55296
	ds_read_b128 v[212:215], v132 offset:36864
	v_mfma_f32_32x32x16_bf16 v[0:15], v[236:239], v[246:249], v[0:15]
	ds_read_b128 v[236:239], v132 offset:41472
	ds_read_b128 v[246:249], v167 offset:59904
	s_waitcnt lgkmcnt(2)
	v_mfma_f32_32x32x16_bf16 v[48:63], v[208:211], v[212:215], v[48:63]
	s_waitcnt lgkmcnt(1)
	v_mfma_f32_32x32x16_bf16 v[32:47], v[208:211], v[236:239], v[32:47]
	ds_read_b128 v[208:211], v167 offset:55328
	s_waitcnt lgkmcnt(1)
	v_mfma_f32_32x32x16_bf16 v[16:31], v[246:249], v[212:215], v[16:31]
	ds_read_b128 v[212:215], v132 offset:36896
	v_mfma_f32_32x32x16_bf16 v[0:15], v[246:249], v[236:239], v[0:15]
	ds_read_b128 v[246:249], v132 offset:41504
	ds_read_b128 v[236:239], v167 offset:59936
	s_waitcnt lgkmcnt(2)
	v_mfma_f32_32x32x16_bf16 v[48:63], v[208:211], v[212:215], v[48:63]
	s_waitcnt lgkmcnt(1)
	v_mfma_f32_32x32x16_bf16 v[32:47], v[208:211], v[246:249], v[32:47]
	ds_read_b128 v[208:211], v167 offset:55360
	s_waitcnt vmcnt(15)
	ds_write_b128 v130, v[120:123]
	s_waitcnt vmcnt(14)
	ds_write_b128 v130, v[124:127] offset:18432
	s_waitcnt lgkmcnt(3)
	v_mfma_f32_32x32x16_bf16 v[16:31], v[236:239], v[212:215], v[16:31]
	ds_read_b128 v[212:215], v132 offset:36928
	v_mfma_f32_32x32x16_bf16 v[0:15], v[236:239], v[246:249], v[0:15]
	ds_read_b128 v[236:239], v132 offset:41536
	ds_read_b128 v[246:249], v167 offset:59968
	s_waitcnt lgkmcnt(2)
	v_mfma_f32_32x32x16_bf16 v[48:63], v[208:211], v[212:215], v[48:63]
	s_waitcnt lgkmcnt(1)
	v_mfma_f32_32x32x16_bf16 v[32:47], v[208:211], v[236:239], v[32:47]
	ds_read_b128 v[208:211], v167 offset:55392
	s_waitcnt vmcnt(13)
	ds_write_b128 v130, v[96:99] offset:4608
	s_waitcnt vmcnt(12)
	ds_write_b128 v130, v[100:103] offset:23040
	s_waitcnt lgkmcnt(3)
	v_mfma_f32_32x32x16_bf16 v[16:31], v[246:249], v[212:215], v[16:31]
	ds_read_b128 v[212:215], v132 offset:36960
	v_mfma_f32_32x32x16_bf16 v[0:15], v[246:249], v[236:239], v[0:15]
	ds_read_b128 v[246:249], v132 offset:41568
	ds_read_b128 v[236:239], v167 offset:60000
	s_waitcnt lgkmcnt(2)
	v_mfma_f32_32x32x16_bf16 v[48:63], v[208:211], v[212:215], v[48:63]
	s_waitcnt lgkmcnt(1)
	v_mfma_f32_32x32x16_bf16 v[32:47], v[208:211], v[246:249], v[32:47]
	s_waitcnt lgkmcnt(0)
	v_mfma_f32_32x32x16_bf16 v[16:31], v[236:239], v[212:215], v[16:31]
	global_load_dwordx4 v[120:123], v[150:151], off offset:3072
	global_load_dwordx4 v[124:127], v[152:153], off offset:3072
	global_load_dwordx4 v[96:99], v[158:159], off offset:3072
	global_load_dwordx4 v[100:103], v[164:165], off offset:3072
	s_waitcnt vmcnt(15)
	ds_write_b128 v130, v[72:75] offset:9216
	s_waitcnt vmcnt(14)
	ds_write_b128 v130, v[76:79] offset:27648
	global_load_dwordx4 v[72:75], v[156:157], off offset:3072
	global_load_dwordx4 v[76:79], v[162:163], off offset:3072
	s_waitcnt vmcnt(15)
	ds_write_b128 v130, v[64:67] offset:13824
	s_waitcnt vmcnt(14)
	ds_write_b128 v130, v[68:71] offset:32256
	global_load_dwordx4 v[64:67], v[154:155], off offset:3072
	global_load_dwordx4 v[68:71], v[160:161], off offset:3072
	s_waitcnt lgkmcnt(0)
	s_barrier
	ds_read_b128 v[208:211], v167 offset:18432
	ds_read_b128 v[212:215], v132
	v_mfma_f32_32x32x16_bf16 v[0:15], v[236:239], v[246:249], v[0:15]
	ds_read_b128 v[236:239], v132 offset:4608
	ds_read_b128 v[246:249], v167 offset:23040
	s_waitcnt lgkmcnt(2)
	v_mfma_f32_32x32x16_bf16 v[48:63], v[208:211], v[212:215], v[48:63]
	s_waitcnt lgkmcnt(1)
	v_mfma_f32_32x32x16_bf16 v[32:47], v[208:211], v[236:239], v[32:47]
	ds_read_b128 v[208:211], v167 offset:18464
	s_waitcnt lgkmcnt(1)
	v_mfma_f32_32x32x16_bf16 v[16:31], v[246:249], v[212:215], v[16:31]
	ds_read_b128 v[212:215], v132 offset:32
	v_mfma_f32_32x32x16_bf16 v[0:15], v[246:249], v[236:239], v[0:15]
	ds_read_b128 v[246:249], v132 offset:4640
	ds_read_b128 v[236:239], v167 offset:23072
	s_waitcnt lgkmcnt(2)
	v_mfma_f32_32x32x16_bf16 v[48:63], v[208:211], v[212:215], v[48:63]
	s_waitcnt lgkmcnt(1)
	v_mfma_f32_32x32x16_bf16 v[32:47], v[208:211], v[246:249], v[32:47]
	ds_read_b128 v[208:211], v167 offset:18496
	s_waitcnt vmcnt(15)
	ds_write_b128 v130, v[186:189] offset:36864
	s_waitcnt vmcnt(14)
	ds_write_b128 v130, v[194:197] offset:55296
	s_waitcnt lgkmcnt(3)
	v_mfma_f32_32x32x16_bf16 v[16:31], v[236:239], v[212:215], v[16:31]
	ds_read_b128 v[212:215], v132 offset:64
	v_mfma_f32_32x32x16_bf16 v[0:15], v[236:239], v[246:249], v[0:15]
	ds_read_b128 v[236:239], v132 offset:4672
	ds_read_b128 v[246:249], v167 offset:23104
	s_waitcnt lgkmcnt(2)
	v_mfma_f32_32x32x16_bf16 v[48:63], v[208:211], v[212:215], v[48:63]
	s_waitcnt lgkmcnt(1)
	v_mfma_f32_32x32x16_bf16 v[32:47], v[208:211], v[236:239], v[32:47]
	ds_read_b128 v[208:211], v167 offset:18528
	s_waitcnt vmcnt(13)
	ds_write_b128 v130, v[104:107] offset:41472
	s_waitcnt vmcnt(12)
	ds_write_b128 v130, v[108:111] offset:59904
	s_waitcnt lgkmcnt(3)
	v_mfma_f32_32x32x16_bf16 v[16:31], v[246:249], v[212:215], v[16:31]
	ds_read_b128 v[212:215], v132 offset:96
	v_mfma_f32_32x32x16_bf16 v[0:15], v[246:249], v[236:239], v[0:15]
	ds_read_b128 v[246:249], v132 offset:4704
	ds_read_b128 v[236:239], v167 offset:23136
	s_waitcnt lgkmcnt(2)
	v_mfma_f32_32x32x16_bf16 v[48:63], v[208:211], v[212:215], v[48:63]
	s_waitcnt lgkmcnt(1)
	v_mfma_f32_32x32x16_bf16 v[32:47], v[208:211], v[246:249], v[32:47]
	s_waitcnt lgkmcnt(0)
	v_mfma_f32_32x32x16_bf16 v[16:31], v[236:239], v[212:215], v[16:31]
	global_load_dwordx4 v[186:189], v[150:151], off offset:3200
	global_load_dwordx4 v[194:197], v[152:153], off offset:3200
	global_load_dwordx4 v[104:107], v[158:159], off offset:3200
	global_load_dwordx4 v[108:111], v[164:165], off offset:3200
	s_waitcnt vmcnt(15)
	ds_write_b128 v130, v[80:83] offset:46080
	s_waitcnt vmcnt(14)
	ds_write_b128 v130, v[84:87] offset:64512
	global_load_dwordx4 v[80:83], v[156:157], off offset:3200
	global_load_dwordx4 v[84:87], v[162:163], off offset:3200
	s_waitcnt vmcnt(15)
	ds_write_b128 v130, v[88:91] offset:50688
	s_waitcnt vmcnt(14)
	ds_write_b128 v131, v[92:95] offset:13824
	global_load_dwordx4 v[88:91], v[154:155], off offset:3200
	global_load_dwordx4 v[92:95], v[160:161], off offset:3200
	s_waitcnt lgkmcnt(0)
	s_barrier
; #define GLOADQ(RA, RB, KT, q) do { const int k0_ = (KT) << 6; \
;     RA[q] = ldg16(ap.ptr(m0 + lrow + 32 * (q), k0_) + lkc); RB[q] = ldg16(W + (size_t)(n0 + lrow + 32 * (q)) * ldw + k0_ + lkc); } while (0)
; #define SSTOREQ(RA, RB, ST, q) do { \
;     *(u32x4*)(sA + (ST) * SBUF + (lrow + 32 * (q)) * GP + lkc) = RA[q]; *(u32x4*)(sB + (ST) * SBUF + (lrow + 32 * (q)) * GP + lkc) = RB[q]; } while (0)
; #define FLOAD(F, ST, ks) do { _Pragma("unroll") for (int a = 0; a < 2; ++a) { \
;     F[a] = *(const bf16x8*)(sB + (ST) * SBUF + (wn * 64 + a * 32 + r) * GP + (ks) * 16 + h * 8); \
;     F[2 + a] = *(const bf16x8*)(sA + (ST) * SBUF + (wm * 64 + a * 32 + r) * GP + (ks) * 16 + h * 8); } } while (0)
; #define FMMA(F) do { _Pragma("unroll") for (int a = 0; a < 2; ++a) _Pragma("unroll") for (int b = 0; b < 2; ++b) acc[a][b] = MFMA(F[a], F[2 + b], acc[a][b]); } while (0)
; template <bool MIDK, class AP, class EPI>
; DI void gemm_tile(const AP& ap, const u16* __restrict__ W, int ldw, int K, int m0, int n0, const EPI& epi, char* smem, float r0, float r1, int tid, bool dry) {
;     ...
;   for (int kt = 0; kt < nk; kt += 2) {
;     const bool l3 = kt + 3 < nk, s2 = kt + 2 < nk, l4 = kt + 4 < nk;
;     FLOAD(f0, 0, 0); FLOAD(f1, 0, 1);
;     FMMA(f0); SSTOREQ(ra1, rb1, 1, 0); if (l3) GLOADQ(ra1, rb1, kt + 3, 0);
;     FLOAD(f0, 0, 2);
;     FMMA(f1); SSTOREQ(ra1, rb1, 1, 1); if (l3) GLOADQ(ra1, rb1, kt + 3, 1);
;     FLOAD(f1, 0, 3);
;     FMMA(f0); SSTOREQ(ra1, rb1, 1, 2); if (l3) GLOADQ(ra1, rb1, kt + 3, 2);
;     FMMA(f1); SSTOREQ(ra1, rb1, 1, 3); if (l3) GLOADQ(ra1, rb1, kt + 3, 3);
;     __syncthreads();
;     FLOAD(f0, 1, 0); FLOAD(f1, 1, 1);
;     FMMA(f0); if (s2) SSTOREQ(ra0, rb0, 0, 0); if (l4) GLOADQ(ra0, rb0, kt + 4, 0);
;     FLOAD(f0, 1, 2);
;     FMMA(f1); if (s2) SSTOREQ(ra0, rb0, 0, 1); if (l4) GLOADQ(ra0, rb0, kt + 4, 1);
;     FLOAD(f1, 1, 3);
;     FMMA(f0); if (s2) SSTOREQ(ra0, rb0, 0, 2); if (l4) GLOADQ(ra0, rb0, kt + 4, 2);
;     FMMA(f1); if (s2) SSTOREQ(ra0, rb0, 0, 3); if (l4) GLOADQ(ra0, rb0, kt + 4, 3);
	ds_read_b128 v[208:211], v167 offset:55296
	ds_read_b128 v[212:215], v132 offset:36864
	v_mfma_f32_32x32x16_bf16 v[0:15], v[236:239], v[246:249], v[0:15]
	ds_read_b128 v[236:239], v132 offset:41472
	ds_read_b128 v[246:249], v167 offset:59904
	s_waitcnt lgkmcnt(2)
	v_mfma_f32_32x32x16_bf16 v[48:63], v[208:211], v[212:215], v[48:63]
	s_waitcnt lgkmcnt(1)
	v_mfma_f32_32x32x16_bf16 v[32:47], v[208:211], v[236:239], v[32:47]
	ds_read_b128 v[208:211], v167 offset:55328
	s_waitcnt lgkmcnt(1)
	v_mfma_f32_32x32x16_bf16 v[16:31], v[246:249], v[212:215], v[16:31]
	ds_read_b128 v[212:215], v132 offset:36896
	v_mfma_f32_32x32x16_bf16 v[0:15], v[246:249], v[236:239], v[0:15]
	ds_read_b128 v[246:249], v132 offset:41504
	ds_read_b128 v[236:239], v167 offset:59936
	s_waitcnt lgkmcnt(2)
	v_mfma_f32_32x32x16_bf16 v[48:63], v[208:211], v[212:215], v[48:63]
	s_waitcnt lgkmcnt(1)
	v_mfma_f32_32x32x16_bf16 v[32:47], v[208:211], v[246:249], v[32:47]
	ds_read_b128 v[208:211], v167 offset:55360
	s_waitcnt vmcnt(15)
	ds_write_b128 v130, v[120:123]
	s_waitcnt vmcnt(14)
	ds_write_b128 v130, v[124:127] offset:18432
	s_waitcnt lgkmcnt(3)
	v_mfma_f32_32x32x16_bf16 v[16:31], v[236:239], v[212:215], v[16:31]
	ds_read_b128 v[212:215], v132 offset:36928
	v_mfma_f32_32x32x16_bf16 v[0:15], v[236:239], v[246:249], v[0:15]
	ds_read_b128 v[236:239], v132 offset:41536
	ds_read_b128 v[246:249], v167 offset:59968
	s_waitcnt lgkmcnt(2)
	v_mfma_f32_32x32x16_bf16 v[48:63], v[208:211], v[212:215], v[48:63]
	s_waitcnt lgkmcnt(1)
	v_mfma_f32_32x32x16_bf16 v[32:47], v[208:211], v[236:239], v[32:47]
	ds_read_b128 v[208:211], v167 offset:55392
	s_waitcnt vmcnt(13)
	ds_write_b128 v130, v[96:99] offset:4608
	s_waitcnt vmcnt(12)
	ds_write_b128 v130, v[100:103] offset:23040
	s_waitcnt lgkmcnt(3)
	v_mfma_f32_32x32x16_bf16 v[16:31], v[246:249], v[212:215], v[16:31]
	ds_read_b128 v[212:215], v132 offset:36960
	v_mfma_f32_32x32x16_bf16 v[0:15], v[246:249], v[236:239], v[0:15]
	ds_read_b128 v[246:249], v132 offset:41568
	ds_read_b128 v[236:239], v167 offset:60000
	s_waitcnt lgkmcnt(2)
	v_mfma_f32_32x32x16_bf16 v[48:63], v[208:211], v[212:215], v[48:63]
	s_waitcnt lgkmcnt(1)
	v_mfma_f32_32x32x16_bf16 v[32:47], v[208:211], v[246:249], v[32:47]
	s_waitcnt lgkmcnt(0)
	v_mfma_f32_32x32x16_bf16 v[16:31], v[236:239], v[212:215], v[16:31]
	global_load_dwordx4 v[120:123], v[150:151], off offset:3328
	global_load_dwordx4 v[124:127], v[152:153], off offset:3328
	global_load_dwordx4 v[96:99], v[158:159], off offset:3328
	global_load_dwordx4 v[100:103], v[164:165], off offset:3328
	s_waitcnt vmcnt(15)
	ds_write_b128 v130, v[72:75] offset:9216
	s_waitcnt vmcnt(14)
	ds_write_b128 v130, v[76:79] offset:27648
	global_load_dwordx4 v[72:75], v[156:157], off offset:3328
	global_load_dwordx4 v[76:79], v[162:163], off offset:3328
	s_waitcnt vmcnt(15)
	ds_write_b128 v130, v[64:67] offset:13824
	s_waitcnt vmcnt(14)
	ds_write_b128 v130, v[68:71] offset:32256
	global_load_dwordx4 v[64:67], v[154:155], off offset:3328
	global_load_dwordx4 v[68:71], v[160:161], off offset:3328
	s_waitcnt lgkmcnt(0)
	s_barrier
	ds_read_b128 v[208:211], v167 offset:18432
	ds_read_b128 v[212:215], v132
	v_mfma_f32_32x32x16_bf16 v[0:15], v[236:239], v[246:249], v[0:15]
	ds_read_b128 v[236:239], v132 offset:4608
	ds_read_b128 v[246:249], v167 offset:23040
	s_waitcnt lgkmcnt(2)
	v_mfma_f32_32x32x16_bf16 v[48:63], v[208:211], v[212:215], v[48:63]
	s_waitcnt lgkmcnt(1)
	v_mfma_f32_32x32x16_bf16 v[32:47], v[208:211], v[236:239], v[32:47]
	ds_read_b128 v[208:211], v167 offset:18464
	s_waitcnt lgkmcnt(1)
	v_mfma_f32_32x32x16_bf16 v[16:31], v[246:249], v[212:215], v[16:31]
	ds_read_b128 v[212:215], v132 offset:32
	v_mfma_f32_32x32x16_bf16 v[0:15], v[246:249], v[236:239], v[0:15]
	ds_read_b128 v[246:249], v132 offset:4640
	ds_read_b128 v[236:239], v167 offset:23072
	s_waitcnt lgkmcnt(2)
	v_mfma_f32_32x32x16_bf16 v[48:63], v[208:211], v[212:215], v[48:63]
	s_waitcnt lgkmcnt(1)
	v_mfma_f32_32x32x16_bf16 v[32:47], v[208:211], v[246:249], v[32:47]
	ds_read_b128 v[208:211], v167 offset:18496
	s_waitcnt vmcnt(15)
	ds_write_b128 v130, v[186:189] offset:36864
	s_waitcnt vmcnt(14)
	ds_write_b128 v130, v[194:197] offset:55296
	s_waitcnt lgkmcnt(3)
	v_mfma_f32_32x32x16_bf16 v[16:31], v[236:239], v[212:215], v[16:31]
	ds_read_b128 v[212:215], v132 offset:64
	v_mfma_f32_32x32x16_bf16 v[0:15], v[236:239], v[246:249], v[0:15]
	ds_read_b128 v[236:239], v132 offset:4672
	ds_read_b128 v[246:249], v167 offset:23104
	s_waitcnt lgkmcnt(2)
	v_mfma_f32_32x32x16_bf16 v[48:63], v[208:211], v[212:215], v[48:63]
	s_waitcnt lgkmcnt(1)
	v_mfma_f32_32x32x16_bf16 v[32:47], v[208:211], v[236:239], v[32:47]
	ds_read_b128 v[208:211], v167 offset:18528
	s_waitcnt vmcnt(13)
	ds_write_b128 v130, v[104:107] offset:41472
	s_waitcnt vmcnt(12)
	ds_write_b128 v130, v[108:111] offset:59904
	s_waitcnt lgkmcnt(3)
	v_mfma_f32_32x32x16_bf16 v[16:31], v[246:249], v[212:215], v[16:31]
	ds_read_b128 v[212:215], v132 offset:96
	v_mfma_f32_32x32x16_bf16 v[0:15], v[246:249], v[236:239], v[0:15]
	ds_read_b128 v[246:249], v132 offset:4704
	ds_read_b128 v[236:239], v167 offset:23136
	s_waitcnt lgkmcnt(2)
	v_mfma_f32_32x32x16_bf16 v[48:63], v[208:211], v[212:215], v[48:63]
	s_waitcnt lgkmcnt(1)
	v_mfma_f32_32x32x16_bf16 v[32:47], v[208:211], v[246:249], v[32:47]
	s_waitcnt lgkmcnt(0)
	v_mfma_f32_32x32x16_bf16 v[16:31], v[236:239], v[212:215], v[16:31]
	global_load_dwordx4 v[186:189], v[150:151], off offset:3456
	global_load_dwordx4 v[194:197], v[152:153], off offset:3456
	global_load_dwordx4 v[104:107], v[158:159], off offset:3456
	global_load_dwordx4 v[108:111], v[164:165], off offset:3456
	s_waitcnt vmcnt(15)
	ds_write_b128 v130, v[80:83] offset:46080
	s_waitcnt vmcnt(14)
	ds_write_b128 v130, v[84:87] offset:64512
	global_load_dwordx4 v[80:83], v[156:157], off offset:3456
	global_load_dwordx4 v[84:87], v[162:163], off offset:3456
	s_waitcnt vmcnt(15)
	ds_write_b128 v130, v[88:91] offset:50688
	s_waitcnt vmcnt(14)
	ds_write_b128 v131, v[92:95] offset:13824
	global_load_dwordx4 v[88:91], v[154:155], off offset:3456
	global_load_dwordx4 v[92:95], v[160:161], off offset:3456
	s_waitcnt lgkmcnt(0)
	s_barrier
; #define GLOADQ(RA, RB, KT, q) do { const int k0_ = (KT) << 6; \
;     RA[q] = ldg16(ap.ptr(m0 + lrow + 32 * (q), k0_) + lkc); RB[q] = ldg16(W + (size_t)(n0 + lrow + 32 * (q)) * ldw + k0_ + lkc); } while (0)
; #define SSTOREQ(RA, RB, ST, q) do { \
;     *(u32x4*)(sA + (ST) * SBUF + (lrow + 32 * (q)) * GP + lkc) = RA[q]; *(u32x4*)(sB + (ST) * SBUF + (lrow + 32 * (q)) * GP + lkc) = RB[q]; } while (0)
; #define FLOAD(F, ST, ks) do { _Pragma("unroll") for (int a = 0; a < 2; ++a) { \
;     F[a] = *(const bf16x8*)(sB + (ST) * SBUF + (wn * 64 + a * 32 + r) * GP + (ks) * 16 + h * 8); \
;     F[2 + a] = *(const bf16x8*)(sA + (ST) * SBUF + (wm * 64 + a * 32 + r) * GP + (ks) * 16 + h * 8); } } while (0)
; #define FMMA(F) do { _Pragma("unroll") for (int a = 0; a < 2; ++a) _Pragma("unroll") for (int b = 0; b < 2; ++b) acc[a][b] = MFMA(F[a], F[2 + b], acc[a][b]); } while (0)
; template <bool MIDK, class AP, class EPI>
; DI void gemm_tile(const AP& ap, const u16* __restrict__ W, int ldw, int K, int m0, int n0, const EPI& epi, char* smem, float r0, float r1, int tid, bool dry) {
;     ...
;   for (int kt = 0; kt < nk; kt += 2) {
;     const bool l3 = kt + 3 < nk, s2 = kt + 2 < nk, l4 = kt + 4 < nk;
;     FLOAD(f0, 0, 0); FLOAD(f1, 0, 1);
;     FMMA(f0); SSTOREQ(ra1, rb1, 1, 0); if (l3) GLOADQ(ra1, rb1, kt + 3, 0);
;     FLOAD(f0, 0, 2);
;     FMMA(f1); SSTOREQ(ra1, rb1, 1, 1); if (l3) GLOADQ(ra1, rb1, kt + 3, 1);
;     FLOAD(f1, 0, 3);
;     FMMA(f0); SSTOREQ(ra1, rb1, 1, 2); if (l3) GLOADQ(ra1, rb1, kt + 3, 2);
;     FMMA(f1); SSTOREQ(ra1, rb1, 1, 3); if (l3) GLOADQ(ra1, rb1, kt + 3, 3);
;     __syncthreads();
;     FLOAD(f0, 1, 0); FLOAD(f1, 1, 1);
;     FMMA(f0); if (s2) SSTOREQ(ra0, rb0, 0, 0); if (l4) GLOADQ(ra0, rb0, kt + 4, 0);
;     FLOAD(f0, 1, 2);
;     FMMA(f1); if (s2) SSTOREQ(ra0, rb0, 0, 1); if (l4) GLOADQ(ra0, rb0, kt + 4, 1);
;     FLOAD(f1, 1, 3);
;     FMMA(f0); if (s2) SSTOREQ(ra0, rb0, 0, 2); if (l4) GLOADQ(ra0, rb0, kt + 4, 2);
;     FMMA(f1); if (s2) SSTOREQ(ra0, rb0, 0, 3); if (l4) GLOADQ(ra0, rb0, kt + 4, 3);
	ds_read_b128 v[208:211], v167 offset:55296
	ds_read_b128 v[212:215], v132 offset:36864
	v_mfma_f32_32x32x16_bf16 v[0:15], v[236:239], v[246:249], v[0:15]
	ds_read_b128 v[236:239], v132 offset:41472
	ds_read_b128 v[246:249], v167 offset:59904
	s_waitcnt lgkmcnt(2)
	v_mfma_f32_32x32x16_bf16 v[48:63], v[208:211], v[212:215], v[48:63]
	s_waitcnt lgkmcnt(1)
	v_mfma_f32_32x32x16_bf16 v[32:47], v[208:211], v[236:239], v[32:47]
	ds_read_b128 v[208:211], v167 offset:55328
	s_waitcnt lgkmcnt(1)
	v_mfma_f32_32x32x16_bf16 v[16:31], v[246:249], v[212:215], v[16:31]
	ds_read_b128 v[212:215], v132 offset:36896
	v_mfma_f32_32x32x16_bf16 v[0:15], v[246:249], v[236:239], v[0:15]
	ds_read_b128 v[246:249], v132 offset:41504
	ds_read_b128 v[236:239], v167 offset:59936
	s_waitcnt lgkmcnt(2)
	v_mfma_f32_32x32x16_bf16 v[48:63], v[208:211], v[212:215], v[48:63]
	s_waitcnt lgkmcnt(1)
	v_mfma_f32_32x32x16_bf16 v[32:47], v[208:211], v[246:249], v[32:47]
	ds_read_b128 v[208:211], v167 offset:55360
	s_waitcnt vmcnt(15)
	ds_write_b128 v130, v[120:123]
	s_waitcnt vmcnt(14)
	ds_write_b128 v130, v[124:127] offset:18432
	s_waitcnt lgkmcnt(3)
	v_mfma_f32_32x32x16_bf16 v[16:31], v[236:239], v[212:215], v[16:31]
	ds_read_b128 v[212:215], v132 offset:36928
	v_mfma_f32_32x32x16_bf16 v[0:15], v[236:239], v[246:249], v[0:15]
	ds_read_b128 v[236:239], v132 offset:41536
	ds_read_b128 v[246:249], v167 offset:59968
	s_waitcnt lgkmcnt(2)
	v_mfma_f32_32x32x16_bf16 v[48:63], v[208:211], v[212:215], v[48:63]
	s_waitcnt lgkmcnt(1)
	v_mfma_f32_32x32x16_bf16 v[32:47], v[208:211], v[236:239], v[32:47]
	ds_read_b128 v[208:211], v167 offset:55392
	s_waitcnt vmcnt(13)
	ds_write_b128 v130, v[96:99] offset:4608
	s_waitcnt vmcnt(12)
	ds_write_b128 v130, v[100:103] offset:23040
	s_waitcnt lgkmcnt(3)
	v_mfma_f32_32x32x16_bf16 v[0:15], v[246:249], v[236:239], v[0:15]
	ds_read_b128 v[236:239], v132 offset:36960
	v_mfma_f32_32x32x16_bf16 v[16:31], v[246:249], v[212:215], v[16:31]
	ds_read_b128 v[246:249], v132 offset:41568
	ds_read_b128 v[212:215], v167 offset:60000
	s_waitcnt lgkmcnt(2)
	v_mfma_f32_32x32x16_bf16 v[48:63], v[208:211], v[236:239], v[48:63]
	s_waitcnt lgkmcnt(1)
	v_mfma_f32_32x32x16_bf16 v[32:47], v[208:211], v[246:249], v[32:47]
	global_load_dwordx4 v[200:203], v[150:151], off offset:3584
	global_load_dwordx4 v[204:207], v[152:153], off offset:3584
	global_load_dwordx4 v[112:115], v[158:159], off offset:3584
	global_load_dwordx4 v[116:119], v[164:165], off offset:3584
	s_waitcnt vmcnt(15)
	ds_write_b128 v130, v[72:75] offset:9216
	s_waitcnt vmcnt(14)
	ds_write_b128 v130, v[76:79] offset:27648
	global_load_dwordx4 v[72:75], v[156:157], off offset:3584
	global_load_dwordx4 v[76:79], v[162:163], off offset:3584
	s_waitcnt vmcnt(15)
	ds_write_b128 v130, v[64:67] offset:13824
	s_waitcnt vmcnt(14)
	ds_write_b128 v130, v[68:71] offset:32256
	s_waitcnt lgkmcnt(4)
	v_mfma_f32_32x32x16_bf16 v[16:31], v[212:215], v[236:239], v[16:31]
	v_mfma_f32_32x32x16_bf16 v[0:15], v[212:215], v[246:249], v[0:15]
	global_load_dwordx4 v[96:99], v[154:155], off offset:3584
	global_load_dwordx4 v[100:103], v[160:161], off offset:3584
	s_waitcnt lgkmcnt(0)
	s_barrier
	ds_read_b128 v[208:211], v167 offset:18432
	ds_read_b128 v[236:239], v132
	ds_read_b128 v[212:215], v132 offset:4608
	ds_read_b128 v[246:249], v167 offset:23040
	s_waitcnt lgkmcnt(2)
	v_mfma_f32_32x32x16_bf16 v[48:63], v[208:211], v[236:239], v[48:63]
	s_waitcnt lgkmcnt(1)
	v_mfma_f32_32x32x16_bf16 v[32:47], v[208:211], v[212:215], v[32:47]
	ds_read_b128 v[208:211], v167 offset:18464
	s_waitcnt lgkmcnt(1)
	v_mfma_f32_32x32x16_bf16 v[16:31], v[246:249], v[236:239], v[16:31]
	ds_read_b128 v[236:239], v132 offset:32
	v_mfma_f32_32x32x16_bf16 v[0:15], v[246:249], v[212:215], v[0:15]
	ds_read_b128 v[246:249], v132 offset:4640
	ds_read_b128 v[212:215], v167 offset:23072
	s_waitcnt lgkmcnt(2)
	v_mfma_f32_32x32x16_bf16 v[48:63], v[208:211], v[236:239], v[48:63]
	s_waitcnt lgkmcnt(1)
	v_mfma_f32_32x32x16_bf16 v[32:47], v[208:211], v[246:249], v[32:47]
	ds_read_b128 v[208:211], v167 offset:18496
	s_waitcnt vmcnt(15)
	ds_write_b128 v130, v[186:189] offset:36864
	s_waitcnt vmcnt(14)
	ds_write_b128 v130, v[194:197] offset:55296
	s_waitcnt lgkmcnt(3)
	v_mfma_f32_32x32x16_bf16 v[16:31], v[212:215], v[236:239], v[16:31]
	ds_read_b128 v[236:239], v132 offset:64
	v_mfma_f32_32x32x16_bf16 v[0:15], v[212:215], v[246:249], v[0:15]
	ds_read_b128 v[212:215], v132 offset:4672
	ds_read_b128 v[246:249], v167 offset:23104
	s_waitcnt lgkmcnt(2)
	v_mfma_f32_32x32x16_bf16 v[48:63], v[208:211], v[236:239], v[48:63]
	s_waitcnt lgkmcnt(1)
	v_mfma_f32_32x32x16_bf16 v[32:47], v[208:211], v[212:215], v[32:47]
	ds_read_b128 v[208:211], v167 offset:18528
	s_waitcnt vmcnt(13)
	ds_write_b128 v130, v[104:107] offset:41472
	s_waitcnt vmcnt(12)
	ds_write_b128 v130, v[108:111] offset:59904
	s_waitcnt lgkmcnt(3)
	v_mfma_f32_32x32x16_bf16 v[16:31], v[246:249], v[236:239], v[16:31]
	ds_read_b128 v[236:239], v132 offset:96
	v_mfma_f32_32x32x16_bf16 v[0:15], v[246:249], v[212:215], v[0:15]
	ds_read_b128 v[246:249], v132 offset:4704
	ds_read_b128 v[212:215], v167 offset:23136
	s_waitcnt lgkmcnt(2)
	v_mfma_f32_32x32x16_bf16 v[48:63], v[208:211], v[236:239], v[48:63]
	s_waitcnt lgkmcnt(1)
	v_mfma_f32_32x32x16_bf16 v[32:47], v[208:211], v[246:249], v[32:47]
	global_load_dwordx4 v[186:189], v[150:151], off offset:3712
	global_load_dwordx4 v[194:197], v[152:153], off offset:3712
	global_load_dwordx4 v[120:123], v[158:159], off offset:3712
	global_load_dwordx4 v[124:127], v[164:165], off offset:3712
	s_waitcnt vmcnt(15)
	ds_write_b128 v130, v[80:83] offset:46080
	s_waitcnt vmcnt(14)
	ds_write_b128 v130, v[84:87] offset:64512
	global_load_dwordx4 v[80:83], v[156:157], off offset:3712
	global_load_dwordx4 v[84:87], v[162:163], off offset:3712
	s_waitcnt vmcnt(15)
	ds_write_b128 v130, v[88:91] offset:50688
	s_waitcnt vmcnt(14)
	ds_write_b128 v131, v[92:95] offset:13824
	global_load_dwordx4 v[88:91], v[154:155], off offset:3712
	global_load_dwordx4 v[92:95], v[160:161], off offset:3712
	s_waitcnt lgkmcnt(4)
	v_mfma_f32_32x32x16_bf16 v[16:31], v[212:215], v[236:239], v[16:31]
	s_waitcnt lgkmcnt(0)
	s_barrier
; #define GLOADQ(RA, RB, KT, q) do { const int k0_ = (KT) << 6; \
;     RA[q] = ldg16(ap.ptr(m0 + lrow + 32 * (q), k0_) + lkc); RB[q] = ldg16(W + (size_t)(n0 + lrow + 32 * (q)) * ldw + k0_ + lkc); } while (0)
; #define SSTOREQ(RA, RB, ST, q) do { \
;     *(u32x4*)(sA + (ST) * SBUF + (lrow + 32 * (q)) * GP + lkc) = RA[q]; *(u32x4*)(sB + (ST) * SBUF + (lrow + 32 * (q)) * GP + lkc) = RB[q]; } while (0)
; #define FLOAD(F, ST, ks) do { _Pragma("unroll") for (int a = 0; a < 2; ++a) { \
;     F[a] = *(const bf16x8*)(sB + (ST) * SBUF + (wn * 64 + a * 32 + r) * GP + (ks) * 16 + h * 8); \
;     F[2 + a] = *(const bf16x8*)(sA + (ST) * SBUF + (wm * 64 + a * 32 + r) * GP + (ks) * 16 + h * 8); } } while (0)
; #define FMMA(F) do { _Pragma("unroll") for (int a = 0; a < 2; ++a) _Pragma("unroll") for (int b = 0; b < 2; ++b) acc[a][b] = MFMA(F[a], F[2 + b], acc[a][b]); } while (0)
; template <bool MIDK, class AP, class EPI>
; DI void gemm_tile(const AP& ap, const u16* __restrict__ W, int ldw, int K, int m0, int n0, const EPI& epi, char* smem, float r0, float r1, int tid, bool dry) {
;     ...
;   for (int kt = 0; kt < nk; kt += 2) {
;     const bool l3 = kt + 3 < nk, s2 = kt + 2 < nk, l4 = kt + 4 < nk;
;     FLOAD(f0, 0, 0); FLOAD(f1, 0, 1);
;     FMMA(f0); SSTOREQ(ra1, rb1, 1, 0); if (l3) GLOADQ(ra1, rb1, kt + 3, 0);
;     FLOAD(f0, 0, 2);
;     FMMA(f1); SSTOREQ(ra1, rb1, 1, 1); if (l3) GLOADQ(ra1, rb1, kt + 3, 1);
;     FLOAD(f1, 0, 3);
;     FMMA(f0); SSTOREQ(ra1, rb1, 1, 2); if (l3) GLOADQ(ra1, rb1, kt + 3, 2);
;     FMMA(f1); SSTOREQ(ra1, rb1, 1, 3); if (l3) GLOADQ(ra1, rb1, kt + 3, 3);
;     __syncthreads();
;     FLOAD(f0, 1, 0); FLOAD(f1, 1, 1);
;     FMMA(f0); if (s2) SSTOREQ(ra0, rb0, 0, 0); if (l4) GLOADQ(ra0, rb0, kt + 4, 0);
;     FLOAD(f0, 1, 2);
;     FMMA(f1); if (s2) SSTOREQ(ra0, rb0, 0, 1); if (l4) GLOADQ(ra0, rb0, kt + 4, 1);
;     FLOAD(f1, 1, 3);
;     FMMA(f0); if (s2) SSTOREQ(ra0, rb0, 0, 2); if (l4) GLOADQ(ra0, rb0, kt + 4, 2);
;     FMMA(f1); if (s2) SSTOREQ(ra0, rb0, 0, 3); if (l4) GLOADQ(ra0, rb0, kt + 4, 3);
	ds_read_b128 v[208:211], v167 offset:55296
	ds_read_b128 v[236:239], v132 offset:36864
	v_mfma_f32_32x32x16_bf16 v[0:15], v[212:215], v[246:249], v[0:15]
	ds_read_b128 v[212:215], v132 offset:41472
	ds_read_b128 v[246:249], v167 offset:59904
	s_waitcnt lgkmcnt(2)
	v_mfma_f32_32x32x16_bf16 v[48:63], v[208:211], v[236:239], v[48:63]
	s_waitcnt lgkmcnt(1)
	v_mfma_f32_32x32x16_bf16 v[32:47], v[208:211], v[212:215], v[32:47]
	ds_read_b128 v[208:211], v167 offset:55328
	s_waitcnt lgkmcnt(1)
	v_mfma_f32_32x32x16_bf16 v[16:31], v[246:249], v[236:239], v[16:31]
	ds_read_b128 v[236:239], v132 offset:36896
	v_mfma_f32_32x32x16_bf16 v[0:15], v[246:249], v[212:215], v[0:15]
	ds_read_b128 v[246:249], v132 offset:41504
	ds_read_b128 v[212:215], v167 offset:59936
	s_waitcnt lgkmcnt(2)
	v_mfma_f32_32x32x16_bf16 v[48:63], v[208:211], v[236:239], v[48:63]
	s_waitcnt lgkmcnt(1)
	v_mfma_f32_32x32x16_bf16 v[32:47], v[208:211], v[246:249], v[32:47]
	ds_read_b128 v[208:211], v167 offset:55360
	s_waitcnt vmcnt(15)
	ds_write_b128 v130, v[200:203]
	s_waitcnt vmcnt(14)
	ds_write_b128 v130, v[204:207] offset:18432
	s_waitcnt lgkmcnt(3)
	v_mfma_f32_32x32x16_bf16 v[16:31], v[212:215], v[236:239], v[16:31]
	ds_read_b128 v[236:239], v132 offset:36928
	v_mfma_f32_32x32x16_bf16 v[0:15], v[212:215], v[246:249], v[0:15]
	ds_read_b128 v[212:215], v132 offset:41536
	ds_read_b128 v[246:249], v167 offset:59968
	s_waitcnt lgkmcnt(2)
	v_mfma_f32_32x32x16_bf16 v[48:63], v[208:211], v[236:239], v[48:63]
	s_waitcnt lgkmcnt(1)
	v_mfma_f32_32x32x16_bf16 v[32:47], v[208:211], v[212:215], v[32:47]
	ds_read_b128 v[208:211], v167 offset:55392
	s_waitcnt vmcnt(13)
	ds_write_b128 v130, v[112:115] offset:4608
	s_waitcnt vmcnt(12)
	ds_write_b128 v130, v[116:119] offset:23040
	s_waitcnt lgkmcnt(3)
	v_mfma_f32_32x32x16_bf16 v[16:31], v[246:249], v[236:239], v[16:31]
	ds_read_b128 v[236:239], v132 offset:36960
	v_mfma_f32_32x32x16_bf16 v[0:15], v[246:249], v[212:215], v[0:15]
	ds_read_b128 v[246:249], v132 offset:41568
	ds_read_b128 v[212:215], v167 offset:60000
	global_load_dwordx4 v[200:203], v[150:151], off offset:3840
	global_load_dwordx4 v[204:207], v[152:153], off offset:3840
	global_load_dwordx4 v[104:107], v[158:159], off offset:3840
	global_load_dwordx4 v[108:111], v[164:165], off offset:3840
	s_waitcnt vmcnt(15)
	ds_write_b128 v130, v[72:75] offset:9216
	s_waitcnt vmcnt(14)
	ds_write_b128 v130, v[76:79] offset:27648
	s_waitcnt lgkmcnt(4)
	v_mfma_f32_32x32x16_bf16 v[48:63], v[208:211], v[236:239], v[48:63]
	s_waitcnt lgkmcnt(3)
	v_mfma_f32_32x32x16_bf16 v[32:47], v[208:211], v[246:249], v[32:47]
	s_waitcnt lgkmcnt(2)
	v_mfma_f32_32x32x16_bf16 v[16:31], v[212:215], v[236:239], v[16:31]
	global_load_dwordx4 v[64:67], v[156:157], off offset:3840
	global_load_dwordx4 v[68:71], v[162:163], off offset:3840
	s_waitcnt vmcnt(15)
	ds_write_b128 v130, v[96:99] offset:13824
	s_waitcnt vmcnt(14)
	ds_write_b128 v130, v[100:103] offset:32256
	global_load_dwordx4 v[72:75], v[154:155], off offset:3840
	global_load_dwordx4 v[76:79], v[160:161], off offset:3840
	s_waitcnt lgkmcnt(0)
	s_barrier
	ds_read_b128 v[208:211], v167 offset:18432
	ds_read_b128 v[236:239], v132
	v_mfma_f32_32x32x16_bf16 v[0:15], v[212:215], v[246:249], v[0:15]
	ds_read_b128 v[212:215], v132 offset:4608
	ds_read_b128 v[246:249], v167 offset:23040
	s_waitcnt lgkmcnt(2)
	v_mfma_f32_32x32x16_bf16 v[48:63], v[208:211], v[236:239], v[48:63]
	s_waitcnt lgkmcnt(1)
	v_mfma_f32_32x32x16_bf16 v[32:47], v[208:211], v[212:215], v[32:47]
	ds_read_b128 v[208:211], v167 offset:18464
	s_waitcnt lgkmcnt(1)
	v_mfma_f32_32x32x16_bf16 v[16:31], v[246:249], v[236:239], v[16:31]
	ds_read_b128 v[236:239], v132 offset:32
	v_mfma_f32_32x32x16_bf16 v[0:15], v[246:249], v[212:215], v[0:15]
	ds_read_b128 v[246:249], v132 offset:4640
	ds_read_b128 v[212:215], v167 offset:23072
	s_waitcnt lgkmcnt(2)
	v_mfma_f32_32x32x16_bf16 v[48:63], v[208:211], v[236:239], v[48:63]
	s_waitcnt lgkmcnt(1)
	v_mfma_f32_32x32x16_bf16 v[32:47], v[208:211], v[246:249], v[32:47]
	ds_read_b128 v[208:211], v167 offset:18496
	s_waitcnt vmcnt(15)
	ds_write_b128 v130, v[186:189] offset:36864
	s_waitcnt vmcnt(14)
	ds_write_b128 v130, v[194:197] offset:55296
	s_waitcnt lgkmcnt(3)
	v_mfma_f32_32x32x16_bf16 v[16:31], v[212:215], v[236:239], v[16:31]
	ds_read_b128 v[236:239], v132 offset:64
	v_mfma_f32_32x32x16_bf16 v[0:15], v[212:215], v[246:249], v[0:15]
	ds_read_b128 v[212:215], v132 offset:4672
	ds_read_b128 v[246:249], v167 offset:23104
	s_waitcnt lgkmcnt(2)
	v_mfma_f32_32x32x16_bf16 v[48:63], v[208:211], v[236:239], v[48:63]
	s_waitcnt lgkmcnt(1)
	v_mfma_f32_32x32x16_bf16 v[32:47], v[208:211], v[212:215], v[32:47]
	ds_read_b128 v[208:211], v167 offset:18528
	s_waitcnt vmcnt(13)
	ds_write_b128 v130, v[120:123] offset:41472
	s_waitcnt vmcnt(12)
	ds_write_b128 v130, v[124:127] offset:59904
	s_waitcnt lgkmcnt(3)
	v_mfma_f32_32x32x16_bf16 v[16:31], v[246:249], v[236:239], v[16:31]
	ds_read_b128 v[236:239], v132 offset:96
	v_mfma_f32_32x32x16_bf16 v[0:15], v[246:249], v[212:215], v[0:15]
	ds_read_b128 v[246:249], v132 offset:4704
	ds_read_b128 v[212:215], v167 offset:23136
	s_waitcnt lgkmcnt(2)
	v_mfma_f32_32x32x16_bf16 v[48:63], v[208:211], v[236:239], v[48:63]
	s_waitcnt lgkmcnt(1)
	v_mfma_f32_32x32x16_bf16 v[32:47], v[208:211], v[246:249], v[32:47]
	s_waitcnt lgkmcnt(0)
	v_mfma_f32_32x32x16_bf16 v[16:31], v[212:215], v[236:239], v[16:31]
	global_load_dwordx4 v[120:123], v[150:151], off offset:3968
	global_load_dwordx4 v[124:127], v[152:153], off offset:3968
	global_load_dwordx4 v[96:99], v[158:159], off offset:3968
	global_load_dwordx4 v[100:103], v[164:165], off offset:3968
	s_waitcnt vmcnt(15)
	ds_write_b128 v130, v[80:83] offset:46080
	s_waitcnt vmcnt(14)
	ds_write_b128 v130, v[84:87] offset:64512
	global_load_dwordx4 v[80:83], v[156:157], off offset:3968
	global_load_dwordx4 v[84:87], v[162:163], off offset:3968
	s_waitcnt vmcnt(15)
	ds_write_b128 v130, v[88:91] offset:50688
	s_waitcnt vmcnt(14)
	ds_write_b128 v131, v[92:95] offset:13824
	global_load_dwordx4 v[88:91], v[154:155], off offset:3968
	global_load_dwordx4 v[92:95], v[160:161], off offset:3968
	s_waitcnt lgkmcnt(0)
	s_barrier
; #define GLOADQ(RA, RB, KT, q) do { const int k0_ = (KT) << 6; \
;     RA[q] = ldg16(ap.ptr(m0 + lrow + 32 * (q), k0_) + lkc); RB[q] = ldg16(W + (size_t)(n0 + lrow + 32 * (q)) * ldw + k0_ + lkc); } while (0)
; #define SSTOREQ(RA, RB, ST, q) do { \
;     *(u32x4*)(sA + (ST) * SBUF + (lrow + 32 * (q)) * GP + lkc) = RA[q]; *(u32x4*)(sB + (ST) * SBUF + (lrow + 32 * (q)) * GP + lkc) = RB[q]; } while (0)
; #define FLOAD(F, ST, ks) do { _Pragma("unroll") for (int a = 0; a < 2; ++a) { \
;     F[a] = *(const bf16x8*)(sB + (ST) * SBUF + (wn * 64 + a * 32 + r) * GP + (ks) * 16 + h * 8); \
;     F[2 + a] = *(const bf16x8*)(sA + (ST) * SBUF + (wm * 64 + a * 32 + r) * GP + (ks) * 16 + h * 8); } } while (0)
; #define FMMA(F) do { _Pragma("unroll") for (int a = 0; a < 2; ++a) _Pragma("unroll") for (int b = 0; b < 2; ++b) acc[a][b] = MFMA(F[a], F[2 + b], acc[a][b]); } while (0)
; template <bool MIDK, class AP, class EPI>
; DI void gemm_tile(const AP& ap, const u16* __restrict__ W, int ldw, int K, int m0, int n0, const EPI& epi, char* smem, float r0, float r1, int tid, bool dry) {
;     ...
;   const int nk = K >> 6;
;     ...
;   for (int kt = 0; kt < nk; kt += 2) {
;     const bool l3 = kt + 3 < nk, s2 = kt + 2 < nk, l4 = kt + 4 < nk;
;     FLOAD(f0, 0, 0); FLOAD(f1, 0, 1);
;     FMMA(f0); SSTOREQ(ra1, rb1, 1, 0); if (l3) GLOADQ(ra1, rb1, kt + 3, 0);
;     FLOAD(f0, 0, 2);
;     FMMA(f1); SSTOREQ(ra1, rb1, 1, 1); if (l3) GLOADQ(ra1, rb1, kt + 3, 1);
;     FLOAD(f1, 0, 3);
;     FMMA(f0); SSTOREQ(ra1, rb1, 1, 2); if (l3) GLOADQ(ra1, rb1, kt + 3, 2);
;     FMMA(f1); SSTOREQ(ra1, rb1, 1, 3); if (l3) GLOADQ(ra1, rb1, kt + 3, 3);
;     __syncthreads();
;     FLOAD(f0, 1, 0); FLOAD(f1, 1, 1);
;     FMMA(f0); if (s2) SSTOREQ(ra0, rb0, 0, 0); if (l4) GLOADQ(ra0, rb0, kt + 4, 0);
;     FLOAD(f0, 1, 2);
;     FMMA(f1); if (s2) SSTOREQ(ra0, rb0, 0, 1); if (l4) GLOADQ(ra0, rb0, kt + 4, 1);
;     FLOAD(f1, 1, 3);
;     FMMA(f0); if (s2) SSTOREQ(ra0, rb0, 0, 2); if (l4) GLOADQ(ra0, rb0, kt + 4, 2);
;     FMMA(f1); if (s2) SSTOREQ(ra0, rb0, 0, 3); if (l4) GLOADQ(ra0, rb0, kt + 4, 3);
	ds_read_b128 v[208:211], v167 offset:55296
	ds_read_b128 v[236:239], v132 offset:36864
	v_mfma_f32_32x32x16_bf16 v[0:15], v[212:215], v[246:249], v[0:15]
	ds_read_b128 v[212:215], v132 offset:41472
	ds_read_b128 v[246:249], v167 offset:59904
	s_waitcnt lgkmcnt(2)
	v_mfma_f32_32x32x16_bf16 v[48:63], v[208:211], v[236:239], v[48:63]
	s_waitcnt lgkmcnt(1)
	v_mfma_f32_32x32x16_bf16 v[32:47], v[208:211], v[212:215], v[32:47]
	ds_read_b128 v[208:211], v167 offset:55328
	s_waitcnt lgkmcnt(1)
	v_mfma_f32_32x32x16_bf16 v[16:31], v[246:249], v[236:239], v[16:31]
	ds_read_b128 v[236:239], v132 offset:36896
	v_mfma_f32_32x32x16_bf16 v[0:15], v[246:249], v[212:215], v[0:15]
	ds_read_b128 v[246:249], v132 offset:41504
	ds_read_b128 v[212:215], v167 offset:59936
	s_waitcnt lgkmcnt(2)
	v_mfma_f32_32x32x16_bf16 v[48:63], v[208:211], v[236:239], v[48:63]
	s_waitcnt lgkmcnt(1)
	v_mfma_f32_32x32x16_bf16 v[32:47], v[208:211], v[246:249], v[32:47]
	ds_read_b128 v[208:211], v167 offset:55360
	s_waitcnt vmcnt(15)
	ds_write_b128 v130, v[200:203]
	s_waitcnt vmcnt(14)
	ds_write_b128 v130, v[204:207] offset:18432
	s_waitcnt lgkmcnt(3)
	v_mfma_f32_32x32x16_bf16 v[16:31], v[212:215], v[236:239], v[16:31]
	ds_read_b128 v[236:239], v132 offset:36928
	v_mfma_f32_32x32x16_bf16 v[0:15], v[212:215], v[246:249], v[0:15]
	ds_read_b128 v[212:215], v132 offset:41536
	ds_read_b128 v[246:249], v167 offset:59968
	s_waitcnt lgkmcnt(2)
	v_mfma_f32_32x32x16_bf16 v[48:63], v[208:211], v[236:239], v[48:63]
	s_waitcnt lgkmcnt(1)
	v_mfma_f32_32x32x16_bf16 v[32:47], v[208:211], v[212:215], v[32:47]
	ds_read_b128 v[208:211], v167 offset:55392
	s_waitcnt vmcnt(13)
	ds_write_b128 v130, v[104:107] offset:4608
	s_waitcnt vmcnt(12)
	ds_write_b128 v130, v[108:111] offset:23040
	s_waitcnt lgkmcnt(3)
	v_mfma_f32_32x32x16_bf16 v[16:31], v[246:249], v[236:239], v[16:31]
	ds_read_b128 v[236:239], v132 offset:36960
	v_mfma_f32_32x32x16_bf16 v[0:15], v[246:249], v[212:215], v[0:15]
	ds_read_b128 v[246:249], v132 offset:41568
	ds_read_b128 v[212:215], v167 offset:60000
	v_add_co_u32_e32 v112, vcc, s5, v150
	s_nop 1
	v_addc_co_u32_e32 v113, vcc, 0, v151, vcc
	v_add_co_u32_e32 v114, vcc, s5, v152
	s_waitcnt lgkmcnt(2)
	v_mfma_f32_32x32x16_bf16 v[48:63], v[208:211], v[236:239], v[48:63]
	v_addc_co_u32_e32 v115, vcc, 0, v153, vcc
	s_andn2_b64 vcc, exec, s[38:39]
	s_waitcnt lgkmcnt(1)
	v_mfma_f32_32x32x16_bf16 v[32:47], v[208:211], v[246:249], v[32:47]
	s_waitcnt lgkmcnt(0)
	v_mfma_f32_32x32x16_bf16 v[16:31], v[212:215], v[236:239], v[16:31]
	global_load_dwordx4 v[150:153], v[112:113], off
	global_load_dwordx4 v[158:161], v[114:115], off
	global_load_dwordx4 v[104:107], v[138:139], off
	global_load_dwordx4 v[108:111], v[140:141], off
	s_waitcnt vmcnt(15)
	ds_write_b128 v130, v[64:67] offset:9216
	s_waitcnt vmcnt(14)
	ds_write_b128 v130, v[68:71] offset:27648
	global_load_dwordx4 v[64:67], v[142:143], off
	global_load_dwordx4 v[68:71], v[144:145], off
	s_waitcnt vmcnt(15)
	ds_write_b128 v130, v[72:75] offset:13824
	s_waitcnt vmcnt(14)
	ds_write_b128 v130, v[76:79] offset:32256
	global_load_dwordx4 v[72:75], v[146:147], off
	global_load_dwordx4 v[76:79], v[148:149], off
	s_waitcnt lgkmcnt(0)
	s_barrier
	ds_read_b128 v[208:211], v167 offset:18432
	ds_read_b128 v[236:239], v132
	v_mfma_f32_32x32x16_bf16 v[0:15], v[212:215], v[246:249], v[0:15]
	ds_read_b128 v[212:215], v132 offset:4608
	ds_read_b128 v[246:249], v167 offset:23040
	s_waitcnt lgkmcnt(2)
	v_mfma_f32_32x32x16_bf16 v[48:63], v[208:211], v[236:239], v[48:63]
	s_waitcnt lgkmcnt(1)
	v_mfma_f32_32x32x16_bf16 v[32:47], v[208:211], v[212:215], v[32:47]
	ds_read_b128 v[208:211], v167 offset:18464
	s_waitcnt lgkmcnt(1)
	v_mfma_f32_32x32x16_bf16 v[16:31], v[246:249], v[236:239], v[16:31]
	ds_read_b128 v[236:239], v132 offset:32
	v_mfma_f32_32x32x16_bf16 v[0:15], v[246:249], v[212:215], v[0:15]
	ds_read_b128 v[246:249], v132 offset:4640
	ds_read_b128 v[212:215], v167 offset:23072
	s_waitcnt lgkmcnt(2)
	v_mfma_f32_32x32x16_bf16 v[48:63], v[208:211], v[236:239], v[48:63]
	s_waitcnt lgkmcnt(1)
	v_mfma_f32_32x32x16_bf16 v[32:47], v[208:211], v[246:249], v[32:47]
	ds_read_b128 v[208:211], v167 offset:18496
	s_waitcnt vmcnt(15)
	ds_write_b128 v130, v[120:123] offset:36864
	s_waitcnt vmcnt(14)
	ds_write_b128 v130, v[124:127] offset:55296
	s_waitcnt lgkmcnt(3)
	v_mfma_f32_32x32x16_bf16 v[16:31], v[212:215], v[236:239], v[16:31]
	ds_read_b128 v[236:239], v132 offset:64
	v_mfma_f32_32x32x16_bf16 v[0:15], v[212:215], v[246:249], v[0:15]
	ds_read_b128 v[212:215], v132 offset:4672
	ds_read_b128 v[246:249], v167 offset:23104
	s_waitcnt lgkmcnt(2)
	v_mfma_f32_32x32x16_bf16 v[48:63], v[208:211], v[236:239], v[48:63]
	s_waitcnt lgkmcnt(1)
	v_mfma_f32_32x32x16_bf16 v[32:47], v[208:211], v[212:215], v[32:47]
	ds_read_b128 v[208:211], v167 offset:18528
	s_waitcnt vmcnt(13)
	ds_write_b128 v130, v[96:99] offset:41472
	s_waitcnt vmcnt(12)
	ds_write_b128 v130, v[100:103] offset:59904
	s_waitcnt lgkmcnt(3)
	v_mfma_f32_32x32x16_bf16 v[16:31], v[246:249], v[236:239], v[16:31]
	ds_read_b128 v[236:239], v132 offset:96
	v_mfma_f32_32x32x16_bf16 v[0:15], v[246:249], v[212:215], v[0:15]
	ds_read_b128 v[246:249], v132 offset:4704
	ds_read_b128 v[212:215], v167 offset:23136
	s_waitcnt lgkmcnt(2)
	v_mfma_f32_32x32x16_bf16 v[48:63], v[208:211], v[236:239], v[48:63]
	s_waitcnt lgkmcnt(1)
	v_mfma_f32_32x32x16_bf16 v[32:47], v[208:211], v[246:249], v[32:47]
	s_waitcnt lgkmcnt(0)
	v_mfma_f32_32x32x16_bf16 v[16:31], v[212:215], v[236:239], v[16:31]
	global_load_dwordx4 v[124:127], v[112:113], off offset:128
	global_load_dwordx4 v[154:157], v[114:115], off offset:128
	global_load_dwordx4 v[96:99], v[138:139], off offset:128
	global_load_dwordx4 v[100:103], v[140:141], off offset:128
	s_waitcnt vmcnt(15)
	ds_write_b128 v130, v[80:83] offset:46080
	s_waitcnt vmcnt(14)
	ds_write_b128 v130, v[84:87] offset:64512
	global_load_dwordx4 v[80:83], v[142:143], off offset:128
	global_load_dwordx4 v[84:87], v[144:145], off offset:128
	s_waitcnt vmcnt(15)
	ds_write_b128 v130, v[88:91] offset:50688
	s_waitcnt vmcnt(14)
	ds_write_b128 v131, v[92:95] offset:13824
	global_load_dwordx4 v[88:91], v[146:147], off offset:128
	global_load_dwordx4 v[92:95], v[148:149], off offset:128
	s_waitcnt lgkmcnt(0)
	s_barrier
; #define GLOADQ(RA, RB, KT, q) do { const int k0_ = (KT) << 6; \
;     RA[q] = ldg16(ap.ptr(m0 + lrow + 32 * (q), k0_) + lkc); RB[q] = ldg16(W + (size_t)(n0 + lrow + 32 * (q)) * ldw + k0_ + lkc); } while (0)
; #define SSTOREQ(RA, RB, ST, q) do { \
;     *(u32x4*)(sA + (ST) * SBUF + (lrow + 32 * (q)) * GP + lkc) = RA[q]; *(u32x4*)(sB + (ST) * SBUF + (lrow + 32 * (q)) * GP + lkc) = RB[q]; } while (0)
; #define FLOAD(F, ST, ks) do { _Pragma("unroll") for (int a = 0; a < 2; ++a) { \
;     F[a] = *(const bf16x8*)(sB + (ST) * SBUF + (wn * 64 + a * 32 + r) * GP + (ks) * 16 + h * 8); \
;     F[2 + a] = *(const bf16x8*)(sA + (ST) * SBUF + (wm * 64 + a * 32 + r) * GP + (ks) * 16 + h * 8); } } while (0)
; #define FMMA(F) do { _Pragma("unroll") for (int a = 0; a < 2; ++a) _Pragma("unroll") for (int b = 0; b < 2; ++b) acc[a][b] = MFMA(F[a], F[2 + b], acc[a][b]); } while (0)
; template <bool MIDK, class AP, class EPI>
; DI void gemm_tile(const AP& ap, const u16* __restrict__ W, int ldw, int K, int m0, int n0, const EPI& epi, char* smem, float r0, float r1, int tid, bool dry) {
;     ...
;   for (int kt = 0; kt < nk; kt += 2) {
;     const bool l3 = kt + 3 < nk, s2 = kt + 2 < nk, l4 = kt + 4 < nk;
;     FLOAD(f0, 0, 0); FLOAD(f1, 0, 1);
;     FMMA(f0); SSTOREQ(ra1, rb1, 1, 0); if (l3) GLOADQ(ra1, rb1, kt + 3, 0);
;     FLOAD(f0, 0, 2);
;     FMMA(f1); SSTOREQ(ra1, rb1, 1, 1); if (l3) GLOADQ(ra1, rb1, kt + 3, 1);
;     FLOAD(f1, 0, 3);
;     FMMA(f0); SSTOREQ(ra1, rb1, 1, 2); if (l3) GLOADQ(ra1, rb1, kt + 3, 2);
;     FMMA(f1); SSTOREQ(ra1, rb1, 1, 3); if (l3) GLOADQ(ra1, rb1, kt + 3, 3);
;     __syncthreads();
;     FLOAD(f0, 1, 0); FLOAD(f1, 1, 1);
;     FMMA(f0); if (s2) SSTOREQ(ra0, rb0, 0, 0); if (l4) GLOADQ(ra0, rb0, kt + 4, 0);
;     FLOAD(f0, 1, 2);
;     FMMA(f1); if (s2) SSTOREQ(ra0, rb0, 0, 1); if (l4) GLOADQ(ra0, rb0, kt + 4, 1);
;     FLOAD(f1, 1, 3);
;     FMMA(f0); if (s2) SSTOREQ(ra0, rb0, 0, 2); if (l4) GLOADQ(ra0, rb0, kt + 4, 2);
;     FMMA(f1); if (s2) SSTOREQ(ra0, rb0, 0, 3); if (l4) GLOADQ(ra0, rb0, kt + 4, 3);
	ds_read_b128 v[208:211], v167 offset:55296
	ds_read_b128 v[236:239], v132 offset:36864
	v_mfma_f32_32x32x16_bf16 v[0:15], v[212:215], v[246:249], v[0:15]
	ds_read_b128 v[212:215], v132 offset:41472
	ds_read_b128 v[246:249], v167 offset:59904
	s_waitcnt lgkmcnt(2)
	v_mfma_f32_32x32x16_bf16 v[48:63], v[208:211], v[236:239], v[48:63]
	s_waitcnt lgkmcnt(1)
	v_mfma_f32_32x32x16_bf16 v[32:47], v[208:211], v[212:215], v[32:47]
	ds_read_b128 v[208:211], v167 offset:55328
	s_waitcnt lgkmcnt(1)
	v_mfma_f32_32x32x16_bf16 v[16:31], v[246:249], v[236:239], v[16:31]
	ds_read_b128 v[236:239], v132 offset:36896
	v_mfma_f32_32x32x16_bf16 v[0:15], v[246:249], v[212:215], v[0:15]
	ds_read_b128 v[246:249], v132 offset:41504
	ds_read_b128 v[212:215], v167 offset:59936
	s_waitcnt lgkmcnt(2)
	v_mfma_f32_32x32x16_bf16 v[48:63], v[208:211], v[236:239], v[48:63]
	s_waitcnt lgkmcnt(1)
	v_mfma_f32_32x32x16_bf16 v[32:47], v[208:211], v[246:249], v[32:47]
	ds_read_b128 v[208:211], v167 offset:55360
	s_waitcnt vmcnt(15)
	ds_write_b128 v130, v[150:153]
	s_waitcnt vmcnt(14)
	ds_write_b128 v130, v[158:161] offset:18432
	s_waitcnt lgkmcnt(3)
	v_mfma_f32_32x32x16_bf16 v[16:31], v[212:215], v[236:239], v[16:31]
	ds_read_b128 v[236:239], v132 offset:36928
	v_mfma_f32_32x32x16_bf16 v[0:15], v[212:215], v[246:249], v[0:15]
	ds_read_b128 v[212:215], v132 offset:41536
	ds_read_b128 v[246:249], v167 offset:59968
	s_waitcnt lgkmcnt(2)
	v_mfma_f32_32x32x16_bf16 v[48:63], v[208:211], v[236:239], v[48:63]
	s_waitcnt lgkmcnt(1)
	v_mfma_f32_32x32x16_bf16 v[32:47], v[208:211], v[212:215], v[32:47]
	ds_read_b128 v[208:211], v167 offset:55392
	s_waitcnt vmcnt(13)
	ds_write_b128 v130, v[104:107] offset:4608
	s_waitcnt vmcnt(12)
	ds_write_b128 v130, v[108:111] offset:23040
	s_waitcnt lgkmcnt(3)
	v_mfma_f32_32x32x16_bf16 v[16:31], v[246:249], v[236:239], v[16:31]
	ds_read_b128 v[236:239], v132 offset:36960
	v_mfma_f32_32x32x16_bf16 v[0:15], v[246:249], v[212:215], v[0:15]
	ds_read_b128 v[246:249], v132 offset:41568
	ds_read_b128 v[212:215], v167 offset:60000
	s_waitcnt lgkmcnt(2)
	v_mfma_f32_32x32x16_bf16 v[48:63], v[208:211], v[236:239], v[48:63]
	s_waitcnt lgkmcnt(1)
	v_mfma_f32_32x32x16_bf16 v[32:47], v[208:211], v[246:249], v[32:47]
	s_waitcnt lgkmcnt(0)
	v_mfma_f32_32x32x16_bf16 v[16:31], v[212:215], v[236:239], v[16:31]
	global_load_dwordx4 v[150:153], v[112:113], off offset:256
	global_load_dwordx4 v[158:161], v[114:115], off offset:256
	global_load_dwordx4 v[104:107], v[138:139], off offset:256
	global_load_dwordx4 v[108:111], v[140:141], off offset:256
	s_waitcnt vmcnt(15)
	ds_write_b128 v130, v[64:67] offset:9216
	s_waitcnt vmcnt(14)
	ds_write_b128 v130, v[68:71] offset:27648
	global_load_dwordx4 v[64:67], v[142:143], off offset:256
	global_load_dwordx4 v[68:71], v[144:145], off offset:256
	s_waitcnt vmcnt(15)
	ds_write_b128 v130, v[72:75] offset:13824
	s_waitcnt vmcnt(14)
	ds_write_b128 v130, v[76:79] offset:32256
	global_load_dwordx4 v[72:75], v[146:147], off offset:256
	global_load_dwordx4 v[76:79], v[148:149], off offset:256
	s_waitcnt lgkmcnt(0)
	s_barrier
	ds_read_b128 v[208:211], v167 offset:18432
	ds_read_b128 v[236:239], v132
	v_mfma_f32_32x32x16_bf16 v[0:15], v[212:215], v[246:249], v[0:15]
	ds_read_b128 v[212:215], v132 offset:4608
	ds_read_b128 v[246:249], v167 offset:23040
	s_waitcnt lgkmcnt(2)
	v_mfma_f32_32x32x16_bf16 v[48:63], v[208:211], v[236:239], v[48:63]
	s_waitcnt lgkmcnt(1)
	v_mfma_f32_32x32x16_bf16 v[32:47], v[208:211], v[212:215], v[32:47]
	ds_read_b128 v[208:211], v167 offset:18464
	s_waitcnt lgkmcnt(1)
	v_mfma_f32_32x32x16_bf16 v[16:31], v[246:249], v[236:239], v[16:31]
	ds_read_b128 v[236:239], v132 offset:32
	v_mfma_f32_32x32x16_bf16 v[0:15], v[246:249], v[212:215], v[0:15]
	ds_read_b128 v[246:249], v132 offset:4640
	ds_read_b128 v[212:215], v167 offset:23072
	s_waitcnt lgkmcnt(2)
	v_mfma_f32_32x32x16_bf16 v[48:63], v[208:211], v[236:239], v[48:63]
	s_waitcnt lgkmcnt(1)
	v_mfma_f32_32x32x16_bf16 v[32:47], v[208:211], v[246:249], v[32:47]
	ds_read_b128 v[208:211], v167 offset:18496
	s_waitcnt vmcnt(15)
	ds_write_b128 v130, v[124:127] offset:36864
	s_waitcnt vmcnt(14)
	ds_write_b128 v130, v[154:157] offset:55296
	s_waitcnt lgkmcnt(3)
	v_mfma_f32_32x32x16_bf16 v[16:31], v[212:215], v[236:239], v[16:31]
	ds_read_b128 v[236:239], v132 offset:64
	v_mfma_f32_32x32x16_bf16 v[0:15], v[212:215], v[246:249], v[0:15]
	ds_read_b128 v[212:215], v132 offset:4672
	ds_read_b128 v[246:249], v167 offset:23104
	s_waitcnt lgkmcnt(2)
	v_mfma_f32_32x32x16_bf16 v[48:63], v[208:211], v[236:239], v[48:63]
	s_waitcnt lgkmcnt(1)
	v_mfma_f32_32x32x16_bf16 v[32:47], v[208:211], v[212:215], v[32:47]
	ds_read_b128 v[208:211], v167 offset:18528
	s_waitcnt vmcnt(13)
	ds_write_b128 v130, v[96:99] offset:41472
	s_waitcnt vmcnt(12)
	ds_write_b128 v130, v[100:103] offset:59904
	s_waitcnt lgkmcnt(3)
	v_mfma_f32_32x32x16_bf16 v[16:31], v[246:249], v[236:239], v[16:31]
	ds_read_b128 v[236:239], v132 offset:96
	v_mfma_f32_32x32x16_bf16 v[0:15], v[246:249], v[212:215], v[0:15]
	ds_read_b128 v[246:249], v132 offset:4704
	ds_read_b128 v[212:215], v167 offset:23136
	s_waitcnt lgkmcnt(2)
	v_mfma_f32_32x32x16_bf16 v[48:63], v[208:211], v[236:239], v[48:63]
	s_waitcnt lgkmcnt(1)
	v_mfma_f32_32x32x16_bf16 v[32:47], v[208:211], v[246:249], v[32:47]
	s_waitcnt lgkmcnt(0)
	v_mfma_f32_32x32x16_bf16 v[16:31], v[212:215], v[236:239], v[16:31]
	global_load_dwordx4 v[124:127], v[112:113], off offset:384
	global_load_dwordx4 v[154:157], v[114:115], off offset:384
	global_load_dwordx4 v[96:99], v[138:139], off offset:384
	global_load_dwordx4 v[100:103], v[140:141], off offset:384
	s_waitcnt vmcnt(15)
	ds_write_b128 v130, v[80:83] offset:46080
	s_waitcnt vmcnt(14)
	ds_write_b128 v130, v[84:87] offset:64512
	global_load_dwordx4 v[80:83], v[142:143], off offset:384
	global_load_dwordx4 v[84:87], v[144:145], off offset:384
	s_waitcnt vmcnt(15)
	ds_write_b128 v130, v[88:91] offset:50688
	s_waitcnt vmcnt(14)
	ds_write_b128 v131, v[92:95] offset:13824
	global_load_dwordx4 v[88:91], v[146:147], off offset:384
	global_load_dwordx4 v[92:95], v[148:149], off offset:384
	s_waitcnt lgkmcnt(0)
	s_barrier
; #define GLOADQ(RA, RB, KT, q) do { const int k0_ = (KT) << 6; \
;     RA[q] = ldg16(ap.ptr(m0 + lrow + 32 * (q), k0_) + lkc); RB[q] = ldg16(W + (size_t)(n0 + lrow + 32 * (q)) * ldw + k0_ + lkc); } while (0)
; #define SSTOREQ(RA, RB, ST, q) do { \
;     *(u32x4*)(sA + (ST) * SBUF + (lrow + 32 * (q)) * GP + lkc) = RA[q]; *(u32x4*)(sB + (ST) * SBUF + (lrow + 32 * (q)) * GP + lkc) = RB[q]; } while (0)
; #define FLOAD(F, ST, ks) do { _Pragma("unroll") for (int a = 0; a < 2; ++a) { \
;     F[a] = *(const bf16x8*)(sB + (ST) * SBUF + (wn * 64 + a * 32 + r) * GP + (ks) * 16 + h * 8); \
;     F[2 + a] = *(const bf16x8*)(sA + (ST) * SBUF + (wm * 64 + a * 32 + r) * GP + (ks) * 16 + h * 8); } } while (0)
; #define FMMA(F) do { _Pragma("unroll") for (int a = 0; a < 2; ++a) _Pragma("unroll") for (int b = 0; b < 2; ++b) acc[a][b] = MFMA(F[a], F[2 + b], acc[a][b]); } while (0)
; template <bool MIDK, class AP, class EPI>
; DI void gemm_tile(const AP& ap, const u16* __restrict__ W, int ldw, int K, int m0, int n0, const EPI& epi, char* smem, float r0, float r1, int tid, bool dry) {
;     ...
;   for (int kt = 0; kt < nk; kt += 2) {
;     const bool l3 = kt + 3 < nk, s2 = kt + 2 < nk, l4 = kt + 4 < nk;
;     FLOAD(f0, 0, 0); FLOAD(f1, 0, 1);
;     FMMA(f0); SSTOREQ(ra1, rb1, 1, 0); if (l3) GLOADQ(ra1, rb1, kt + 3, 0);
;     FLOAD(f0, 0, 2);
;     FMMA(f1); SSTOREQ(ra1, rb1, 1, 1); if (l3) GLOADQ(ra1, rb1, kt + 3, 1);
;     FLOAD(f1, 0, 3);
;     FMMA(f0); SSTOREQ(ra1, rb1, 1, 2); if (l3) GLOADQ(ra1, rb1, kt + 3, 2);
;     FMMA(f1); SSTOREQ(ra1, rb1, 1, 3); if (l3) GLOADQ(ra1, rb1, kt + 3, 3);
;     __syncthreads();
;     FLOAD(f0, 1, 0); FLOAD(f1, 1, 1);
;     FMMA(f0); if (s2) SSTOREQ(ra0, rb0, 0, 0); if (l4) GLOADQ(ra0, rb0, kt + 4, 0);
;     FLOAD(f0, 1, 2);
;     FMMA(f1); if (s2) SSTOREQ(ra0, rb0, 0, 1); if (l4) GLOADQ(ra0, rb0, kt + 4, 1);
;     FLOAD(f1, 1, 3);
;     FMMA(f0); if (s2) SSTOREQ(ra0, rb0, 0, 2); if (l4) GLOADQ(ra0, rb0, kt + 4, 2);
;     FMMA(f1); if (s2) SSTOREQ(ra0, rb0, 0, 3); if (l4) GLOADQ(ra0, rb0, kt + 4, 3);
	ds_read_b128 v[208:211], v167 offset:55296
	ds_read_b128 v[236:239], v132 offset:36864
	v_mfma_f32_32x32x16_bf16 v[0:15], v[212:215], v[246:249], v[0:15]
	ds_read_b128 v[212:215], v132 offset:41472
	ds_read_b128 v[246:249], v167 offset:59904
	s_waitcnt lgkmcnt(2)
	v_mfma_f32_32x32x16_bf16 v[48:63], v[208:211], v[236:239], v[48:63]
	s_waitcnt lgkmcnt(1)
	v_mfma_f32_32x32x16_bf16 v[32:47], v[208:211], v[212:215], v[32:47]
	ds_read_b128 v[208:211], v167 offset:55328
	s_waitcnt lgkmcnt(1)
	v_mfma_f32_32x32x16_bf16 v[16:31], v[246:249], v[236:239], v[16:31]
	ds_read_b128 v[236:239], v132 offset:36896
	v_mfma_f32_32x32x16_bf16 v[0:15], v[246:249], v[212:215], v[0:15]
	ds_read_b128 v[246:249], v132 offset:41504
	ds_read_b128 v[212:215], v167 offset:59936
	s_waitcnt lgkmcnt(2)
	v_mfma_f32_32x32x16_bf16 v[48:63], v[208:211], v[236:239], v[48:63]
	s_waitcnt lgkmcnt(1)
	v_mfma_f32_32x32x16_bf16 v[32:47], v[208:211], v[246:249], v[32:47]
	ds_read_b128 v[208:211], v167 offset:55360
	s_waitcnt vmcnt(15)
	ds_write_b128 v130, v[150:153]
	s_waitcnt vmcnt(14)
	ds_write_b128 v130, v[158:161] offset:18432
	s_waitcnt lgkmcnt(3)
	v_mfma_f32_32x32x16_bf16 v[16:31], v[212:215], v[236:239], v[16:31]
	ds_read_b128 v[236:239], v132 offset:36928
	v_mfma_f32_32x32x16_bf16 v[0:15], v[212:215], v[246:249], v[0:15]
	ds_read_b128 v[212:215], v132 offset:41536
	ds_read_b128 v[246:249], v167 offset:59968
	s_waitcnt lgkmcnt(2)
	v_mfma_f32_32x32x16_bf16 v[48:63], v[208:211], v[236:239], v[48:63]
	s_waitcnt lgkmcnt(1)
	v_mfma_f32_32x32x16_bf16 v[32:47], v[208:211], v[212:215], v[32:47]
	ds_read_b128 v[208:211], v167 offset:55392
	s_waitcnt vmcnt(13)
	ds_write_b128 v130, v[104:107] offset:4608
	s_waitcnt vmcnt(12)
	ds_write_b128 v130, v[108:111] offset:23040
	s_waitcnt lgkmcnt(3)
	v_mfma_f32_32x32x16_bf16 v[16:31], v[246:249], v[236:239], v[16:31]
	ds_read_b128 v[236:239], v132 offset:36960
	v_mfma_f32_32x32x16_bf16 v[0:15], v[246:249], v[212:215], v[0:15]
	ds_read_b128 v[246:249], v132 offset:41568
	ds_read_b128 v[212:215], v167 offset:60000
	s_waitcnt lgkmcnt(2)
	v_mfma_f32_32x32x16_bf16 v[48:63], v[208:211], v[236:239], v[48:63]
	s_waitcnt lgkmcnt(1)
	v_mfma_f32_32x32x16_bf16 v[32:47], v[208:211], v[246:249], v[32:47]
	s_waitcnt lgkmcnt(0)
	v_mfma_f32_32x32x16_bf16 v[16:31], v[212:215], v[236:239], v[16:31]
	global_load_dwordx4 v[150:153], v[112:113], off offset:512
	global_load_dwordx4 v[158:161], v[114:115], off offset:512
	global_load_dwordx4 v[104:107], v[138:139], off offset:512
	global_load_dwordx4 v[108:111], v[140:141], off offset:512
	s_waitcnt vmcnt(15)
	ds_write_b128 v130, v[64:67] offset:9216
	s_waitcnt vmcnt(14)
	ds_write_b128 v130, v[68:71] offset:27648
	global_load_dwordx4 v[64:67], v[142:143], off offset:512
	global_load_dwordx4 v[68:71], v[144:145], off offset:512
	s_waitcnt vmcnt(15)
	ds_write_b128 v130, v[72:75] offset:13824
	s_waitcnt vmcnt(14)
	ds_write_b128 v130, v[76:79] offset:32256
	global_load_dwordx4 v[72:75], v[146:147], off offset:512
	global_load_dwordx4 v[76:79], v[148:149], off offset:512
	s_waitcnt lgkmcnt(0)
	s_barrier
	ds_read_b128 v[208:211], v167 offset:18432
	ds_read_b128 v[236:239], v132
	v_mfma_f32_32x32x16_bf16 v[0:15], v[212:215], v[246:249], v[0:15]
	ds_read_b128 v[212:215], v132 offset:4608
	ds_read_b128 v[246:249], v167 offset:23040
	s_waitcnt lgkmcnt(2)
	v_mfma_f32_32x32x16_bf16 v[48:63], v[208:211], v[236:239], v[48:63]
	s_waitcnt lgkmcnt(1)
	v_mfma_f32_32x32x16_bf16 v[32:47], v[208:211], v[212:215], v[32:47]
	ds_read_b128 v[208:211], v167 offset:18464
	s_waitcnt lgkmcnt(1)
	v_mfma_f32_32x32x16_bf16 v[16:31], v[246:249], v[236:239], v[16:31]
	ds_read_b128 v[236:239], v132 offset:32
	v_mfma_f32_32x32x16_bf16 v[0:15], v[246:249], v[212:215], v[0:15]
	ds_read_b128 v[246:249], v132 offset:4640
	ds_read_b128 v[212:215], v167 offset:23072
	s_waitcnt lgkmcnt(2)
	v_mfma_f32_32x32x16_bf16 v[48:63], v[208:211], v[236:239], v[48:63]
	s_waitcnt lgkmcnt(1)
	v_mfma_f32_32x32x16_bf16 v[32:47], v[208:211], v[246:249], v[32:47]
	ds_read_b128 v[208:211], v167 offset:18496
	s_waitcnt vmcnt(15)
	ds_write_b128 v130, v[124:127] offset:36864
	s_waitcnt vmcnt(14)
	ds_write_b128 v130, v[154:157] offset:55296
	s_waitcnt lgkmcnt(3)
	v_mfma_f32_32x32x16_bf16 v[16:31], v[212:215], v[236:239], v[16:31]
	ds_read_b128 v[236:239], v132 offset:64
	v_mfma_f32_32x32x16_bf16 v[0:15], v[212:215], v[246:249], v[0:15]
	ds_read_b128 v[212:215], v132 offset:4672
	ds_read_b128 v[246:249], v167 offset:23104
	s_waitcnt lgkmcnt(2)
	v_mfma_f32_32x32x16_bf16 v[48:63], v[208:211], v[236:239], v[48:63]
	s_waitcnt lgkmcnt(1)
	v_mfma_f32_32x32x16_bf16 v[32:47], v[208:211], v[212:215], v[32:47]
	ds_read_b128 v[208:211], v167 offset:18528
	s_waitcnt vmcnt(13)
	ds_write_b128 v130, v[96:99] offset:41472
	s_waitcnt vmcnt(12)
	ds_write_b128 v130, v[100:103] offset:59904
	s_waitcnt lgkmcnt(3)
	v_mfma_f32_32x32x16_bf16 v[16:31], v[246:249], v[236:239], v[16:31]
	ds_read_b128 v[236:239], v132 offset:96
	v_mfma_f32_32x32x16_bf16 v[0:15], v[246:249], v[212:215], v[0:15]
	ds_read_b128 v[246:249], v132 offset:4704
	ds_read_b128 v[212:215], v167 offset:23136
	s_waitcnt lgkmcnt(2)
	v_mfma_f32_32x32x16_bf16 v[48:63], v[208:211], v[236:239], v[48:63]
	s_waitcnt lgkmcnt(1)
	v_mfma_f32_32x32x16_bf16 v[32:47], v[208:211], v[246:249], v[32:47]
	s_waitcnt lgkmcnt(0)
	v_mfma_f32_32x32x16_bf16 v[16:31], v[212:215], v[236:239], v[16:31]
	global_load_dwordx4 v[124:127], v[112:113], off offset:640
	global_load_dwordx4 v[154:157], v[114:115], off offset:640
	global_load_dwordx4 v[96:99], v[138:139], off offset:640
	global_load_dwordx4 v[100:103], v[140:141], off offset:640
	s_waitcnt vmcnt(15)
	ds_write_b128 v130, v[80:83] offset:46080
	s_waitcnt vmcnt(14)
	ds_write_b128 v130, v[84:87] offset:64512
	global_load_dwordx4 v[80:83], v[142:143], off offset:640
	global_load_dwordx4 v[84:87], v[144:145], off offset:640
	s_waitcnt vmcnt(15)
	ds_write_b128 v130, v[88:91] offset:50688
	s_waitcnt vmcnt(14)
	ds_write_b128 v131, v[92:95] offset:13824
	global_load_dwordx4 v[88:91], v[146:147], off offset:640
	global_load_dwordx4 v[92:95], v[148:149], off offset:640
	s_waitcnt lgkmcnt(0)
	s_barrier
; #define GLOADQ(RA, RB, KT, q) do { const int k0_ = (KT) << 6; \
;     RA[q] = ldg16(ap.ptr(m0 + lrow + 32 * (q), k0_) + lkc); RB[q] = ldg16(W + (size_t)(n0 + lrow + 32 * (q)) * ldw + k0_ + lkc); } while (0)
; #define SSTOREQ(RA, RB, ST, q) do { \
;     *(u32x4*)(sA + (ST) * SBUF + (lrow + 32 * (q)) * GP + lkc) = RA[q]; *(u32x4*)(sB + (ST) * SBUF + (lrow + 32 * (q)) * GP + lkc) = RB[q]; } while (0)
; #define FLOAD(F, ST, ks) do { _Pragma("unroll") for (int a = 0; a < 2; ++a) { \
;     F[a] = *(const bf16x8*)(sB + (ST) * SBUF + (wn * 64 + a * 32 + r) * GP + (ks) * 16 + h * 8); \
;     F[2 + a] = *(const bf16x8*)(sA + (ST) * SBUF + (wm * 64 + a * 32 + r) * GP + (ks) * 16 + h * 8); } } while (0)
; #define FMMA(F) do { _Pragma("unroll") for (int a = 0; a < 2; ++a) _Pragma("unroll") for (int b = 0; b < 2; ++b) acc[a][b] = MFMA(F[a], F[2 + b], acc[a][b]); } while (0)
; template <bool MIDK, class AP, class EPI>
; DI void gemm_tile(const AP& ap, const u16* __restrict__ W, int ldw, int K, int m0, int n0, const EPI& epi, char* smem, float r0, float r1, int tid, bool dry) {
;     ...
;   for (int kt = 0; kt < nk; kt += 2) {
;     const bool l3 = kt + 3 < nk, s2 = kt + 2 < nk, l4 = kt + 4 < nk;
;     FLOAD(f0, 0, 0); FLOAD(f1, 0, 1);
;     FMMA(f0); SSTOREQ(ra1, rb1, 1, 0); if (l3) GLOADQ(ra1, rb1, kt + 3, 0);
;     FLOAD(f0, 0, 2);
;     FMMA(f1); SSTOREQ(ra1, rb1, 1, 1); if (l3) GLOADQ(ra1, rb1, kt + 3, 1);
;     FLOAD(f1, 0, 3);
;     FMMA(f0); SSTOREQ(ra1, rb1, 1, 2); if (l3) GLOADQ(ra1, rb1, kt + 3, 2);
;     FMMA(f1); SSTOREQ(ra1, rb1, 1, 3); if (l3) GLOADQ(ra1, rb1, kt + 3, 3);
;     __syncthreads();
;     FLOAD(f0, 1, 0); FLOAD(f1, 1, 1);
;     FMMA(f0); if (s2) SSTOREQ(ra0, rb0, 0, 0); if (l4) GLOADQ(ra0, rb0, kt + 4, 0);
;     FLOAD(f0, 1, 2);
;     FMMA(f1); if (s2) SSTOREQ(ra0, rb0, 0, 1); if (l4) GLOADQ(ra0, rb0, kt + 4, 1);
;     FLOAD(f1, 1, 3);
;     FMMA(f0); if (s2) SSTOREQ(ra0, rb0, 0, 2); if (l4) GLOADQ(ra0, rb0, kt + 4, 2);
;     FMMA(f1); if (s2) SSTOREQ(ra0, rb0, 0, 3); if (l4) GLOADQ(ra0, rb0, kt + 4, 3);
	ds_read_b128 v[208:211], v167 offset:55296
	ds_read_b128 v[236:239], v132 offset:36864
	v_mfma_f32_32x32x16_bf16 v[0:15], v[212:215], v[246:249], v[0:15]
	ds_read_b128 v[212:215], v132 offset:41472
	ds_read_b128 v[246:249], v167 offset:59904
	s_waitcnt lgkmcnt(2)
	v_mfma_f32_32x32x16_bf16 v[48:63], v[208:211], v[236:239], v[48:63]
	s_waitcnt lgkmcnt(1)
	v_mfma_f32_32x32x16_bf16 v[32:47], v[208:211], v[212:215], v[32:47]
	ds_read_b128 v[208:211], v167 offset:55328
	s_waitcnt lgkmcnt(1)
	v_mfma_f32_32x32x16_bf16 v[16:31], v[246:249], v[236:239], v[16:31]
	ds_read_b128 v[236:239], v132 offset:36896
	v_mfma_f32_32x32x16_bf16 v[0:15], v[246:249], v[212:215], v[0:15]
	ds_read_b128 v[246:249], v132 offset:41504
	ds_read_b128 v[212:215], v167 offset:59936
	s_waitcnt lgkmcnt(2)
	v_mfma_f32_32x32x16_bf16 v[48:63], v[208:211], v[236:239], v[48:63]
	s_waitcnt lgkmcnt(1)
	v_mfma_f32_32x32x16_bf16 v[32:47], v[208:211], v[246:249], v[32:47]
	ds_read_b128 v[208:211], v167 offset:55360
	s_waitcnt vmcnt(15)
	ds_write_b128 v130, v[150:153]
	s_waitcnt vmcnt(14)
	ds_write_b128 v130, v[158:161] offset:18432
	s_waitcnt lgkmcnt(3)
	v_mfma_f32_32x32x16_bf16 v[16:31], v[212:215], v[236:239], v[16:31]
	ds_read_b128 v[236:239], v132 offset:36928
	v_mfma_f32_32x32x16_bf16 v[0:15], v[212:215], v[246:249], v[0:15]
	ds_read_b128 v[212:215], v132 offset:41536
	ds_read_b128 v[246:249], v167 offset:59968
	s_waitcnt lgkmcnt(2)
	v_mfma_f32_32x32x16_bf16 v[48:63], v[208:211], v[236:239], v[48:63]
	s_waitcnt lgkmcnt(1)
	v_mfma_f32_32x32x16_bf16 v[32:47], v[208:211], v[212:215], v[32:47]
	ds_read_b128 v[208:211], v167 offset:55392
	s_waitcnt vmcnt(13)
	ds_write_b128 v130, v[104:107] offset:4608
	s_waitcnt vmcnt(12)
	ds_write_b128 v130, v[108:111] offset:23040
	s_waitcnt lgkmcnt(3)
	v_mfma_f32_32x32x16_bf16 v[16:31], v[246:249], v[236:239], v[16:31]
	ds_read_b128 v[236:239], v132 offset:36960
	v_mfma_f32_32x32x16_bf16 v[0:15], v[246:249], v[212:215], v[0:15]
	ds_read_b128 v[246:249], v132 offset:41568
	ds_read_b128 v[212:215], v167 offset:60000
	s_waitcnt lgkmcnt(2)
	v_mfma_f32_32x32x16_bf16 v[48:63], v[208:211], v[236:239], v[48:63]
	s_waitcnt lgkmcnt(1)
	v_mfma_f32_32x32x16_bf16 v[32:47], v[208:211], v[246:249], v[32:47]
	s_waitcnt lgkmcnt(0)
	v_mfma_f32_32x32x16_bf16 v[16:31], v[212:215], v[236:239], v[16:31]
	global_load_dwordx4 v[150:153], v[112:113], off offset:768
	global_load_dwordx4 v[158:161], v[114:115], off offset:768
	global_load_dwordx4 v[104:107], v[138:139], off offset:768
	global_load_dwordx4 v[108:111], v[140:141], off offset:768
	s_waitcnt vmcnt(15)
	ds_write_b128 v130, v[64:67] offset:9216
	s_waitcnt vmcnt(14)
	ds_write_b128 v130, v[68:71] offset:27648
	global_load_dwordx4 v[64:67], v[142:143], off offset:768
	global_load_dwordx4 v[68:71], v[144:145], off offset:768
	s_waitcnt vmcnt(15)
	ds_write_b128 v130, v[72:75] offset:13824
	s_waitcnt vmcnt(14)
	ds_write_b128 v130, v[76:79] offset:32256
	global_load_dwordx4 v[72:75], v[146:147], off offset:768
	global_load_dwordx4 v[76:79], v[148:149], off offset:768
	s_waitcnt lgkmcnt(0)
	s_barrier
	ds_read_b128 v[208:211], v167 offset:18432
	ds_read_b128 v[236:239], v132
	v_mfma_f32_32x32x16_bf16 v[0:15], v[212:215], v[246:249], v[0:15]
	ds_read_b128 v[212:215], v132 offset:4608
	ds_read_b128 v[246:249], v167 offset:23040
	s_waitcnt lgkmcnt(2)
	v_mfma_f32_32x32x16_bf16 v[48:63], v[208:211], v[236:239], v[48:63]
	s_waitcnt lgkmcnt(1)
	v_mfma_f32_32x32x16_bf16 v[32:47], v[208:211], v[212:215], v[32:47]
	ds_read_b128 v[208:211], v167 offset:18464
	s_waitcnt lgkmcnt(1)
	v_mfma_f32_32x32x16_bf16 v[16:31], v[246:249], v[236:239], v[16:31]
	ds_read_b128 v[236:239], v132 offset:32
	v_mfma_f32_32x32x16_bf16 v[0:15], v[246:249], v[212:215], v[0:15]
	ds_read_b128 v[246:249], v132 offset:4640
	ds_read_b128 v[212:215], v167 offset:23072
	s_waitcnt lgkmcnt(2)
	v_mfma_f32_32x32x16_bf16 v[48:63], v[208:211], v[236:239], v[48:63]
	s_waitcnt lgkmcnt(1)
	v_mfma_f32_32x32x16_bf16 v[32:47], v[208:211], v[246:249], v[32:47]
	ds_read_b128 v[208:211], v167 offset:18496
	s_waitcnt vmcnt(15)
	ds_write_b128 v130, v[124:127] offset:36864
	s_waitcnt vmcnt(14)
	ds_write_b128 v130, v[154:157] offset:55296
	s_waitcnt lgkmcnt(3)
	v_mfma_f32_32x32x16_bf16 v[16:31], v[212:215], v[236:239], v[16:31]
	ds_read_b128 v[236:239], v132 offset:64
	v_mfma_f32_32x32x16_bf16 v[0:15], v[212:215], v[246:249], v[0:15]
	ds_read_b128 v[212:215], v132 offset:4672
	ds_read_b128 v[246:249], v167 offset:23104
	s_waitcnt lgkmcnt(2)
	v_mfma_f32_32x32x16_bf16 v[48:63], v[208:211], v[236:239], v[48:63]
	s_waitcnt lgkmcnt(1)
	v_mfma_f32_32x32x16_bf16 v[32:47], v[208:211], v[212:215], v[32:47]
	ds_read_b128 v[208:211], v167 offset:18528
	s_waitcnt vmcnt(13)
	ds_write_b128 v130, v[96:99] offset:41472
	s_waitcnt vmcnt(12)
	ds_write_b128 v130, v[100:103] offset:59904
	s_waitcnt lgkmcnt(3)
	v_mfma_f32_32x32x16_bf16 v[16:31], v[246:249], v[236:239], v[16:31]
	ds_read_b128 v[236:239], v132 offset:96
	v_mfma_f32_32x32x16_bf16 v[0:15], v[246:249], v[212:215], v[0:15]
	ds_read_b128 v[246:249], v132 offset:4704
	ds_read_b128 v[212:215], v167 offset:23136
	s_waitcnt lgkmcnt(2)
	v_mfma_f32_32x32x16_bf16 v[48:63], v[208:211], v[236:239], v[48:63]
	s_waitcnt lgkmcnt(1)
	v_mfma_f32_32x32x16_bf16 v[32:47], v[208:211], v[246:249], v[32:47]
	s_waitcnt lgkmcnt(0)
	v_mfma_f32_32x32x16_bf16 v[16:31], v[212:215], v[236:239], v[16:31]
	global_load_dwordx4 v[124:127], v[112:113], off offset:896
	global_load_dwordx4 v[154:157], v[114:115], off offset:896
	global_load_dwordx4 v[96:99], v[138:139], off offset:896
	global_load_dwordx4 v[100:103], v[140:141], off offset:896
	s_waitcnt vmcnt(15)
	ds_write_b128 v130, v[80:83] offset:46080
	s_waitcnt vmcnt(14)
	ds_write_b128 v130, v[84:87] offset:64512
	global_load_dwordx4 v[80:83], v[142:143], off offset:896
	global_load_dwordx4 v[84:87], v[144:145], off offset:896
	s_waitcnt vmcnt(15)
	ds_write_b128 v130, v[88:91] offset:50688
	s_waitcnt vmcnt(14)
	ds_write_b128 v131, v[92:95] offset:13824
	global_load_dwordx4 v[88:91], v[146:147], off offset:896
	global_load_dwordx4 v[92:95], v[148:149], off offset:896
	s_waitcnt lgkmcnt(0)
	s_barrier
; #define GLOADQ(RA, RB, KT, q) do { const int k0_ = (KT) << 6; \
;     RA[q] = ldg16(ap.ptr(m0 + lrow + 32 * (q), k0_) + lkc); RB[q] = ldg16(W + (size_t)(n0 + lrow + 32 * (q)) * ldw + k0_ + lkc); } while (0)
; #define SSTOREQ(RA, RB, ST, q) do { \
;     *(u32x4*)(sA + (ST) * SBUF + (lrow + 32 * (q)) * GP + lkc) = RA[q]; *(u32x4*)(sB + (ST) * SBUF + (lrow + 32 * (q)) * GP + lkc) = RB[q]; } while (0)
; #define FLOAD(F, ST, ks) do { _Pragma("unroll") for (int a = 0; a < 2; ++a) { \
;     F[a] = *(const bf16x8*)(sB + (ST) * SBUF + (wn * 64 + a * 32 + r) * GP + (ks) * 16 + h * 8); \
;     F[2 + a] = *(const bf16x8*)(sA + (ST) * SBUF + (wm * 64 + a * 32 + r) * GP + (ks) * 16 + h * 8); } } while (0)
; #define FMMA(F) do { _Pragma("unroll") for (int a = 0; a < 2; ++a) _Pragma("unroll") for (int b = 0; b < 2; ++b) acc[a][b] = MFMA(F[a], F[2 + b], acc[a][b]); } while (0)
; template <bool MIDK, class AP, class EPI>
; DI void gemm_tile(const AP& ap, const u16* __restrict__ W, int ldw, int K, int m0, int n0, const EPI& epi, char* smem, float r0, float r1, int tid, bool dry) {
;     ...
;   for (int kt = 0; kt < nk; kt += 2) {
;     const bool l3 = kt + 3 < nk, s2 = kt + 2 < nk, l4 = kt + 4 < nk;
;     FLOAD(f0, 0, 0); FLOAD(f1, 0, 1);
;     FMMA(f0); SSTOREQ(ra1, rb1, 1, 0); if (l3) GLOADQ(ra1, rb1, kt + 3, 0);
;     FLOAD(f0, 0, 2);
;     FMMA(f1); SSTOREQ(ra1, rb1, 1, 1); if (l3) GLOADQ(ra1, rb1, kt + 3, 1);
;     FLOAD(f1, 0, 3);
;     FMMA(f0); SSTOREQ(ra1, rb1, 1, 2); if (l3) GLOADQ(ra1, rb1, kt + 3, 2);
;     FMMA(f1); SSTOREQ(ra1, rb1, 1, 3); if (l3) GLOADQ(ra1, rb1, kt + 3, 3);
;     __syncthreads();
;     FLOAD(f0, 1, 0); FLOAD(f1, 1, 1);
;     FMMA(f0); if (s2) SSTOREQ(ra0, rb0, 0, 0); if (l4) GLOADQ(ra0, rb0, kt + 4, 0);
;     FLOAD(f0, 1, 2);
;     FMMA(f1); if (s2) SSTOREQ(ra0, rb0, 0, 1); if (l4) GLOADQ(ra0, rb0, kt + 4, 1);
;     FLOAD(f1, 1, 3);
;     FMMA(f0); if (s2) SSTOREQ(ra0, rb0, 0, 2); if (l4) GLOADQ(ra0, rb0, kt + 4, 2);
;     FMMA(f1); if (s2) SSTOREQ(ra0, rb0, 0, 3); if (l4) GLOADQ(ra0, rb0, kt + 4, 3);
;     if (MIDK && kt == 6) {
; #pragma unroll
;       for (int a = 0; a < 2; ++a)
; #pragma unroll
;         for (int i = 0; i < 16; ++i) { acc[a][0][i] *= r0; acc[a][1][i] *= r1; }
;     }
;     __syncthreads();
	ds_read_b128 v[208:211], v167 offset:55296
	ds_read_b128 v[236:239], v132 offset:36864
	v_mfma_f32_32x32x16_bf16 v[0:15], v[212:215], v[246:249], v[0:15]
	ds_read_b128 v[212:215], v132 offset:41472
	ds_read_b128 v[246:249], v167 offset:59904
	s_waitcnt lgkmcnt(2)
	v_mfma_f32_32x32x16_bf16 v[48:63], v[208:211], v[236:239], v[48:63]
	s_waitcnt lgkmcnt(1)
	v_mfma_f32_32x32x16_bf16 v[32:47], v[208:211], v[212:215], v[32:47]
	ds_read_b128 v[208:211], v167 offset:55328
	s_waitcnt lgkmcnt(1)
	v_mfma_f32_32x32x16_bf16 v[16:31], v[246:249], v[236:239], v[16:31]
	ds_read_b128 v[236:239], v132 offset:36896
	v_mfma_f32_32x32x16_bf16 v[0:15], v[246:249], v[212:215], v[0:15]
	ds_read_b128 v[246:249], v132 offset:41504
	ds_read_b128 v[212:215], v167 offset:59936
	s_waitcnt lgkmcnt(2)
	v_mfma_f32_32x32x16_bf16 v[48:63], v[208:211], v[236:239], v[48:63]
	s_waitcnt lgkmcnt(1)
	v_mfma_f32_32x32x16_bf16 v[32:47], v[208:211], v[246:249], v[32:47]
	ds_read_b128 v[208:211], v167 offset:55360
	s_waitcnt vmcnt(15)
	ds_write_b128 v130, v[150:153]
	s_waitcnt vmcnt(14)
	ds_write_b128 v130, v[158:161] offset:18432
	s_waitcnt lgkmcnt(3)
	v_mfma_f32_32x32x16_bf16 v[16:31], v[212:215], v[236:239], v[16:31]
	ds_read_b128 v[236:239], v132 offset:36928
	v_mfma_f32_32x32x16_bf16 v[0:15], v[212:215], v[246:249], v[0:15]
	ds_read_b128 v[212:215], v132 offset:41536
	ds_read_b128 v[246:249], v167 offset:59968
	s_waitcnt lgkmcnt(2)
	v_mfma_f32_32x32x16_bf16 v[48:63], v[208:211], v[236:239], v[48:63]
	s_waitcnt lgkmcnt(1)
	v_mfma_f32_32x32x16_bf16 v[32:47], v[208:211], v[212:215], v[32:47]
	ds_read_b128 v[208:211], v167 offset:55392
	s_waitcnt vmcnt(13)
	ds_write_b128 v130, v[104:107] offset:4608
	s_waitcnt vmcnt(12)
	ds_write_b128 v130, v[108:111] offset:23040
	s_waitcnt lgkmcnt(3)
	v_mfma_f32_32x32x16_bf16 v[16:31], v[246:249], v[236:239], v[16:31]
	ds_read_b128 v[236:239], v132 offset:36960
	v_mfma_f32_32x32x16_bf16 v[0:15], v[246:249], v[212:215], v[0:15]
	ds_read_b128 v[246:249], v132 offset:41568
	ds_read_b128 v[212:215], v167 offset:60000
	s_waitcnt lgkmcnt(2)
	v_mfma_f32_32x32x16_bf16 v[48:63], v[208:211], v[236:239], v[48:63]
	s_waitcnt lgkmcnt(1)
	v_mfma_f32_32x32x16_bf16 v[32:47], v[208:211], v[246:249], v[32:47]
	s_waitcnt lgkmcnt(0)
	v_mfma_f32_32x32x16_bf16 v[16:31], v[212:215], v[236:239], v[16:31]
	global_load_dwordx4 v[150:153], v[112:113], off offset:1024
	global_load_dwordx4 v[158:161], v[114:115], off offset:1024
	global_load_dwordx4 v[104:107], v[138:139], off offset:1024
	global_load_dwordx4 v[108:111], v[140:141], off offset:1024
	s_waitcnt vmcnt(15)
	ds_write_b128 v130, v[64:67] offset:9216
	s_waitcnt vmcnt(14)
	ds_write_b128 v130, v[68:71] offset:27648
	global_load_dwordx4 v[64:67], v[142:143], off offset:1024
	global_load_dwordx4 v[68:71], v[144:145], off offset:1024
	s_waitcnt vmcnt(15)
	ds_write_b128 v130, v[72:75] offset:13824
	s_waitcnt vmcnt(14)
	ds_write_b128 v130, v[76:79] offset:32256
	global_load_dwordx4 v[72:75], v[146:147], off offset:1024
	global_load_dwordx4 v[76:79], v[148:149], off offset:1024
	s_waitcnt lgkmcnt(0)
	s_barrier
	ds_read_b128 v[208:211], v167 offset:18432
	ds_read_b128 v[236:239], v132
	v_mfma_f32_32x32x16_bf16 v[0:15], v[212:215], v[246:249], v[0:15]
	ds_read_b128 v[212:215], v132 offset:4608
	ds_read_b128 v[246:249], v167 offset:23040
	s_waitcnt lgkmcnt(2)
	v_mfma_f32_32x32x16_bf16 v[48:63], v[208:211], v[236:239], v[48:63]
	s_waitcnt lgkmcnt(1)
	v_mfma_f32_32x32x16_bf16 v[32:47], v[208:211], v[212:215], v[32:47]
	ds_read_b128 v[208:211], v167 offset:18464
	s_waitcnt lgkmcnt(1)
	v_mfma_f32_32x32x16_bf16 v[16:31], v[246:249], v[236:239], v[16:31]
	ds_read_b128 v[236:239], v132 offset:32
	v_mfma_f32_32x32x16_bf16 v[0:15], v[246:249], v[212:215], v[0:15]
	ds_read_b128 v[246:249], v132 offset:4640
	ds_read_b128 v[212:215], v167 offset:23072
	s_waitcnt lgkmcnt(2)
	v_mfma_f32_32x32x16_bf16 v[48:63], v[208:211], v[236:239], v[48:63]
	s_waitcnt lgkmcnt(1)
	v_mfma_f32_32x32x16_bf16 v[32:47], v[208:211], v[246:249], v[32:47]
	ds_read_b128 v[208:211], v167 offset:18496
	s_waitcnt vmcnt(15)
	ds_write_b128 v130, v[124:127] offset:36864
	s_waitcnt vmcnt(14)
	ds_write_b128 v130, v[154:157] offset:55296
	s_waitcnt lgkmcnt(3)
	v_mfma_f32_32x32x16_bf16 v[16:31], v[212:215], v[236:239], v[16:31]
	ds_read_b128 v[236:239], v132 offset:64
	v_mfma_f32_32x32x16_bf16 v[0:15], v[212:215], v[246:249], v[0:15]
	ds_read_b128 v[212:215], v132 offset:4672
	ds_read_b128 v[246:249], v167 offset:23104
	s_waitcnt lgkmcnt(2)
	v_mfma_f32_32x32x16_bf16 v[48:63], v[208:211], v[236:239], v[48:63]
	s_waitcnt lgkmcnt(1)
	v_mfma_f32_32x32x16_bf16 v[32:47], v[208:211], v[212:215], v[32:47]
	ds_read_b128 v[208:211], v167 offset:18528
	s_waitcnt vmcnt(13)
	ds_write_b128 v130, v[96:99] offset:41472
	s_waitcnt vmcnt(12)
	ds_write_b128 v130, v[100:103] offset:59904
	s_waitcnt lgkmcnt(3)
	v_mfma_f32_32x32x16_bf16 v[16:31], v[246:249], v[236:239], v[16:31]
	ds_read_b128 v[236:239], v132 offset:96
	v_mfma_f32_32x32x16_bf16 v[0:15], v[246:249], v[212:215], v[0:15]
	ds_read_b128 v[246:249], v132 offset:4704
	ds_read_b128 v[212:215], v167 offset:23136
	s_waitcnt lgkmcnt(2)
	v_mfma_f32_32x32x16_bf16 v[48:63], v[208:211], v[236:239], v[48:63]
	s_waitcnt lgkmcnt(1)
	v_mfma_f32_32x32x16_bf16 v[32:47], v[208:211], v[246:249], v[32:47]
	s_waitcnt lgkmcnt(0)
	v_mfma_f32_32x32x16_bf16 v[16:31], v[212:215], v[236:239], v[16:31]
	global_load_dwordx4 v[124:127], v[112:113], off offset:1152
	global_load_dwordx4 v[154:157], v[114:115], off offset:1152
	global_load_dwordx4 v[96:99], v[138:139], off offset:1152
	global_load_dwordx4 v[100:103], v[140:141], off offset:1152
	s_waitcnt vmcnt(15)
	ds_write_b128 v130, v[80:83] offset:46080
	s_waitcnt vmcnt(14)
	ds_write_b128 v130, v[84:87] offset:64512
	global_load_dwordx4 v[80:83], v[142:143], off offset:1152
	global_load_dwordx4 v[84:87], v[144:145], off offset:1152
	s_waitcnt vmcnt(15)
	ds_write_b128 v130, v[88:91] offset:50688
	s_waitcnt vmcnt(14)
	ds_write_b128 v131, v[92:95] offset:13824
	global_load_dwordx4 v[88:91], v[146:147], off offset:1152
	global_load_dwordx4 v[92:95], v[148:149], off offset:1152
	s_waitcnt lgkmcnt(0)
	s_barrier
; #define GLOADQ(RA, RB, KT, q) do { const int k0_ = (KT) << 6; \
;     RA[q] = ldg16(ap.ptr(m0 + lrow + 32 * (q), k0_) + lkc); RB[q] = ldg16(W + (size_t)(n0 + lrow + 32 * (q)) * ldw + k0_ + lkc); } while (0)
; #define SSTOREQ(RA, RB, ST, q) do { \
;     *(u32x4*)(sA + (ST) * SBUF + (lrow + 32 * (q)) * GP + lkc) = RA[q]; *(u32x4*)(sB + (ST) * SBUF + (lrow + 32 * (q)) * GP + lkc) = RB[q]; } while (0)
; #define FLOAD(F, ST, ks) do { _Pragma("unroll") for (int a = 0; a < 2; ++a) { \
;     F[a] = *(const bf16x8*)(sB + (ST) * SBUF + (wn * 64 + a * 32 + r) * GP + (ks) * 16 + h * 8); \
;     F[2 + a] = *(const bf16x8*)(sA + (ST) * SBUF + (wm * 64 + a * 32 + r) * GP + (ks) * 16 + h * 8); } } while (0)
; #define FMMA(F) do { _Pragma("unroll") for (int a = 0; a < 2; ++a) _Pragma("unroll") for (int b = 0; b < 2; ++b) acc[a][b] = MFMA(F[a], F[2 + b], acc[a][b]); } while (0)
; template <bool MIDK, class AP, class EPI>
; DI void gemm_tile(const AP& ap, const u16* __restrict__ W, int ldw, int K, int m0, int n0, const EPI& epi, char* smem, float r0, float r1, int tid, bool dry) {
;     ...
;   for (int kt = 0; kt < nk; kt += 2) {
;     const bool l3 = kt + 3 < nk, s2 = kt + 2 < nk, l4 = kt + 4 < nk;
;     FLOAD(f0, 0, 0); FLOAD(f1, 0, 1);
;     FMMA(f0); SSTOREQ(ra1, rb1, 1, 0); if (l3) GLOADQ(ra1, rb1, kt + 3, 0);
;     FLOAD(f0, 0, 2);
;     FMMA(f1); SSTOREQ(ra1, rb1, 1, 1); if (l3) GLOADQ(ra1, rb1, kt + 3, 1);
;     FLOAD(f1, 0, 3);
;     FMMA(f0); SSTOREQ(ra1, rb1, 1, 2); if (l3) GLOADQ(ra1, rb1, kt + 3, 2);
;     FMMA(f1); SSTOREQ(ra1, rb1, 1, 3); if (l3) GLOADQ(ra1, rb1, kt + 3, 3);
;     __syncthreads();
;     FLOAD(f0, 1, 0); FLOAD(f1, 1, 1);
;     FMMA(f0); if (s2) SSTOREQ(ra0, rb0, 0, 0); if (l4) GLOADQ(ra0, rb0, kt + 4, 0);
;     FLOAD(f0, 1, 2);
;     FMMA(f1); if (s2) SSTOREQ(ra0, rb0, 0, 1); if (l4) GLOADQ(ra0, rb0, kt + 4, 1);
;     FLOAD(f1, 1, 3);
;     FMMA(f0); if (s2) SSTOREQ(ra0, rb0, 0, 2); if (l4) GLOADQ(ra0, rb0, kt + 4, 2);
;     FMMA(f1); if (s2) SSTOREQ(ra0, rb0, 0, 3); if (l4) GLOADQ(ra0, rb0, kt + 4, 3);
;     if (MIDK && kt == 6) {
; #pragma unroll
;       for (int a = 0; a < 2; ++a)
; #pragma unroll
;         for (int i = 0; i < 16; ++i) { acc[a][0][i] *= r0; acc[a][1][i] *= r1; }
;     }
;     __syncthreads();
	ds_read_b128 v[208:211], v167 offset:55296
	ds_read_b128 v[236:239], v132 offset:36864
	v_mfma_f32_32x32x16_bf16 v[0:15], v[212:215], v[246:249], v[0:15]
	ds_read_b128 v[212:215], v132 offset:41472
	ds_read_b128 v[246:249], v167 offset:59904
	s_waitcnt lgkmcnt(2)
	v_mfma_f32_32x32x16_bf16 v[48:63], v[208:211], v[236:239], v[48:63]
	s_waitcnt lgkmcnt(1)
	v_mfma_f32_32x32x16_bf16 v[32:47], v[208:211], v[212:215], v[32:47]
	ds_read_b128 v[208:211], v167 offset:55328
	s_waitcnt lgkmcnt(1)
	v_mfma_f32_32x32x16_bf16 v[16:31], v[246:249], v[236:239], v[16:31]
	ds_read_b128 v[236:239], v132 offset:36896
	v_mfma_f32_32x32x16_bf16 v[0:15], v[246:249], v[212:215], v[0:15]
	ds_read_b128 v[246:249], v132 offset:41504
	ds_read_b128 v[212:215], v167 offset:59936
	s_waitcnt lgkmcnt(2)
	v_mfma_f32_32x32x16_bf16 v[48:63], v[208:211], v[236:239], v[48:63]
	s_waitcnt lgkmcnt(1)
	v_mfma_f32_32x32x16_bf16 v[32:47], v[208:211], v[246:249], v[32:47]
	ds_read_b128 v[208:211], v167 offset:55360
	s_waitcnt vmcnt(15)
	ds_write_b128 v130, v[150:153]
	s_waitcnt vmcnt(14)
	ds_write_b128 v130, v[158:161] offset:18432
	s_waitcnt lgkmcnt(3)
	v_mfma_f32_32x32x16_bf16 v[16:31], v[212:215], v[236:239], v[16:31]
	ds_read_b128 v[236:239], v132 offset:36928
	v_mfma_f32_32x32x16_bf16 v[0:15], v[212:215], v[246:249], v[0:15]
	ds_read_b128 v[212:215], v132 offset:41536
	ds_read_b128 v[246:249], v167 offset:59968
	s_waitcnt lgkmcnt(2)
	v_mfma_f32_32x32x16_bf16 v[48:63], v[208:211], v[236:239], v[48:63]
	s_waitcnt lgkmcnt(1)
	v_mfma_f32_32x32x16_bf16 v[32:47], v[208:211], v[212:215], v[32:47]
	ds_read_b128 v[208:211], v167 offset:55392
	s_waitcnt vmcnt(13)
	ds_write_b128 v130, v[104:107] offset:4608
	s_waitcnt vmcnt(12)
	ds_write_b128 v130, v[108:111] offset:23040
	s_waitcnt lgkmcnt(3)
	v_mfma_f32_32x32x16_bf16 v[16:31], v[246:249], v[236:239], v[16:31]
	ds_read_b128 v[236:239], v132 offset:36960
	v_mfma_f32_32x32x16_bf16 v[0:15], v[246:249], v[212:215], v[0:15]
	ds_read_b128 v[246:249], v132 offset:41568
	ds_read_b128 v[212:215], v167 offset:60000
	s_waitcnt lgkmcnt(2)
	v_mfma_f32_32x32x16_bf16 v[48:63], v[208:211], v[236:239], v[48:63]
	s_waitcnt lgkmcnt(1)
	v_mfma_f32_32x32x16_bf16 v[32:47], v[208:211], v[246:249], v[32:47]
	s_waitcnt lgkmcnt(0)
	v_mfma_f32_32x32x16_bf16 v[16:31], v[212:215], v[236:239], v[16:31]
	global_load_dwordx4 v[150:153], v[112:113], off offset:1280
	global_load_dwordx4 v[158:161], v[114:115], off offset:1280
	global_load_dwordx4 v[104:107], v[138:139], off offset:1280
	global_load_dwordx4 v[108:111], v[140:141], off offset:1280
	s_waitcnt vmcnt(15)
	ds_write_b128 v130, v[64:67] offset:9216
	s_waitcnt vmcnt(14)
	ds_write_b128 v130, v[68:71] offset:27648
	global_load_dwordx4 v[64:67], v[142:143], off offset:1280
	global_load_dwordx4 v[68:71], v[144:145], off offset:1280
	s_waitcnt vmcnt(15)
	ds_write_b128 v130, v[72:75] offset:13824
	s_waitcnt vmcnt(14)
	ds_write_b128 v130, v[76:79] offset:32256
	global_load_dwordx4 v[72:75], v[146:147], off offset:1280
	global_load_dwordx4 v[76:79], v[148:149], off offset:1280
	s_waitcnt lgkmcnt(0)
	s_barrier
	ds_read_b128 v[208:211], v167 offset:18432
	ds_read_b128 v[236:239], v132
	v_mfma_f32_32x32x16_bf16 v[0:15], v[212:215], v[246:249], v[0:15]
	ds_read_b128 v[212:215], v132 offset:4608
	ds_read_b128 v[246:249], v167 offset:23040
	s_waitcnt lgkmcnt(2)
	v_mfma_f32_32x32x16_bf16 v[48:63], v[208:211], v[236:239], v[48:63]
	s_waitcnt lgkmcnt(1)
	v_mfma_f32_32x32x16_bf16 v[32:47], v[208:211], v[212:215], v[32:47]
	ds_read_b128 v[208:211], v167 offset:18464
	s_waitcnt lgkmcnt(1)
	v_mfma_f32_32x32x16_bf16 v[16:31], v[246:249], v[236:239], v[16:31]
	ds_read_b128 v[236:239], v132 offset:32
	v_mfma_f32_32x32x16_bf16 v[0:15], v[246:249], v[212:215], v[0:15]
	ds_read_b128 v[246:249], v132 offset:4640
	ds_read_b128 v[212:215], v167 offset:23072
	s_waitcnt lgkmcnt(2)
	v_mfma_f32_32x32x16_bf16 v[48:63], v[208:211], v[236:239], v[48:63]
	s_waitcnt lgkmcnt(1)
	v_mfma_f32_32x32x16_bf16 v[32:47], v[208:211], v[246:249], v[32:47]
	ds_read_b128 v[208:211], v167 offset:18496
	s_waitcnt vmcnt(15)
	ds_write_b128 v130, v[124:127] offset:36864
	s_waitcnt vmcnt(14)
	ds_write_b128 v130, v[154:157] offset:55296
	s_waitcnt lgkmcnt(3)
	v_mfma_f32_32x32x16_bf16 v[16:31], v[212:215], v[236:239], v[16:31]
	ds_read_b128 v[236:239], v132 offset:64
	v_mfma_f32_32x32x16_bf16 v[0:15], v[212:215], v[246:249], v[0:15]
	ds_read_b128 v[212:215], v132 offset:4672
	ds_read_b128 v[246:249], v167 offset:23104
	s_waitcnt lgkmcnt(2)
	v_mfma_f32_32x32x16_bf16 v[48:63], v[208:211], v[236:239], v[48:63]
	s_waitcnt lgkmcnt(1)
	v_mfma_f32_32x32x16_bf16 v[32:47], v[208:211], v[212:215], v[32:47]
	ds_read_b128 v[208:211], v167 offset:18528
	s_waitcnt vmcnt(13)
	ds_write_b128 v130, v[96:99] offset:41472
	s_waitcnt vmcnt(12)
	ds_write_b128 v130, v[100:103] offset:59904
	s_waitcnt lgkmcnt(3)
	v_mfma_f32_32x32x16_bf16 v[16:31], v[246:249], v[236:239], v[16:31]
	ds_read_b128 v[236:239], v132 offset:96
	v_mfma_f32_32x32x16_bf16 v[0:15], v[246:249], v[212:215], v[0:15]
	ds_read_b128 v[246:249], v132 offset:4704
	ds_read_b128 v[212:215], v167 offset:23136
	s_waitcnt lgkmcnt(2)
	v_mfma_f32_32x32x16_bf16 v[48:63], v[208:211], v[236:239], v[48:63]
	s_waitcnt lgkmcnt(1)
	v_mfma_f32_32x32x16_bf16 v[32:47], v[208:211], v[246:249], v[32:47]
	s_waitcnt lgkmcnt(0)
	v_mfma_f32_32x32x16_bf16 v[16:31], v[212:215], v[236:239], v[16:31]
	global_load_dwordx4 v[124:127], v[112:113], off offset:1408
	global_load_dwordx4 v[154:157], v[114:115], off offset:1408
	global_load_dwordx4 v[96:99], v[138:139], off offset:1408
	global_load_dwordx4 v[100:103], v[140:141], off offset:1408
	s_waitcnt vmcnt(15)
	ds_write_b128 v130, v[80:83] offset:46080
	s_waitcnt vmcnt(14)
	ds_write_b128 v130, v[84:87] offset:64512
	global_load_dwordx4 v[80:83], v[142:143], off offset:1408
	global_load_dwordx4 v[84:87], v[144:145], off offset:1408
	s_waitcnt vmcnt(15)
	ds_write_b128 v130, v[88:91] offset:50688
	s_waitcnt vmcnt(14)
	ds_write_b128 v131, v[92:95] offset:13824
	global_load_dwordx4 v[88:91], v[146:147], off offset:1408
	global_load_dwordx4 v[92:95], v[148:149], off offset:1408
	s_waitcnt lgkmcnt(0)
	s_barrier
; #define GLOADQ(RA, RB, KT, q) do { const int k0_ = (KT) << 6; \
;     RA[q] = ldg16(ap.ptr(m0 + lrow + 32 * (q), k0_) + lkc); RB[q] = ldg16(W + (size_t)(n0 + lrow + 32 * (q)) * ldw + k0_ + lkc); } while (0)
; #define SSTOREQ(RA, RB, ST, q) do { \
;     *(u32x4*)(sA + (ST) * SBUF + (lrow + 32 * (q)) * GP + lkc) = RA[q]; *(u32x4*)(sB + (ST) * SBUF + (lrow + 32 * (q)) * GP + lkc) = RB[q]; } while (0)
; #define FLOAD(F, ST, ks) do { _Pragma("unroll") for (int a = 0; a < 2; ++a) { \
;     F[a] = *(const bf16x8*)(sB + (ST) * SBUF + (wn * 64 + a * 32 + r) * GP + (ks) * 16 + h * 8); \
;     F[2 + a] = *(const bf16x8*)(sA + (ST) * SBUF + (wm * 64 + a * 32 + r) * GP + (ks) * 16 + h * 8); } } while (0)
; #define FMMA(F) do { _Pragma("unroll") for (int a = 0; a < 2; ++a) _Pragma("unroll") for (int b = 0; b < 2; ++b) acc[a][b] = MFMA(F[a], F[2 + b], acc[a][b]); } while (0)
; template <bool MIDK, class AP, class EPI>
; DI void gemm_tile(const AP& ap, const u16* __restrict__ W, int ldw, int K, int m0, int n0, const EPI& epi, char* smem, float r0, float r1, int tid, bool dry) {
;     ...
;   for (int kt = 0; kt < nk; kt += 2) {
;     const bool l3 = kt + 3 < nk, s2 = kt + 2 < nk, l4 = kt + 4 < nk;
;     FLOAD(f0, 0, 0); FLOAD(f1, 0, 1);
;     FMMA(f0); SSTOREQ(ra1, rb1, 1, 0); if (l3) GLOADQ(ra1, rb1, kt + 3, 0);
;     FLOAD(f0, 0, 2);
;     FMMA(f1); SSTOREQ(ra1, rb1, 1, 1); if (l3) GLOADQ(ra1, rb1, kt + 3, 1);
;     FLOAD(f1, 0, 3);
;     FMMA(f0); SSTOREQ(ra1, rb1, 1, 2); if (l3) GLOADQ(ra1, rb1, kt + 3, 2);
;     FMMA(f1); SSTOREQ(ra1, rb1, 1, 3); if (l3) GLOADQ(ra1, rb1, kt + 3, 3);
;     __syncthreads();
;     FLOAD(f0, 1, 0); FLOAD(f1, 1, 1);
;     FMMA(f0); if (s2) SSTOREQ(ra0, rb0, 0, 0); if (l4) GLOADQ(ra0, rb0, kt + 4, 0);
;     FLOAD(f0, 1, 2);
;     FMMA(f1); if (s2) SSTOREQ(ra0, rb0, 0, 1); if (l4) GLOADQ(ra0, rb0, kt + 4, 1);
;     FLOAD(f1, 1, 3);
;     FMMA(f0); if (s2) SSTOREQ(ra0, rb0, 0, 2); if (l4) GLOADQ(ra0, rb0, kt + 4, 2);
;     FMMA(f1); if (s2) SSTOREQ(ra0, rb0, 0, 3); if (l4) GLOADQ(ra0, rb0, kt + 4, 3);
;     if (MIDK && kt == 6) {
; #pragma unroll
;       for (int a = 0; a < 2; ++a)
; #pragma unroll
;         for (int i = 0; i < 16; ++i) { acc[a][0][i] *= r0; acc[a][1][i] *= r1; }
;     }
;     __syncthreads();
	ds_read_b128 v[208:211], v167 offset:55296
	ds_read_b128 v[236:239], v132 offset:36864
	v_mfma_f32_32x32x16_bf16 v[0:15], v[212:215], v[246:249], v[0:15]
	ds_read_b128 v[212:215], v132 offset:41472
	ds_read_b128 v[246:249], v167 offset:59904
	s_waitcnt lgkmcnt(2)
	v_mfma_f32_32x32x16_bf16 v[48:63], v[208:211], v[236:239], v[48:63]
	s_waitcnt lgkmcnt(1)
	v_mfma_f32_32x32x16_bf16 v[32:47], v[208:211], v[212:215], v[32:47]
	ds_read_b128 v[208:211], v167 offset:55328
	s_waitcnt lgkmcnt(1)
	v_mfma_f32_32x32x16_bf16 v[16:31], v[246:249], v[236:239], v[16:31]
	ds_read_b128 v[236:239], v132 offset:36896
	v_mfma_f32_32x32x16_bf16 v[0:15], v[246:249], v[212:215], v[0:15]
	ds_read_b128 v[246:249], v132 offset:41504
	ds_read_b128 v[212:215], v167 offset:59936
	s_waitcnt lgkmcnt(2)
	v_mfma_f32_32x32x16_bf16 v[48:63], v[208:211], v[236:239], v[48:63]
	s_waitcnt lgkmcnt(1)
	v_mfma_f32_32x32x16_bf16 v[32:47], v[208:211], v[246:249], v[32:47]
	ds_read_b128 v[208:211], v167 offset:55360
	s_waitcnt vmcnt(15)
	ds_write_b128 v130, v[150:153]
	s_waitcnt vmcnt(14)
	ds_write_b128 v130, v[158:161] offset:18432
	s_waitcnt lgkmcnt(3)
	v_mfma_f32_32x32x16_bf16 v[16:31], v[212:215], v[236:239], v[16:31]
	ds_read_b128 v[236:239], v132 offset:36928
	v_mfma_f32_32x32x16_bf16 v[0:15], v[212:215], v[246:249], v[0:15]
	ds_read_b128 v[212:215], v132 offset:41536
	ds_read_b128 v[246:249], v167 offset:59968
	s_waitcnt lgkmcnt(2)
	v_mfma_f32_32x32x16_bf16 v[48:63], v[208:211], v[236:239], v[48:63]
	s_waitcnt lgkmcnt(1)
	v_mfma_f32_32x32x16_bf16 v[32:47], v[208:211], v[212:215], v[32:47]
	ds_read_b128 v[208:211], v167 offset:55392
	s_waitcnt vmcnt(13)
	ds_write_b128 v130, v[104:107] offset:4608
	s_waitcnt vmcnt(12)
	ds_write_b128 v130, v[108:111] offset:23040
	s_waitcnt lgkmcnt(3)
	v_mfma_f32_32x32x16_bf16 v[16:31], v[246:249], v[236:239], v[16:31]
	ds_read_b128 v[236:239], v132 offset:36960
	v_mfma_f32_32x32x16_bf16 v[0:15], v[246:249], v[212:215], v[0:15]
	ds_read_b128 v[246:249], v132 offset:41568
	ds_read_b128 v[212:215], v167 offset:60000
	s_waitcnt lgkmcnt(2)
	v_mfma_f32_32x32x16_bf16 v[48:63], v[208:211], v[236:239], v[48:63]
	s_waitcnt lgkmcnt(1)
	v_mfma_f32_32x32x16_bf16 v[32:47], v[208:211], v[246:249], v[32:47]
	s_waitcnt lgkmcnt(0)
	v_mfma_f32_32x32x16_bf16 v[16:31], v[212:215], v[236:239], v[16:31]
	global_load_dwordx4 v[150:153], v[112:113], off offset:1536
	global_load_dwordx4 v[158:161], v[114:115], off offset:1536
	global_load_dwordx4 v[104:107], v[138:139], off offset:1536
	global_load_dwordx4 v[108:111], v[140:141], off offset:1536
	s_waitcnt vmcnt(15)
	ds_write_b128 v130, v[64:67] offset:9216
	s_waitcnt vmcnt(14)
	ds_write_b128 v130, v[68:71] offset:27648
	global_load_dwordx4 v[64:67], v[142:143], off offset:1536
	global_load_dwordx4 v[68:71], v[144:145], off offset:1536
	s_waitcnt vmcnt(15)
	ds_write_b128 v130, v[72:75] offset:13824
	s_waitcnt vmcnt(14)
	ds_write_b128 v130, v[76:79] offset:32256
	global_load_dwordx4 v[72:75], v[146:147], off offset:1536
	global_load_dwordx4 v[76:79], v[148:149], off offset:1536
	s_waitcnt lgkmcnt(0)
	s_barrier
	ds_read_b128 v[208:211], v167 offset:18432
	ds_read_b128 v[236:239], v132
	v_mfma_f32_32x32x16_bf16 v[0:15], v[212:215], v[246:249], v[0:15]
	ds_read_b128 v[212:215], v132 offset:4608
	ds_read_b128 v[246:249], v167 offset:23040
	s_waitcnt lgkmcnt(2)
	v_mfma_f32_32x32x16_bf16 v[48:63], v[208:211], v[236:239], v[48:63]
	s_waitcnt lgkmcnt(1)
	v_mfma_f32_32x32x16_bf16 v[32:47], v[208:211], v[212:215], v[32:47]
	ds_read_b128 v[208:211], v167 offset:18464
	s_waitcnt lgkmcnt(1)
	v_mfma_f32_32x32x16_bf16 v[16:31], v[246:249], v[236:239], v[16:31]
	ds_read_b128 v[236:239], v132 offset:32
	v_mfma_f32_32x32x16_bf16 v[0:15], v[246:249], v[212:215], v[0:15]
	ds_read_b128 v[246:249], v132 offset:4640
	ds_read_b128 v[212:215], v167 offset:23072
	s_waitcnt lgkmcnt(2)
	v_mfma_f32_32x32x16_bf16 v[48:63], v[208:211], v[236:239], v[48:63]
	s_waitcnt lgkmcnt(1)
	v_mfma_f32_32x32x16_bf16 v[32:47], v[208:211], v[246:249], v[32:47]
	ds_read_b128 v[208:211], v167 offset:18496
	s_waitcnt vmcnt(15)
	ds_write_b128 v130, v[124:127] offset:36864
	s_waitcnt vmcnt(14)
	ds_write_b128 v130, v[154:157] offset:55296
	s_waitcnt lgkmcnt(3)
	v_mfma_f32_32x32x16_bf16 v[16:31], v[212:215], v[236:239], v[16:31]
	ds_read_b128 v[236:239], v132 offset:64
	v_mfma_f32_32x32x16_bf16 v[0:15], v[212:215], v[246:249], v[0:15]
	ds_read_b128 v[212:215], v132 offset:4672
	ds_read_b128 v[246:249], v167 offset:23104
	s_waitcnt lgkmcnt(2)
	v_mfma_f32_32x32x16_bf16 v[48:63], v[208:211], v[236:239], v[48:63]
	s_waitcnt lgkmcnt(1)
	v_mfma_f32_32x32x16_bf16 v[32:47], v[208:211], v[212:215], v[32:47]
	ds_read_b128 v[208:211], v167 offset:18528
	s_waitcnt vmcnt(13)
	ds_write_b128 v130, v[96:99] offset:41472
	s_waitcnt vmcnt(12)
	ds_write_b128 v130, v[100:103] offset:59904
	s_waitcnt lgkmcnt(3)
	v_mfma_f32_32x32x16_bf16 v[16:31], v[246:249], v[236:239], v[16:31]
	ds_read_b128 v[236:239], v132 offset:96
	v_mfma_f32_32x32x16_bf16 v[0:15], v[246:249], v[212:215], v[0:15]
	ds_read_b128 v[246:249], v132 offset:4704
	ds_read_b128 v[212:215], v167 offset:23136
	s_waitcnt lgkmcnt(2)
	v_mfma_f32_32x32x16_bf16 v[48:63], v[208:211], v[236:239], v[48:63]
	s_waitcnt lgkmcnt(1)
	v_mfma_f32_32x32x16_bf16 v[32:47], v[208:211], v[246:249], v[32:47]
	s_waitcnt lgkmcnt(0)
	v_mfma_f32_32x32x16_bf16 v[16:31], v[212:215], v[236:239], v[16:31]
	global_load_dwordx4 v[124:127], v[112:113], off offset:1664
	global_load_dwordx4 v[154:157], v[114:115], off offset:1664
	global_load_dwordx4 v[96:99], v[138:139], off offset:1664
	global_load_dwordx4 v[100:103], v[140:141], off offset:1664
	s_waitcnt vmcnt(15)
	ds_write_b128 v130, v[80:83] offset:46080
	s_waitcnt vmcnt(14)
	ds_write_b128 v130, v[84:87] offset:64512
	global_load_dwordx4 v[80:83], v[142:143], off offset:1664
	global_load_dwordx4 v[84:87], v[144:145], off offset:1664
	s_waitcnt vmcnt(15)
	ds_write_b128 v130, v[88:91] offset:50688
	s_waitcnt vmcnt(14)
	ds_write_b128 v131, v[92:95] offset:13824
	global_load_dwordx4 v[88:91], v[146:147], off offset:1664
	global_load_dwordx4 v[92:95], v[148:149], off offset:1664
	s_waitcnt lgkmcnt(0)
	s_barrier
; #define GLOADQ(RA, RB, KT, q) do { const int k0_ = (KT) << 6; \
;     RA[q] = ldg16(ap.ptr(m0 + lrow + 32 * (q), k0_) + lkc); RB[q] = ldg16(W + (size_t)(n0 + lrow + 32 * (q)) * ldw + k0_ + lkc); } while (0)
; #define SSTOREQ(RA, RB, ST, q) do { \
;     *(u32x4*)(sA + (ST) * SBUF + (lrow + 32 * (q)) * GP + lkc) = RA[q]; *(u32x4*)(sB + (ST) * SBUF + (lrow + 32 * (q)) * GP + lkc) = RB[q]; } while (0)
; #define FLOAD(F, ST, ks) do { _Pragma("unroll") for (int a = 0; a < 2; ++a) { \
;     F[a] = *(const bf16x8*)(sB + (ST) * SBUF + (wn * 64 + a * 32 + r) * GP + (ks) * 16 + h * 8); \
;     F[2 + a] = *(const bf16x8*)(sA + (ST) * SBUF + (wm * 64 + a * 32 + r) * GP + (ks) * 16 + h * 8); } } while (0)
; #define FMMA(F) do { _Pragma("unroll") for (int a = 0; a < 2; ++a) _Pragma("unroll") for (int b = 0; b < 2; ++b) acc[a][b] = MFMA(F[a], F[2 + b], acc[a][b]); } while (0)
; template <bool MIDK, class AP, class EPI>
; DI void gemm_tile(const AP& ap, const u16* __restrict__ W, int ldw, int K, int m0, int n0, const EPI& epi, char* smem, float r0, float r1, int tid, bool dry) {
;     ...
;   for (int kt = 0; kt < nk; kt += 2) {
;     const bool l3 = kt + 3 < nk, s2 = kt + 2 < nk, l4 = kt + 4 < nk;
;     FLOAD(f0, 0, 0); FLOAD(f1, 0, 1);
;     FMMA(f0); SSTOREQ(ra1, rb1, 1, 0); if (l3) GLOADQ(ra1, rb1, kt + 3, 0);
;     FLOAD(f0, 0, 2);
;     FMMA(f1); SSTOREQ(ra1, rb1, 1, 1); if (l3) GLOADQ(ra1, rb1, kt + 3, 1);
;     FLOAD(f1, 0, 3);
;     FMMA(f0); SSTOREQ(ra1, rb1, 1, 2); if (l3) GLOADQ(ra1, rb1, kt + 3, 2);
;     FMMA(f1); SSTOREQ(ra1, rb1, 1, 3); if (l3) GLOADQ(ra1, rb1, kt + 3, 3);
;     __syncthreads();
;     FLOAD(f0, 1, 0); FLOAD(f1, 1, 1);
;     FMMA(f0); if (s2) SSTOREQ(ra0, rb0, 0, 0); if (l4) GLOADQ(ra0, rb0, kt + 4, 0);
;     FLOAD(f0, 1, 2);
;     FMMA(f1); if (s2) SSTOREQ(ra0, rb0, 0, 1); if (l4) GLOADQ(ra0, rb0, kt + 4, 1);
;     FLOAD(f1, 1, 3);
;     FMMA(f0); if (s2) SSTOREQ(ra0, rb0, 0, 2); if (l4) GLOADQ(ra0, rb0, kt + 4, 2);
;     FMMA(f1); if (s2) SSTOREQ(ra0, rb0, 0, 3); if (l4) GLOADQ(ra0, rb0, kt + 4, 3);
;     if (MIDK && kt == 6) {
; #pragma unroll
;       for (int a = 0; a < 2; ++a)
; #pragma unroll
;         for (int i = 0; i < 16; ++i) { acc[a][0][i] *= r0; acc[a][1][i] *= r1; }
;     }
;     __syncthreads();
	ds_read_b128 v[208:211], v167 offset:55296
	ds_read_b128 v[236:239], v132 offset:36864
	v_mfma_f32_32x32x16_bf16 v[0:15], v[212:215], v[246:249], v[0:15]
	ds_read_b128 v[212:215], v132 offset:41472
	ds_read_b128 v[246:249], v167 offset:59904
	s_waitcnt lgkmcnt(2)
	v_mfma_f32_32x32x16_bf16 v[48:63], v[208:211], v[236:239], v[48:63]
	s_waitcnt lgkmcnt(1)
	v_mfma_f32_32x32x16_bf16 v[32:47], v[208:211], v[212:215], v[32:47]
	ds_read_b128 v[208:211], v167 offset:55328
	s_waitcnt lgkmcnt(1)
	v_mfma_f32_32x32x16_bf16 v[16:31], v[246:249], v[236:239], v[16:31]
	ds_read_b128 v[236:239], v132 offset:36896
	v_mfma_f32_32x32x16_bf16 v[0:15], v[246:249], v[212:215], v[0:15]
	ds_read_b128 v[246:249], v132 offset:41504
	ds_read_b128 v[212:215], v167 offset:59936
	s_waitcnt lgkmcnt(2)
	v_mfma_f32_32x32x16_bf16 v[48:63], v[208:211], v[236:239], v[48:63]
	s_waitcnt lgkmcnt(1)
	v_mfma_f32_32x32x16_bf16 v[32:47], v[208:211], v[246:249], v[32:47]
	ds_read_b128 v[208:211], v167 offset:55360
	s_waitcnt vmcnt(15)
	ds_write_b128 v130, v[150:153]
	s_waitcnt vmcnt(14)
	ds_write_b128 v130, v[158:161] offset:18432
	s_waitcnt lgkmcnt(3)
	v_mfma_f32_32x32x16_bf16 v[16:31], v[212:215], v[236:239], v[16:31]
	ds_read_b128 v[236:239], v132 offset:36928
	v_mfma_f32_32x32x16_bf16 v[0:15], v[212:215], v[246:249], v[0:15]
	ds_read_b128 v[212:215], v132 offset:41536
	ds_read_b128 v[246:249], v167 offset:59968
	s_waitcnt lgkmcnt(2)
	v_mfma_f32_32x32x16_bf16 v[48:63], v[208:211], v[236:239], v[48:63]
	s_waitcnt lgkmcnt(1)
	v_mfma_f32_32x32x16_bf16 v[32:47], v[208:211], v[212:215], v[32:47]
	ds_read_b128 v[208:211], v167 offset:55392
	s_waitcnt vmcnt(13)
	ds_write_b128 v130, v[104:107] offset:4608
	s_waitcnt vmcnt(12)
	ds_write_b128 v130, v[108:111] offset:23040
	s_waitcnt lgkmcnt(3)
	v_mfma_f32_32x32x16_bf16 v[16:31], v[246:249], v[236:239], v[16:31]
	ds_read_b128 v[236:239], v132 offset:36960
	v_mfma_f32_32x32x16_bf16 v[0:15], v[246:249], v[212:215], v[0:15]
	ds_read_b128 v[246:249], v132 offset:41568
	ds_read_b128 v[212:215], v167 offset:60000
	s_waitcnt lgkmcnt(2)
	v_mfma_f32_32x32x16_bf16 v[48:63], v[208:211], v[236:239], v[48:63]
	s_waitcnt lgkmcnt(1)
	v_mfma_f32_32x32x16_bf16 v[32:47], v[208:211], v[246:249], v[32:47]
	s_waitcnt lgkmcnt(0)
	v_mfma_f32_32x32x16_bf16 v[16:31], v[212:215], v[236:239], v[16:31]
	global_load_dwordx4 v[150:153], v[112:113], off offset:1792
	global_load_dwordx4 v[158:161], v[114:115], off offset:1792
	global_load_dwordx4 v[104:107], v[138:139], off offset:1792
	global_load_dwordx4 v[108:111], v[140:141], off offset:1792
	s_waitcnt vmcnt(15)
	ds_write_b128 v130, v[64:67] offset:9216
	s_waitcnt vmcnt(14)
	ds_write_b128 v130, v[68:71] offset:27648
	global_load_dwordx4 v[64:67], v[142:143], off offset:1792
	global_load_dwordx4 v[68:71], v[144:145], off offset:1792
	s_waitcnt vmcnt(15)
	ds_write_b128 v130, v[72:75] offset:13824
	s_waitcnt vmcnt(14)
	ds_write_b128 v130, v[76:79] offset:32256
	global_load_dwordx4 v[72:75], v[146:147], off offset:1792
	global_load_dwordx4 v[76:79], v[148:149], off offset:1792
	s_waitcnt lgkmcnt(0)
	s_barrier
	ds_read_b128 v[208:211], v167 offset:18432
	ds_read_b128 v[236:239], v132
	v_mfma_f32_32x32x16_bf16 v[0:15], v[212:215], v[246:249], v[0:15]
	ds_read_b128 v[212:215], v132 offset:4608
	ds_read_b128 v[246:249], v167 offset:23040
	s_waitcnt lgkmcnt(2)
	v_mfma_f32_32x32x16_bf16 v[48:63], v[208:211], v[236:239], v[48:63]
	s_waitcnt lgkmcnt(1)
	v_mfma_f32_32x32x16_bf16 v[32:47], v[208:211], v[212:215], v[32:47]
	ds_read_b128 v[208:211], v167 offset:18464
	s_waitcnt lgkmcnt(1)
	v_mfma_f32_32x32x16_bf16 v[16:31], v[246:249], v[236:239], v[16:31]
	ds_read_b128 v[236:239], v132 offset:32
	v_mfma_f32_32x32x16_bf16 v[0:15], v[246:249], v[212:215], v[0:15]
	ds_read_b128 v[246:249], v132 offset:4640
	ds_read_b128 v[212:215], v167 offset:23072
	s_waitcnt lgkmcnt(2)
	v_mfma_f32_32x32x16_bf16 v[48:63], v[208:211], v[236:239], v[48:63]
	s_waitcnt lgkmcnt(1)
	v_mfma_f32_32x32x16_bf16 v[32:47], v[208:211], v[246:249], v[32:47]
	ds_read_b128 v[208:211], v167 offset:18496
	s_waitcnt vmcnt(15)
	ds_write_b128 v130, v[124:127] offset:36864
	s_waitcnt vmcnt(14)
	ds_write_b128 v130, v[154:157] offset:55296
	s_waitcnt lgkmcnt(3)
	v_mfma_f32_32x32x16_bf16 v[16:31], v[212:215], v[236:239], v[16:31]
	ds_read_b128 v[236:239], v132 offset:64
	v_mfma_f32_32x32x16_bf16 v[0:15], v[212:215], v[246:249], v[0:15]
	ds_read_b128 v[212:215], v132 offset:4672
	ds_read_b128 v[246:249], v167 offset:23104
	s_waitcnt lgkmcnt(2)
	v_mfma_f32_32x32x16_bf16 v[48:63], v[208:211], v[236:239], v[48:63]
	s_waitcnt lgkmcnt(1)
	v_mfma_f32_32x32x16_bf16 v[32:47], v[208:211], v[212:215], v[32:47]
	ds_read_b128 v[208:211], v167 offset:18528
	s_waitcnt vmcnt(13)
	ds_write_b128 v130, v[96:99] offset:41472
	s_waitcnt vmcnt(12)
	ds_write_b128 v130, v[100:103] offset:59904
	s_waitcnt lgkmcnt(3)
	v_mfma_f32_32x32x16_bf16 v[16:31], v[246:249], v[236:239], v[16:31]
	ds_read_b128 v[236:239], v132 offset:96
	v_mfma_f32_32x32x16_bf16 v[0:15], v[246:249], v[212:215], v[0:15]
	ds_read_b128 v[246:249], v132 offset:4704
	ds_read_b128 v[212:215], v167 offset:23136
	s_waitcnt lgkmcnt(2)
	v_mfma_f32_32x32x16_bf16 v[48:63], v[208:211], v[236:239], v[48:63]
	s_waitcnt lgkmcnt(1)
	v_mfma_f32_32x32x16_bf16 v[32:47], v[208:211], v[246:249], v[32:47]
	s_waitcnt lgkmcnt(0)
	v_mfma_f32_32x32x16_bf16 v[16:31], v[212:215], v[236:239], v[16:31]
	global_load_dwordx4 v[124:127], v[112:113], off offset:1920
	global_load_dwordx4 v[154:157], v[114:115], off offset:1920
	global_load_dwordx4 v[96:99], v[138:139], off offset:1920
	global_load_dwordx4 v[100:103], v[140:141], off offset:1920
	s_waitcnt vmcnt(15)
	ds_write_b128 v130, v[80:83] offset:46080
	s_waitcnt vmcnt(14)
	ds_write_b128 v130, v[84:87] offset:64512
	global_load_dwordx4 v[80:83], v[142:143], off offset:1920
	global_load_dwordx4 v[84:87], v[144:145], off offset:1920
	s_waitcnt vmcnt(15)
	ds_write_b128 v130, v[88:91] offset:50688
	s_waitcnt vmcnt(14)
	ds_write_b128 v131, v[92:95] offset:13824
	global_load_dwordx4 v[88:91], v[146:147], off offset:1920
	global_load_dwordx4 v[92:95], v[148:149], off offset:1920
	s_waitcnt lgkmcnt(0)
	s_barrier
; #define GLOADQ(RA, RB, KT, q) do { const int k0_ = (KT) << 6; \
;     RA[q] = ldg16(ap.ptr(m0 + lrow + 32 * (q), k0_) + lkc); RB[q] = ldg16(W + (size_t)(n0 + lrow + 32 * (q)) * ldw + k0_ + lkc); } while (0)
; #define SSTOREQ(RA, RB, ST, q) do { \
;     *(u32x4*)(sA + (ST) * SBUF + (lrow + 32 * (q)) * GP + lkc) = RA[q]; *(u32x4*)(sB + (ST) * SBUF + (lrow + 32 * (q)) * GP + lkc) = RB[q]; } while (0)
; #define FLOAD(F, ST, ks) do { _Pragma("unroll") for (int a = 0; a < 2; ++a) { \
;     F[a] = *(const bf16x8*)(sB + (ST) * SBUF + (wn * 64 + a * 32 + r) * GP + (ks) * 16 + h * 8); \
;     F[2 + a] = *(const bf16x8*)(sA + (ST) * SBUF + (wm * 64 + a * 32 + r) * GP + (ks) * 16 + h * 8); } } while (0)
; #define FMMA(F) do { _Pragma("unroll") for (int a = 0; a < 2; ++a) _Pragma("unroll") for (int b = 0; b < 2; ++b) acc[a][b] = MFMA(F[a], F[2 + b], acc[a][b]); } while (0)
; template <bool MIDK, class AP, class EPI>
; DI void gemm_tile(const AP& ap, const u16* __restrict__ W, int ldw, int K, int m0, int n0, const EPI& epi, char* smem, float r0, float r1, int tid, bool dry) {
;     ...
;   for (int kt = 0; kt < nk; kt += 2) {
;     const bool l3 = kt + 3 < nk, s2 = kt + 2 < nk, l4 = kt + 4 < nk;
;     FLOAD(f0, 0, 0); FLOAD(f1, 0, 1);
;     FMMA(f0); SSTOREQ(ra1, rb1, 1, 0); if (l3) GLOADQ(ra1, rb1, kt + 3, 0);
;     FLOAD(f0, 0, 2);
;     FMMA(f1); SSTOREQ(ra1, rb1, 1, 1); if (l3) GLOADQ(ra1, rb1, kt + 3, 1);
;     FLOAD(f1, 0, 3);
;     FMMA(f0); SSTOREQ(ra1, rb1, 1, 2); if (l3) GLOADQ(ra1, rb1, kt + 3, 2);
;     FMMA(f1); SSTOREQ(ra1, rb1, 1, 3); if (l3) GLOADQ(ra1, rb1, kt + 3, 3);
;     __syncthreads();
;     FLOAD(f0, 1, 0); FLOAD(f1, 1, 1);
;     FMMA(f0); if (s2) SSTOREQ(ra0, rb0, 0, 0); if (l4) GLOADQ(ra0, rb0, kt + 4, 0);
;     FLOAD(f0, 1, 2);
;     FMMA(f1); if (s2) SSTOREQ(ra0, rb0, 0, 1); if (l4) GLOADQ(ra0, rb0, kt + 4, 1);
;     FLOAD(f1, 1, 3);
;     FMMA(f0); if (s2) SSTOREQ(ra0, rb0, 0, 2); if (l4) GLOADQ(ra0, rb0, kt + 4, 2);
;     FMMA(f1); if (s2) SSTOREQ(ra0, rb0, 0, 3); if (l4) GLOADQ(ra0, rb0, kt + 4, 3);
;     if (MIDK && kt == 6) {
; #pragma unroll
;       for (int a = 0; a < 2; ++a)
; #pragma unroll
;         for (int i = 0; i < 16; ++i) { acc[a][0][i] *= r0; acc[a][1][i] *= r1; }
;     }
;     __syncthreads();
	ds_read_b128 v[208:211], v167 offset:55296
	ds_read_b128 v[236:239], v132 offset:36864
	v_mfma_f32_32x32x16_bf16 v[0:15], v[212:215], v[246:249], v[0:15]
	ds_read_b128 v[212:215], v132 offset:41472
	ds_read_b128 v[246:249], v167 offset:59904
	s_waitcnt lgkmcnt(2)
	v_mfma_f32_32x32x16_bf16 v[48:63], v[208:211], v[236:239], v[48:63]
	s_waitcnt lgkmcnt(1)
	v_mfma_f32_32x32x16_bf16 v[32:47], v[208:211], v[212:215], v[32:47]
	ds_read_b128 v[208:211], v167 offset:55328
	s_waitcnt lgkmcnt(1)
	v_mfma_f32_32x32x16_bf16 v[16:31], v[246:249], v[236:239], v[16:31]
	ds_read_b128 v[236:239], v132 offset:36896
	v_mfma_f32_32x32x16_bf16 v[0:15], v[246:249], v[212:215], v[0:15]
	ds_read_b128 v[246:249], v132 offset:41504
	ds_read_b128 v[212:215], v167 offset:59936
	s_waitcnt lgkmcnt(2)
	v_mfma_f32_32x32x16_bf16 v[48:63], v[208:211], v[236:239], v[48:63]
	s_waitcnt lgkmcnt(1)
	v_mfma_f32_32x32x16_bf16 v[32:47], v[208:211], v[246:249], v[32:47]
	ds_read_b128 v[208:211], v167 offset:55360
	s_waitcnt vmcnt(15)
	ds_write_b128 v130, v[150:153]
	s_waitcnt vmcnt(14)
	ds_write_b128 v130, v[158:161] offset:18432
	s_waitcnt lgkmcnt(3)
	v_mfma_f32_32x32x16_bf16 v[16:31], v[212:215], v[236:239], v[16:31]
	ds_read_b128 v[236:239], v132 offset:36928
	v_mfma_f32_32x32x16_bf16 v[0:15], v[212:215], v[246:249], v[0:15]
	ds_read_b128 v[212:215], v132 offset:41536
	ds_read_b128 v[246:249], v167 offset:59968
	s_waitcnt lgkmcnt(2)
	v_mfma_f32_32x32x16_bf16 v[48:63], v[208:211], v[236:239], v[48:63]
	s_waitcnt lgkmcnt(1)
	v_mfma_f32_32x32x16_bf16 v[32:47], v[208:211], v[212:215], v[32:47]
	ds_read_b128 v[208:211], v167 offset:55392
	s_waitcnt vmcnt(13)
	ds_write_b128 v130, v[104:107] offset:4608
	s_waitcnt vmcnt(12)
	ds_write_b128 v130, v[108:111] offset:23040
	s_waitcnt lgkmcnt(3)
	v_mfma_f32_32x32x16_bf16 v[16:31], v[246:249], v[236:239], v[16:31]
	ds_read_b128 v[236:239], v132 offset:36960
	v_mfma_f32_32x32x16_bf16 v[0:15], v[246:249], v[212:215], v[0:15]
	ds_read_b128 v[246:249], v132 offset:41568
	ds_read_b128 v[212:215], v167 offset:60000
	s_waitcnt lgkmcnt(2)
	v_mfma_f32_32x32x16_bf16 v[48:63], v[208:211], v[236:239], v[48:63]
	s_waitcnt lgkmcnt(1)
	v_mfma_f32_32x32x16_bf16 v[32:47], v[208:211], v[246:249], v[32:47]
	s_waitcnt lgkmcnt(0)
	v_mfma_f32_32x32x16_bf16 v[16:31], v[212:215], v[236:239], v[16:31]
	global_load_dwordx4 v[150:153], v[112:113], off offset:2048
	global_load_dwordx4 v[158:161], v[114:115], off offset:2048
	global_load_dwordx4 v[104:107], v[138:139], off offset:2048
	global_load_dwordx4 v[108:111], v[140:141], off offset:2048
	s_waitcnt vmcnt(15)
	ds_write_b128 v130, v[64:67] offset:9216
	s_waitcnt vmcnt(14)
	ds_write_b128 v130, v[68:71] offset:27648
	global_load_dwordx4 v[64:67], v[142:143], off offset:2048
	global_load_dwordx4 v[68:71], v[144:145], off offset:2048
	s_waitcnt vmcnt(15)
	ds_write_b128 v130, v[72:75] offset:13824
	s_waitcnt vmcnt(14)
	ds_write_b128 v130, v[76:79] offset:32256
	global_load_dwordx4 v[72:75], v[146:147], off offset:2048
	global_load_dwordx4 v[76:79], v[148:149], off offset:2048
	s_waitcnt lgkmcnt(0)
	s_barrier
	ds_read_b128 v[208:211], v167 offset:18432
	ds_read_b128 v[236:239], v132
	v_mfma_f32_32x32x16_bf16 v[0:15], v[212:215], v[246:249], v[0:15]
	ds_read_b128 v[212:215], v132 offset:4608
	ds_read_b128 v[246:249], v167 offset:23040
	s_waitcnt lgkmcnt(2)
	v_mfma_f32_32x32x16_bf16 v[48:63], v[208:211], v[236:239], v[48:63]
	s_waitcnt lgkmcnt(1)
	v_mfma_f32_32x32x16_bf16 v[32:47], v[208:211], v[212:215], v[32:47]
	ds_read_b128 v[208:211], v167 offset:18464
	s_waitcnt lgkmcnt(1)
	v_mfma_f32_32x32x16_bf16 v[16:31], v[246:249], v[236:239], v[16:31]
	ds_read_b128 v[236:239], v132 offset:32
	v_mfma_f32_32x32x16_bf16 v[0:15], v[246:249], v[212:215], v[0:15]
	ds_read_b128 v[246:249], v132 offset:4640
	ds_read_b128 v[212:215], v167 offset:23072
	s_waitcnt lgkmcnt(2)
	v_mfma_f32_32x32x16_bf16 v[48:63], v[208:211], v[236:239], v[48:63]
	s_waitcnt lgkmcnt(1)
	v_mfma_f32_32x32x16_bf16 v[32:47], v[208:211], v[246:249], v[32:47]
	ds_read_b128 v[208:211], v167 offset:18496
	s_waitcnt vmcnt(15)
	ds_write_b128 v130, v[124:127] offset:36864
	s_waitcnt vmcnt(14)
	ds_write_b128 v130, v[154:157] offset:55296
	s_waitcnt lgkmcnt(3)
	v_mfma_f32_32x32x16_bf16 v[16:31], v[212:215], v[236:239], v[16:31]
	ds_read_b128 v[236:239], v132 offset:64
	v_mfma_f32_32x32x16_bf16 v[0:15], v[212:215], v[246:249], v[0:15]
	ds_read_b128 v[212:215], v132 offset:4672
	ds_read_b128 v[246:249], v167 offset:23104
	s_waitcnt lgkmcnt(2)
	v_mfma_f32_32x32x16_bf16 v[48:63], v[208:211], v[236:239], v[48:63]
	s_waitcnt lgkmcnt(1)
	v_mfma_f32_32x32x16_bf16 v[32:47], v[208:211], v[212:215], v[32:47]
	ds_read_b128 v[208:211], v167 offset:18528
	s_waitcnt vmcnt(13)
	ds_write_b128 v130, v[96:99] offset:41472
	s_waitcnt vmcnt(12)
	ds_write_b128 v130, v[100:103] offset:59904
	s_waitcnt lgkmcnt(3)
	v_mfma_f32_32x32x16_bf16 v[16:31], v[246:249], v[236:239], v[16:31]
	ds_read_b128 v[236:239], v132 offset:96
	v_mfma_f32_32x32x16_bf16 v[0:15], v[246:249], v[212:215], v[0:15]
	ds_read_b128 v[246:249], v132 offset:4704
	ds_read_b128 v[212:215], v167 offset:23136
	s_waitcnt lgkmcnt(2)
	v_mfma_f32_32x32x16_bf16 v[48:63], v[208:211], v[236:239], v[48:63]
	s_waitcnt lgkmcnt(1)
	v_mfma_f32_32x32x16_bf16 v[32:47], v[208:211], v[246:249], v[32:47]
	s_waitcnt lgkmcnt(0)
	v_mfma_f32_32x32x16_bf16 v[16:31], v[212:215], v[236:239], v[16:31]
	global_load_dwordx4 v[124:127], v[112:113], off offset:2176
	global_load_dwordx4 v[154:157], v[114:115], off offset:2176
	global_load_dwordx4 v[96:99], v[138:139], off offset:2176
	global_load_dwordx4 v[100:103], v[140:141], off offset:2176
	s_waitcnt vmcnt(15)
	ds_write_b128 v130, v[80:83] offset:46080
	s_waitcnt vmcnt(14)
	ds_write_b128 v130, v[84:87] offset:64512
	global_load_dwordx4 v[80:83], v[142:143], off offset:2176
	global_load_dwordx4 v[84:87], v[144:145], off offset:2176
	s_waitcnt vmcnt(15)
	ds_write_b128 v130, v[88:91] offset:50688
	s_waitcnt vmcnt(14)
	ds_write_b128 v131, v[92:95] offset:13824
	global_load_dwordx4 v[88:91], v[146:147], off offset:2176
	global_load_dwordx4 v[92:95], v[148:149], off offset:2176
	s_waitcnt lgkmcnt(0)
	s_barrier
; #define GLOADQ(RA, RB, KT, q) do { const int k0_ = (KT) << 6; \
;     RA[q] = ldg16(ap.ptr(m0 + lrow + 32 * (q), k0_) + lkc); RB[q] = ldg16(W + (size_t)(n0 + lrow + 32 * (q)) * ldw + k0_ + lkc); } while (0)
; #define SSTOREQ(RA, RB, ST, q) do { \
;     *(u32x4*)(sA + (ST) * SBUF + (lrow + 32 * (q)) * GP + lkc) = RA[q]; *(u32x4*)(sB + (ST) * SBUF + (lrow + 32 * (q)) * GP + lkc) = RB[q]; } while (0)
; #define FLOAD(F, ST, ks) do { _Pragma("unroll") for (int a = 0; a < 2; ++a) { \
;     F[a] = *(const bf16x8*)(sB + (ST) * SBUF + (wn * 64 + a * 32 + r) * GP + (ks) * 16 + h * 8); \
;     F[2 + a] = *(const bf16x8*)(sA + (ST) * SBUF + (wm * 64 + a * 32 + r) * GP + (ks) * 16 + h * 8); } } while (0)
; #define FMMA(F) do { _Pragma("unroll") for (int a = 0; a < 2; ++a) _Pragma("unroll") for (int b = 0; b < 2; ++b) acc[a][b] = MFMA(F[a], F[2 + b], acc[a][b]); } while (0)
; template <bool MIDK, class AP, class EPI>
; DI void gemm_tile(const AP& ap, const u16* __restrict__ W, int ldw, int K, int m0, int n0, const EPI& epi, char* smem, float r0, float r1, int tid, bool dry) {
;     ...
;   for (int kt = 0; kt < nk; kt += 2) {
;     const bool l3 = kt + 3 < nk, s2 = kt + 2 < nk, l4 = kt + 4 < nk;
;     FLOAD(f0, 0, 0); FLOAD(f1, 0, 1);
;     FMMA(f0); SSTOREQ(ra1, rb1, 1, 0); if (l3) GLOADQ(ra1, rb1, kt + 3, 0);
;     FLOAD(f0, 0, 2);
;     FMMA(f1); SSTOREQ(ra1, rb1, 1, 1); if (l3) GLOADQ(ra1, rb1, kt + 3, 1);
;     FLOAD(f1, 0, 3);
;     FMMA(f0); SSTOREQ(ra1, rb1, 1, 2); if (l3) GLOADQ(ra1, rb1, kt + 3, 2);
;     FMMA(f1); SSTOREQ(ra1, rb1, 1, 3); if (l3) GLOADQ(ra1, rb1, kt + 3, 3);
;     __syncthreads();
;     FLOAD(f0, 1, 0); FLOAD(f1, 1, 1);
;     FMMA(f0); if (s2) SSTOREQ(ra0, rb0, 0, 0); if (l4) GLOADQ(ra0, rb0, kt + 4, 0);
;     FLOAD(f0, 1, 2);
;     FMMA(f1); if (s2) SSTOREQ(ra0, rb0, 0, 1); if (l4) GLOADQ(ra0, rb0, kt + 4, 1);
;     FLOAD(f1, 1, 3);
;     FMMA(f0); if (s2) SSTOREQ(ra0, rb0, 0, 2); if (l4) GLOADQ(ra0, rb0, kt + 4, 2);
;     FMMA(f1); if (s2) SSTOREQ(ra0, rb0, 0, 3); if (l4) GLOADQ(ra0, rb0, kt + 4, 3);
;     if (MIDK && kt == 6) {
; #pragma unroll
;       for (int a = 0; a < 2; ++a)
; #pragma unroll
;         for (int i = 0; i < 16; ++i) { acc[a][0][i] *= r0; acc[a][1][i] *= r1; }
;     }
;     __syncthreads();
	ds_read_b128 v[208:211], v167 offset:55296
	ds_read_b128 v[236:239], v132 offset:36864
	v_mfma_f32_32x32x16_bf16 v[0:15], v[212:215], v[246:249], v[0:15]
	ds_read_b128 v[212:215], v132 offset:41472
	ds_read_b128 v[246:249], v167 offset:59904
	s_waitcnt lgkmcnt(2)
	v_mfma_f32_32x32x16_bf16 v[48:63], v[208:211], v[236:239], v[48:63]
	s_waitcnt lgkmcnt(1)
	v_mfma_f32_32x32x16_bf16 v[32:47], v[208:211], v[212:215], v[32:47]
	ds_read_b128 v[208:211], v167 offset:55328
	s_waitcnt lgkmcnt(1)
	v_mfma_f32_32x32x16_bf16 v[16:31], v[246:249], v[236:239], v[16:31]
	ds_read_b128 v[236:239], v132 offset:36896
	v_mfma_f32_32x32x16_bf16 v[0:15], v[246:249], v[212:215], v[0:15]
	ds_read_b128 v[246:249], v132 offset:41504
	ds_read_b128 v[212:215], v167 offset:59936
	s_waitcnt lgkmcnt(2)
	v_mfma_f32_32x32x16_bf16 v[48:63], v[208:211], v[236:239], v[48:63]
	s_waitcnt lgkmcnt(1)
	v_mfma_f32_32x32x16_bf16 v[32:47], v[208:211], v[246:249], v[32:47]
	ds_read_b128 v[208:211], v167 offset:55360
	s_waitcnt vmcnt(15)
	ds_write_b128 v130, v[150:153]
	s_waitcnt vmcnt(14)
	ds_write_b128 v130, v[158:161] offset:18432
	s_waitcnt lgkmcnt(3)
	v_mfma_f32_32x32x16_bf16 v[16:31], v[212:215], v[236:239], v[16:31]
	ds_read_b128 v[236:239], v132 offset:36928
	v_mfma_f32_32x32x16_bf16 v[0:15], v[212:215], v[246:249], v[0:15]
	ds_read_b128 v[212:215], v132 offset:41536
	ds_read_b128 v[246:249], v167 offset:59968
	s_waitcnt lgkmcnt(2)
	v_mfma_f32_32x32x16_bf16 v[48:63], v[208:211], v[236:239], v[48:63]
	s_waitcnt lgkmcnt(1)
	v_mfma_f32_32x32x16_bf16 v[32:47], v[208:211], v[212:215], v[32:47]
	ds_read_b128 v[208:211], v167 offset:55392
	s_waitcnt vmcnt(13)
	ds_write_b128 v130, v[104:107] offset:4608
	s_waitcnt vmcnt(12)
	ds_write_b128 v130, v[108:111] offset:23040
	s_waitcnt lgkmcnt(3)
	v_mfma_f32_32x32x16_bf16 v[16:31], v[246:249], v[236:239], v[16:31]
	ds_read_b128 v[236:239], v132 offset:36960
	v_mfma_f32_32x32x16_bf16 v[0:15], v[246:249], v[212:215], v[0:15]
	ds_read_b128 v[246:249], v132 offset:41568
	ds_read_b128 v[212:215], v167 offset:60000
	s_waitcnt lgkmcnt(2)
	v_mfma_f32_32x32x16_bf16 v[48:63], v[208:211], v[236:239], v[48:63]
	s_waitcnt lgkmcnt(1)
	v_mfma_f32_32x32x16_bf16 v[32:47], v[208:211], v[246:249], v[32:47]
	s_waitcnt lgkmcnt(0)
	v_mfma_f32_32x32x16_bf16 v[16:31], v[212:215], v[236:239], v[16:31]
	global_load_dwordx4 v[150:153], v[112:113], off offset:2304
	global_load_dwordx4 v[158:161], v[114:115], off offset:2304
	global_load_dwordx4 v[104:107], v[138:139], off offset:2304
	global_load_dwordx4 v[108:111], v[140:141], off offset:2304
	s_waitcnt vmcnt(15)
	ds_write_b128 v130, v[64:67] offset:9216
	s_waitcnt vmcnt(14)
	ds_write_b128 v130, v[68:71] offset:27648
	global_load_dwordx4 v[64:67], v[142:143], off offset:2304
	global_load_dwordx4 v[68:71], v[144:145], off offset:2304
	s_waitcnt vmcnt(15)
	ds_write_b128 v130, v[72:75] offset:13824
	s_waitcnt vmcnt(14)
	ds_write_b128 v130, v[76:79] offset:32256
	global_load_dwordx4 v[72:75], v[146:147], off offset:2304
	global_load_dwordx4 v[76:79], v[148:149], off offset:2304
	s_waitcnt lgkmcnt(0)
	s_barrier
	ds_read_b128 v[208:211], v167 offset:18432
	ds_read_b128 v[236:239], v132
	v_mfma_f32_32x32x16_bf16 v[0:15], v[212:215], v[246:249], v[0:15]
	ds_read_b128 v[212:215], v132 offset:4608
	ds_read_b128 v[246:249], v167 offset:23040
	s_waitcnt lgkmcnt(2)
	v_mfma_f32_32x32x16_bf16 v[48:63], v[208:211], v[236:239], v[48:63]
	s_waitcnt lgkmcnt(1)
	v_mfma_f32_32x32x16_bf16 v[32:47], v[208:211], v[212:215], v[32:47]
	ds_read_b128 v[208:211], v167 offset:18464
	s_waitcnt lgkmcnt(1)
	v_mfma_f32_32x32x16_bf16 v[16:31], v[246:249], v[236:239], v[16:31]
	ds_read_b128 v[236:239], v132 offset:32
	v_mfma_f32_32x32x16_bf16 v[0:15], v[246:249], v[212:215], v[0:15]
	ds_read_b128 v[246:249], v132 offset:4640
	ds_read_b128 v[212:215], v167 offset:23072
	s_waitcnt lgkmcnt(2)
	v_mfma_f32_32x32x16_bf16 v[48:63], v[208:211], v[236:239], v[48:63]
	s_waitcnt lgkmcnt(1)
	v_mfma_f32_32x32x16_bf16 v[32:47], v[208:211], v[246:249], v[32:47]
	ds_read_b128 v[208:211], v167 offset:18496
	s_waitcnt vmcnt(15)
	ds_write_b128 v130, v[124:127] offset:36864
	s_waitcnt vmcnt(14)
	ds_write_b128 v130, v[154:157] offset:55296
	s_waitcnt lgkmcnt(3)
	v_mfma_f32_32x32x16_bf16 v[16:31], v[212:215], v[236:239], v[16:31]
	ds_read_b128 v[236:239], v132 offset:64
	v_mfma_f32_32x32x16_bf16 v[0:15], v[212:215], v[246:249], v[0:15]
	ds_read_b128 v[212:215], v132 offset:4672
	ds_read_b128 v[246:249], v167 offset:23104
	s_waitcnt lgkmcnt(2)
	v_mfma_f32_32x32x16_bf16 v[48:63], v[208:211], v[236:239], v[48:63]
	s_waitcnt lgkmcnt(1)
	v_mfma_f32_32x32x16_bf16 v[32:47], v[208:211], v[212:215], v[32:47]
	ds_read_b128 v[208:211], v167 offset:18528
	s_waitcnt vmcnt(13)
	ds_write_b128 v130, v[96:99] offset:41472
	s_waitcnt vmcnt(12)
	ds_write_b128 v130, v[100:103] offset:59904
	s_waitcnt lgkmcnt(3)
	v_mfma_f32_32x32x16_bf16 v[16:31], v[246:249], v[236:239], v[16:31]
	ds_read_b128 v[236:239], v132 offset:96
	v_mfma_f32_32x32x16_bf16 v[0:15], v[246:249], v[212:215], v[0:15]
	ds_read_b128 v[246:249], v132 offset:4704
	ds_read_b128 v[212:215], v167 offset:23136
	s_waitcnt lgkmcnt(2)
	v_mfma_f32_32x32x16_bf16 v[48:63], v[208:211], v[236:239], v[48:63]
	s_waitcnt lgkmcnt(1)
	v_mfma_f32_32x32x16_bf16 v[32:47], v[208:211], v[246:249], v[32:47]
	s_waitcnt lgkmcnt(0)
	v_mfma_f32_32x32x16_bf16 v[16:31], v[212:215], v[236:239], v[16:31]
	global_load_dwordx4 v[124:127], v[112:113], off offset:2432
	global_load_dwordx4 v[154:157], v[114:115], off offset:2432
	global_load_dwordx4 v[96:99], v[138:139], off offset:2432
	global_load_dwordx4 v[100:103], v[140:141], off offset:2432
	s_waitcnt vmcnt(15)
	ds_write_b128 v130, v[80:83] offset:46080
	s_waitcnt vmcnt(14)
	ds_write_b128 v130, v[84:87] offset:64512
	global_load_dwordx4 v[80:83], v[142:143], off offset:2432
	global_load_dwordx4 v[84:87], v[144:145], off offset:2432
	s_waitcnt vmcnt(15)
	ds_write_b128 v130, v[88:91] offset:50688
	s_waitcnt vmcnt(14)
	ds_write_b128 v131, v[92:95] offset:13824
	global_load_dwordx4 v[88:91], v[146:147], off offset:2432
	global_load_dwordx4 v[92:95], v[148:149], off offset:2432
	s_waitcnt lgkmcnt(0)
	s_barrier
; #define GLOADQ(RA, RB, KT, q) do { const int k0_ = (KT) << 6; \
;     RA[q] = ldg16(ap.ptr(m0 + lrow + 32 * (q), k0_) + lkc); RB[q] = ldg16(W + (size_t)(n0 + lrow + 32 * (q)) * ldw + k0_ + lkc); } while (0)
; #define SSTOREQ(RA, RB, ST, q) do { \
;     *(u32x4*)(sA + (ST) * SBUF + (lrow + 32 * (q)) * GP + lkc) = RA[q]; *(u32x4*)(sB + (ST) * SBUF + (lrow + 32 * (q)) * GP + lkc) = RB[q]; } while (0)
; #define FLOAD(F, ST, ks) do { _Pragma("unroll") for (int a = 0; a < 2; ++a) { \
;     F[a] = *(const bf16x8*)(sB + (ST) * SBUF + (wn * 64 + a * 32 + r) * GP + (ks) * 16 + h * 8); \
;     F[2 + a] = *(const bf16x8*)(sA + (ST) * SBUF + (wm * 64 + a * 32 + r) * GP + (ks) * 16 + h * 8); } } while (0)
; #define FMMA(F) do { _Pragma("unroll") for (int a = 0; a < 2; ++a) _Pragma("unroll") for (int b = 0; b < 2; ++b) acc[a][b] = MFMA(F[a], F[2 + b], acc[a][b]); } while (0)
; template <bool MIDK, class AP, class EPI>
; DI void gemm_tile(const AP& ap, const u16* __restrict__ W, int ldw, int K, int m0, int n0, const EPI& epi, char* smem, float r0, float r1, int tid, bool dry) {
;     ...
;   for (int kt = 0; kt < nk; kt += 2) {
;     const bool l3 = kt + 3 < nk, s2 = kt + 2 < nk, l4 = kt + 4 < nk;
;     FLOAD(f0, 0, 0); FLOAD(f1, 0, 1);
;     FMMA(f0); SSTOREQ(ra1, rb1, 1, 0); if (l3) GLOADQ(ra1, rb1, kt + 3, 0);
;     FLOAD(f0, 0, 2);
;     FMMA(f1); SSTOREQ(ra1, rb1, 1, 1); if (l3) GLOADQ(ra1, rb1, kt + 3, 1);
;     FLOAD(f1, 0, 3);
;     FMMA(f0); SSTOREQ(ra1, rb1, 1, 2); if (l3) GLOADQ(ra1, rb1, kt + 3, 2);
;     FMMA(f1); SSTOREQ(ra1, rb1, 1, 3); if (l3) GLOADQ(ra1, rb1, kt + 3, 3);
;     __syncthreads();
;     FLOAD(f0, 1, 0); FLOAD(f1, 1, 1);
;     FMMA(f0); if (s2) SSTOREQ(ra0, rb0, 0, 0); if (l4) GLOADQ(ra0, rb0, kt + 4, 0);
;     FLOAD(f0, 1, 2);
;     FMMA(f1); if (s2) SSTOREQ(ra0, rb0, 0, 1); if (l4) GLOADQ(ra0, rb0, kt + 4, 1);
;     FLOAD(f1, 1, 3);
;     FMMA(f0); if (s2) SSTOREQ(ra0, rb0, 0, 2); if (l4) GLOADQ(ra0, rb0, kt + 4, 2);
;     FMMA(f1); if (s2) SSTOREQ(ra0, rb0, 0, 3); if (l4) GLOADQ(ra0, rb0, kt + 4, 3);
;     if (MIDK && kt == 6) {
; #pragma unroll
;       for (int a = 0; a < 2; ++a)
; #pragma unroll
;         for (int i = 0; i < 16; ++i) { acc[a][0][i] *= r0; acc[a][1][i] *= r1; }
;     }
;     __syncthreads();
	ds_read_b128 v[208:211], v167 offset:55296
	ds_read_b128 v[236:239], v132 offset:36864
	v_mfma_f32_32x32x16_bf16 v[0:15], v[212:215], v[246:249], v[0:15]
	ds_read_b128 v[212:215], v132 offset:41472
	ds_read_b128 v[246:249], v167 offset:59904
	s_waitcnt lgkmcnt(2)
	v_mfma_f32_32x32x16_bf16 v[48:63], v[208:211], v[236:239], v[48:63]
	s_waitcnt lgkmcnt(1)
	v_mfma_f32_32x32x16_bf16 v[32:47], v[208:211], v[212:215], v[32:47]
	ds_read_b128 v[208:211], v167 offset:55328
	s_waitcnt lgkmcnt(1)
	v_mfma_f32_32x32x16_bf16 v[16:31], v[246:249], v[236:239], v[16:31]
	ds_read_b128 v[236:239], v132 offset:36896
	v_mfma_f32_32x32x16_bf16 v[0:15], v[246:249], v[212:215], v[0:15]
	ds_read_b128 v[246:249], v132 offset:41504
	ds_read_b128 v[212:215], v167 offset:59936
	s_waitcnt lgkmcnt(2)
	v_mfma_f32_32x32x16_bf16 v[48:63], v[208:211], v[236:239], v[48:63]
	s_waitcnt lgkmcnt(1)
	v_mfma_f32_32x32x16_bf16 v[32:47], v[208:211], v[246:249], v[32:47]
	ds_read_b128 v[208:211], v167 offset:55360
	s_waitcnt vmcnt(15)
	ds_write_b128 v130, v[150:153]
	s_waitcnt vmcnt(14)
	ds_write_b128 v130, v[158:161] offset:18432
	s_waitcnt lgkmcnt(3)
	v_mfma_f32_32x32x16_bf16 v[16:31], v[212:215], v[236:239], v[16:31]
	ds_read_b128 v[236:239], v132 offset:36928
	v_mfma_f32_32x32x16_bf16 v[0:15], v[212:215], v[246:249], v[0:15]
	ds_read_b128 v[212:215], v132 offset:41536
	ds_read_b128 v[246:249], v167 offset:59968
	s_waitcnt lgkmcnt(2)
	v_mfma_f32_32x32x16_bf16 v[48:63], v[208:211], v[236:239], v[48:63]
	s_waitcnt lgkmcnt(1)
	v_mfma_f32_32x32x16_bf16 v[32:47], v[208:211], v[212:215], v[32:47]
	ds_read_b128 v[208:211], v167 offset:55392
	s_waitcnt vmcnt(13)
	ds_write_b128 v130, v[104:107] offset:4608
	s_waitcnt vmcnt(12)
	ds_write_b128 v130, v[108:111] offset:23040
	s_waitcnt lgkmcnt(3)
	v_mfma_f32_32x32x16_bf16 v[16:31], v[246:249], v[236:239], v[16:31]
	ds_read_b128 v[236:239], v132 offset:36960
	v_mfma_f32_32x32x16_bf16 v[0:15], v[246:249], v[212:215], v[0:15]
	ds_read_b128 v[246:249], v132 offset:41568
	ds_read_b128 v[212:215], v167 offset:60000
	s_waitcnt lgkmcnt(2)
	v_mfma_f32_32x32x16_bf16 v[48:63], v[208:211], v[236:239], v[48:63]
	s_waitcnt lgkmcnt(1)
	v_mfma_f32_32x32x16_bf16 v[32:47], v[208:211], v[246:249], v[32:47]
	s_waitcnt lgkmcnt(0)
	v_mfma_f32_32x32x16_bf16 v[16:31], v[212:215], v[236:239], v[16:31]
	global_load_dwordx4 v[150:153], v[112:113], off offset:2560
	global_load_dwordx4 v[158:161], v[114:115], off offset:2560
	global_load_dwordx4 v[104:107], v[138:139], off offset:2560
	global_load_dwordx4 v[108:111], v[140:141], off offset:2560
	s_waitcnt vmcnt(15)
	ds_write_b128 v130, v[64:67] offset:9216
	s_waitcnt vmcnt(14)
	ds_write_b128 v130, v[68:71] offset:27648
	global_load_dwordx4 v[64:67], v[142:143], off offset:2560
	global_load_dwordx4 v[68:71], v[144:145], off offset:2560
	s_waitcnt vmcnt(15)
	ds_write_b128 v130, v[72:75] offset:13824
	s_waitcnt vmcnt(14)
	ds_write_b128 v130, v[76:79] offset:32256
	global_load_dwordx4 v[72:75], v[146:147], off offset:2560
	global_load_dwordx4 v[76:79], v[148:149], off offset:2560
	s_waitcnt lgkmcnt(0)
	s_barrier
	ds_read_b128 v[208:211], v167 offset:18432
	ds_read_b128 v[236:239], v132
	v_mfma_f32_32x32x16_bf16 v[0:15], v[212:215], v[246:249], v[0:15]
	ds_read_b128 v[212:215], v132 offset:4608
	ds_read_b128 v[246:249], v167 offset:23040
	s_waitcnt lgkmcnt(2)
	v_mfma_f32_32x32x16_bf16 v[48:63], v[208:211], v[236:239], v[48:63]
	s_waitcnt lgkmcnt(1)
	v_mfma_f32_32x32x16_bf16 v[32:47], v[208:211], v[212:215], v[32:47]
	ds_read_b128 v[208:211], v167 offset:18464
	s_waitcnt lgkmcnt(1)
	v_mfma_f32_32x32x16_bf16 v[16:31], v[246:249], v[236:239], v[16:31]
	ds_read_b128 v[236:239], v132 offset:32
	v_mfma_f32_32x32x16_bf16 v[0:15], v[246:249], v[212:215], v[0:15]
	ds_read_b128 v[246:249], v132 offset:4640
	ds_read_b128 v[212:215], v167 offset:23072
	s_waitcnt lgkmcnt(2)
	v_mfma_f32_32x32x16_bf16 v[48:63], v[208:211], v[236:239], v[48:63]
	s_waitcnt lgkmcnt(1)
	v_mfma_f32_32x32x16_bf16 v[32:47], v[208:211], v[246:249], v[32:47]
	ds_read_b128 v[208:211], v167 offset:18496
	s_waitcnt vmcnt(15)
	ds_write_b128 v130, v[124:127] offset:36864
	s_waitcnt vmcnt(14)
	ds_write_b128 v130, v[154:157] offset:55296
	s_waitcnt lgkmcnt(3)
	v_mfma_f32_32x32x16_bf16 v[16:31], v[212:215], v[236:239], v[16:31]
	ds_read_b128 v[236:239], v132 offset:64
	v_mfma_f32_32x32x16_bf16 v[0:15], v[212:215], v[246:249], v[0:15]
	ds_read_b128 v[212:215], v132 offset:4672
	ds_read_b128 v[246:249], v167 offset:23104
	s_waitcnt lgkmcnt(2)
	v_mfma_f32_32x32x16_bf16 v[48:63], v[208:211], v[236:239], v[48:63]
	s_waitcnt lgkmcnt(1)
	v_mfma_f32_32x32x16_bf16 v[32:47], v[208:211], v[212:215], v[32:47]
	ds_read_b128 v[208:211], v167 offset:18528
	s_waitcnt vmcnt(13)
	ds_write_b128 v130, v[96:99] offset:41472
	s_waitcnt vmcnt(12)
	ds_write_b128 v130, v[100:103] offset:59904
	s_waitcnt lgkmcnt(3)
	v_mfma_f32_32x32x16_bf16 v[16:31], v[246:249], v[236:239], v[16:31]
	ds_read_b128 v[236:239], v132 offset:96
	v_mfma_f32_32x32x16_bf16 v[0:15], v[246:249], v[212:215], v[0:15]
	ds_read_b128 v[246:249], v132 offset:4704
	ds_read_b128 v[212:215], v167 offset:23136
	s_waitcnt lgkmcnt(2)
	v_mfma_f32_32x32x16_bf16 v[48:63], v[208:211], v[236:239], v[48:63]
	s_waitcnt lgkmcnt(1)
	v_mfma_f32_32x32x16_bf16 v[32:47], v[208:211], v[246:249], v[32:47]
	s_waitcnt lgkmcnt(0)
	v_mfma_f32_32x32x16_bf16 v[16:31], v[212:215], v[236:239], v[16:31]
	global_load_dwordx4 v[124:127], v[112:113], off offset:2688
	global_load_dwordx4 v[154:157], v[114:115], off offset:2688
	global_load_dwordx4 v[96:99], v[138:139], off offset:2688
	global_load_dwordx4 v[100:103], v[140:141], off offset:2688
	s_waitcnt vmcnt(15)
	ds_write_b128 v130, v[80:83] offset:46080
	s_waitcnt vmcnt(14)
	ds_write_b128 v130, v[84:87] offset:64512
	global_load_dwordx4 v[80:83], v[142:143], off offset:2688
	global_load_dwordx4 v[84:87], v[144:145], off offset:2688
	s_waitcnt vmcnt(15)
	ds_write_b128 v130, v[88:91] offset:50688
	s_waitcnt vmcnt(14)
	ds_write_b128 v131, v[92:95] offset:13824
	global_load_dwordx4 v[88:91], v[146:147], off offset:2688
	global_load_dwordx4 v[92:95], v[148:149], off offset:2688
	s_waitcnt lgkmcnt(0)
	s_barrier
; #define GLOADQ(RA, RB, KT, q) do { const int k0_ = (KT) << 6; \
;     RA[q] = ldg16(ap.ptr(m0 + lrow + 32 * (q), k0_) + lkc); RB[q] = ldg16(W + (size_t)(n0 + lrow + 32 * (q)) * ldw + k0_ + lkc); } while (0)
; #define SSTOREQ(RA, RB, ST, q) do { \
;     *(u32x4*)(sA + (ST) * SBUF + (lrow + 32 * (q)) * GP + lkc) = RA[q]; *(u32x4*)(sB + (ST) * SBUF + (lrow + 32 * (q)) * GP + lkc) = RB[q]; } while (0)
; #define FLOAD(F, ST, ks) do { _Pragma("unroll") for (int a = 0; a < 2; ++a) { \
;     F[a] = *(const bf16x8*)(sB + (ST) * SBUF + (wn * 64 + a * 32 + r) * GP + (ks) * 16 + h * 8); \
;     F[2 + a] = *(const bf16x8*)(sA + (ST) * SBUF + (wm * 64 + a * 32 + r) * GP + (ks) * 16 + h * 8); } } while (0)
; #define FMMA(F) do { _Pragma("unroll") for (int a = 0; a < 2; ++a) _Pragma("unroll") for (int b = 0; b < 2; ++b) acc[a][b] = MFMA(F[a], F[2 + b], acc[a][b]); } while (0)
; template <bool MIDK, class AP, class EPI>
; DI void gemm_tile(const AP& ap, const u16* __restrict__ W, int ldw, int K, int m0, int n0, const EPI& epi, char* smem, float r0, float r1, int tid, bool dry) {
;     ...
;   for (int kt = 0; kt < nk; kt += 2) {
;     const bool l3 = kt + 3 < nk, s2 = kt + 2 < nk, l4 = kt + 4 < nk;
;     FLOAD(f0, 0, 0); FLOAD(f1, 0, 1);
;     FMMA(f0); SSTOREQ(ra1, rb1, 1, 0); if (l3) GLOADQ(ra1, rb1, kt + 3, 0);
;     FLOAD(f0, 0, 2);
;     FMMA(f1); SSTOREQ(ra1, rb1, 1, 1); if (l3) GLOADQ(ra1, rb1, kt + 3, 1);
;     FLOAD(f1, 0, 3);
;     FMMA(f0); SSTOREQ(ra1, rb1, 1, 2); if (l3) GLOADQ(ra1, rb1, kt + 3, 2);
;     FMMA(f1); SSTOREQ(ra1, rb1, 1, 3); if (l3) GLOADQ(ra1, rb1, kt + 3, 3);
;     __syncthreads();
;     FLOAD(f0, 1, 0); FLOAD(f1, 1, 1);
;     FMMA(f0); if (s2) SSTOREQ(ra0, rb0, 0, 0); if (l4) GLOADQ(ra0, rb0, kt + 4, 0);
;     FLOAD(f0, 1, 2);
;     FMMA(f1); if (s2) SSTOREQ(ra0, rb0, 0, 1); if (l4) GLOADQ(ra0, rb0, kt + 4, 1);
;     FLOAD(f1, 1, 3);
;     FMMA(f0); if (s2) SSTOREQ(ra0, rb0, 0, 2); if (l4) GLOADQ(ra0, rb0, kt + 4, 2);
;     FMMA(f1); if (s2) SSTOREQ(ra0, rb0, 0, 3); if (l4) GLOADQ(ra0, rb0, kt + 4, 3);
;     if (MIDK && kt == 6) {
; #pragma unroll
;       for (int a = 0; a < 2; ++a)
; #pragma unroll
;         for (int i = 0; i < 16; ++i) { acc[a][0][i] *= r0; acc[a][1][i] *= r1; }
;     }
;     __syncthreads();
	ds_read_b128 v[208:211], v167 offset:55296
	ds_read_b128 v[236:239], v132 offset:36864
	v_mfma_f32_32x32x16_bf16 v[0:15], v[212:215], v[246:249], v[0:15]
	ds_read_b128 v[212:215], v132 offset:41472
	ds_read_b128 v[246:249], v167 offset:59904
	s_waitcnt lgkmcnt(2)
	v_mfma_f32_32x32x16_bf16 v[48:63], v[208:211], v[236:239], v[48:63]
	s_waitcnt lgkmcnt(1)
	v_mfma_f32_32x32x16_bf16 v[32:47], v[208:211], v[212:215], v[32:47]
	ds_read_b128 v[208:211], v167 offset:55328
	s_waitcnt lgkmcnt(1)
	v_mfma_f32_32x32x16_bf16 v[16:31], v[246:249], v[236:239], v[16:31]
	ds_read_b128 v[236:239], v132 offset:36896
	v_mfma_f32_32x32x16_bf16 v[0:15], v[246:249], v[212:215], v[0:15]
	ds_read_b128 v[246:249], v132 offset:41504
	ds_read_b128 v[212:215], v167 offset:59936
	s_waitcnt lgkmcnt(2)
	v_mfma_f32_32x32x16_bf16 v[48:63], v[208:211], v[236:239], v[48:63]
	s_waitcnt lgkmcnt(1)
	v_mfma_f32_32x32x16_bf16 v[32:47], v[208:211], v[246:249], v[32:47]
	ds_read_b128 v[208:211], v167 offset:55360
	s_waitcnt vmcnt(15)
	ds_write_b128 v130, v[150:153]
	s_waitcnt vmcnt(14)
	ds_write_b128 v130, v[158:161] offset:18432
	s_waitcnt lgkmcnt(3)
	v_mfma_f32_32x32x16_bf16 v[16:31], v[212:215], v[236:239], v[16:31]
	ds_read_b128 v[236:239], v132 offset:36928
	v_mfma_f32_32x32x16_bf16 v[0:15], v[212:215], v[246:249], v[0:15]
	ds_read_b128 v[212:215], v132 offset:41536
	ds_read_b128 v[246:249], v167 offset:59968
	s_waitcnt lgkmcnt(2)
	v_mfma_f32_32x32x16_bf16 v[48:63], v[208:211], v[236:239], v[48:63]
	s_waitcnt lgkmcnt(1)
	v_mfma_f32_32x32x16_bf16 v[32:47], v[208:211], v[212:215], v[32:47]
	ds_read_b128 v[208:211], v167 offset:55392
	s_waitcnt vmcnt(13)
	ds_write_b128 v130, v[104:107] offset:4608
	s_waitcnt vmcnt(12)
	ds_write_b128 v130, v[108:111] offset:23040
	s_waitcnt lgkmcnt(3)
	v_mfma_f32_32x32x16_bf16 v[16:31], v[246:249], v[236:239], v[16:31]
	ds_read_b128 v[236:239], v132 offset:36960
	v_mfma_f32_32x32x16_bf16 v[0:15], v[246:249], v[212:215], v[0:15]
	ds_read_b128 v[246:249], v132 offset:41568
	ds_read_b128 v[212:215], v167 offset:60000
	s_waitcnt lgkmcnt(2)
	v_mfma_f32_32x32x16_bf16 v[48:63], v[208:211], v[236:239], v[48:63]
	s_waitcnt lgkmcnt(1)
	v_mfma_f32_32x32x16_bf16 v[32:47], v[208:211], v[246:249], v[32:47]
	s_waitcnt lgkmcnt(0)
	v_mfma_f32_32x32x16_bf16 v[16:31], v[212:215], v[236:239], v[16:31]
	global_load_dwordx4 v[150:153], v[112:113], off offset:2816
	global_load_dwordx4 v[158:161], v[114:115], off offset:2816
	global_load_dwordx4 v[104:107], v[138:139], off offset:2816
	global_load_dwordx4 v[108:111], v[140:141], off offset:2816
	s_waitcnt vmcnt(15)
	ds_write_b128 v130, v[64:67] offset:9216
	s_waitcnt vmcnt(14)
	ds_write_b128 v130, v[68:71] offset:27648
	global_load_dwordx4 v[64:67], v[142:143], off offset:2816
	global_load_dwordx4 v[68:71], v[144:145], off offset:2816
	s_waitcnt vmcnt(15)
	ds_write_b128 v130, v[72:75] offset:13824
	s_waitcnt vmcnt(14)
	ds_write_b128 v130, v[76:79] offset:32256
	global_load_dwordx4 v[72:75], v[146:147], off offset:2816
	global_load_dwordx4 v[76:79], v[148:149], off offset:2816
	s_waitcnt lgkmcnt(0)
	s_barrier
	ds_read_b128 v[208:211], v167 offset:18432
	ds_read_b128 v[236:239], v132
	v_mfma_f32_32x32x16_bf16 v[0:15], v[212:215], v[246:249], v[0:15]
	ds_read_b128 v[212:215], v132 offset:4608
	ds_read_b128 v[246:249], v167 offset:23040
	s_waitcnt lgkmcnt(2)
	v_mfma_f32_32x32x16_bf16 v[48:63], v[208:211], v[236:239], v[48:63]
	s_waitcnt lgkmcnt(1)
	v_mfma_f32_32x32x16_bf16 v[32:47], v[208:211], v[212:215], v[32:47]
	ds_read_b128 v[208:211], v167 offset:18464
	s_waitcnt lgkmcnt(1)
	v_mfma_f32_32x32x16_bf16 v[16:31], v[246:249], v[236:239], v[16:31]
	ds_read_b128 v[236:239], v132 offset:32
	v_mfma_f32_32x32x16_bf16 v[0:15], v[246:249], v[212:215], v[0:15]
	ds_read_b128 v[246:249], v132 offset:4640
	ds_read_b128 v[212:215], v167 offset:23072
	s_waitcnt lgkmcnt(2)
	v_mfma_f32_32x32x16_bf16 v[48:63], v[208:211], v[236:239], v[48:63]
	s_waitcnt lgkmcnt(1)
	v_mfma_f32_32x32x16_bf16 v[32:47], v[208:211], v[246:249], v[32:47]
	ds_read_b128 v[208:211], v167 offset:18496
	s_waitcnt vmcnt(15)
	ds_write_b128 v130, v[124:127] offset:36864
	s_waitcnt vmcnt(14)
	ds_write_b128 v130, v[154:157] offset:55296
	s_waitcnt lgkmcnt(3)
	v_mfma_f32_32x32x16_bf16 v[16:31], v[212:215], v[236:239], v[16:31]
	ds_read_b128 v[236:239], v132 offset:64
	v_mfma_f32_32x32x16_bf16 v[0:15], v[212:215], v[246:249], v[0:15]
	ds_read_b128 v[212:215], v132 offset:4672
	ds_read_b128 v[246:249], v167 offset:23104
	s_waitcnt lgkmcnt(2)
	v_mfma_f32_32x32x16_bf16 v[48:63], v[208:211], v[236:239], v[48:63]
	s_waitcnt lgkmcnt(1)
	v_mfma_f32_32x32x16_bf16 v[32:47], v[208:211], v[212:215], v[32:47]
	ds_read_b128 v[208:211], v167 offset:18528
	s_waitcnt vmcnt(13)
	ds_write_b128 v130, v[96:99] offset:41472
	s_waitcnt vmcnt(12)
	ds_write_b128 v130, v[100:103] offset:59904
	s_waitcnt lgkmcnt(3)
	v_mfma_f32_32x32x16_bf16 v[16:31], v[246:249], v[236:239], v[16:31]
	ds_read_b128 v[236:239], v132 offset:96
	v_mfma_f32_32x32x16_bf16 v[0:15], v[246:249], v[212:215], v[0:15]
	ds_read_b128 v[246:249], v132 offset:4704
	ds_read_b128 v[212:215], v167 offset:23136
	s_waitcnt lgkmcnt(2)
	v_mfma_f32_32x32x16_bf16 v[48:63], v[208:211], v[236:239], v[48:63]
	s_waitcnt lgkmcnt(1)
	v_mfma_f32_32x32x16_bf16 v[32:47], v[208:211], v[246:249], v[32:47]
	s_waitcnt lgkmcnt(0)
	v_mfma_f32_32x32x16_bf16 v[16:31], v[212:215], v[236:239], v[16:31]
	global_load_dwordx4 v[124:127], v[112:113], off offset:2944
	global_load_dwordx4 v[154:157], v[114:115], off offset:2944
	global_load_dwordx4 v[96:99], v[138:139], off offset:2944
	global_load_dwordx4 v[100:103], v[140:141], off offset:2944
	s_waitcnt vmcnt(15)
	ds_write_b128 v130, v[80:83] offset:46080
	s_waitcnt vmcnt(14)
	ds_write_b128 v130, v[84:87] offset:64512
	global_load_dwordx4 v[80:83], v[142:143], off offset:2944
	global_load_dwordx4 v[84:87], v[144:145], off offset:2944
	s_waitcnt vmcnt(15)
	ds_write_b128 v130, v[88:91] offset:50688
	s_waitcnt vmcnt(14)
	ds_write_b128 v131, v[92:95] offset:13824
	global_load_dwordx4 v[88:91], v[146:147], off offset:2944
	global_load_dwordx4 v[92:95], v[148:149], off offset:2944
	s_waitcnt lgkmcnt(0)
	s_barrier
; #define GLOADQ(RA, RB, KT, q) do { const int k0_ = (KT) << 6; \
;     RA[q] = ldg16(ap.ptr(m0 + lrow + 32 * (q), k0_) + lkc); RB[q] = ldg16(W + (size_t)(n0 + lrow + 32 * (q)) * ldw + k0_ + lkc); } while (0)
; #define SSTOREQ(RA, RB, ST, q) do { \
;     *(u32x4*)(sA + (ST) * SBUF + (lrow + 32 * (q)) * GP + lkc) = RA[q]; *(u32x4*)(sB + (ST) * SBUF + (lrow + 32 * (q)) * GP + lkc) = RB[q]; } while (0)
; #define FLOAD(F, ST, ks) do { _Pragma("unroll") for (int a = 0; a < 2; ++a) { \
;     F[a] = *(const bf16x8*)(sB + (ST) * SBUF + (wn * 64 + a * 32 + r) * GP + (ks) * 16 + h * 8); \
;     F[2 + a] = *(const bf16x8*)(sA + (ST) * SBUF + (wm * 64 + a * 32 + r) * GP + (ks) * 16 + h * 8); } } while (0)
; #define FMMA(F) do { _Pragma("unroll") for (int a = 0; a < 2; ++a) _Pragma("unroll") for (int b = 0; b < 2; ++b) acc[a][b] = MFMA(F[a], F[2 + b], acc[a][b]); } while (0)
; template <bool MIDK, class AP, class EPI>
; DI void gemm_tile(const AP& ap, const u16* __restrict__ W, int ldw, int K, int m0, int n0, const EPI& epi, char* smem, float r0, float r1, int tid, bool dry) {
;     ...
;   for (int kt = 0; kt < nk; kt += 2) {
;     const bool l3 = kt + 3 < nk, s2 = kt + 2 < nk, l4 = kt + 4 < nk;
;     FLOAD(f0, 0, 0); FLOAD(f1, 0, 1);
;     FMMA(f0); SSTOREQ(ra1, rb1, 1, 0); if (l3) GLOADQ(ra1, rb1, kt + 3, 0);
;     FLOAD(f0, 0, 2);
;     FMMA(f1); SSTOREQ(ra1, rb1, 1, 1); if (l3) GLOADQ(ra1, rb1, kt + 3, 1);
;     FLOAD(f1, 0, 3);
;     FMMA(f0); SSTOREQ(ra1, rb1, 1, 2); if (l3) GLOADQ(ra1, rb1, kt + 3, 2);
;     FMMA(f1); SSTOREQ(ra1, rb1, 1, 3); if (l3) GLOADQ(ra1, rb1, kt + 3, 3);
;     __syncthreads();
;     FLOAD(f0, 1, 0); FLOAD(f1, 1, 1);
;     FMMA(f0); if (s2) SSTOREQ(ra0, rb0, 0, 0); if (l4) GLOADQ(ra0, rb0, kt + 4, 0);
;     FLOAD(f0, 1, 2);
;     FMMA(f1); if (s2) SSTOREQ(ra0, rb0, 0, 1); if (l4) GLOADQ(ra0, rb0, kt + 4, 1);
;     FLOAD(f1, 1, 3);
;     FMMA(f0); if (s2) SSTOREQ(ra0, rb0, 0, 2); if (l4) GLOADQ(ra0, rb0, kt + 4, 2);
;     FMMA(f1); if (s2) SSTOREQ(ra0, rb0, 0, 3); if (l4) GLOADQ(ra0, rb0, kt + 4, 3);
;     if (MIDK && kt == 6) {
; #pragma unroll
;       for (int a = 0; a < 2; ++a)
; #pragma unroll
;         for (int i = 0; i < 16; ++i) { acc[a][0][i] *= r0; acc[a][1][i] *= r1; }
;     }
;     __syncthreads();
	ds_read_b128 v[208:211], v167 offset:55296
	ds_read_b128 v[236:239], v132 offset:36864
	v_mfma_f32_32x32x16_bf16 v[0:15], v[212:215], v[246:249], v[0:15]
	ds_read_b128 v[212:215], v132 offset:41472
	ds_read_b128 v[246:249], v167 offset:59904
	s_waitcnt lgkmcnt(2)
	v_mfma_f32_32x32x16_bf16 v[48:63], v[208:211], v[236:239], v[48:63]
	s_waitcnt lgkmcnt(1)
	v_mfma_f32_32x32x16_bf16 v[32:47], v[208:211], v[212:215], v[32:47]
	ds_read_b128 v[208:211], v167 offset:55328
	s_waitcnt lgkmcnt(1)
	v_mfma_f32_32x32x16_bf16 v[16:31], v[246:249], v[236:239], v[16:31]
	ds_read_b128 v[236:239], v132 offset:36896
	v_mfma_f32_32x32x16_bf16 v[0:15], v[246:249], v[212:215], v[0:15]
	ds_read_b128 v[246:249], v132 offset:41504
	ds_read_b128 v[212:215], v167 offset:59936
	s_waitcnt lgkmcnt(2)
	v_mfma_f32_32x32x16_bf16 v[48:63], v[208:211], v[236:239], v[48:63]
	s_waitcnt lgkmcnt(1)
	v_mfma_f32_32x32x16_bf16 v[32:47], v[208:211], v[246:249], v[32:47]
	ds_read_b128 v[208:211], v167 offset:55360
	s_waitcnt vmcnt(15)
	ds_write_b128 v130, v[150:153]
	s_waitcnt vmcnt(14)
	ds_write_b128 v130, v[158:161] offset:18432
	s_waitcnt lgkmcnt(3)
	v_mfma_f32_32x32x16_bf16 v[16:31], v[212:215], v[236:239], v[16:31]
	ds_read_b128 v[236:239], v132 offset:36928
	v_mfma_f32_32x32x16_bf16 v[0:15], v[212:215], v[246:249], v[0:15]
	ds_read_b128 v[212:215], v132 offset:41536
	ds_read_b128 v[246:249], v167 offset:59968
	s_waitcnt lgkmcnt(2)
	v_mfma_f32_32x32x16_bf16 v[48:63], v[208:211], v[236:239], v[48:63]
	s_waitcnt lgkmcnt(1)
	v_mfma_f32_32x32x16_bf16 v[32:47], v[208:211], v[212:215], v[32:47]
	ds_read_b128 v[208:211], v167 offset:55392
	s_waitcnt vmcnt(13)
	ds_write_b128 v130, v[104:107] offset:4608
	s_waitcnt vmcnt(12)
	ds_write_b128 v130, v[108:111] offset:23040
	s_waitcnt lgkmcnt(3)
	v_mfma_f32_32x32x16_bf16 v[16:31], v[246:249], v[236:239], v[16:31]
	ds_read_b128 v[236:239], v132 offset:36960
	v_mfma_f32_32x32x16_bf16 v[0:15], v[246:249], v[212:215], v[0:15]
	ds_read_b128 v[246:249], v132 offset:41568
	ds_read_b128 v[212:215], v167 offset:60000
	s_waitcnt lgkmcnt(2)
	v_mfma_f32_32x32x16_bf16 v[48:63], v[208:211], v[236:239], v[48:63]
	s_waitcnt lgkmcnt(1)
	v_mfma_f32_32x32x16_bf16 v[32:47], v[208:211], v[246:249], v[32:47]
	s_waitcnt lgkmcnt(0)
	v_mfma_f32_32x32x16_bf16 v[16:31], v[212:215], v[236:239], v[16:31]
	global_load_dwordx4 v[150:153], v[112:113], off offset:3072
	global_load_dwordx4 v[158:161], v[114:115], off offset:3072
	global_load_dwordx4 v[104:107], v[138:139], off offset:3072
	global_load_dwordx4 v[108:111], v[140:141], off offset:3072
	s_waitcnt vmcnt(15)
	ds_write_b128 v130, v[64:67] offset:9216
	s_waitcnt vmcnt(14)
	ds_write_b128 v130, v[68:71] offset:27648
	global_load_dwordx4 v[64:67], v[142:143], off offset:3072
	global_load_dwordx4 v[68:71], v[144:145], off offset:3072
	s_waitcnt vmcnt(15)
	ds_write_b128 v130, v[72:75] offset:13824
	s_waitcnt vmcnt(14)
	ds_write_b128 v130, v[76:79] offset:32256
	global_load_dwordx4 v[72:75], v[146:147], off offset:3072
	global_load_dwordx4 v[76:79], v[148:149], off offset:3072
	s_waitcnt lgkmcnt(0)
	s_barrier
	ds_read_b128 v[208:211], v167 offset:18432
	ds_read_b128 v[236:239], v132
	v_mfma_f32_32x32x16_bf16 v[0:15], v[212:215], v[246:249], v[0:15]
	ds_read_b128 v[212:215], v132 offset:4608
	ds_read_b128 v[246:249], v167 offset:23040
	s_waitcnt lgkmcnt(2)
	v_mfma_f32_32x32x16_bf16 v[48:63], v[208:211], v[236:239], v[48:63]
	s_waitcnt lgkmcnt(1)
	v_mfma_f32_32x32x16_bf16 v[32:47], v[208:211], v[212:215], v[32:47]
	ds_read_b128 v[208:211], v167 offset:18464
	s_waitcnt lgkmcnt(1)
	v_mfma_f32_32x32x16_bf16 v[16:31], v[246:249], v[236:239], v[16:31]
	ds_read_b128 v[236:239], v132 offset:32
	v_mfma_f32_32x32x16_bf16 v[0:15], v[246:249], v[212:215], v[0:15]
	ds_read_b128 v[246:249], v132 offset:4640
	ds_read_b128 v[212:215], v167 offset:23072
	s_waitcnt lgkmcnt(2)
	v_mfma_f32_32x32x16_bf16 v[48:63], v[208:211], v[236:239], v[48:63]
	s_waitcnt lgkmcnt(1)
	v_mfma_f32_32x32x16_bf16 v[32:47], v[208:211], v[246:249], v[32:47]
	ds_read_b128 v[208:211], v167 offset:18496
	s_waitcnt vmcnt(15)
	ds_write_b128 v130, v[124:127] offset:36864
	s_waitcnt vmcnt(14)
	ds_write_b128 v130, v[154:157] offset:55296
	s_waitcnt lgkmcnt(3)
	v_mfma_f32_32x32x16_bf16 v[16:31], v[212:215], v[236:239], v[16:31]
	ds_read_b128 v[236:239], v132 offset:64
	v_mfma_f32_32x32x16_bf16 v[0:15], v[212:215], v[246:249], v[0:15]
	ds_read_b128 v[212:215], v132 offset:4672
	ds_read_b128 v[246:249], v167 offset:23104
	s_waitcnt lgkmcnt(2)
	v_mfma_f32_32x32x16_bf16 v[48:63], v[208:211], v[236:239], v[48:63]
	s_waitcnt lgkmcnt(1)
	v_mfma_f32_32x32x16_bf16 v[32:47], v[208:211], v[212:215], v[32:47]
	ds_read_b128 v[208:211], v167 offset:18528
	s_waitcnt vmcnt(13)
	ds_write_b128 v130, v[96:99] offset:41472
	s_waitcnt vmcnt(12)
	ds_write_b128 v130, v[100:103] offset:59904
	s_waitcnt lgkmcnt(3)
	v_mfma_f32_32x32x16_bf16 v[16:31], v[246:249], v[236:239], v[16:31]
	ds_read_b128 v[236:239], v132 offset:96
	v_mfma_f32_32x32x16_bf16 v[0:15], v[246:249], v[212:215], v[0:15]
	ds_read_b128 v[246:249], v132 offset:4704
	ds_read_b128 v[212:215], v167 offset:23136
	s_waitcnt lgkmcnt(2)
	v_mfma_f32_32x32x16_bf16 v[48:63], v[208:211], v[236:239], v[48:63]
	s_waitcnt lgkmcnt(1)
	v_mfma_f32_32x32x16_bf16 v[32:47], v[208:211], v[246:249], v[32:47]
	s_waitcnt lgkmcnt(0)
	v_mfma_f32_32x32x16_bf16 v[16:31], v[212:215], v[236:239], v[16:31]
	global_load_dwordx4 v[124:127], v[112:113], off offset:3200
	global_load_dwordx4 v[154:157], v[114:115], off offset:3200
	global_load_dwordx4 v[96:99], v[138:139], off offset:3200
	global_load_dwordx4 v[100:103], v[140:141], off offset:3200
	s_waitcnt vmcnt(15)
	ds_write_b128 v130, v[80:83] offset:46080
	s_waitcnt vmcnt(14)
	ds_write_b128 v130, v[84:87] offset:64512
	global_load_dwordx4 v[80:83], v[142:143], off offset:3200
	global_load_dwordx4 v[84:87], v[144:145], off offset:3200
	s_waitcnt vmcnt(15)
	ds_write_b128 v130, v[88:91] offset:50688
	s_waitcnt vmcnt(14)
	ds_write_b128 v131, v[92:95] offset:13824
	global_load_dwordx4 v[88:91], v[146:147], off offset:3200
	global_load_dwordx4 v[92:95], v[148:149], off offset:3200
	s_waitcnt lgkmcnt(0)
	s_barrier
; #define GLOADQ(RA, RB, KT, q) do { const int k0_ = (KT) << 6; \
;     RA[q] = ldg16(ap.ptr(m0 + lrow + 32 * (q), k0_) + lkc); RB[q] = ldg16(W + (size_t)(n0 + lrow + 32 * (q)) * ldw + k0_ + lkc); } while (0)
; #define SSTOREQ(RA, RB, ST, q) do { \
;     *(u32x4*)(sA + (ST) * SBUF + (lrow + 32 * (q)) * GP + lkc) = RA[q]; *(u32x4*)(sB + (ST) * SBUF + (lrow + 32 * (q)) * GP + lkc) = RB[q]; } while (0)
; #define FLOAD(F, ST, ks) do { _Pragma("unroll") for (int a = 0; a < 2; ++a) { \
;     F[a] = *(const bf16x8*)(sB + (ST) * SBUF + (wn * 64 + a * 32 + r) * GP + (ks) * 16 + h * 8); \
;     F[2 + a] = *(const bf16x8*)(sA + (ST) * SBUF + (wm * 64 + a * 32 + r) * GP + (ks) * 16 + h * 8); } } while (0)
; #define FMMA(F) do { _Pragma("unroll") for (int a = 0; a < 2; ++a) _Pragma("unroll") for (int b = 0; b < 2; ++b) acc[a][b] = MFMA(F[a], F[2 + b], acc[a][b]); } while (0)
; template <bool MIDK, class AP, class EPI>
; DI void gemm_tile(const AP& ap, const u16* __restrict__ W, int ldw, int K, int m0, int n0, const EPI& epi, char* smem, float r0, float r1, int tid, bool dry) {
;     ...
;   for (int kt = 0; kt < nk; kt += 2) {
;     const bool l3 = kt + 3 < nk, s2 = kt + 2 < nk, l4 = kt + 4 < nk;
;     FLOAD(f0, 0, 0); FLOAD(f1, 0, 1);
;     FMMA(f0); SSTOREQ(ra1, rb1, 1, 0); if (l3) GLOADQ(ra1, rb1, kt + 3, 0);
;     FLOAD(f0, 0, 2);
;     FMMA(f1); SSTOREQ(ra1, rb1, 1, 1); if (l3) GLOADQ(ra1, rb1, kt + 3, 1);
;     FLOAD(f1, 0, 3);
;     FMMA(f0); SSTOREQ(ra1, rb1, 1, 2); if (l3) GLOADQ(ra1, rb1, kt + 3, 2);
;     FMMA(f1); SSTOREQ(ra1, rb1, 1, 3); if (l3) GLOADQ(ra1, rb1, kt + 3, 3);
;     __syncthreads();
;     FLOAD(f0, 1, 0); FLOAD(f1, 1, 1);
;     FMMA(f0); if (s2) SSTOREQ(ra0, rb0, 0, 0); if (l4) GLOADQ(ra0, rb0, kt + 4, 0);
;     FLOAD(f0, 1, 2);
;     FMMA(f1); if (s2) SSTOREQ(ra0, rb0, 0, 1); if (l4) GLOADQ(ra0, rb0, kt + 4, 1);
;     FLOAD(f1, 1, 3);
;     FMMA(f0); if (s2) SSTOREQ(ra0, rb0, 0, 2); if (l4) GLOADQ(ra0, rb0, kt + 4, 2);
;     FMMA(f1); if (s2) SSTOREQ(ra0, rb0, 0, 3); if (l4) GLOADQ(ra0, rb0, kt + 4, 3);
;     if (MIDK && kt == 6) {
; #pragma unroll
;       for (int a = 0; a < 2; ++a)
; #pragma unroll
;         for (int i = 0; i < 16; ++i) { acc[a][0][i] *= r0; acc[a][1][i] *= r1; }
;     }
;     __syncthreads();
	ds_read_b128 v[208:211], v167 offset:55296
	ds_read_b128 v[236:239], v132 offset:36864
	v_mfma_f32_32x32x16_bf16 v[0:15], v[212:215], v[246:249], v[0:15]
	ds_read_b128 v[212:215], v132 offset:41472
	ds_read_b128 v[246:249], v167 offset:59904
	s_waitcnt lgkmcnt(2)
	v_mfma_f32_32x32x16_bf16 v[48:63], v[208:211], v[236:239], v[48:63]
	s_waitcnt lgkmcnt(1)
	v_mfma_f32_32x32x16_bf16 v[32:47], v[208:211], v[212:215], v[32:47]
	ds_read_b128 v[208:211], v167 offset:55328
	s_waitcnt lgkmcnt(1)
	v_mfma_f32_32x32x16_bf16 v[16:31], v[246:249], v[236:239], v[16:31]
	ds_read_b128 v[236:239], v132 offset:36896
	v_mfma_f32_32x32x16_bf16 v[0:15], v[246:249], v[212:215], v[0:15]
	ds_read_b128 v[246:249], v132 offset:41504
	ds_read_b128 v[212:215], v167 offset:59936
	s_waitcnt lgkmcnt(2)
	v_mfma_f32_32x32x16_bf16 v[48:63], v[208:211], v[236:239], v[48:63]
	s_waitcnt lgkmcnt(1)
	v_mfma_f32_32x32x16_bf16 v[32:47], v[208:211], v[246:249], v[32:47]
	ds_read_b128 v[208:211], v167 offset:55360
	s_waitcnt vmcnt(15)
	ds_write_b128 v130, v[150:153]
	s_waitcnt vmcnt(14)
	ds_write_b128 v130, v[158:161] offset:18432
	s_waitcnt lgkmcnt(3)
	v_mfma_f32_32x32x16_bf16 v[16:31], v[212:215], v[236:239], v[16:31]
	ds_read_b128 v[236:239], v132 offset:36928
	v_mfma_f32_32x32x16_bf16 v[0:15], v[212:215], v[246:249], v[0:15]
	ds_read_b128 v[212:215], v132 offset:41536
	ds_read_b128 v[246:249], v167 offset:59968
	s_waitcnt lgkmcnt(2)
	v_mfma_f32_32x32x16_bf16 v[48:63], v[208:211], v[236:239], v[48:63]
	s_waitcnt lgkmcnt(1)
	v_mfma_f32_32x32x16_bf16 v[32:47], v[208:211], v[212:215], v[32:47]
	ds_read_b128 v[208:211], v167 offset:55392
	s_waitcnt vmcnt(13)
	ds_write_b128 v130, v[104:107] offset:4608
	s_waitcnt vmcnt(12)
	ds_write_b128 v130, v[108:111] offset:23040
	s_waitcnt lgkmcnt(3)
	v_mfma_f32_32x32x16_bf16 v[16:31], v[246:249], v[236:239], v[16:31]
	ds_read_b128 v[236:239], v132 offset:36960
	v_mfma_f32_32x32x16_bf16 v[0:15], v[246:249], v[212:215], v[0:15]
	ds_read_b128 v[246:249], v132 offset:41568
	ds_read_b128 v[212:215], v167 offset:60000
	s_waitcnt lgkmcnt(2)
	v_mfma_f32_32x32x16_bf16 v[48:63], v[208:211], v[236:239], v[48:63]
	s_waitcnt lgkmcnt(1)
	v_mfma_f32_32x32x16_bf16 v[32:47], v[208:211], v[246:249], v[32:47]
	s_waitcnt lgkmcnt(0)
	v_mfma_f32_32x32x16_bf16 v[16:31], v[212:215], v[236:239], v[16:31]
	global_load_dwordx4 v[150:153], v[112:113], off offset:3328
	global_load_dwordx4 v[158:161], v[114:115], off offset:3328
	global_load_dwordx4 v[104:107], v[138:139], off offset:3328
	global_load_dwordx4 v[108:111], v[140:141], off offset:3328
	s_waitcnt vmcnt(15)
	ds_write_b128 v130, v[64:67] offset:9216
	s_waitcnt vmcnt(14)
	ds_write_b128 v130, v[68:71] offset:27648
	global_load_dwordx4 v[64:67], v[142:143], off offset:3328
	global_load_dwordx4 v[68:71], v[144:145], off offset:3328
	s_waitcnt vmcnt(15)
	ds_write_b128 v130, v[72:75] offset:13824
	s_waitcnt vmcnt(14)
	ds_write_b128 v130, v[76:79] offset:32256
	global_load_dwordx4 v[72:75], v[146:147], off offset:3328
	global_load_dwordx4 v[76:79], v[148:149], off offset:3328
	s_waitcnt lgkmcnt(0)
	s_barrier
	ds_read_b128 v[208:211], v167 offset:18432
	ds_read_b128 v[236:239], v132
	v_mfma_f32_32x32x16_bf16 v[0:15], v[212:215], v[246:249], v[0:15]
	ds_read_b128 v[212:215], v132 offset:4608
	ds_read_b128 v[246:249], v167 offset:23040
	s_waitcnt lgkmcnt(2)
	v_mfma_f32_32x32x16_bf16 v[48:63], v[208:211], v[236:239], v[48:63]
	s_waitcnt lgkmcnt(1)
	v_mfma_f32_32x32x16_bf16 v[32:47], v[208:211], v[212:215], v[32:47]
	ds_read_b128 v[208:211], v167 offset:18464
	s_waitcnt lgkmcnt(1)
	v_mfma_f32_32x32x16_bf16 v[16:31], v[246:249], v[236:239], v[16:31]
	ds_read_b128 v[236:239], v132 offset:32
	v_mfma_f32_32x32x16_bf16 v[0:15], v[246:249], v[212:215], v[0:15]
	ds_read_b128 v[246:249], v132 offset:4640
	ds_read_b128 v[212:215], v167 offset:23072
	s_waitcnt lgkmcnt(2)
	v_mfma_f32_32x32x16_bf16 v[48:63], v[208:211], v[236:239], v[48:63]
	s_waitcnt lgkmcnt(1)
	v_mfma_f32_32x32x16_bf16 v[32:47], v[208:211], v[246:249], v[32:47]
	ds_read_b128 v[208:211], v167 offset:18496
	s_waitcnt vmcnt(15)
	ds_write_b128 v130, v[124:127] offset:36864
	s_waitcnt vmcnt(14)
	ds_write_b128 v130, v[154:157] offset:55296
	s_waitcnt lgkmcnt(3)
	v_mfma_f32_32x32x16_bf16 v[16:31], v[212:215], v[236:239], v[16:31]
	ds_read_b128 v[236:239], v132 offset:64
	v_mfma_f32_32x32x16_bf16 v[0:15], v[212:215], v[246:249], v[0:15]
	ds_read_b128 v[212:215], v132 offset:4672
	ds_read_b128 v[246:249], v167 offset:23104
	s_waitcnt lgkmcnt(2)
	v_mfma_f32_32x32x16_bf16 v[48:63], v[208:211], v[236:239], v[48:63]
	s_waitcnt lgkmcnt(1)
	v_mfma_f32_32x32x16_bf16 v[32:47], v[208:211], v[212:215], v[32:47]
	ds_read_b128 v[208:211], v167 offset:18528
	s_waitcnt vmcnt(13)
	ds_write_b128 v130, v[96:99] offset:41472
	s_waitcnt vmcnt(12)
	ds_write_b128 v130, v[100:103] offset:59904
	s_waitcnt lgkmcnt(3)
	v_mfma_f32_32x32x16_bf16 v[16:31], v[246:249], v[236:239], v[16:31]
	ds_read_b128 v[236:239], v132 offset:96
	v_mfma_f32_32x32x16_bf16 v[0:15], v[246:249], v[212:215], v[0:15]
	ds_read_b128 v[246:249], v132 offset:4704
	ds_read_b128 v[212:215], v167 offset:23136
	s_waitcnt lgkmcnt(2)
	v_mfma_f32_32x32x16_bf16 v[48:63], v[208:211], v[236:239], v[48:63]
	s_waitcnt lgkmcnt(1)
	v_mfma_f32_32x32x16_bf16 v[32:47], v[208:211], v[246:249], v[32:47]
	s_waitcnt lgkmcnt(0)
	v_mfma_f32_32x32x16_bf16 v[16:31], v[212:215], v[236:239], v[16:31]
	global_load_dwordx4 v[124:127], v[112:113], off offset:3456
	global_load_dwordx4 v[154:157], v[114:115], off offset:3456
	global_load_dwordx4 v[96:99], v[138:139], off offset:3456
	global_load_dwordx4 v[100:103], v[140:141], off offset:3456
	s_waitcnt vmcnt(15)
	ds_write_b128 v130, v[80:83] offset:46080
	s_waitcnt vmcnt(14)
	ds_write_b128 v130, v[84:87] offset:64512
	global_load_dwordx4 v[80:83], v[142:143], off offset:3456
	global_load_dwordx4 v[84:87], v[144:145], off offset:3456
	s_waitcnt vmcnt(15)
	ds_write_b128 v130, v[88:91] offset:50688
	s_waitcnt vmcnt(14)
	ds_write_b128 v131, v[92:95] offset:13824
	global_load_dwordx4 v[88:91], v[146:147], off offset:3456
	global_load_dwordx4 v[92:95], v[148:149], off offset:3456
	s_waitcnt lgkmcnt(0)
	s_barrier
; #define GLOADQ(RA, RB, KT, q) do { const int k0_ = (KT) << 6; \
;     RA[q] = ldg16(ap.ptr(m0 + lrow + 32 * (q), k0_) + lkc); RB[q] = ldg16(W + (size_t)(n0 + lrow + 32 * (q)) * ldw + k0_ + lkc); } while (0)
; #define SSTOREQ(RA, RB, ST, q) do { \
;     *(u32x4*)(sA + (ST) * SBUF + (lrow + 32 * (q)) * GP + lkc) = RA[q]; *(u32x4*)(sB + (ST) * SBUF + (lrow + 32 * (q)) * GP + lkc) = RB[q]; } while (0)
; #define FLOAD(F, ST, ks) do { _Pragma("unroll") for (int a = 0; a < 2; ++a) { \
;     F[a] = *(const bf16x8*)(sB + (ST) * SBUF + (wn * 64 + a * 32 + r) * GP + (ks) * 16 + h * 8); \
;     F[2 + a] = *(const bf16x8*)(sA + (ST) * SBUF + (wm * 64 + a * 32 + r) * GP + (ks) * 16 + h * 8); } } while (0)
; #define FMMA(F) do { _Pragma("unroll") for (int a = 0; a < 2; ++a) _Pragma("unroll") for (int b = 0; b < 2; ++b) acc[a][b] = MFMA(F[a], F[2 + b], acc[a][b]); } while (0)
; template <bool MIDK, class AP, class EPI>
; DI void gemm_tile(const AP& ap, const u16* __restrict__ W, int ldw, int K, int m0, int n0, const EPI& epi, char* smem, float r0, float r1, int tid, bool dry) {
;     ...
;   for (int kt = 0; kt < nk; kt += 2) {
;     const bool l3 = kt + 3 < nk, s2 = kt + 2 < nk, l4 = kt + 4 < nk;
;     FLOAD(f0, 0, 0); FLOAD(f1, 0, 1);
;     FMMA(f0); SSTOREQ(ra1, rb1, 1, 0); if (l3) GLOADQ(ra1, rb1, kt + 3, 0);
;     FLOAD(f0, 0, 2);
;     FMMA(f1); SSTOREQ(ra1, rb1, 1, 1); if (l3) GLOADQ(ra1, rb1, kt + 3, 1);
;     FLOAD(f1, 0, 3);
;     FMMA(f0); SSTOREQ(ra1, rb1, 1, 2); if (l3) GLOADQ(ra1, rb1, kt + 3, 2);
;     FMMA(f1); SSTOREQ(ra1, rb1, 1, 3); if (l3) GLOADQ(ra1, rb1, kt + 3, 3);
;     __syncthreads();
;     FLOAD(f0, 1, 0); FLOAD(f1, 1, 1);
;     FMMA(f0); if (s2) SSTOREQ(ra0, rb0, 0, 0); if (l4) GLOADQ(ra0, rb0, kt + 4, 0);
;     FLOAD(f0, 1, 2);
;     FMMA(f1); if (s2) SSTOREQ(ra0, rb0, 0, 1); if (l4) GLOADQ(ra0, rb0, kt + 4, 1);
;     FLOAD(f1, 1, 3);
;     FMMA(f0); if (s2) SSTOREQ(ra0, rb0, 0, 2); if (l4) GLOADQ(ra0, rb0, kt + 4, 2);
;     FMMA(f1); if (s2) SSTOREQ(ra0, rb0, 0, 3); if (l4) GLOADQ(ra0, rb0, kt + 4, 3);
;     if (MIDK && kt == 6) {
; #pragma unroll
;       for (int a = 0; a < 2; ++a)
; #pragma unroll
;         for (int i = 0; i < 16; ++i) { acc[a][0][i] *= r0; acc[a][1][i] *= r1; }
;     }
;     __syncthreads();
	ds_read_b128 v[208:211], v167 offset:55296
	ds_read_b128 v[236:239], v132 offset:36864
	v_mfma_f32_32x32x16_bf16 v[0:15], v[212:215], v[246:249], v[0:15]
	ds_read_b128 v[212:215], v132 offset:41472
	ds_read_b128 v[246:249], v167 offset:59904
	s_waitcnt lgkmcnt(2)
	v_mfma_f32_32x32x16_bf16 v[48:63], v[208:211], v[236:239], v[48:63]
	s_waitcnt lgkmcnt(1)
	v_mfma_f32_32x32x16_bf16 v[32:47], v[208:211], v[212:215], v[32:47]
	ds_read_b128 v[208:211], v167 offset:55328
	s_waitcnt lgkmcnt(1)
	v_mfma_f32_32x32x16_bf16 v[16:31], v[246:249], v[236:239], v[16:31]
	ds_read_b128 v[236:239], v132 offset:36896
	v_mfma_f32_32x32x16_bf16 v[0:15], v[246:249], v[212:215], v[0:15]
	ds_read_b128 v[246:249], v132 offset:41504
	ds_read_b128 v[212:215], v167 offset:59936
	s_waitcnt lgkmcnt(2)
	v_mfma_f32_32x32x16_bf16 v[48:63], v[208:211], v[236:239], v[48:63]
	s_waitcnt lgkmcnt(1)
	v_mfma_f32_32x32x16_bf16 v[32:47], v[208:211], v[246:249], v[32:47]
	ds_read_b128 v[208:211], v167 offset:55360
	s_waitcnt vmcnt(15)
	ds_write_b128 v130, v[150:153]
	s_waitcnt vmcnt(14)
	ds_write_b128 v130, v[158:161] offset:18432
	s_waitcnt lgkmcnt(3)
	v_mfma_f32_32x32x16_bf16 v[16:31], v[212:215], v[236:239], v[16:31]
	ds_read_b128 v[236:239], v132 offset:36928
	v_mfma_f32_32x32x16_bf16 v[0:15], v[212:215], v[246:249], v[0:15]
	ds_read_b128 v[212:215], v132 offset:41536
	ds_read_b128 v[246:249], v167 offset:59968
	s_waitcnt lgkmcnt(2)
	v_mfma_f32_32x32x16_bf16 v[48:63], v[208:211], v[236:239], v[48:63]
	s_waitcnt lgkmcnt(1)
	v_mfma_f32_32x32x16_bf16 v[32:47], v[208:211], v[212:215], v[32:47]
	ds_read_b128 v[208:211], v167 offset:55392
	s_waitcnt vmcnt(13)
	ds_write_b128 v130, v[104:107] offset:4608
	s_waitcnt vmcnt(12)
	ds_write_b128 v130, v[108:111] offset:23040
	s_waitcnt lgkmcnt(3)
	v_mfma_f32_32x32x16_bf16 v[16:31], v[246:249], v[236:239], v[16:31]
	ds_read_b128 v[236:239], v132 offset:36960
	v_mfma_f32_32x32x16_bf16 v[0:15], v[246:249], v[212:215], v[0:15]
	ds_read_b128 v[246:249], v132 offset:41568
	ds_read_b128 v[212:215], v167 offset:60000
	s_waitcnt lgkmcnt(2)
	v_mfma_f32_32x32x16_bf16 v[48:63], v[208:211], v[236:239], v[48:63]
	s_waitcnt lgkmcnt(1)
	v_mfma_f32_32x32x16_bf16 v[32:47], v[208:211], v[246:249], v[32:47]
	s_waitcnt lgkmcnt(0)
	v_mfma_f32_32x32x16_bf16 v[16:31], v[212:215], v[236:239], v[16:31]
	global_load_dwordx4 v[150:153], v[112:113], off offset:3584
	global_load_dwordx4 v[158:161], v[114:115], off offset:3584
	global_load_dwordx4 v[104:107], v[138:139], off offset:3584
	global_load_dwordx4 v[108:111], v[140:141], off offset:3584
	s_waitcnt vmcnt(15)
	ds_write_b128 v130, v[64:67] offset:9216
	s_waitcnt vmcnt(14)
	ds_write_b128 v130, v[68:71] offset:27648
	global_load_dwordx4 v[64:67], v[142:143], off offset:3584
	global_load_dwordx4 v[68:71], v[144:145], off offset:3584
	s_waitcnt vmcnt(15)
	ds_write_b128 v130, v[72:75] offset:13824
	s_waitcnt vmcnt(14)
	ds_write_b128 v130, v[76:79] offset:32256
	global_load_dwordx4 v[72:75], v[146:147], off offset:3584
	global_load_dwordx4 v[76:79], v[148:149], off offset:3584
	s_waitcnt lgkmcnt(0)
	s_barrier
	ds_read_b128 v[208:211], v167 offset:18432
	ds_read_b128 v[236:239], v132
	v_mfma_f32_32x32x16_bf16 v[0:15], v[212:215], v[246:249], v[0:15]
	ds_read_b128 v[212:215], v132 offset:4608
	ds_read_b128 v[246:249], v167 offset:23040
	s_waitcnt lgkmcnt(2)
	v_mfma_f32_32x32x16_bf16 v[48:63], v[208:211], v[236:239], v[48:63]
	s_waitcnt lgkmcnt(1)
	v_mfma_f32_32x32x16_bf16 v[32:47], v[208:211], v[212:215], v[32:47]
	ds_read_b128 v[208:211], v167 offset:18464
	s_waitcnt lgkmcnt(1)
	v_mfma_f32_32x32x16_bf16 v[16:31], v[246:249], v[236:239], v[16:31]
	ds_read_b128 v[236:239], v132 offset:32
	v_mfma_f32_32x32x16_bf16 v[0:15], v[246:249], v[212:215], v[0:15]
	ds_read_b128 v[246:249], v132 offset:4640
	ds_read_b128 v[212:215], v167 offset:23072
	s_waitcnt lgkmcnt(2)
	v_mfma_f32_32x32x16_bf16 v[48:63], v[208:211], v[236:239], v[48:63]
	s_waitcnt lgkmcnt(1)
	v_mfma_f32_32x32x16_bf16 v[32:47], v[208:211], v[246:249], v[32:47]
	ds_read_b128 v[208:211], v167 offset:18496
	s_waitcnt vmcnt(15)
	ds_write_b128 v130, v[124:127] offset:36864
	s_waitcnt vmcnt(14)
	ds_write_b128 v130, v[154:157] offset:55296
	s_waitcnt lgkmcnt(3)
	v_mfma_f32_32x32x16_bf16 v[16:31], v[212:215], v[236:239], v[16:31]
	ds_read_b128 v[236:239], v132 offset:64
	v_mfma_f32_32x32x16_bf16 v[0:15], v[212:215], v[246:249], v[0:15]
	ds_read_b128 v[212:215], v132 offset:4672
	ds_read_b128 v[246:249], v167 offset:23104
	s_waitcnt lgkmcnt(2)
	v_mfma_f32_32x32x16_bf16 v[48:63], v[208:211], v[236:239], v[48:63]
	s_waitcnt lgkmcnt(1)
	v_mfma_f32_32x32x16_bf16 v[32:47], v[208:211], v[212:215], v[32:47]
	ds_read_b128 v[208:211], v167 offset:18528
	s_waitcnt vmcnt(13)
	ds_write_b128 v130, v[96:99] offset:41472
	s_waitcnt vmcnt(12)
	ds_write_b128 v130, v[100:103] offset:59904
	s_waitcnt lgkmcnt(3)
	v_mfma_f32_32x32x16_bf16 v[16:31], v[246:249], v[236:239], v[16:31]
	ds_read_b128 v[236:239], v132 offset:96
	v_mfma_f32_32x32x16_bf16 v[0:15], v[246:249], v[212:215], v[0:15]
	ds_read_b128 v[246:249], v132 offset:4704
	ds_read_b128 v[212:215], v167 offset:23136
	s_waitcnt lgkmcnt(2)
	v_mfma_f32_32x32x16_bf16 v[48:63], v[208:211], v[236:239], v[48:63]
	s_waitcnt lgkmcnt(1)
	v_mfma_f32_32x32x16_bf16 v[32:47], v[208:211], v[246:249], v[32:47]
	s_waitcnt lgkmcnt(0)
	v_mfma_f32_32x32x16_bf16 v[16:31], v[212:215], v[236:239], v[16:31]
	global_load_dwordx4 v[124:127], v[112:113], off offset:3712
	global_load_dwordx4 v[154:157], v[114:115], off offset:3712
	global_load_dwordx4 v[96:99], v[138:139], off offset:3712
	global_load_dwordx4 v[100:103], v[140:141], off offset:3712
	s_waitcnt vmcnt(15)
	ds_write_b128 v130, v[80:83] offset:46080
	s_waitcnt vmcnt(14)
	ds_write_b128 v130, v[84:87] offset:64512
	global_load_dwordx4 v[80:83], v[142:143], off offset:3712
	global_load_dwordx4 v[84:87], v[144:145], off offset:3712
	s_waitcnt vmcnt(15)
	ds_write_b128 v130, v[88:91] offset:50688
	s_waitcnt vmcnt(14)
	ds_write_b128 v131, v[92:95] offset:13824
	global_load_dwordx4 v[88:91], v[146:147], off offset:3712
	global_load_dwordx4 v[92:95], v[148:149], off offset:3712
	s_waitcnt lgkmcnt(0)
	s_barrier
; #define GLOADQ(RA, RB, KT, q) do { const int k0_ = (KT) << 6; \
;     RA[q] = ldg16(ap.ptr(m0 + lrow + 32 * (q), k0_) + lkc); RB[q] = ldg16(W + (size_t)(n0 + lrow + 32 * (q)) * ldw + k0_ + lkc); } while (0)
; #define SSTOREQ(RA, RB, ST, q) do { \
;     *(u32x4*)(sA + (ST) * SBUF + (lrow + 32 * (q)) * GP + lkc) = RA[q]; *(u32x4*)(sB + (ST) * SBUF + (lrow + 32 * (q)) * GP + lkc) = RB[q]; } while (0)
; #define FLOAD(F, ST, ks) do { _Pragma("unroll") for (int a = 0; a < 2; ++a) { \
;     F[a] = *(const bf16x8*)(sB + (ST) * SBUF + (wn * 64 + a * 32 + r) * GP + (ks) * 16 + h * 8); \
;     F[2 + a] = *(const bf16x8*)(sA + (ST) * SBUF + (wm * 64 + a * 32 + r) * GP + (ks) * 16 + h * 8); } } while (0)
; #define FMMA(F) do { _Pragma("unroll") for (int a = 0; a < 2; ++a) _Pragma("unroll") for (int b = 0; b < 2; ++b) acc[a][b] = MFMA(F[a], F[2 + b], acc[a][b]); } while (0)
; template <bool MIDK, class AP, class EPI>
; DI void gemm_tile(const AP& ap, const u16* __restrict__ W, int ldw, int K, int m0, int n0, const EPI& epi, char* smem, float r0, float r1, int tid, bool dry) {
;     ...
;   for (int kt = 0; kt < nk; kt += 2) {
;     const bool l3 = kt + 3 < nk, s2 = kt + 2 < nk, l4 = kt + 4 < nk;
;     FLOAD(f0, 0, 0); FLOAD(f1, 0, 1);
;     FMMA(f0); SSTOREQ(ra1, rb1, 1, 0); if (l3) GLOADQ(ra1, rb1, kt + 3, 0);
;     FLOAD(f0, 0, 2);
;     FMMA(f1); SSTOREQ(ra1, rb1, 1, 1); if (l3) GLOADQ(ra1, rb1, kt + 3, 1);
;     FLOAD(f1, 0, 3);
;     FMMA(f0); SSTOREQ(ra1, rb1, 1, 2); if (l3) GLOADQ(ra1, rb1, kt + 3, 2);
;     FMMA(f1); SSTOREQ(ra1, rb1, 1, 3); if (l3) GLOADQ(ra1, rb1, kt + 3, 3);
;     __syncthreads();
;     FLOAD(f0, 1, 0); FLOAD(f1, 1, 1);
;     FMMA(f0); if (s2) SSTOREQ(ra0, rb0, 0, 0); if (l4) GLOADQ(ra0, rb0, kt + 4, 0);
;     FLOAD(f0, 1, 2);
;     FMMA(f1); if (s2) SSTOREQ(ra0, rb0, 0, 1); if (l4) GLOADQ(ra0, rb0, kt + 4, 1);
;     FLOAD(f1, 1, 3);
;     FMMA(f0); if (s2) SSTOREQ(ra0, rb0, 0, 2); if (l4) GLOADQ(ra0, rb0, kt + 4, 2);
;     FMMA(f1); if (s2) SSTOREQ(ra0, rb0, 0, 3); if (l4) GLOADQ(ra0, rb0, kt + 4, 3);
;     if (MIDK && kt == 6) {
; #pragma unroll
;       for (int a = 0; a < 2; ++a)
; #pragma unroll
;         for (int i = 0; i < 16; ++i) { acc[a][0][i] *= r0; acc[a][1][i] *= r1; }
;     }
;     __syncthreads();
	ds_read_b128 v[208:211], v167 offset:55296
	ds_read_b128 v[236:239], v132 offset:36864
	v_mfma_f32_32x32x16_bf16 v[0:15], v[212:215], v[246:249], v[0:15]
	ds_read_b128 v[212:215], v132 offset:41472
	ds_read_b128 v[246:249], v167 offset:59904
	s_waitcnt lgkmcnt(2)
	v_mfma_f32_32x32x16_bf16 v[48:63], v[208:211], v[236:239], v[48:63]
	s_waitcnt lgkmcnt(1)
	v_mfma_f32_32x32x16_bf16 v[32:47], v[208:211], v[212:215], v[32:47]
	ds_read_b128 v[208:211], v167 offset:55328
	s_waitcnt lgkmcnt(1)
	v_mfma_f32_32x32x16_bf16 v[16:31], v[246:249], v[236:239], v[16:31]
	ds_read_b128 v[236:239], v132 offset:36896
	v_mfma_f32_32x32x16_bf16 v[0:15], v[246:249], v[212:215], v[0:15]
	ds_read_b128 v[246:249], v132 offset:41504
	ds_read_b128 v[212:215], v167 offset:59936
	s_waitcnt lgkmcnt(2)
	v_mfma_f32_32x32x16_bf16 v[48:63], v[208:211], v[236:239], v[48:63]
	s_waitcnt lgkmcnt(1)
	v_mfma_f32_32x32x16_bf16 v[32:47], v[208:211], v[246:249], v[32:47]
	ds_read_b128 v[208:211], v167 offset:55360
	s_waitcnt vmcnt(15)
	ds_write_b128 v130, v[150:153]
	s_waitcnt vmcnt(14)
	ds_write_b128 v130, v[158:161] offset:18432
	s_waitcnt lgkmcnt(3)
	v_mfma_f32_32x32x16_bf16 v[16:31], v[212:215], v[236:239], v[16:31]
	ds_read_b128 v[236:239], v132 offset:36928
	v_mfma_f32_32x32x16_bf16 v[0:15], v[212:215], v[246:249], v[0:15]
	ds_read_b128 v[212:215], v132 offset:41536
	ds_read_b128 v[246:249], v167 offset:59968
	s_waitcnt lgkmcnt(2)
	v_mfma_f32_32x32x16_bf16 v[48:63], v[208:211], v[236:239], v[48:63]
	s_waitcnt lgkmcnt(1)
	v_mfma_f32_32x32x16_bf16 v[32:47], v[208:211], v[212:215], v[32:47]
	ds_read_b128 v[208:211], v167 offset:55392
	s_waitcnt vmcnt(13)
	ds_write_b128 v130, v[104:107] offset:4608
	s_waitcnt vmcnt(12)
	ds_write_b128 v130, v[108:111] offset:23040
	s_waitcnt lgkmcnt(3)
	v_mfma_f32_32x32x16_bf16 v[16:31], v[246:249], v[236:239], v[16:31]
	ds_read_b128 v[236:239], v132 offset:36960
	v_mfma_f32_32x32x16_bf16 v[0:15], v[246:249], v[212:215], v[0:15]
	ds_read_b128 v[246:249], v132 offset:41568
	ds_read_b128 v[212:215], v167 offset:60000
	s_waitcnt lgkmcnt(2)
	v_mfma_f32_32x32x16_bf16 v[48:63], v[208:211], v[236:239], v[48:63]
	s_waitcnt lgkmcnt(1)
	v_mfma_f32_32x32x16_bf16 v[32:47], v[208:211], v[246:249], v[32:47]
	s_waitcnt lgkmcnt(0)
	v_mfma_f32_32x32x16_bf16 v[16:31], v[212:215], v[236:239], v[16:31]
	global_load_dwordx4 v[150:153], v[112:113], off offset:3840
	global_load_dwordx4 v[158:161], v[114:115], off offset:3840
	global_load_dwordx4 v[104:107], v[138:139], off offset:3840
	global_load_dwordx4 v[108:111], v[140:141], off offset:3840
	s_waitcnt vmcnt(15)
	ds_write_b128 v130, v[64:67] offset:9216
	s_waitcnt vmcnt(14)
	ds_write_b128 v130, v[68:71] offset:27648
	global_load_dwordx4 v[64:67], v[142:143], off offset:3840
	global_load_dwordx4 v[68:71], v[144:145], off offset:3840
	s_waitcnt vmcnt(15)
	ds_write_b128 v130, v[72:75] offset:13824
	s_waitcnt vmcnt(14)
	ds_write_b128 v130, v[76:79] offset:32256
	global_load_dwordx4 v[72:75], v[146:147], off offset:3840
	global_load_dwordx4 v[76:79], v[148:149], off offset:3840
	s_waitcnt lgkmcnt(0)
	s_barrier
	ds_read_b128 v[208:211], v167 offset:18432
	ds_read_b128 v[236:239], v132
	v_mfma_f32_32x32x16_bf16 v[0:15], v[212:215], v[246:249], v[0:15]
	ds_read_b128 v[212:215], v132 offset:4608
	ds_read_b128 v[246:249], v167 offset:23040
	s_waitcnt lgkmcnt(2)
	v_mfma_f32_32x32x16_bf16 v[48:63], v[208:211], v[236:239], v[48:63]
	s_waitcnt lgkmcnt(1)
	v_mfma_f32_32x32x16_bf16 v[32:47], v[208:211], v[212:215], v[32:47]
	ds_read_b128 v[208:211], v167 offset:18464
	s_waitcnt lgkmcnt(1)
	v_mfma_f32_32x32x16_bf16 v[16:31], v[246:249], v[236:239], v[16:31]
	ds_read_b128 v[236:239], v132 offset:32
	v_mfma_f32_32x32x16_bf16 v[0:15], v[246:249], v[212:215], v[0:15]
	ds_read_b128 v[246:249], v132 offset:4640
	ds_read_b128 v[212:215], v167 offset:23072
	s_waitcnt lgkmcnt(2)
	v_mfma_f32_32x32x16_bf16 v[48:63], v[208:211], v[236:239], v[48:63]
	s_waitcnt lgkmcnt(1)
	v_mfma_f32_32x32x16_bf16 v[32:47], v[208:211], v[246:249], v[32:47]
	ds_read_b128 v[208:211], v167 offset:18496
	s_waitcnt vmcnt(15)
	ds_write_b128 v130, v[124:127] offset:36864
	s_waitcnt vmcnt(14)
	ds_write_b128 v130, v[154:157] offset:55296
	s_waitcnt lgkmcnt(3)
	v_mfma_f32_32x32x16_bf16 v[16:31], v[212:215], v[236:239], v[16:31]
	ds_read_b128 v[236:239], v132 offset:64
	v_mfma_f32_32x32x16_bf16 v[0:15], v[212:215], v[246:249], v[0:15]
	ds_read_b128 v[212:215], v132 offset:4672
	ds_read_b128 v[246:249], v167 offset:23104
	s_waitcnt lgkmcnt(2)
	v_mfma_f32_32x32x16_bf16 v[48:63], v[208:211], v[236:239], v[48:63]
	s_waitcnt lgkmcnt(1)
	v_mfma_f32_32x32x16_bf16 v[32:47], v[208:211], v[212:215], v[32:47]
	ds_read_b128 v[208:211], v167 offset:18528
	s_waitcnt vmcnt(13)
	ds_write_b128 v130, v[96:99] offset:41472
	s_waitcnt vmcnt(12)
	ds_write_b128 v130, v[100:103] offset:59904
	s_waitcnt lgkmcnt(3)
	v_mfma_f32_32x32x16_bf16 v[16:31], v[246:249], v[236:239], v[16:31]
	ds_read_b128 v[236:239], v132 offset:96
	v_mfma_f32_32x32x16_bf16 v[0:15], v[246:249], v[212:215], v[0:15]
	ds_read_b128 v[246:249], v132 offset:4704
	ds_read_b128 v[212:215], v167 offset:23136
	s_waitcnt lgkmcnt(2)
	v_mfma_f32_32x32x16_bf16 v[48:63], v[208:211], v[236:239], v[48:63]
	s_waitcnt lgkmcnt(1)
	v_mfma_f32_32x32x16_bf16 v[32:47], v[208:211], v[246:249], v[32:47]
	s_waitcnt lgkmcnt(0)
	v_mfma_f32_32x32x16_bf16 v[16:31], v[212:215], v[236:239], v[16:31]
	global_load_dwordx4 v[100:103], v[112:113], off offset:3968
	s_nop 0
	global_load_dwordx4 v[112:115], v[114:115], off offset:3968
	s_nop 0
	global_load_dwordx4 v[120:123], v[138:139], off offset:3968
	global_load_dwordx4 v[124:127], v[140:141], off offset:3968
	s_waitcnt vmcnt(15)
	ds_write_b128 v130, v[80:83] offset:46080
	s_waitcnt vmcnt(14)
	ds_write_b128 v130, v[84:87] offset:64512
	global_load_dwordx4 v[80:83], v[142:143], off offset:3968
	global_load_dwordx4 v[84:87], v[144:145], off offset:3968
	s_waitcnt vmcnt(15)
	ds_write_b128 v130, v[88:91] offset:50688
	s_waitcnt vmcnt(14)
	ds_write_b128 v131, v[92:95] offset:13824
	global_load_dwordx4 v[88:91], v[146:147], off offset:3968
	global_load_dwordx4 v[92:95], v[148:149], off offset:3968
	s_waitcnt lgkmcnt(0)
	s_barrier
; #define GLOADQ(RA, RB, KT, q) do { const int k0_ = (KT) << 6; \
;     RA[q] = ldg16(ap.ptr(m0 + lrow + 32 * (q), k0_) + lkc); RB[q] = ldg16(W + (size_t)(n0 + lrow + 32 * (q)) * ldw + k0_ + lkc); } while (0)
; #define SSTOREQ(RA, RB, ST, q) do { \
;     *(u32x4*)(sA + (ST) * SBUF + (lrow + 32 * (q)) * GP + lkc) = RA[q]; *(u32x4*)(sB + (ST) * SBUF + (lrow + 32 * (q)) * GP + lkc) = RB[q]; } while (0)
; #define FLOAD(F, ST, ks) do { _Pragma("unroll") for (int a = 0; a < 2; ++a) { \
;     F[a] = *(const bf16x8*)(sB + (ST) * SBUF + (wn * 64 + a * 32 + r) * GP + (ks) * 16 + h * 8); \
;     F[2 + a] = *(const bf16x8*)(sA + (ST) * SBUF + (wm * 64 + a * 32 + r) * GP + (ks) * 16 + h * 8); } } while (0)
; #define FMMA(F) do { _Pragma("unroll") for (int a = 0; a < 2; ++a) _Pragma("unroll") for (int b = 0; b < 2; ++b) acc[a][b] = MFMA(F[a], F[2 + b], acc[a][b]); } while (0)
; template <bool MIDK, class AP, class EPI>
; DI void gemm_tile(const AP& ap, const u16* __restrict__ W, int ldw, int K, int m0, int n0, const EPI& epi, char* smem, float r0, float r1, int tid, bool dry) {
;     ...
;   for (int kt = 0; kt < nk; kt += 2) {
;     const bool l3 = kt + 3 < nk, s2 = kt + 2 < nk, l4 = kt + 4 < nk;
;     FLOAD(f0, 0, 0); FLOAD(f1, 0, 1);
;     FMMA(f0); SSTOREQ(ra1, rb1, 1, 0); if (l3) GLOADQ(ra1, rb1, kt + 3, 0);
;     FLOAD(f0, 0, 2);
;     FMMA(f1); SSTOREQ(ra1, rb1, 1, 1); if (l3) GLOADQ(ra1, rb1, kt + 3, 1);
;     FLOAD(f1, 0, 3);
;     FMMA(f0); SSTOREQ(ra1, rb1, 1, 2); if (l3) GLOADQ(ra1, rb1, kt + 3, 2);
;     FMMA(f1); SSTOREQ(ra1, rb1, 1, 3); if (l3) GLOADQ(ra1, rb1, kt + 3, 3);
;     __syncthreads();
;     FLOAD(f0, 1, 0); FLOAD(f1, 1, 1);
;     FMMA(f0); if (s2) SSTOREQ(ra0, rb0, 0, 0); if (l4) GLOADQ(ra0, rb0, kt + 4, 0);
;     FLOAD(f0, 1, 2);
;     FMMA(f1); if (s2) SSTOREQ(ra0, rb0, 0, 1); if (l4) GLOADQ(ra0, rb0, kt + 4, 1);
;     FLOAD(f1, 1, 3);
;     FMMA(f0); if (s2) SSTOREQ(ra0, rb0, 0, 2); if (l4) GLOADQ(ra0, rb0, kt + 4, 2);
;     FMMA(f1); if (s2) SSTOREQ(ra0, rb0, 0, 3); if (l4) GLOADQ(ra0, rb0, kt + 4, 3);
;     if (MIDK && kt == 6) {
; #pragma unroll
;       for (int a = 0; a < 2; ++a)
; #pragma unroll
;         for (int i = 0; i < 16; ++i) { acc[a][0][i] *= r0; acc[a][1][i] *= r1; }
;     }
;     __syncthreads();
;   }
	ds_read_b128 v[208:211], v167 offset:55296
	ds_read_b128 v[236:239], v132 offset:36864
	v_mfma_f32_32x32x16_bf16 v[0:15], v[212:215], v[246:249], v[0:15]
	ds_read_b128 v[212:215], v132 offset:41472
	ds_read_b128 v[246:249], v167 offset:59904
	s_waitcnt lgkmcnt(2)
	v_mfma_f32_32x32x16_bf16 v[48:63], v[208:211], v[236:239], v[48:63]
	s_waitcnt lgkmcnt(1)
	v_mfma_f32_32x32x16_bf16 v[32:47], v[208:211], v[212:215], v[32:47]
	ds_read_b128 v[208:211], v167 offset:55328
	s_waitcnt lgkmcnt(1)
	v_mfma_f32_32x32x16_bf16 v[16:31], v[246:249], v[236:239], v[16:31]
	ds_read_b128 v[236:239], v132 offset:36896
	v_mfma_f32_32x32x16_bf16 v[0:15], v[246:249], v[212:215], v[0:15]
	ds_read_b128 v[246:249], v132 offset:41504
	ds_read_b128 v[212:215], v167 offset:59936
	s_waitcnt lgkmcnt(2)
	v_mfma_f32_32x32x16_bf16 v[48:63], v[208:211], v[236:239], v[48:63]
	s_waitcnt lgkmcnt(1)
	v_mfma_f32_32x32x16_bf16 v[32:47], v[208:211], v[246:249], v[32:47]
	ds_read_b128 v[208:211], v167 offset:55360
	s_waitcnt vmcnt(15)
	ds_write_b128 v130, v[150:153]
	s_waitcnt vmcnt(14)
	ds_write_b128 v130, v[158:161] offset:18432
	s_waitcnt lgkmcnt(3)
	v_mfma_f32_32x32x16_bf16 v[16:31], v[212:215], v[236:239], v[16:31]
	ds_read_b128 v[236:239], v132 offset:36928
	v_mfma_f32_32x32x16_bf16 v[0:15], v[212:215], v[246:249], v[0:15]
	ds_read_b128 v[212:215], v132 offset:41536
	ds_read_b128 v[246:249], v167 offset:59968
	s_waitcnt lgkmcnt(2)
	v_mfma_f32_32x32x16_bf16 v[48:63], v[208:211], v[236:239], v[48:63]
	s_waitcnt lgkmcnt(1)
	v_mfma_f32_32x32x16_bf16 v[32:47], v[208:211], v[212:215], v[32:47]
	ds_read_b128 v[208:211], v167 offset:55392
	s_waitcnt vmcnt(13)
	ds_write_b128 v130, v[104:107] offset:4608
	s_waitcnt vmcnt(12)
	ds_write_b128 v130, v[108:111] offset:23040
	s_waitcnt lgkmcnt(3)
	v_mfma_f32_32x32x16_bf16 v[16:31], v[246:249], v[236:239], v[16:31]
	ds_read_b128 v[236:239], v132 offset:36960
	v_mfma_f32_32x32x16_bf16 v[0:15], v[246:249], v[212:215], v[0:15]
	ds_read_b128 v[246:249], v132 offset:41568
	ds_read_b128 v[212:215], v167 offset:60000
	s_waitcnt lgkmcnt(2)
	v_mfma_f32_32x32x16_bf16 v[48:63], v[208:211], v[236:239], v[48:63]
	s_waitcnt lgkmcnt(1)
	v_mfma_f32_32x32x16_bf16 v[32:47], v[208:211], v[246:249], v[32:47]
	s_waitcnt vmcnt(11)
	ds_write_b128 v130, v[64:67] offset:9216
	s_waitcnt vmcnt(10)
	ds_write_b128 v130, v[68:71] offset:27648
	s_waitcnt vmcnt(9)
	ds_write_b128 v130, v[72:75] offset:13824
	s_waitcnt vmcnt(8)
	ds_write_b128 v130, v[76:79] offset:32256
	s_waitcnt lgkmcnt(0)
	s_barrier
	ds_read_b128 v[208:211], v167 offset:18432
	v_mfma_f32_32x32x16_bf16 v[16:31], v[212:215], v[236:239], v[16:31]
	ds_read_b128 v[236:239], v132
	v_mfma_f32_32x32x16_bf16 v[0:15], v[212:215], v[246:249], v[0:15]
	ds_read_b128 v[212:215], v132 offset:4608
	ds_read_b128 v[246:249], v167 offset:23040
	s_waitcnt lgkmcnt(2)
	v_mfma_f32_32x32x16_bf16 v[48:63], v[208:211], v[236:239], v[48:63]
	s_waitcnt lgkmcnt(1)
	v_mfma_f32_32x32x16_bf16 v[32:47], v[208:211], v[212:215], v[32:47]
	ds_read_b128 v[208:211], v167 offset:18464
	s_waitcnt lgkmcnt(1)
	v_mfma_f32_32x32x16_bf16 v[16:31], v[246:249], v[236:239], v[16:31]
	ds_read_b128 v[236:239], v132 offset:32
	v_mfma_f32_32x32x16_bf16 v[0:15], v[246:249], v[212:215], v[0:15]
	ds_read_b128 v[246:249], v132 offset:4640
	ds_read_b128 v[212:215], v167 offset:23072
	s_waitcnt lgkmcnt(2)
	v_mfma_f32_32x32x16_bf16 v[48:63], v[208:211], v[236:239], v[48:63]
	s_waitcnt lgkmcnt(1)
	v_mfma_f32_32x32x16_bf16 v[32:47], v[208:211], v[246:249], v[32:47]
	ds_read_b128 v[208:211], v167 offset:18496
	s_waitcnt vmcnt(7)
	ds_write_b128 v130, v[100:103] offset:36864
	s_waitcnt vmcnt(6)
	ds_write_b128 v130, v[112:115] offset:55296
	s_waitcnt lgkmcnt(3)
	v_mfma_f32_32x32x16_bf16 v[16:31], v[212:215], v[236:239], v[16:31]
	ds_read_b128 v[236:239], v132 offset:64
	v_mfma_f32_32x32x16_bf16 v[0:15], v[212:215], v[246:249], v[0:15]
	ds_read_b128 v[212:215], v132 offset:4672
	ds_read_b128 v[246:249], v167 offset:23104
	s_waitcnt lgkmcnt(2)
	v_mfma_f32_32x32x16_bf16 v[48:63], v[208:211], v[236:239], v[48:63]
	s_waitcnt lgkmcnt(1)
	v_mfma_f32_32x32x16_bf16 v[32:47], v[208:211], v[212:215], v[32:47]
	ds_read_b128 v[208:211], v167 offset:18528
	s_waitcnt vmcnt(5)
	ds_write_b128 v130, v[120:123] offset:41472
	s_waitcnt vmcnt(4)
	ds_write_b128 v130, v[124:127] offset:59904
	s_waitcnt lgkmcnt(3)
	v_mfma_f32_32x32x16_bf16 v[16:31], v[246:249], v[236:239], v[16:31]
	ds_read_b128 v[236:239], v132 offset:96
	v_mfma_f32_32x32x16_bf16 v[0:15], v[246:249], v[212:215], v[0:15]
	ds_read_b128 v[246:249], v132 offset:4704
	ds_read_b128 v[212:215], v167 offset:23136
	s_waitcnt lgkmcnt(2)
	v_mfma_f32_32x32x16_bf16 v[48:63], v[208:211], v[236:239], v[48:63]
	s_waitcnt lgkmcnt(1)
	v_mfma_f32_32x32x16_bf16 v[32:47], v[208:211], v[246:249], v[32:47]
	s_waitcnt vmcnt(3)
	ds_write_b128 v130, v[80:83] offset:46080
	s_waitcnt vmcnt(2)
	ds_write_b128 v130, v[84:87] offset:64512
	s_waitcnt vmcnt(1)
	ds_write_b128 v130, v[88:91] offset:50688
	s_waitcnt vmcnt(0)
	ds_write_b128 v131, v[92:95] offset:13824
	s_waitcnt lgkmcnt(0)
	s_barrier
; template <bool MIDK, class AP, class EPI>
; DI void gemm_tile(const AP& ap, const u16* __restrict__ W, int ldw, int K, int m0, int n0, const EPI& epi, char* smem, float r0, float r1, int tid, bool dry) {
;     ...
;   for (int kt = 0; kt < nk; kt += 2) {
;     const bool l3 = kt + 3 < nk, s2 = kt + 2 < nk, l4 = kt + 4 < nk;
;     FLOAD(f0, 0, 0); FLOAD(f1, 0, 1);
;     FMMA(f0); SSTOREQ(ra1, rb1, 1, 0); if (l3) GLOADQ(ra1, rb1, kt + 3, 0);
;     FLOAD(f0, 0, 2);
;     FMMA(f1); SSTOREQ(ra1, rb1, 1, 1); if (l3) GLOADQ(ra1, rb1, kt + 3, 1);
;     FLOAD(f1, 0, 3);
;     FMMA(f0); SSTOREQ(ra1, rb1, 1, 2); if (l3) GLOADQ(ra1, rb1, kt + 3, 2);
;     FMMA(f1); SSTOREQ(ra1, rb1, 1, 3); if (l3) GLOADQ(ra1, rb1, kt + 3, 3);
;     __syncthreads();
;     FLOAD(f0, 1, 0); FLOAD(f1, 1, 1);
;     FMMA(f0); if (s2) SSTOREQ(ra0, rb0, 0, 0); if (l4) GLOADQ(ra0, rb0, kt + 4, 0);
;     FLOAD(f0, 1, 2);
;     FMMA(f1); if (s2) SSTOREQ(ra0, rb0, 0, 1); if (l4) GLOADQ(ra0, rb0, kt + 4, 1);
;     FLOAD(f1, 1, 3);
;     FMMA(f0); if (s2) SSTOREQ(ra0, rb0, 0, 2); if (l4) GLOADQ(ra0, rb0, kt + 4, 2);
;     FMMA(f1); if (s2) SSTOREQ(ra0, rb0, 0, 3); if (l4) GLOADQ(ra0, rb0, kt + 4, 3);
;     if (MIDK && kt == 6) {
; #pragma unroll
;       for (int a = 0; a < 2; ++a)
; #pragma unroll
;         for (int i = 0; i < 16; ++i) { acc[a][0][i] *= r0; acc[a][1][i] *= r1; }
;     }
;     __syncthreads();
;   }
;   DI void operator()(f32x16 (&acc)[2][2], int nb, int mb, int lane, u16* wl) const {
;     const int r = lane & 31, h = lane >> 5, mbl = mb & 127;
;     float* wf = (float*)wl;
; #pragma unroll
;     for (int fi = 0; fi < 2; ++fi) {
; #pragma unroll
;       for (int ti = 0; ti < 2; ++ti) {
;         const float sc = ti == 0 ? fin0 : fin1;
; #pragma unroll
;         for (int g4 = 0; g4 < 4; ++g4) {
;           float4 o = make_float4(acc[fi][ti][4 * g4] * sc, acc[fi][ti][4 * g4 + 1] * sc, acc[fi][ti][4 * g4 + 2] * sc, acc[fi][ti][4 * g4 + 3] * sc);
;           *(float4*)(wf + (ti * 32 + r) * 36 + 8 * g4 + 4 * h) = o;
;         }
;       }
;       WAVE_LDS_FENCE();
; #pragma unroll
;       for (int it = 0; it < 8; ++it) {
;         const int row = it * 8 + (lane >> 3), ch = lane & 7;
;         const float4 a = *(const float4*)(wf + row * 36 + ch * 4);
;         const int trow = mbl + row;
;         if (trow >= minrow) {
;           const size_t off = (size_t)trow * 1024 + nb + fi * 32 + ch * 4;
	ds_read_b128 v[208:211], v167 offset:55296
	v_mfma_f32_32x32x16_bf16 v[16:31], v[212:215], v[236:239], v[16:31]
	ds_read_b128 v[236:239], v132 offset:36864
	v_mfma_f32_32x32x16_bf16 v[0:15], v[212:215], v[246:249], v[0:15]
	ds_read_b128 v[212:215], v132 offset:41472
	ds_read_b128 v[246:249], v167 offset:59904
	s_waitcnt lgkmcnt(2)
	v_mfma_f32_32x32x16_bf16 v[48:63], v[208:211], v[236:239], v[48:63]
	s_waitcnt lgkmcnt(1)
	v_mfma_f32_32x32x16_bf16 v[32:47], v[208:211], v[212:215], v[32:47]
	ds_read_b128 v[208:211], v167 offset:55328
	s_waitcnt lgkmcnt(1)
	v_mfma_f32_32x32x16_bf16 v[16:31], v[246:249], v[236:239], v[16:31]
	ds_read_b128 v[236:239], v132 offset:36896
	v_mfma_f32_32x32x16_bf16 v[0:15], v[246:249], v[212:215], v[0:15]
	ds_read_b128 v[246:249], v132 offset:41504
	ds_read_b128 v[212:215], v167 offset:59936
	s_waitcnt lgkmcnt(2)
	v_mfma_f32_32x32x16_bf16 v[48:63], v[208:211], v[236:239], v[48:63]
	s_waitcnt lgkmcnt(1)
	v_mfma_f32_32x32x16_bf16 v[32:47], v[208:211], v[246:249], v[32:47]
	ds_read_b128 v[208:211], v167 offset:55360
	s_waitcnt lgkmcnt(1)
	v_mfma_f32_32x32x16_bf16 v[16:31], v[212:215], v[236:239], v[16:31]
	ds_read_b128 v[236:239], v132 offset:36928
	v_mfma_f32_32x32x16_bf16 v[0:15], v[212:215], v[246:249], v[0:15]
	ds_read_b128 v[212:215], v132 offset:41536
	ds_read_b128 v[246:249], v167 offset:59968
	s_waitcnt lgkmcnt(2)
	v_mfma_f32_32x32x16_bf16 v[48:63], v[208:211], v[236:239], v[48:63]
	s_waitcnt lgkmcnt(1)
	v_mfma_f32_32x32x16_bf16 v[32:47], v[208:211], v[212:215], v[32:47]
	ds_read_b128 v[208:211], v167 offset:55392
	s_waitcnt lgkmcnt(1)
	v_mfma_f32_32x32x16_bf16 v[16:31], v[246:249], v[236:239], v[16:31]
	ds_read_b128 v[236:239], v132 offset:36960
	v_mfma_f32_32x32x16_bf16 v[0:15], v[246:249], v[212:215], v[0:15]
	ds_read_b128 v[246:249], v132 offset:41568
	ds_read_b128 v[212:215], v167 offset:60000
	s_waitcnt lgkmcnt(2)
	v_mfma_f32_32x32x16_bf16 v[48:63], v[208:211], v[236:239], v[48:63]
	s_waitcnt lgkmcnt(1)
	v_mfma_f32_32x32x16_bf16 v[32:47], v[208:211], v[246:249], v[32:47]
	s_waitcnt lgkmcnt(0)
	s_barrier
	v_mfma_f32_32x32x16_bf16 v[16:31], v[212:215], v[236:239], v[16:31]
	v_mfma_f32_32x32x16_bf16 v[0:15], v[212:215], v[246:249], v[0:15]
	s_cbranch_vccnz .LBB0_386
	s_nop 3
	s_cmp_lg_u32 s23, 0
	s_cbranch_scc1 .Lepi_down_orig
	ds_write_b128 v128, v[48:51]
	ds_write_b128 v128, v[52:55] offset:32
	ds_write_b128 v128, v[56:59] offset:64
	ds_write_b128 v128, v[60:63] offset:96
	ds_write_b128 v184, v[32:35]
	ds_write_b128 v184, v[36:39] offset:32
	ds_write_b128 v184, v[40:43] offset:64
	ds_write_b128 v184, v[44:47] offset:96
	s_waitcnt lgkmcnt(0)
	v_or_b32_e32 v64, s4, v133
	v_add_lshl_u32 v36, v64, v169, 2
	global_load_dwordx4 v[68:71], v36, s[2:3]
	ds_read_b128 v[100:103], v185
	v_add_lshl_u32 v37, v64, v171, 2
	global_load_dwordx4 v[72:75], v37, s[2:3]
	ds_read_b128 v[104:107], v185 offset:1152
	v_add_lshl_u32 v38, v64, v173, 2
	global_load_dwordx4 v[76:79], v38, s[2:3]
	ds_read_b128 v[108:111], v185 offset:2304
	v_add_lshl_u32 v39, v64, v175, 2
	global_load_dwordx4 v[80:83], v39, s[2:3]
	ds_read_b128 v[112:115], v185 offset:3456
	v_add_lshl_u32 v40, v64, v177, 2
	global_load_dwordx4 v[84:87], v40, s[2:3]
	ds_read_b128 v[116:119], v185 offset:4608
	v_add_lshl_u32 v41, v64, v179, 2
	global_load_dwordx4 v[88:91], v41, s[2:3]
	ds_read_b128 v[120:123], v185 offset:5760
	v_add_lshl_u32 v42, v64, v181, 2
	global_load_dwordx4 v[92:95], v42, s[2:3]
	ds_read_b128 v[124:127], v185 offset:6912
	v_add_lshl_u32 v43, v64, v183, 2
	global_load_dwordx4 v[96:99], v43, s[2:3]
	ds_read_b128 v[44:47], v185 offset:8064
	s_waitcnt vmcnt(0) lgkmcnt(0)
	v_pk_add_f32 v[68:69], v[100:101], v[68:69]
	v_pk_add_f32 v[70:71], v[102:103], v[70:71]
	global_store_dwordx4 v36, v[68:71], s[2:3]
	v_pk_add_f32 v[72:73], v[104:105], v[72:73]
	v_pk_add_f32 v[74:75], v[106:107], v[74:75]
	global_store_dwordx4 v37, v[72:75], s[2:3]
	v_pk_add_f32 v[76:77], v[108:109], v[76:77]
	v_pk_add_f32 v[78:79], v[110:111], v[78:79]
	global_store_dwordx4 v38, v[76:79], s[2:3]
	v_pk_add_f32 v[80:81], v[112:113], v[80:81]
	v_pk_add_f32 v[82:83], v[114:115], v[82:83]
	global_store_dwordx4 v39, v[80:83], s[2:3]
	v_pk_add_f32 v[84:85], v[116:117], v[84:85]
	v_pk_add_f32 v[86:87], v[118:119], v[86:87]
	global_store_dwordx4 v40, v[84:87], s[2:3]
	v_pk_add_f32 v[88:89], v[120:121], v[88:89]
	v_pk_add_f32 v[90:91], v[122:123], v[90:91]
	global_store_dwordx4 v41, v[88:91], s[2:3]
	v_pk_add_f32 v[92:93], v[124:125], v[92:93]
	v_pk_add_f32 v[94:95], v[126:127], v[94:95]
	global_store_dwordx4 v42, v[92:95], s[2:3]
	v_pk_add_f32 v[96:97], v[44:45], v[96:97]
	v_pk_add_f32 v[98:99], v[46:47], v[98:99]
	global_store_dwordx4 v43, v[96:99], s[2:3]
	s_waitcnt lgkmcnt(0)
	ds_write_b128 v128, v[16:19]
	ds_write_b128 v128, v[20:23] offset:32
	ds_write_b128 v128, v[24:27] offset:64
	ds_write_b128 v128, v[28:31] offset:96
	ds_write_b128 v184, v[0:3]
	ds_write_b128 v184, v[4:7] offset:32
	ds_write_b128 v184, v[8:11] offset:64
	ds_write_b128 v184, v[12:15] offset:96
	s_waitcnt lgkmcnt(0)
	global_load_dwordx4 v[68:71], v36, s[2:3] offset:128
	ds_read_b128 v[100:103], v185
	global_load_dwordx4 v[72:75], v37, s[2:3] offset:128
	ds_read_b128 v[104:107], v185 offset:1152
	global_load_dwordx4 v[76:79], v38, s[2:3] offset:128
	ds_read_b128 v[108:111], v185 offset:2304
	global_load_dwordx4 v[80:83], v39, s[2:3] offset:128
	ds_read_b128 v[112:115], v185 offset:3456
	global_load_dwordx4 v[84:87], v40, s[2:3] offset:128
	ds_read_b128 v[116:119], v185 offset:4608
	global_load_dwordx4 v[88:91], v41, s[2:3] offset:128
	ds_read_b128 v[120:123], v185 offset:5760
	global_load_dwordx4 v[92:95], v42, s[2:3] offset:128
	ds_read_b128 v[124:127], v185 offset:6912
	global_load_dwordx4 v[96:99], v43, s[2:3] offset:128
	ds_read_b128 v[44:47], v185 offset:8064
	s_waitcnt vmcnt(0) lgkmcnt(0)
	v_pk_add_f32 v[68:69], v[100:101], v[68:69]
	v_pk_add_f32 v[70:71], v[102:103], v[70:71]
	global_store_dwordx4 v36, v[68:71], s[2:3] offset:128
	v_pk_add_f32 v[72:73], v[104:105], v[72:73]
	v_pk_add_f32 v[74:75], v[106:107], v[74:75]
	global_store_dwordx4 v37, v[72:75], s[2:3] offset:128
	v_pk_add_f32 v[76:77], v[108:109], v[76:77]
	v_pk_add_f32 v[78:79], v[110:111], v[78:79]
	global_store_dwordx4 v38, v[76:79], s[2:3] offset:128
	v_pk_add_f32 v[80:81], v[112:113], v[80:81]
	v_pk_add_f32 v[82:83], v[114:115], v[82:83]
	global_store_dwordx4 v39, v[80:83], s[2:3] offset:128
	v_pk_add_f32 v[84:85], v[116:117], v[84:85]
	v_pk_add_f32 v[86:87], v[118:119], v[86:87]
	global_store_dwordx4 v40, v[84:87], s[2:3] offset:128
	v_pk_add_f32 v[88:89], v[120:121], v[88:89]
	v_pk_add_f32 v[90:91], v[122:123], v[90:91]
	global_store_dwordx4 v41, v[88:91], s[2:3] offset:128
	v_pk_add_f32 v[92:93], v[124:125], v[92:93]
	v_pk_add_f32 v[94:95], v[126:127], v[94:95]
	global_store_dwordx4 v42, v[92:95], s[2:3] offset:128
	v_pk_add_f32 v[96:97], v[44:45], v[96:97]
	v_pk_add_f32 v[98:99], v[46:47], v[98:99]
	global_store_dwordx4 v43, v[96:99], s[2:3] offset:128
	s_branch .LBB0_386
